# speedup vs baseline: 1.0130x; 1.0064x over previous
; #define STAGE_A(b, h, kt) { const u16* ap_ = A + (size_t)((h) * ahalf + (unsigned)(kt) * 64u); glds16(ap_ + ao0, l0 + SA_(b, h)); glds16(ap_ + ao1, l0 + SA_(b, h) + 8192); }
; #define STAGE_B(b, h, kt) { const u16* bp_ = ((h) ? B1 : B0) + (unsigned)(kt) * 64u; glds16(bp_ + bo0, l0 + SB_(b, h)); glds16(bp_ + bo1, l0 + SB_(b, h) + 8192); }
; #define LDA(dst, b, h) _Pragma("unroll") for (int m = 0; m < 4; ++m) _Pragma("unroll") for (int k = 0; k < 2; ++k) \
;     dst[m][k] = *(const bf16x8*)(lds + SA_(b, h) + lds_byte(wr * 64 + m * 16 + fr, k * 32 + fq * 8));
; #define LDB(dst, b, h) _Pragma("unroll") for (int n = 0; n < 2; ++n) _Pragma("unroll") for (int k = 0; k < 2; ++k) \
;     dst[n][k] = *(const bf16x8*)(lds + SB_(b, h) + lds_byte(wc * 32 + n * 16 + fr, k * 32 + fq * 8));
; #define MMA(ai, bj, At_, Bt_) { __builtin_amdgcn_s_setprio(1); \
;     _Pragma("unroll") for (int m = 0; m < 4; ++m) _Pragma("unroll") for (int n = 0; n < 2; ++n) _Pragma("unroll") for (int k = 0; k < 2; ++k) \
;       acc[ai][bj][m][n] = MFMA16(Bt_[n][k], At_[m][k], acc[ai][bj][m][n]); \
;     __builtin_amdgcn_s_setprio(0); }
; #define WAIT_V(n) asm volatile("s_waitcnt vmcnt(" #n ")" ::: "memory");
; #define WAIT_L(n) asm volatile("s_waitcnt lgkmcnt(" #n ")" ::: "memory");
; #define BAR __builtin_amdgcn_s_barrier();
; #define SCHED __builtin_amdgcn_sched_barrier(0);
; DI void gemm256(const u16* __restrict__ A, int lda, const u16* __restrict__ B0, const u16* __restrict__ B1, int ldb, int nt, acc_t& acc, char* lds) {
;     ...
;   for (int t = 0; t < nt - 2; t += 2) {
;     LDB(Bq0, 0, 0) SCHED LDA(At, 0, 0) STAGE_A(1, 1, t + 1)
;     WAIT_L(8) BAR WAIT_L(0) MMA(0, 0, At, Bq0) BAR SCHED
;     LDB(Bq1, 0, 1) STAGE_B(0, 0, t + 2)
;     BAR WAIT_L(0) MMA(0, 1, At, Bq1) BAR
;     LDA(At, 0, 1) STAGE_A(0, 0, t + 2)
;     BAR WAIT_L(0) MMA(1, 0, At, Bq0) BAR SCHED
;     STAGE_B(0, 1, t + 2)
;     WAIT_V(6) BAR MMA(1, 1, At, Bq1) BAR
;     LDB(Bq0, 1, 0) SCHED LDA(At, 1, 0) STAGE_A(0, 1, t + 2)
;     WAIT_L(8) BAR WAIT_L(0) MMA(0, 0, At, Bq0) BAR SCHED
.LBB0_168:
	ds_read_b128 v[142:145], v166
	ds_read_b128 v[170:173], v166 offset:1024
	ds_read_b128 v[174:177], v166 offset:2048
	ds_read_b128 v[178:181], v166 offset:3072
	v_add_u32_e32 v167, 0xc000, v149
	v_lshl_add_u64 v[222:223], s[22:23], 0, v[136:137]
	v_readfirstlane_b32 s7, v167
	v_lshl_add_u64 v[168:169], v[222:223], 0, s[0:1]
	s_mov_b32 m0, s7
	ds_read_b128 v[182:185], v148
	ds_read_b128 v[186:189], v148 offset:1024
	ds_read_b128 v[190:193], v147
	ds_read_b128 v[194:197], v147 offset:1024
	ds_read_b128 v[198:201], v146
	ds_read_b128 v[202:205], v146 offset:1024
	ds_read_b128 v[206:209], v141
	ds_read_b128 v[210:213], v141 offset:1024
	global_load_lds_dwordx4 v[168:169], off
	v_add_u32_e32 v168, 0xe000, v149
	v_lshl_add_u64 v[224:225], s[22:23], 0, v[138:139]
	v_readfirstlane_b32 s7, v168
	v_lshl_add_u64 v[216:217], v[224:225], 0, s[0:1]
	s_mov_b32 m0, s7
	s_nop 0
	global_load_lds_dwordx4 v[216:217], off
	s_waitcnt lgkmcnt(8)
	s_barrier
	s_waitcnt lgkmcnt(0)
	s_waitcnt lgkmcnt(0)
	v_mfma_f32_16x16x32_bf16 v[126:129], v[142:145], v[182:185], v[126:129]
	v_mfma_f32_16x16x32_bf16 v[122:125], v[174:177], v[182:185], v[122:125]
	v_mfma_f32_16x16x32_bf16 v[118:121], v[142:145], v[190:193], v[118:121]
	v_mfma_f32_16x16x32_bf16 v[114:117], v[174:177], v[190:193], v[114:117]
	v_mfma_f32_16x16x32_bf16 v[110:113], v[142:145], v[198:201], v[110:113]
	v_mfma_f32_16x16x32_bf16 v[106:109], v[174:177], v[198:201], v[106:109]
	v_mfma_f32_16x16x32_bf16 v[102:105], v[142:145], v[206:209], v[102:105]
	v_mfma_f32_16x16x32_bf16 v[98:101], v[174:177], v[206:209], v[98:101]
	v_mfma_f32_16x16x32_bf16 v[126:129], v[170:173], v[186:189], v[126:129]
	v_mfma_f32_16x16x32_bf16 v[122:125], v[178:181], v[186:189], v[122:125]
	v_mfma_f32_16x16x32_bf16 v[118:121], v[170:173], v[194:197], v[118:121]
	v_mfma_f32_16x16x32_bf16 v[114:117], v[178:181], v[194:197], v[114:117]
	v_mfma_f32_16x16x32_bf16 v[110:113], v[170:173], v[202:205], v[110:113]
	v_mfma_f32_16x16x32_bf16 v[106:109], v[178:181], v[202:205], v[106:109]
	v_mfma_f32_16x16x32_bf16 v[102:105], v[170:173], v[210:213], v[102:105]
	v_mfma_f32_16x16x32_bf16 v[98:101], v[178:181], v[210:213], v[98:101]
	s_barrier
	v_lshl_add_u64 v[238:239], s[22:23], 0, v[132:133]
	v_readfirstlane_b32 s7, v151
	v_lshl_add_u64 v[240:241], v[238:239], 0, s[28:29]
	s_mov_b32 m0, s7
	ds_read_b128 v[216:219], v165
	ds_read_b128 v[226:229], v165 offset:1024
	ds_read_b128 v[230:233], v165 offset:2048
	ds_read_b128 v[234:237], v165 offset:3072
	global_load_lds_dwordx4 v[240:241], off
	v_lshl_add_u64 v[240:241], s[22:23], 0, v[134:135]
	v_readfirstlane_b32 s7, v152
	v_lshl_add_u64 v[242:243], v[240:241], 0, s[28:29]
	s_mov_b32 m0, s7
	s_nop 0
	global_load_lds_dwordx4 v[242:243], off
	s_barrier
	s_waitcnt lgkmcnt(0)
	s_waitcnt lgkmcnt(0)
	v_mfma_f32_16x16x32_bf16 v[94:97], v[216:219], v[182:185], v[94:97]
	v_mfma_f32_16x16x32_bf16 v[90:93], v[230:233], v[182:185], v[90:93]
	v_mfma_f32_16x16x32_bf16 v[86:89], v[216:219], v[190:193], v[86:89]
	v_mfma_f32_16x16x32_bf16 v[82:85], v[230:233], v[190:193], v[82:85]
	v_mfma_f32_16x16x32_bf16 v[78:81], v[216:219], v[198:201], v[78:81]
	v_mfma_f32_16x16x32_bf16 v[74:77], v[230:233], v[198:201], v[74:77]
	v_mfma_f32_16x16x32_bf16 v[70:73], v[216:219], v[206:209], v[70:73]
	v_mfma_f32_16x16x32_bf16 v[66:69], v[230:233], v[206:209], v[66:69]
	v_mfma_f32_16x16x32_bf16 v[94:97], v[226:229], v[186:189], v[94:97]
	v_mfma_f32_16x16x32_bf16 v[90:93], v[234:237], v[186:189], v[90:93]
	v_mfma_f32_16x16x32_bf16 v[86:89], v[226:229], v[194:197], v[86:89]
	v_mfma_f32_16x16x32_bf16 v[82:85], v[234:237], v[194:197], v[82:85]
	v_mfma_f32_16x16x32_bf16 v[78:81], v[226:229], v[202:205], v[78:81]
	v_mfma_f32_16x16x32_bf16 v[74:77], v[234:237], v[202:205], v[74:77]
	v_mfma_f32_16x16x32_bf16 v[70:73], v[226:229], v[210:213], v[70:73]
	v_mfma_f32_16x16x32_bf16 v[66:69], v[234:237], v[210:213], v[66:69]
	v_readfirstlane_b32 s7, v149
	v_lshl_add_u64 v[242:243], v[222:223], 0, s[20:21]
	s_mov_b32 m0, s7
	v_readfirstlane_b32 s7, v153
	s_barrier
	ds_read_b128 v[182:185], v148 offset:16384
	ds_read_b128 v[186:189], v148 offset:17408
	ds_read_b128 v[190:193], v147 offset:16384
	ds_read_b128 v[194:197], v147 offset:17408
	ds_read_b128 v[198:201], v146 offset:16384
	ds_read_b128 v[202:205], v146 offset:17408
	ds_read_b128 v[206:209], v141 offset:16384
	ds_read_b128 v[210:213], v141 offset:17408
	global_load_lds_dwordx4 v[242:243], off
	v_lshl_add_u64 v[242:243], v[224:225], 0, s[20:21]
	s_mov_b32 m0, s7
	s_nop 0
	global_load_lds_dwordx4 v[242:243], off
	s_barrier
	s_waitcnt lgkmcnt(0)
	s_waitcnt lgkmcnt(0)
	v_mfma_f32_16x16x32_bf16 v[60:63], v[142:145], v[182:185], v[60:63]
	v_mfma_f32_16x16x32_bf16 v[56:59], v[174:177], v[182:185], v[56:59]
	v_mfma_f32_16x16x32_bf16 v[52:55], v[142:145], v[190:193], v[52:55]
	v_mfma_f32_16x16x32_bf16 v[48:51], v[174:177], v[190:193], v[48:51]
	v_mfma_f32_16x16x32_bf16 v[44:47], v[142:145], v[198:201], v[44:47]
	v_mfma_f32_16x16x32_bf16 v[40:43], v[174:177], v[198:201], v[40:43]
	v_mfma_f32_16x16x32_bf16 v[36:39], v[142:145], v[206:209], v[36:39]
	v_mfma_f32_16x16x32_bf16 v[32:35], v[174:177], v[206:209], v[32:35]
	v_mfma_f32_16x16x32_bf16 v[60:63], v[170:173], v[186:189], v[60:63]
	v_mfma_f32_16x16x32_bf16 v[56:59], v[178:181], v[186:189], v[56:59]
	v_mfma_f32_16x16x32_bf16 v[52:55], v[170:173], v[194:197], v[52:55]
	v_mfma_f32_16x16x32_bf16 v[48:51], v[178:181], v[194:197], v[48:51]
	v_mfma_f32_16x16x32_bf16 v[44:47], v[170:173], v[202:205], v[44:47]
	v_mfma_f32_16x16x32_bf16 v[40:43], v[178:181], v[202:205], v[40:43]
	v_mfma_f32_16x16x32_bf16 v[36:39], v[170:173], v[210:213], v[36:39]
	v_mfma_f32_16x16x32_bf16 v[32:35], v[178:181], v[210:213], v[32:35]
	s_barrier
; #define STAGE_A(b, h, kt) { const u16* ap_ = A + (size_t)((h) * ahalf + (unsigned)(kt) * 64u); glds16(ap_ + ao0, l0 + SA_(b, h)); glds16(ap_ + ao1, l0 + SA_(b, h) + 8192); }
; #define STAGE_B(b, h, kt) { const u16* bp_ = ((h) ? B1 : B0) + (unsigned)(kt) * 64u; glds16(bp_ + bo0, l0 + SB_(b, h)); glds16(bp_ + bo1, l0 + SB_(b, h) + 8192); }
; #define LDA(dst, b, h) _Pragma("unroll") for (int m = 0; m < 4; ++m) _Pragma("unroll") for (int k = 0; k < 2; ++k) \
;     dst[m][k] = *(const bf16x8*)(lds + SA_(b, h) + lds_byte(wr * 64 + m * 16 + fr, k * 32 + fq * 8));
; #define LDB(dst, b, h) _Pragma("unroll") for (int n = 0; n < 2; ++n) _Pragma("unroll") for (int k = 0; k < 2; ++k) \
;     dst[n][k] = *(const bf16x8*)(lds + SB_(b, h) + lds_byte(wc * 32 + n * 16 + fr, k * 32 + fq * 8));
; #define MMA(ai, bj, At_, Bt_) { __builtin_amdgcn_s_setprio(1); \
;     _Pragma("unroll") for (int m = 0; m < 4; ++m) _Pragma("unroll") for (int n = 0; n < 2; ++n) _Pragma("unroll") for (int k = 0; k < 2; ++k) \
;       acc[ai][bj][m][n] = MFMA16(Bt_[n][k], At_[m][k], acc[ai][bj][m][n]); \
;     __builtin_amdgcn_s_setprio(0); }
; #define WAIT_V(n) asm volatile("s_waitcnt vmcnt(" #n ")" ::: "memory");
; #define WAIT_L(n) asm volatile("s_waitcnt lgkmcnt(" #n ")" ::: "memory");
; #define BAR __builtin_amdgcn_s_barrier();
; #define SCHED __builtin_amdgcn_sched_barrier(0);
; DI void gemm256(const u16* __restrict__ A, int lda, const u16* __restrict__ B0, const u16* __restrict__ B1, int ldb, int nt, acc_t& acc, char* lds) {
;     ...
;     WAIT_V(6) BAR MMA(1, 1, At, Bq1) BAR
;     LDB(Bq0, 1, 0) SCHED LDA(At, 1, 0) STAGE_A(0, 1, t + 2)
;     WAIT_L(8) BAR WAIT_L(0) MMA(0, 0, At, Bq0) BAR SCHED
;     LDB(Bq1, 1, 1) STAGE_B(1, 0, t + 3)
;     BAR WAIT_L(0) MMA(0, 1, At, Bq1) BAR
;     LDA(At, 1, 1) STAGE_A(1, 0, t + 3)
;     BAR WAIT_L(0) MMA(1, 0, At, Bq0) BAR SCHED
;     STAGE_B(1, 1, t + 3)
;     WAIT_V(6) BAR MMA(1, 1, At, Bq1) BAR
	v_readfirstlane_b32 s7, v154
	v_lshl_add_u64 v[142:143], v[238:239], 0, s[36:37]
	s_mov_b32 m0, s7
	v_readfirstlane_b32 s7, v156
	global_load_lds_dwordx4 v[142:143], off
	v_lshl_add_u64 v[142:143], v[240:241], 0, s[36:37]
	s_mov_b32 m0, s7
	s_nop 0
	global_load_lds_dwordx4 v[142:143], off
	s_waitcnt vmcnt(6)
	s_barrier
	v_mfma_f32_16x16x32_bf16 v[28:31], v[216:219], v[182:185], v[28:31]
	v_mfma_f32_16x16x32_bf16 v[24:27], v[230:233], v[182:185], v[24:27]
	v_mfma_f32_16x16x32_bf16 v[20:23], v[216:219], v[190:193], v[20:23]
	v_mfma_f32_16x16x32_bf16 v[16:19], v[230:233], v[190:193], v[16:19]
	v_mfma_f32_16x16x32_bf16 v[12:15], v[216:219], v[198:201], v[12:15]
	v_mfma_f32_16x16x32_bf16 v[8:11], v[230:233], v[198:201], v[8:11]
	v_mfma_f32_16x16x32_bf16 v[4:7], v[216:219], v[206:209], v[4:7]
	v_mfma_f32_16x16x32_bf16 v[0:3], v[230:233], v[206:209], v[0:3]
	v_mfma_f32_16x16x32_bf16 v[28:31], v[226:229], v[186:189], v[28:31]
	v_mfma_f32_16x16x32_bf16 v[24:27], v[234:237], v[186:189], v[24:27]
	v_mfma_f32_16x16x32_bf16 v[20:23], v[226:229], v[194:197], v[20:23]
	v_mfma_f32_16x16x32_bf16 v[16:19], v[234:237], v[194:197], v[16:19]
	v_mfma_f32_16x16x32_bf16 v[12:15], v[226:229], v[202:205], v[12:15]
	v_mfma_f32_16x16x32_bf16 v[8:11], v[234:237], v[202:205], v[8:11]
	v_mfma_f32_16x16x32_bf16 v[4:7], v[226:229], v[210:213], v[4:7]
	v_mfma_f32_16x16x32_bf16 v[0:3], v[234:237], v[210:213], v[0:3]
	s_barrier
	ds_read_b128 v[142:145], v155
	ds_read_b128 v[170:173], v155 offset:1024
	ds_read_b128 v[174:177], v155 offset:2048
	ds_read_b128 v[178:181], v155 offset:3072
	v_readfirstlane_b32 s7, v157
	v_lshl_add_u64 v[216:217], v[222:223], 0, s[24:25]
	s_mov_b32 m0, s7
	v_readfirstlane_b32 s7, v158
	ds_read_b128 v[182:185], v148 offset:32768
	ds_read_b128 v[186:189], v148 offset:33792
	ds_read_b128 v[190:193], v147 offset:32768
	ds_read_b128 v[194:197], v147 offset:33792
	ds_read_b128 v[198:201], v146 offset:32768
	ds_read_b128 v[202:205], v146 offset:33792
	ds_read_b128 v[206:209], v141 offset:32768
	ds_read_b128 v[210:213], v141 offset:33792
	global_load_lds_dwordx4 v[216:217], off
	v_lshl_add_u64 v[216:217], v[224:225], 0, s[24:25]
	s_mov_b32 m0, s7
	s_nop 0
	global_load_lds_dwordx4 v[216:217], off
	s_waitcnt lgkmcnt(8)
	s_barrier
	s_waitcnt lgkmcnt(0)
	s_waitcnt lgkmcnt(0)
	v_mfma_f32_16x16x32_bf16 v[126:129], v[142:145], v[182:185], v[126:129]
	v_mfma_f32_16x16x32_bf16 v[122:125], v[174:177], v[182:185], v[122:125]
	v_mfma_f32_16x16x32_bf16 v[118:121], v[142:145], v[190:193], v[118:121]
	v_mfma_f32_16x16x32_bf16 v[114:117], v[174:177], v[190:193], v[114:117]
	v_mfma_f32_16x16x32_bf16 v[110:113], v[142:145], v[198:201], v[110:113]
	v_mfma_f32_16x16x32_bf16 v[106:109], v[174:177], v[198:201], v[106:109]
	v_mfma_f32_16x16x32_bf16 v[102:105], v[142:145], v[206:209], v[102:105]
	v_mfma_f32_16x16x32_bf16 v[98:101], v[174:177], v[206:209], v[98:101]
	v_mfma_f32_16x16x32_bf16 v[126:129], v[170:173], v[186:189], v[126:129]
	v_mfma_f32_16x16x32_bf16 v[122:125], v[178:181], v[186:189], v[122:125]
	v_mfma_f32_16x16x32_bf16 v[118:121], v[170:173], v[194:197], v[118:121]
	v_mfma_f32_16x16x32_bf16 v[114:117], v[178:181], v[194:197], v[114:117]
	v_mfma_f32_16x16x32_bf16 v[110:113], v[170:173], v[202:205], v[110:113]
	v_mfma_f32_16x16x32_bf16 v[106:109], v[178:181], v[202:205], v[106:109]
	v_mfma_f32_16x16x32_bf16 v[102:105], v[170:173], v[210:213], v[102:105]
	v_mfma_f32_16x16x32_bf16 v[98:101], v[178:181], v[210:213], v[98:101]
	s_barrier
	v_readfirstlane_b32 s7, v159
	v_lshl_add_u64 v[242:243], v[238:239], 0, s[26:27]
	s_mov_b32 m0, s7
	v_readfirstlane_b32 s7, v160
	ds_read_b128 v[216:219], v150
	ds_read_b128 v[226:229], v150 offset:1024
	ds_read_b128 v[230:233], v150 offset:2048
	ds_read_b128 v[234:237], v150 offset:3072
	global_load_lds_dwordx4 v[242:243], off
	v_lshl_add_u64 v[242:243], v[240:241], 0, s[26:27]
	s_mov_b32 m0, s7
	s_nop 0
	global_load_lds_dwordx4 v[242:243], off
	s_barrier
	s_waitcnt lgkmcnt(0)
	s_waitcnt lgkmcnt(0)
	v_mfma_f32_16x16x32_bf16 v[94:97], v[216:219], v[182:185], v[94:97]
	v_mfma_f32_16x16x32_bf16 v[90:93], v[230:233], v[182:185], v[90:93]
	v_mfma_f32_16x16x32_bf16 v[86:89], v[216:219], v[190:193], v[86:89]
	v_mfma_f32_16x16x32_bf16 v[82:85], v[230:233], v[190:193], v[82:85]
	v_mfma_f32_16x16x32_bf16 v[78:81], v[216:219], v[198:201], v[78:81]
	v_mfma_f32_16x16x32_bf16 v[74:77], v[230:233], v[198:201], v[74:77]
	v_mfma_f32_16x16x32_bf16 v[70:73], v[216:219], v[206:209], v[70:73]
	v_mfma_f32_16x16x32_bf16 v[66:69], v[230:233], v[206:209], v[66:69]
	v_mfma_f32_16x16x32_bf16 v[94:97], v[226:229], v[186:189], v[94:97]
	v_mfma_f32_16x16x32_bf16 v[90:93], v[234:237], v[186:189], v[90:93]
	v_mfma_f32_16x16x32_bf16 v[86:89], v[226:229], v[194:197], v[86:89]
	v_mfma_f32_16x16x32_bf16 v[82:85], v[234:237], v[194:197], v[82:85]
	v_mfma_f32_16x16x32_bf16 v[78:81], v[226:229], v[202:205], v[78:81]
	v_mfma_f32_16x16x32_bf16 v[74:77], v[234:237], v[202:205], v[74:77]
	v_mfma_f32_16x16x32_bf16 v[70:73], v[226:229], v[210:213], v[70:73]
	v_mfma_f32_16x16x32_bf16 v[66:69], v[234:237], v[210:213], v[66:69]
	v_readfirstlane_b32 s7, v161
	v_lshl_add_u64 v[222:223], v[222:223], 0, s[34:35]
	s_mov_b32 m0, s7
	v_readfirstlane_b32 s7, v162
	s_barrier
	ds_read_b128 v[182:185], v148 offset:49152
	ds_read_b128 v[186:189], v148 offset:50176
	ds_read_b128 v[190:193], v147 offset:49152
	ds_read_b128 v[194:197], v147 offset:50176
	ds_read_b128 v[198:201], v146 offset:49152
	ds_read_b128 v[202:205], v146 offset:50176
	ds_read_b128 v[206:209], v141 offset:49152
	ds_read_b128 v[210:213], v141 offset:50176
	global_load_lds_dwordx4 v[222:223], off
	v_lshl_add_u64 v[222:223], v[224:225], 0, s[34:35]
	s_mov_b32 m0, s7
	s_nop 0
	global_load_lds_dwordx4 v[222:223], off
	s_barrier
; #define STAGE_A(b, h, kt) { const u16* ap_ = A + (size_t)((h) * ahalf + (unsigned)(kt) * 64u); glds16(ap_ + ao0, l0 + SA_(b, h)); glds16(ap_ + ao1, l0 + SA_(b, h) + 8192); }
; #define STAGE_B(b, h, kt) { const u16* bp_ = ((h) ? B1 : B0) + (unsigned)(kt) * 64u; glds16(bp_ + bo0, l0 + SB_(b, h)); glds16(bp_ + bo1, l0 + SB_(b, h) + 8192); }
; #define LDA(dst, b, h) _Pragma("unroll") for (int m = 0; m < 4; ++m) _Pragma("unroll") for (int k = 0; k < 2; ++k) \
;     dst[m][k] = *(const bf16x8*)(lds + SA_(b, h) + lds_byte(wr * 64 + m * 16 + fr, k * 32 + fq * 8));
; #define LDB(dst, b, h) _Pragma("unroll") for (int n = 0; n < 2; ++n) _Pragma("unroll") for (int k = 0; k < 2; ++k) \
;     dst[n][k] = *(const bf16x8*)(lds + SB_(b, h) + lds_byte(wc * 32 + n * 16 + fr, k * 32 + fq * 8));
; #define MMA(ai, bj, At_, Bt_) { __builtin_amdgcn_s_setprio(1); \
;     _Pragma("unroll") for (int m = 0; m < 4; ++m) _Pragma("unroll") for (int n = 0; n < 2; ++n) _Pragma("unroll") for (int k = 0; k < 2; ++k) \
;       acc[ai][bj][m][n] = MFMA16(Bt_[n][k], At_[m][k], acc[ai][bj][m][n]); \
;     __builtin_amdgcn_s_setprio(0); }
; #define WAIT_V(n) asm volatile("s_waitcnt vmcnt(" #n ")" ::: "memory");
; #define WAIT_L(n) asm volatile("s_waitcnt lgkmcnt(" #n ")" ::: "memory");
; #define BAR __builtin_amdgcn_s_barrier();
; #define SCHED __builtin_amdgcn_sched_barrier(0);
; DI void gemm256(const u16* __restrict__ A, int lda, const u16* __restrict__ B0, const u16* __restrict__ B1, int ldb, int nt, acc_t& acc, char* lds) {
;     ...
;     LDA(At, 1, 1) STAGE_A(1, 0, t + 3)
;     BAR WAIT_L(0) MMA(1, 0, At, Bq0) BAR SCHED
;     STAGE_B(1, 1, t + 3)
;     WAIT_V(6) BAR MMA(1, 1, At, Bq1) BAR
;   }
;   { LDB(Bq0, 0, 0) LDA(At, 0, 0) STAGE_A(1, 1, nt - 1)
;     BAR WAIT_L(0) MMA(0, 0, At, Bq0) BAR
;     LDB(Bq1, 0, 1) BAR WAIT_L(0) MMA(0, 1, At, Bq1) BAR
	s_waitcnt lgkmcnt(0)
	s_waitcnt lgkmcnt(0)
	v_mfma_f32_16x16x32_bf16 v[60:63], v[142:145], v[182:185], v[60:63]
	v_mfma_f32_16x16x32_bf16 v[56:59], v[174:177], v[182:185], v[56:59]
	v_mfma_f32_16x16x32_bf16 v[52:55], v[142:145], v[190:193], v[52:55]
	v_mfma_f32_16x16x32_bf16 v[48:51], v[174:177], v[190:193], v[48:51]
	v_mfma_f32_16x16x32_bf16 v[44:47], v[142:145], v[198:201], v[44:47]
	v_mfma_f32_16x16x32_bf16 v[40:43], v[174:177], v[198:201], v[40:43]
	v_mfma_f32_16x16x32_bf16 v[36:39], v[142:145], v[206:209], v[36:39]
	v_mfma_f32_16x16x32_bf16 v[32:35], v[174:177], v[206:209], v[32:35]
	v_mfma_f32_16x16x32_bf16 v[60:63], v[170:173], v[186:189], v[60:63]
	v_mfma_f32_16x16x32_bf16 v[56:59], v[178:181], v[186:189], v[56:59]
	v_mfma_f32_16x16x32_bf16 v[52:55], v[170:173], v[194:197], v[52:55]
	v_mfma_f32_16x16x32_bf16 v[48:51], v[178:181], v[194:197], v[48:51]
	v_mfma_f32_16x16x32_bf16 v[44:47], v[170:173], v[202:205], v[44:47]
	v_mfma_f32_16x16x32_bf16 v[40:43], v[178:181], v[202:205], v[40:43]
	v_mfma_f32_16x16x32_bf16 v[36:39], v[170:173], v[210:213], v[36:39]
	v_mfma_f32_16x16x32_bf16 v[32:35], v[178:181], v[210:213], v[32:35]
	s_barrier
	v_readfirstlane_b32 s7, v163
	v_lshl_add_u64 v[142:143], v[238:239], 0, s[38:39]
	s_mov_b32 m0, s7
	v_readfirstlane_b32 s7, v164
	global_load_lds_dwordx4 v[142:143], off
	v_lshl_add_u64 v[142:143], v[240:241], 0, s[38:39]
	s_mov_b32 m0, s7
	s_nop 0
	global_load_lds_dwordx4 v[142:143], off
	s_waitcnt vmcnt(6)
	s_barrier
	v_mfma_f32_16x16x32_bf16 v[28:31], v[216:219], v[182:185], v[28:31]
	v_mfma_f32_16x16x32_bf16 v[24:27], v[230:233], v[182:185], v[24:27]
	v_mfma_f32_16x16x32_bf16 v[20:23], v[216:219], v[190:193], v[20:23]
	v_mfma_f32_16x16x32_bf16 v[16:19], v[230:233], v[190:193], v[16:19]
	v_mfma_f32_16x16x32_bf16 v[12:15], v[216:219], v[198:201], v[12:15]
	v_mfma_f32_16x16x32_bf16 v[8:11], v[230:233], v[198:201], v[8:11]
	v_mfma_f32_16x16x32_bf16 v[4:7], v[216:219], v[206:209], v[4:7]
	v_mfma_f32_16x16x32_bf16 v[0:3], v[230:233], v[206:209], v[0:3]
	v_mfma_f32_16x16x32_bf16 v[28:31], v[226:229], v[186:189], v[28:31]
	v_mfma_f32_16x16x32_bf16 v[24:27], v[234:237], v[186:189], v[24:27]
	v_mfma_f32_16x16x32_bf16 v[20:23], v[226:229], v[194:197], v[20:23]
	v_mfma_f32_16x16x32_bf16 v[16:19], v[234:237], v[194:197], v[16:19]
	v_mfma_f32_16x16x32_bf16 v[12:15], v[226:229], v[202:205], v[12:15]
	v_mfma_f32_16x16x32_bf16 v[8:11], v[234:237], v[202:205], v[8:11]
	v_mfma_f32_16x16x32_bf16 v[4:7], v[226:229], v[210:213], v[4:7]
	v_mfma_f32_16x16x32_bf16 v[0:3], v[234:237], v[210:213], v[0:3]
	s_add_i32 s3, s3, 2
	s_add_u32 s22, s22, 0x100
	s_addc_u32 s23, s23, 0
	s_cmp_lt_u32 s3, 12
	s_barrier
	s_cbranch_scc1 .LBB0_168
	s_add_u32 s8, s8, 0x40780
	s_addc_u32 s9, s9, 0
	v_readfirstlane_b32 s3, v167
	v_lshl_add_u64 v[152:153], v[64:65], 1, s[8:9]
	s_mov_b32 m0, s3
	v_readfirstlane_b32 s3, v168
	ds_read_b128 v[132:135], v166
	ds_read_b128 v[136:139], v166 offset:1024
	ds_read_b128 v[142:145], v166 offset:2048
	ds_read_b128 v[156:159], v166 offset:3072
	ds_read_b128 v[160:163], v148
	ds_read_b128 v[170:173], v148 offset:1024
	ds_read_b128 v[174:177], v147
	ds_read_b128 v[178:181], v147 offset:1024
	ds_read_b128 v[182:185], v146
	ds_read_b128 v[186:189], v146 offset:1024
	ds_read_b128 v[190:193], v141
	ds_read_b128 v[194:197], v141 offset:1024
	global_load_lds_dwordx4 v[152:153], off
	v_lshl_add_u64 v[130:131], v[130:131], 1, s[8:9]
	s_mov_b32 m0, s3
	s_nop 0
	global_load_lds_dwordx4 v[130:131], off
	s_barrier
	s_waitcnt lgkmcnt(0)
	s_waitcnt lgkmcnt(0)
	v_mfma_f32_16x16x32_bf16 v[126:129], v[132:135], v[160:163], v[126:129]
	v_mfma_f32_16x16x32_bf16 v[122:125], v[142:145], v[160:163], v[122:125]
	v_mfma_f32_16x16x32_bf16 v[118:121], v[132:135], v[174:177], v[118:121]
	v_mfma_f32_16x16x32_bf16 v[114:117], v[142:145], v[174:177], v[114:117]
	v_mfma_f32_16x16x32_bf16 v[102:105], v[132:135], v[190:193], v[102:105]
	v_mfma_f32_16x16x32_bf16 v[98:101], v[142:145], v[190:193], v[98:101]
	v_mfma_f32_16x16x32_bf16 v[126:129], v[136:139], v[170:173], v[126:129]
	v_mfma_f32_16x16x32_bf16 v[122:125], v[156:159], v[170:173], v[122:125]
	v_mfma_f32_16x16x32_bf16 v[118:121], v[136:139], v[178:181], v[118:121]
	v_mfma_f32_16x16x32_bf16 v[114:117], v[156:159], v[178:181], v[114:117]
	v_mfma_f32_16x16x32_bf16 v[110:113], v[132:135], v[182:185], v[110:113]
	v_mfma_f32_16x16x32_bf16 v[106:109], v[142:145], v[182:185], v[106:109]
	v_mfma_f32_16x16x32_bf16 v[102:105], v[136:139], v[194:197], v[102:105]
	v_mfma_f32_16x16x32_bf16 v[98:101], v[156:159], v[194:197], v[98:101]
	v_mfma_f32_16x16x32_bf16 v[166:169], v[136:139], v[186:189], v[110:113]
	v_mfma_f32_16x16x32_bf16 v[198:201], v[156:159], v[186:189], v[106:109]
	s_barrier
	s_nop 1
	ds_read_b128 v[106:109], v165
	ds_read_b128 v[110:113], v165 offset:1024
	ds_read_b128 v[202:205], v165 offset:2048
	ds_read_b128 v[206:209], v165 offset:3072
	s_barrier
	s_waitcnt lgkmcnt(0)
	s_waitcnt lgkmcnt(0)
	v_mfma_f32_16x16x32_bf16 v[86:89], v[106:109], v[174:177], v[86:89]
	v_mfma_f32_16x16x32_bf16 v[82:85], v[202:205], v[174:177], v[82:85]
	v_mfma_f32_16x16x32_bf16 v[70:73], v[106:109], v[190:193], v[70:73]
	v_mfma_f32_16x16x32_bf16 v[66:69], v[202:205], v[190:193], v[66:69]
	v_mfma_f32_16x16x32_bf16 v[94:97], v[106:109], v[160:163], v[94:97]
	v_mfma_f32_16x16x32_bf16 v[90:93], v[202:205], v[160:163], v[90:93]
	v_mfma_f32_16x16x32_bf16 v[86:89], v[110:113], v[178:181], v[86:89]
	v_mfma_f32_16x16x32_bf16 v[82:85], v[206:209], v[178:181], v[82:85]
	v_mfma_f32_16x16x32_bf16 v[78:81], v[106:109], v[182:185], v[78:81]
	v_mfma_f32_16x16x32_bf16 v[74:77], v[202:205], v[182:185], v[74:77]
	v_mfma_f32_16x16x32_bf16 v[70:73], v[110:113], v[194:197], v[70:73]
	v_mfma_f32_16x16x32_bf16 v[66:69], v[206:209], v[194:197], v[66:69]
	v_mfma_f32_16x16x32_bf16 v[210:213], v[110:113], v[170:173], v[94:97]
	v_mfma_f32_16x16x32_bf16 v[160:163], v[206:209], v[170:173], v[90:93]
	v_mfma_f32_16x16x32_bf16 v[170:173], v[110:113], v[186:189], v[78:81]
	v_mfma_f32_16x16x32_bf16 v[174:177], v[206:209], v[186:189], v[74:77]
	s_barrier
; #define LDA(dst, b, h) _Pragma("unroll") for (int m = 0; m < 4; ++m) _Pragma("unroll") for (int k = 0; k < 2; ++k) \
;     dst[m][k] = *(const bf16x8*)(lds + SA_(b, h) + lds_byte(wr * 64 + m * 16 + fr, k * 32 + fq * 8));
; #define LDB(dst, b, h) _Pragma("unroll") for (int n = 0; n < 2; ++n) _Pragma("unroll") for (int k = 0; k < 2; ++k) \
;     dst[n][k] = *(const bf16x8*)(lds + SB_(b, h) + lds_byte(wc * 32 + n * 16 + fr, k * 32 + fq * 8));
; #define MMA(ai, bj, At_, Bt_) { __builtin_amdgcn_s_setprio(1); \
;     _Pragma("unroll") for (int m = 0; m < 4; ++m) _Pragma("unroll") for (int n = 0; n < 2; ++n) _Pragma("unroll") for (int k = 0; k < 2; ++k) \
;       acc[ai][bj][m][n] = MFMA16(Bt_[n][k], At_[m][k], acc[ai][bj][m][n]); \
;     __builtin_amdgcn_s_setprio(0); }
; #define WAIT_V(n) asm volatile("s_waitcnt vmcnt(" #n ")" ::: "memory");
; #define WAIT_L(n) asm volatile("s_waitcnt lgkmcnt(" #n ")" ::: "memory");
; #define BAR __builtin_amdgcn_s_barrier();
; DI void gemm256(const u16* __restrict__ A, int lda, const u16* __restrict__ B0, const u16* __restrict__ B1, int ldb, int nt, acc_t& acc, char* lds) {
;     ...
;     LDA(At, 0, 1) WAIT_V(4) BAR WAIT_L(0) MMA(1, 0, At, Bq0) MMA(1, 1, At, Bq1) BAR }
;   { LDB(Bq0, 1, 0) LDA(At, 1, 0) WAIT_V(2) BAR WAIT_L(0) MMA(0, 0, At, Bq0) BAR
;     LDB(Bq1, 1, 1) WAIT_V(0) BAR WAIT_L(0) MMA(0, 1, At, Bq1) BAR
	s_nop 0
	ds_read_b128 v[74:77], v148 offset:16384
	ds_read_b128 v[78:81], v148 offset:17408
	ds_read_b128 v[90:93], v147 offset:16384
	ds_read_b128 v[94:97], v147 offset:17408
	ds_read_b128 v[178:181], v146 offset:16384
	ds_read_b128 v[182:185], v146 offset:17408
	ds_read_b128 v[186:189], v141 offset:16384
	ds_read_b128 v[190:193], v141 offset:17408
	s_waitcnt vmcnt(4)
	s_barrier
	s_waitcnt lgkmcnt(0)
	s_waitcnt lgkmcnt(0)
	v_mfma_f32_16x16x32_bf16 v[60:63], v[132:135], v[74:77], v[60:63]
	v_mfma_f32_16x16x32_bf16 v[56:59], v[142:145], v[74:77], v[56:59]
	v_mfma_f32_16x16x32_bf16 v[52:55], v[132:135], v[90:93], v[52:55]
	v_mfma_f32_16x16x32_bf16 v[48:51], v[142:145], v[90:93], v[48:51]
	v_mfma_f32_16x16x32_bf16 v[36:39], v[132:135], v[186:189], v[36:39]
	v_mfma_f32_16x16x32_bf16 v[32:35], v[142:145], v[186:189], v[32:35]
	v_mfma_f32_16x16x32_bf16 v[60:63], v[136:139], v[78:81], v[60:63]
	v_mfma_f32_16x16x32_bf16 v[56:59], v[156:159], v[78:81], v[56:59]
	v_mfma_f32_16x16x32_bf16 v[52:55], v[136:139], v[94:97], v[52:55]
	v_mfma_f32_16x16x32_bf16 v[48:51], v[156:159], v[94:97], v[48:51]
	v_mfma_f32_16x16x32_bf16 v[44:47], v[132:135], v[178:181], v[44:47]
	v_mfma_f32_16x16x32_bf16 v[40:43], v[142:145], v[178:181], v[40:43]
	v_mfma_f32_16x16x32_bf16 v[36:39], v[136:139], v[190:193], v[36:39]
	v_mfma_f32_16x16x32_bf16 v[32:35], v[156:159], v[190:193], v[32:35]
	v_mfma_f32_16x16x32_bf16 v[194:197], v[136:139], v[182:185], v[44:47]
	v_mfma_f32_16x16x32_bf16 v[216:219], v[156:159], v[182:185], v[40:43]
	v_mfma_f32_16x16x32_bf16 v[20:23], v[106:109], v[90:93], v[20:23]
	v_mfma_f32_16x16x32_bf16 v[16:19], v[202:205], v[90:93], v[16:19]
	v_mfma_f32_16x16x32_bf16 v[4:7], v[106:109], v[186:189], v[4:7]
	v_mfma_f32_16x16x32_bf16 v[0:3], v[202:205], v[186:189], v[0:3]
	v_mfma_f32_16x16x32_bf16 v[28:31], v[106:109], v[74:77], v[28:31]
	v_mfma_f32_16x16x32_bf16 v[24:27], v[202:205], v[74:77], v[24:27]
	v_mfma_f32_16x16x32_bf16 v[20:23], v[110:113], v[94:97], v[20:23]
	v_mfma_f32_16x16x32_bf16 v[16:19], v[206:209], v[94:97], v[16:19]
	v_mfma_f32_16x16x32_bf16 v[12:15], v[106:109], v[178:181], v[12:15]
	v_mfma_f32_16x16x32_bf16 v[8:11], v[202:205], v[178:181], v[8:11]
	v_mfma_f32_16x16x32_bf16 v[4:7], v[110:113], v[190:193], v[4:7]
	v_mfma_f32_16x16x32_bf16 v[0:3], v[206:209], v[190:193], v[0:3]
	v_mfma_f32_16x16x32_bf16 v[130:133], v[110:113], v[78:81], v[28:31]
	v_mfma_f32_16x16x32_bf16 v[134:137], v[206:209], v[78:81], v[24:27]
	v_mfma_f32_16x16x32_bf16 v[142:145], v[110:113], v[182:185], v[12:15]
	v_mfma_f32_16x16x32_bf16 v[156:159], v[206:209], v[182:185], v[8:11]
	s_barrier
	s_nop 0
	ds_read_b128 v[8:11], v155
	ds_read_b128 v[12:15], v155 offset:1024
	ds_read_b128 v[178:181], v155 offset:2048
	ds_read_b128 v[152:155], v155 offset:3072
	ds_read_b128 v[24:27], v148 offset:32768
	ds_read_b128 v[28:31], v148 offset:33792
	ds_read_b128 v[40:43], v147 offset:32768
	ds_read_b128 v[44:47], v147 offset:33792
	ds_read_b128 v[182:185], v146 offset:32768
	ds_read_b128 v[186:189], v146 offset:33792
	ds_read_b128 v[190:193], v141 offset:32768
	ds_read_b128 v[202:205], v141 offset:33792
	s_waitcnt vmcnt(2)
	s_barrier
	s_waitcnt lgkmcnt(0)
	s_waitcnt lgkmcnt(0)
	v_mfma_f32_16x16x32_bf16 v[74:77], v[8:11], v[24:27], v[126:129]
	v_mfma_f32_16x16x32_bf16 v[126:129], v[12:15], v[28:31], v[74:77]
	v_mfma_f32_16x16x32_bf16 v[74:77], v[178:181], v[24:27], v[122:125]
	v_mfma_f32_16x16x32_bf16 v[122:125], v[152:155], v[28:31], v[74:77]
	v_mfma_f32_16x16x32_bf16 v[74:77], v[8:11], v[40:43], v[118:121]
	v_mfma_f32_16x16x32_bf16 v[110:113], v[12:15], v[44:47], v[74:77]
	v_mfma_f32_16x16x32_bf16 v[74:77], v[178:181], v[40:43], v[114:117]
	v_mfma_f32_16x16x32_bf16 v[106:109], v[152:155], v[44:47], v[74:77]
	v_mfma_f32_16x16x32_bf16 v[74:77], v[8:11], v[182:185], v[166:169]
	v_mfma_f32_16x16x32_bf16 v[94:97], v[12:15], v[186:189], v[74:77]
	v_mfma_f32_16x16x32_bf16 v[74:77], v[178:181], v[182:185], v[198:201]
	v_mfma_f32_16x16x32_bf16 v[90:93], v[152:155], v[186:189], v[74:77]
	v_mfma_f32_16x16x32_bf16 v[74:77], v[8:11], v[190:193], v[102:105]
	v_mfma_f32_16x16x32_bf16 v[78:81], v[12:15], v[202:205], v[74:77]
	v_mfma_f32_16x16x32_bf16 v[74:77], v[178:181], v[190:193], v[98:101]
	v_mfma_f32_16x16x32_bf16 v[74:77], v[152:155], v[202:205], v[74:77]
	s_barrier
; #define LDA(dst, b, h) _Pragma("unroll") for (int m = 0; m < 4; ++m) _Pragma("unroll") for (int k = 0; k < 2; ++k) \
;     dst[m][k] = *(const bf16x8*)(lds + SA_(b, h) + lds_byte(wr * 64 + m * 16 + fr, k * 32 + fq * 8));
; #define LDB(dst, b, h) _Pragma("unroll") for (int n = 0; n < 2; ++n) _Pragma("unroll") for (int k = 0; k < 2; ++k) \
;     dst[n][k] = *(const bf16x8*)(lds + SB_(b, h) + lds_byte(wc * 32 + n * 16 + fr, k * 32 + fq * 8));
; #define MMA(ai, bj, At_, Bt_) { __builtin_amdgcn_s_setprio(1); \
;     _Pragma("unroll") for (int m = 0; m < 4; ++m) _Pragma("unroll") for (int n = 0; n < 2; ++n) _Pragma("unroll") for (int k = 0; k < 2; ++k) \
;       acc[ai][bj][m][n] = MFMA16(Bt_[n][k], At_[m][k], acc[ai][bj][m][n]); \
;     __builtin_amdgcn_s_setprio(0); }
; #define WAIT_V(n) asm volatile("s_waitcnt vmcnt(" #n ")" ::: "memory");
; #define WAIT_L(n) asm volatile("s_waitcnt lgkmcnt(" #n ")" ::: "memory");
; #define BAR __builtin_amdgcn_s_barrier();
; DI void gemm256(const u16* __restrict__ A, int lda, const u16* __restrict__ B0, const u16* __restrict__ B1, int ldb, int nt, acc_t& acc, char* lds) {
;     ...
;   { LDB(Bq0, 1, 0) LDA(At, 1, 0) WAIT_V(2) BAR WAIT_L(0) MMA(0, 0, At, Bq0) BAR
;     LDB(Bq1, 1, 1) WAIT_V(0) BAR WAIT_L(0) MMA(0, 1, At, Bq1) BAR
;     LDA(At, 1, 1) BAR WAIT_L(0) MMA(1, 0, At, Bq0) MMA(1, 1, At, Bq1) BAR }
;   if (wr == 0) BAR
;   __syncthreads();
	ds_read_b128 v[164:167], v150
	ds_read_b128 v[198:201], v150 offset:1024
	ds_read_b128 v[206:209], v150 offset:2048
	ds_read_b128 v[226:229], v150 offset:3072
	s_waitcnt vmcnt(0)
	s_barrier
	s_waitcnt lgkmcnt(0)
	s_waitcnt lgkmcnt(0)
	v_mfma_f32_16x16x32_bf16 v[98:101], v[164:167], v[24:27], v[210:213]
	v_mfma_f32_16x16x32_bf16 v[24:27], v[206:209], v[24:27], v[160:163]
	v_mfma_f32_16x16x32_bf16 v[114:117], v[226:229], v[28:31], v[24:27]
	v_mfma_f32_16x16x32_bf16 v[24:27], v[164:167], v[40:43], v[86:89]
	v_mfma_f32_16x16x32_bf16 v[102:105], v[198:201], v[44:47], v[24:27]
	v_mfma_f32_16x16x32_bf16 v[24:27], v[206:209], v[40:43], v[82:85]
	v_mfma_f32_16x16x32_bf16 v[118:121], v[198:201], v[28:31], v[98:101]
	v_mfma_f32_16x16x32_bf16 v[98:101], v[226:229], v[44:47], v[24:27]
	v_mfma_f32_16x16x32_bf16 v[24:27], v[164:167], v[182:185], v[170:173]
	v_mfma_f32_16x16x32_bf16 v[86:89], v[198:201], v[186:189], v[24:27]
	v_mfma_f32_16x16x32_bf16 v[24:27], v[206:209], v[182:185], v[174:177]
	v_mfma_f32_16x16x32_bf16 v[82:85], v[226:229], v[186:189], v[24:27]
	v_mfma_f32_16x16x32_bf16 v[24:27], v[164:167], v[190:193], v[70:73]
	v_mfma_f32_16x16x32_bf16 v[70:73], v[198:201], v[202:205], v[24:27]
	v_mfma_f32_16x16x32_bf16 v[24:27], v[206:209], v[190:193], v[66:69]
	v_mfma_f32_16x16x32_bf16 v[66:69], v[226:229], v[202:205], v[24:27]
	s_barrier
	ds_read_b128 v[160:163], v148 offset:49152
	ds_read_b128 v[148:151], v148 offset:50176
	ds_read_b128 v[168:171], v147 offset:49152
	ds_read_b128 v[172:175], v147 offset:50176
	ds_read_b128 v[182:185], v146 offset:49152
	ds_read_b128 v[186:189], v146 offset:50176
	ds_read_b128 v[190:193], v141 offset:49152
	ds_read_b128 v[202:205], v141 offset:50176
	s_barrier
	s_waitcnt lgkmcnt(0)
	s_waitcnt lgkmcnt(0)
	v_mfma_f32_16x16x32_bf16 v[24:27], v[8:11], v[160:163], v[60:63]
	v_mfma_f32_16x16x32_bf16 v[60:63], v[12:15], v[148:151], v[24:27]
	v_mfma_f32_16x16x32_bf16 v[24:27], v[178:181], v[160:163], v[56:59]
	v_mfma_f32_16x16x32_bf16 v[56:59], v[152:155], v[148:151], v[24:27]
	v_mfma_f32_16x16x32_bf16 v[24:27], v[8:11], v[168:171], v[52:55]
	v_mfma_f32_16x16x32_bf16 v[44:47], v[12:15], v[172:175], v[24:27]
	v_mfma_f32_16x16x32_bf16 v[24:27], v[178:181], v[168:171], v[48:51]
	v_mfma_f32_16x16x32_bf16 v[40:43], v[152:155], v[172:175], v[24:27]
	v_mfma_f32_16x16x32_bf16 v[24:27], v[8:11], v[182:185], v[194:197]
	v_mfma_f32_16x16x32_bf16 v[8:11], v[8:11], v[190:193], v[36:39]
	v_mfma_f32_16x16x32_bf16 v[28:31], v[12:15], v[186:189], v[24:27]
	v_mfma_f32_16x16x32_bf16 v[24:27], v[178:181], v[182:185], v[216:219]
	v_mfma_f32_16x16x32_bf16 v[12:15], v[12:15], v[202:205], v[8:11]
	v_mfma_f32_16x16x32_bf16 v[8:11], v[178:181], v[190:193], v[32:35]
	v_mfma_f32_16x16x32_bf16 v[24:27], v[152:155], v[186:189], v[24:27]
	v_mfma_f32_16x16x32_bf16 v[8:11], v[152:155], v[202:205], v[8:11]
	v_mfma_f32_16x16x32_bf16 v[32:35], v[164:167], v[160:163], v[130:133]
	v_mfma_f32_16x16x32_bf16 v[52:55], v[198:201], v[148:151], v[32:35]
	v_mfma_f32_16x16x32_bf16 v[32:35], v[206:209], v[160:163], v[134:137]
	v_mfma_f32_16x16x32_bf16 v[16:19], v[206:209], v[168:171], v[16:19]
	v_mfma_f32_16x16x32_bf16 v[48:51], v[226:229], v[148:151], v[32:35]
	v_mfma_f32_16x16x32_bf16 v[20:23], v[164:167], v[168:171], v[20:23]
	v_mfma_f32_16x16x32_bf16 v[32:35], v[226:229], v[172:175], v[16:19]
	v_mfma_f32_16x16x32_bf16 v[16:19], v[164:167], v[182:185], v[142:145]
	v_mfma_f32_16x16x32_bf16 v[36:39], v[198:201], v[172:175], v[20:23]
	v_mfma_f32_16x16x32_bf16 v[20:23], v[198:201], v[186:189], v[16:19]
	v_mfma_f32_16x16x32_bf16 v[16:19], v[206:209], v[182:185], v[156:159]
	v_mfma_f32_16x16x32_bf16 v[4:7], v[164:167], v[190:193], v[4:7]
	v_mfma_f32_16x16x32_bf16 v[0:3], v[206:209], v[190:193], v[0:3]
	v_mfma_f32_16x16x32_bf16 v[16:19], v[226:229], v[186:189], v[16:19]
	v_mfma_f32_16x16x32_bf16 v[4:7], v[198:201], v[202:205], v[4:7]
	v_mfma_f32_16x16x32_bf16 v[0:3], v[226:229], v[202:205], v[0:3]
	s_movk_i32 s3, 0x100
	v_cmp_gt_u32_e32 vcc, s3, v140
	s_barrier
	s_and_saveexec_b64 s[8:9], vcc
	s_cbranch_execz .LBB0_171
	s_barrier

; #define STAGE_A(b, h, kt) { const u16* ap_ = A + (size_t)((h) * ahalf + (unsigned)(kt) * 64u); glds16(ap_ + ao0, l0 + SA_(b, h)); glds16(ap_ + ao1, l0 + SA_(b, h) + 8192); }
; #define STAGE_B(b, h, kt) { const u16* bp_ = ((h) ? B1 : B0) + (unsigned)(kt) * 64u; glds16(bp_ + bo0, l0 + SB_(b, h)); glds16(bp_ + bo1, l0 + SB_(b, h) + 8192); }
; #define LDA(dst, b, h) _Pragma("unroll") for (int m = 0; m < 4; ++m) _Pragma("unroll") for (int k = 0; k < 2; ++k) \
;     dst[m][k] = *(const bf16x8*)(lds + SA_(b, h) + lds_byte(wr * 64 + m * 16 + fr, k * 32 + fq * 8));
; #define LDB(dst, b, h) _Pragma("unroll") for (int n = 0; n < 2; ++n) _Pragma("unroll") for (int k = 0; k < 2; ++k) \
;     dst[n][k] = *(const bf16x8*)(lds + SB_(b, h) + lds_byte(wc * 32 + n * 16 + fr, k * 32 + fq * 8));
; #define MMA(ai, bj, At_, Bt_) { __builtin_amdgcn_s_setprio(1); \
;     _Pragma("unroll") for (int m = 0; m < 4; ++m) _Pragma("unroll") for (int n = 0; n < 2; ++n) _Pragma("unroll") for (int k = 0; k < 2; ++k) \
;       acc[ai][bj][m][n] = MFMA16(Bt_[n][k], At_[m][k], acc[ai][bj][m][n]); \
;     __builtin_amdgcn_s_setprio(0); }
; #define WAIT_V(n) asm volatile("s_waitcnt vmcnt(" #n ")" ::: "memory");
; #define WAIT_L(n) asm volatile("s_waitcnt lgkmcnt(" #n ")" ::: "memory");
; #define BAR __builtin_amdgcn_s_barrier();
; #define SCHED __builtin_amdgcn_sched_barrier(0);
; DI void gemm256(const u16* __restrict__ A, int lda, const u16* __restrict__ B0, const u16* __restrict__ B1, int ldb, int nt, acc_t& acc, char* lds) {
;     ...
;   for (int t = 0; t < nt - 2; t += 2) {
;     LDB(Bq0, 0, 0) SCHED LDA(At, 0, 0) STAGE_A(1, 1, t + 1)
;     WAIT_L(8) BAR WAIT_L(0) MMA(0, 0, At, Bq0) BAR SCHED
;     LDB(Bq1, 0, 1) STAGE_B(0, 0, t + 2)
;     BAR WAIT_L(0) MMA(0, 1, At, Bq1) BAR
;     LDA(At, 0, 1) STAGE_A(0, 0, t + 2)
;     BAR WAIT_L(0) MMA(1, 0, At, Bq0) BAR SCHED
;     STAGE_B(0, 1, t + 2)
;     WAIT_V(6) BAR MMA(1, 1, At, Bq1) BAR
;     LDB(Bq0, 1, 0) SCHED LDA(At, 1, 0) STAGE_A(0, 1, t + 2)
;     WAIT_L(8) BAR WAIT_L(0) MMA(0, 0, At, Bq0) BAR SCHED
.LBB0_564:
	ds_read_b128 v[170:173], v166
	ds_read_b128 v[174:177], v166 offset:1024
	ds_read_b128 v[178:181], v166 offset:2048
	ds_read_b128 v[182:185], v166 offset:3072
	v_add_u32_e32 v167, 0xc000, v149
	v_lshl_add_u64 v[142:143], s[22:23], 0, v[138:139]
	v_readfirstlane_b32 s3, v167
	v_lshl_add_u64 v[144:145], v[142:143], 0, s[38:39]
	s_mov_b32 m0, s3
	v_add_u32_e32 v168, 0xe000, v149
	ds_read_b128 v[186:189], v148
	ds_read_b128 v[190:193], v148 offset:1024
	ds_read_b128 v[194:197], v147
	ds_read_b128 v[198:201], v147 offset:1024
	ds_read_b128 v[202:205], v146
	ds_read_b128 v[206:209], v146 offset:1024
	ds_read_b128 v[210:213], v141
	ds_read_b128 v[226:229], v141 offset:1024
	global_load_lds_dwordx4 v[144:145], off
	v_lshl_add_u64 v[144:145], s[22:23], 0, v[136:137]
	v_readfirstlane_b32 s3, v168
	v_lshl_add_u64 v[216:217], v[144:145], 0, s[38:39]
	s_mov_b32 m0, s3
	s_nop 0
	global_load_lds_dwordx4 v[216:217], off
	s_waitcnt lgkmcnt(8)
	s_barrier
	s_waitcnt lgkmcnt(0)
	s_waitcnt lgkmcnt(0)
	v_mfma_f32_16x16x32_bf16 v[126:129], v[170:173], v[186:189], v[126:129]
	v_mfma_f32_16x16x32_bf16 v[122:125], v[178:181], v[186:189], v[122:125]
	v_mfma_f32_16x16x32_bf16 v[118:121], v[170:173], v[194:197], v[118:121]
	v_mfma_f32_16x16x32_bf16 v[114:117], v[178:181], v[194:197], v[114:117]
	v_mfma_f32_16x16x32_bf16 v[110:113], v[170:173], v[202:205], v[110:113]
	v_mfma_f32_16x16x32_bf16 v[106:109], v[178:181], v[202:205], v[106:109]
	v_mfma_f32_16x16x32_bf16 v[102:105], v[170:173], v[210:213], v[102:105]
	v_mfma_f32_16x16x32_bf16 v[98:101], v[178:181], v[210:213], v[98:101]
	v_mfma_f32_16x16x32_bf16 v[126:129], v[174:177], v[190:193], v[126:129]
	v_mfma_f32_16x16x32_bf16 v[122:125], v[182:185], v[190:193], v[122:125]
	v_mfma_f32_16x16x32_bf16 v[118:121], v[174:177], v[198:201], v[118:121]
	v_mfma_f32_16x16x32_bf16 v[114:117], v[182:185], v[198:201], v[114:117]
	v_mfma_f32_16x16x32_bf16 v[110:113], v[174:177], v[206:209], v[110:113]
	v_mfma_f32_16x16x32_bf16 v[106:109], v[182:185], v[206:209], v[106:109]
	v_mfma_f32_16x16x32_bf16 v[102:105], v[174:177], v[226:229], v[102:105]
	v_mfma_f32_16x16x32_bf16 v[98:101], v[182:185], v[226:229], v[98:101]
	s_barrier
	v_lshl_add_u64 v[216:217], s[22:23], 0, v[132:133]
	v_readfirstlane_b32 s3, v150
	v_lshl_add_u64 v[218:219], v[216:217], 0, s[20:21]
	s_mov_b32 m0, s3
	ds_read_b128 v[230:233], v165
	ds_read_b128 v[234:237], v165 offset:1024
	ds_read_b128 v[238:241], v165 offset:2048
	ds_read_b128 v[242:245], v165 offset:3072
	global_load_lds_dwordx4 v[218:219], off
	v_lshl_add_u64 v[218:219], s[22:23], 0, v[134:135]
	v_readfirstlane_b32 s3, v152
	v_lshl_add_u64 v[222:223], v[218:219], 0, s[20:21]
	s_mov_b32 m0, s3
	s_nop 0
	global_load_lds_dwordx4 v[222:223], off
	s_barrier
	s_waitcnt lgkmcnt(0)
	s_waitcnt lgkmcnt(0)
	v_mfma_f32_16x16x32_bf16 v[94:97], v[230:233], v[186:189], v[94:97]
	v_mfma_f32_16x16x32_bf16 v[90:93], v[238:241], v[186:189], v[90:93]
	v_mfma_f32_16x16x32_bf16 v[86:89], v[230:233], v[194:197], v[86:89]
	v_mfma_f32_16x16x32_bf16 v[82:85], v[238:241], v[194:197], v[82:85]
	v_mfma_f32_16x16x32_bf16 v[78:81], v[230:233], v[202:205], v[78:81]
	v_mfma_f32_16x16x32_bf16 v[74:77], v[238:241], v[202:205], v[74:77]
	v_mfma_f32_16x16x32_bf16 v[70:73], v[230:233], v[210:213], v[70:73]
	v_mfma_f32_16x16x32_bf16 v[66:69], v[238:241], v[210:213], v[66:69]
	v_mfma_f32_16x16x32_bf16 v[94:97], v[234:237], v[190:193], v[94:97]
	v_mfma_f32_16x16x32_bf16 v[90:93], v[242:245], v[190:193], v[90:93]
	v_mfma_f32_16x16x32_bf16 v[86:89], v[234:237], v[198:201], v[86:89]
	v_mfma_f32_16x16x32_bf16 v[82:85], v[242:245], v[198:201], v[82:85]
	v_mfma_f32_16x16x32_bf16 v[78:81], v[234:237], v[206:209], v[78:81]
	v_mfma_f32_16x16x32_bf16 v[74:77], v[242:245], v[206:209], v[74:77]
	v_mfma_f32_16x16x32_bf16 v[70:73], v[234:237], v[226:229], v[70:73]
	v_mfma_f32_16x16x32_bf16 v[66:69], v[242:245], v[226:229], v[66:69]
	v_readfirstlane_b32 s3, v149
	v_lshl_add_u64 v[222:223], v[142:143], 0, s[28:29]
	s_mov_b32 m0, s3
	v_readfirstlane_b32 s3, v153
	s_barrier
	ds_read_b128 v[186:189], v148 offset:16384
	ds_read_b128 v[190:193], v148 offset:17408
	ds_read_b128 v[194:197], v147 offset:16384
	ds_read_b128 v[198:201], v147 offset:17408
	ds_read_b128 v[202:205], v146 offset:16384
	ds_read_b128 v[206:209], v146 offset:17408
	ds_read_b128 v[210:213], v141 offset:16384
	ds_read_b128 v[226:229], v141 offset:17408
	global_load_lds_dwordx4 v[222:223], off
	v_lshl_add_u64 v[222:223], v[144:145], 0, s[28:29]
	s_mov_b32 m0, s3
	s_nop 0
	global_load_lds_dwordx4 v[222:223], off
	s_barrier
	s_waitcnt lgkmcnt(0)
	s_waitcnt lgkmcnt(0)
	v_mfma_f32_16x16x32_bf16 v[60:63], v[170:173], v[186:189], v[60:63]
	v_mfma_f32_16x16x32_bf16 v[56:59], v[178:181], v[186:189], v[56:59]
	v_mfma_f32_16x16x32_bf16 v[52:55], v[170:173], v[194:197], v[52:55]
	v_mfma_f32_16x16x32_bf16 v[48:51], v[178:181], v[194:197], v[48:51]
	v_mfma_f32_16x16x32_bf16 v[44:47], v[170:173], v[202:205], v[44:47]
	v_mfma_f32_16x16x32_bf16 v[40:43], v[178:181], v[202:205], v[40:43]
	v_mfma_f32_16x16x32_bf16 v[36:39], v[170:173], v[210:213], v[36:39]
	v_mfma_f32_16x16x32_bf16 v[32:35], v[178:181], v[210:213], v[32:35]
	v_mfma_f32_16x16x32_bf16 v[60:63], v[174:177], v[190:193], v[60:63]
	v_mfma_f32_16x16x32_bf16 v[56:59], v[182:185], v[190:193], v[56:59]
	v_mfma_f32_16x16x32_bf16 v[52:55], v[174:177], v[198:201], v[52:55]
	v_mfma_f32_16x16x32_bf16 v[48:51], v[182:185], v[198:201], v[48:51]
	v_mfma_f32_16x16x32_bf16 v[44:47], v[174:177], v[206:209], v[44:47]
	v_mfma_f32_16x16x32_bf16 v[40:43], v[182:185], v[206:209], v[40:43]
	v_mfma_f32_16x16x32_bf16 v[36:39], v[174:177], v[226:229], v[36:39]
	v_mfma_f32_16x16x32_bf16 v[32:35], v[182:185], v[226:229], v[32:35]
	s_barrier
; #define STAGE_A(b, h, kt) { const u16* ap_ = A + (size_t)((h) * ahalf + (unsigned)(kt) * 64u); glds16(ap_ + ao0, l0 + SA_(b, h)); glds16(ap_ + ao1, l0 + SA_(b, h) + 8192); }
; #define STAGE_B(b, h, kt) { const u16* bp_ = ((h) ? B1 : B0) + (unsigned)(kt) * 64u; glds16(bp_ + bo0, l0 + SB_(b, h)); glds16(bp_ + bo1, l0 + SB_(b, h) + 8192); }
; #define LDA(dst, b, h) _Pragma("unroll") for (int m = 0; m < 4; ++m) _Pragma("unroll") for (int k = 0; k < 2; ++k) \
;     dst[m][k] = *(const bf16x8*)(lds + SA_(b, h) + lds_byte(wr * 64 + m * 16 + fr, k * 32 + fq * 8));
; #define LDB(dst, b, h) _Pragma("unroll") for (int n = 0; n < 2; ++n) _Pragma("unroll") for (int k = 0; k < 2; ++k) \
;     dst[n][k] = *(const bf16x8*)(lds + SB_(b, h) + lds_byte(wc * 32 + n * 16 + fr, k * 32 + fq * 8));
; #define MMA(ai, bj, At_, Bt_) { __builtin_amdgcn_s_setprio(1); \
;     _Pragma("unroll") for (int m = 0; m < 4; ++m) _Pragma("unroll") for (int n = 0; n < 2; ++n) _Pragma("unroll") for (int k = 0; k < 2; ++k) \
;       acc[ai][bj][m][n] = MFMA16(Bt_[n][k], At_[m][k], acc[ai][bj][m][n]); \
;     __builtin_amdgcn_s_setprio(0); }
; #define WAIT_V(n) asm volatile("s_waitcnt vmcnt(" #n ")" ::: "memory");
; #define WAIT_L(n) asm volatile("s_waitcnt lgkmcnt(" #n ")" ::: "memory");
; #define BAR __builtin_amdgcn_s_barrier();
; #define SCHED __builtin_amdgcn_sched_barrier(0);
; DI void gemm256(const u16* __restrict__ A, int lda, const u16* __restrict__ B0, const u16* __restrict__ B1, int ldb, int nt, acc_t& acc, char* lds) {
;     ...
;     WAIT_V(6) BAR MMA(1, 1, At, Bq1) BAR
;     LDB(Bq0, 1, 0) SCHED LDA(At, 1, 0) STAGE_A(0, 1, t + 2)
;     WAIT_L(8) BAR WAIT_L(0) MMA(0, 0, At, Bq0) BAR SCHED
;     LDB(Bq1, 1, 1) STAGE_B(1, 0, t + 3)
;     BAR WAIT_L(0) MMA(0, 1, At, Bq1) BAR
;     LDA(At, 1, 1) STAGE_A(1, 0, t + 3)
;     BAR WAIT_L(0) MMA(1, 0, At, Bq0) BAR SCHED
;     STAGE_B(1, 1, t + 3)
;     WAIT_V(6) BAR MMA(1, 1, At, Bq1) BAR
	v_readfirstlane_b32 s3, v154
	v_lshl_add_u64 v[170:171], v[216:217], 0, s[24:25]
	s_mov_b32 m0, s3
	v_readfirstlane_b32 s3, v155
	global_load_lds_dwordx4 v[170:171], off
	v_lshl_add_u64 v[170:171], v[218:219], 0, s[24:25]
	s_mov_b32 m0, s3
	s_nop 0
	global_load_lds_dwordx4 v[170:171], off
	s_waitcnt vmcnt(6)
	s_barrier
	v_mfma_f32_16x16x32_bf16 v[28:31], v[230:233], v[186:189], v[28:31]
	v_mfma_f32_16x16x32_bf16 v[24:27], v[238:241], v[186:189], v[24:27]
	v_mfma_f32_16x16x32_bf16 v[20:23], v[230:233], v[194:197], v[20:23]
	v_mfma_f32_16x16x32_bf16 v[16:19], v[238:241], v[194:197], v[16:19]
	v_mfma_f32_16x16x32_bf16 v[12:15], v[230:233], v[202:205], v[12:15]
	v_mfma_f32_16x16x32_bf16 v[8:11], v[238:241], v[202:205], v[8:11]
	v_mfma_f32_16x16x32_bf16 v[4:7], v[230:233], v[210:213], v[4:7]
	v_mfma_f32_16x16x32_bf16 v[0:3], v[238:241], v[210:213], v[0:3]
	v_mfma_f32_16x16x32_bf16 v[28:31], v[234:237], v[190:193], v[28:31]
	v_mfma_f32_16x16x32_bf16 v[24:27], v[242:245], v[190:193], v[24:27]
	v_mfma_f32_16x16x32_bf16 v[20:23], v[234:237], v[198:201], v[20:23]
	v_mfma_f32_16x16x32_bf16 v[16:19], v[242:245], v[198:201], v[16:19]
	v_mfma_f32_16x16x32_bf16 v[12:15], v[234:237], v[206:209], v[12:15]
	v_mfma_f32_16x16x32_bf16 v[8:11], v[242:245], v[206:209], v[8:11]
	v_mfma_f32_16x16x32_bf16 v[4:7], v[234:237], v[226:229], v[4:7]
	v_mfma_f32_16x16x32_bf16 v[0:3], v[242:245], v[226:229], v[0:3]
	s_barrier
	ds_read_b128 v[170:173], v156
	ds_read_b128 v[174:177], v156 offset:1024
	ds_read_b128 v[178:181], v156 offset:2048
	ds_read_b128 v[182:185], v156 offset:3072
	v_readfirstlane_b32 s3, v157
	v_lshl_add_u64 v[222:223], v[142:143], 0, s[36:37]
	s_mov_b32 m0, s3
	v_readfirstlane_b32 s3, v158
	ds_read_b128 v[186:189], v148 offset:32768
	ds_read_b128 v[190:193], v148 offset:33792
	ds_read_b128 v[194:197], v147 offset:32768
	ds_read_b128 v[198:201], v147 offset:33792
	ds_read_b128 v[202:205], v146 offset:32768
	ds_read_b128 v[206:209], v146 offset:33792
	ds_read_b128 v[210:213], v141 offset:32768
	ds_read_b128 v[226:229], v141 offset:33792
	global_load_lds_dwordx4 v[222:223], off
	v_lshl_add_u64 v[222:223], v[144:145], 0, s[36:37]
	s_mov_b32 m0, s3
	s_nop 0
	global_load_lds_dwordx4 v[222:223], off
	s_waitcnt lgkmcnt(8)
	s_barrier
	s_waitcnt lgkmcnt(0)
	s_waitcnt lgkmcnt(0)
	v_mfma_f32_16x16x32_bf16 v[126:129], v[170:173], v[186:189], v[126:129]
	v_mfma_f32_16x16x32_bf16 v[122:125], v[178:181], v[186:189], v[122:125]
	v_mfma_f32_16x16x32_bf16 v[118:121], v[170:173], v[194:197], v[118:121]
	v_mfma_f32_16x16x32_bf16 v[114:117], v[178:181], v[194:197], v[114:117]
	v_mfma_f32_16x16x32_bf16 v[110:113], v[170:173], v[202:205], v[110:113]
	v_mfma_f32_16x16x32_bf16 v[106:109], v[178:181], v[202:205], v[106:109]
	v_mfma_f32_16x16x32_bf16 v[102:105], v[170:173], v[210:213], v[102:105]
	v_mfma_f32_16x16x32_bf16 v[98:101], v[178:181], v[210:213], v[98:101]
	v_mfma_f32_16x16x32_bf16 v[126:129], v[174:177], v[190:193], v[126:129]
	v_mfma_f32_16x16x32_bf16 v[122:125], v[182:185], v[190:193], v[122:125]
	v_mfma_f32_16x16x32_bf16 v[118:121], v[174:177], v[198:201], v[118:121]
	v_mfma_f32_16x16x32_bf16 v[114:117], v[182:185], v[198:201], v[114:117]
	v_mfma_f32_16x16x32_bf16 v[110:113], v[174:177], v[206:209], v[110:113]
	v_mfma_f32_16x16x32_bf16 v[106:109], v[182:185], v[206:209], v[106:109]
	v_mfma_f32_16x16x32_bf16 v[102:105], v[174:177], v[226:229], v[102:105]
	v_mfma_f32_16x16x32_bf16 v[98:101], v[182:185], v[226:229], v[98:101]
	s_barrier
	v_readfirstlane_b32 s3, v159
	v_lshl_add_u64 v[222:223], v[216:217], 0, s[34:35]
	s_mov_b32 m0, s3
	v_readfirstlane_b32 s3, v160
	ds_read_b128 v[230:233], v151
	ds_read_b128 v[234:237], v151 offset:1024
	ds_read_b128 v[238:241], v151 offset:2048
	ds_read_b128 v[242:245], v151 offset:3072
	global_load_lds_dwordx4 v[222:223], off
	v_lshl_add_u64 v[222:223], v[218:219], 0, s[34:35]
	s_mov_b32 m0, s3
	s_nop 0
	global_load_lds_dwordx4 v[222:223], off
	s_barrier
	s_waitcnt lgkmcnt(0)
	s_waitcnt lgkmcnt(0)
	v_mfma_f32_16x16x32_bf16 v[94:97], v[230:233], v[186:189], v[94:97]
	v_mfma_f32_16x16x32_bf16 v[90:93], v[238:241], v[186:189], v[90:93]
	v_mfma_f32_16x16x32_bf16 v[86:89], v[230:233], v[194:197], v[86:89]
	v_mfma_f32_16x16x32_bf16 v[82:85], v[238:241], v[194:197], v[82:85]
	v_mfma_f32_16x16x32_bf16 v[78:81], v[230:233], v[202:205], v[78:81]
	v_mfma_f32_16x16x32_bf16 v[74:77], v[238:241], v[202:205], v[74:77]
	v_mfma_f32_16x16x32_bf16 v[70:73], v[230:233], v[210:213], v[70:73]
	v_mfma_f32_16x16x32_bf16 v[66:69], v[238:241], v[210:213], v[66:69]
	v_mfma_f32_16x16x32_bf16 v[94:97], v[234:237], v[190:193], v[94:97]
	v_mfma_f32_16x16x32_bf16 v[90:93], v[242:245], v[190:193], v[90:93]
	v_mfma_f32_16x16x32_bf16 v[86:89], v[234:237], v[198:201], v[86:89]
	v_mfma_f32_16x16x32_bf16 v[82:85], v[242:245], v[198:201], v[82:85]
	v_mfma_f32_16x16x32_bf16 v[78:81], v[234:237], v[206:209], v[78:81]
	v_mfma_f32_16x16x32_bf16 v[74:77], v[242:245], v[206:209], v[74:77]
	v_mfma_f32_16x16x32_bf16 v[70:73], v[234:237], v[226:229], v[70:73]
	v_mfma_f32_16x16x32_bf16 v[66:69], v[242:245], v[226:229], v[66:69]
	v_readfirstlane_b32 s3, v161
	v_lshl_add_u64 v[142:143], v[142:143], 0, s[26:27]
	s_mov_b32 m0, s3
	v_readfirstlane_b32 s3, v162
	s_barrier
	ds_read_b128 v[186:189], v148 offset:49152
	ds_read_b128 v[190:193], v148 offset:50176
	ds_read_b128 v[194:197], v147 offset:49152
	ds_read_b128 v[198:201], v147 offset:50176
	ds_read_b128 v[202:205], v146 offset:49152
	ds_read_b128 v[206:209], v146 offset:50176
	ds_read_b128 v[210:213], v141 offset:49152
	ds_read_b128 v[226:229], v141 offset:50176
	global_load_lds_dwordx4 v[142:143], off
	v_lshl_add_u64 v[142:143], v[144:145], 0, s[26:27]
	s_mov_b32 m0, s3
	s_nop 0
	global_load_lds_dwordx4 v[142:143], off
	s_barrier
; #define STAGE_A(b, h, kt) { const u16* ap_ = A + (size_t)((h) * ahalf + (unsigned)(kt) * 64u); glds16(ap_ + ao0, l0 + SA_(b, h)); glds16(ap_ + ao1, l0 + SA_(b, h) + 8192); }
; #define STAGE_B(b, h, kt) { const u16* bp_ = ((h) ? B1 : B0) + (unsigned)(kt) * 64u; glds16(bp_ + bo0, l0 + SB_(b, h)); glds16(bp_ + bo1, l0 + SB_(b, h) + 8192); }
; #define LDA(dst, b, h) _Pragma("unroll") for (int m = 0; m < 4; ++m) _Pragma("unroll") for (int k = 0; k < 2; ++k) \
;     dst[m][k] = *(const bf16x8*)(lds + SA_(b, h) + lds_byte(wr * 64 + m * 16 + fr, k * 32 + fq * 8));
; #define LDB(dst, b, h) _Pragma("unroll") for (int n = 0; n < 2; ++n) _Pragma("unroll") for (int k = 0; k < 2; ++k) \
;     dst[n][k] = *(const bf16x8*)(lds + SB_(b, h) + lds_byte(wc * 32 + n * 16 + fr, k * 32 + fq * 8));
; #define MMA(ai, bj, At_, Bt_) { __builtin_amdgcn_s_setprio(1); \
;     _Pragma("unroll") for (int m = 0; m < 4; ++m) _Pragma("unroll") for (int n = 0; n < 2; ++n) _Pragma("unroll") for (int k = 0; k < 2; ++k) \
;       acc[ai][bj][m][n] = MFMA16(Bt_[n][k], At_[m][k], acc[ai][bj][m][n]); \
;     __builtin_amdgcn_s_setprio(0); }
; #define WAIT_V(n) asm volatile("s_waitcnt vmcnt(" #n ")" ::: "memory");
; #define WAIT_L(n) asm volatile("s_waitcnt lgkmcnt(" #n ")" ::: "memory");
; #define BAR __builtin_amdgcn_s_barrier();
; #define SCHED __builtin_amdgcn_sched_barrier(0);
; DI void gemm256(const u16* __restrict__ A, int lda, const u16* __restrict__ B0, const u16* __restrict__ B1, int ldb, int nt, acc_t& acc, char* lds) {
;     ...
;     LDA(At, 1, 1) STAGE_A(1, 0, t + 3)
;     BAR WAIT_L(0) MMA(1, 0, At, Bq0) BAR SCHED
;     STAGE_B(1, 1, t + 3)
;     WAIT_V(6) BAR MMA(1, 1, At, Bq1) BAR
;   }
;   { LDB(Bq0, 0, 0) LDA(At, 0, 0) STAGE_A(1, 1, nt - 1)
;     BAR WAIT_L(0) MMA(0, 0, At, Bq0) BAR
;     LDB(Bq1, 0, 1) BAR WAIT_L(0) MMA(0, 1, At, Bq1) BAR
	s_waitcnt lgkmcnt(0)
	s_waitcnt lgkmcnt(0)
	v_mfma_f32_16x16x32_bf16 v[60:63], v[170:173], v[186:189], v[60:63]
	v_mfma_f32_16x16x32_bf16 v[56:59], v[178:181], v[186:189], v[56:59]
	v_mfma_f32_16x16x32_bf16 v[52:55], v[170:173], v[194:197], v[52:55]
	v_mfma_f32_16x16x32_bf16 v[48:51], v[178:181], v[194:197], v[48:51]
	v_mfma_f32_16x16x32_bf16 v[44:47], v[170:173], v[202:205], v[44:47]
	v_mfma_f32_16x16x32_bf16 v[40:43], v[178:181], v[202:205], v[40:43]
	v_mfma_f32_16x16x32_bf16 v[36:39], v[170:173], v[210:213], v[36:39]
	v_mfma_f32_16x16x32_bf16 v[32:35], v[178:181], v[210:213], v[32:35]
	v_mfma_f32_16x16x32_bf16 v[60:63], v[174:177], v[190:193], v[60:63]
	v_mfma_f32_16x16x32_bf16 v[56:59], v[182:185], v[190:193], v[56:59]
	v_mfma_f32_16x16x32_bf16 v[52:55], v[174:177], v[198:201], v[52:55]
	v_mfma_f32_16x16x32_bf16 v[48:51], v[182:185], v[198:201], v[48:51]
	v_mfma_f32_16x16x32_bf16 v[44:47], v[174:177], v[206:209], v[44:47]
	v_mfma_f32_16x16x32_bf16 v[40:43], v[182:185], v[206:209], v[40:43]
	v_mfma_f32_16x16x32_bf16 v[36:39], v[174:177], v[226:229], v[36:39]
	v_mfma_f32_16x16x32_bf16 v[32:35], v[182:185], v[226:229], v[32:35]
	s_barrier
	v_readfirstlane_b32 s3, v163
	v_lshl_add_u64 v[142:143], v[216:217], 0, s[50:51]
	s_mov_b32 m0, s3
	v_readfirstlane_b32 s3, v164
	global_load_lds_dwordx4 v[142:143], off
	v_lshl_add_u64 v[142:143], v[218:219], 0, s[50:51]
	s_mov_b32 m0, s3
	s_nop 0
	global_load_lds_dwordx4 v[142:143], off
	s_waitcnt vmcnt(6)
	s_barrier
	v_mfma_f32_16x16x32_bf16 v[28:31], v[230:233], v[186:189], v[28:31]
	v_mfma_f32_16x16x32_bf16 v[24:27], v[238:241], v[186:189], v[24:27]
	v_mfma_f32_16x16x32_bf16 v[20:23], v[230:233], v[194:197], v[20:23]
	v_mfma_f32_16x16x32_bf16 v[16:19], v[238:241], v[194:197], v[16:19]
	v_mfma_f32_16x16x32_bf16 v[12:15], v[230:233], v[202:205], v[12:15]
	v_mfma_f32_16x16x32_bf16 v[8:11], v[238:241], v[202:205], v[8:11]
	v_mfma_f32_16x16x32_bf16 v[4:7], v[230:233], v[210:213], v[4:7]
	v_mfma_f32_16x16x32_bf16 v[0:3], v[238:241], v[210:213], v[0:3]
	v_mfma_f32_16x16x32_bf16 v[28:31], v[234:237], v[190:193], v[28:31]
	v_mfma_f32_16x16x32_bf16 v[24:27], v[242:245], v[190:193], v[24:27]
	v_mfma_f32_16x16x32_bf16 v[20:23], v[234:237], v[198:201], v[20:23]
	v_mfma_f32_16x16x32_bf16 v[16:19], v[242:245], v[198:201], v[16:19]
	v_mfma_f32_16x16x32_bf16 v[12:15], v[234:237], v[206:209], v[12:15]
	v_mfma_f32_16x16x32_bf16 v[8:11], v[242:245], v[206:209], v[8:11]
	v_mfma_f32_16x16x32_bf16 v[4:7], v[234:237], v[226:229], v[4:7]
	v_mfma_f32_16x16x32_bf16 v[0:3], v[242:245], v[226:229], v[0:3]
	s_add_i32 s2, s2, 2
	s_add_u32 s22, s22, 0x100
	s_addc_u32 s23, s23, 0
	s_cmp_lt_u32 s2, 12
	s_barrier
	s_cbranch_scc1 .LBB0_564
	s_add_u32 s2, s8, 0x40780
	s_addc_u32 s3, s9, 0
	v_readfirstlane_b32 s7, v167
	v_lshl_add_u64 v[142:143], v[64:65], 1, s[2:3]
	s_mov_b32 m0, s7
	v_lshl_add_u64 v[130:131], v[130:131], 1, s[2:3]
	v_readfirstlane_b32 s2, v168
	ds_read_b128 v[132:135], v166
	ds_read_b128 v[136:139], v166 offset:1024
	ds_read_b128 v[152:155], v166 offset:2048
	ds_read_b128 v[158:161], v166 offset:3072
	ds_read_b128 v[170:173], v148
	ds_read_b128 v[174:177], v148 offset:1024
	ds_read_b128 v[178:181], v147
	ds_read_b128 v[182:185], v147 offset:1024
	ds_read_b128 v[186:189], v146
	ds_read_b128 v[190:193], v146 offset:1024
	ds_read_b128 v[194:197], v141
	ds_read_b128 v[198:201], v141 offset:1024
	global_load_lds_dwordx4 v[142:143], off
	s_mov_b32 m0, s2
	s_nop 0
	global_load_lds_dwordx4 v[130:131], off
	s_barrier
	s_waitcnt lgkmcnt(0)
	s_waitcnt lgkmcnt(0)
	v_mfma_f32_16x16x32_bf16 v[126:129], v[132:135], v[170:173], v[126:129]
	v_mfma_f32_16x16x32_bf16 v[122:125], v[152:155], v[170:173], v[122:125]
	v_mfma_f32_16x16x32_bf16 v[118:121], v[132:135], v[178:181], v[118:121]
	v_mfma_f32_16x16x32_bf16 v[114:117], v[152:155], v[178:181], v[114:117]
	v_mfma_f32_16x16x32_bf16 v[110:113], v[132:135], v[186:189], v[110:113]
	v_mfma_f32_16x16x32_bf16 v[106:109], v[152:155], v[186:189], v[106:109]
	v_mfma_f32_16x16x32_bf16 v[102:105], v[132:135], v[194:197], v[102:105]
	v_mfma_f32_16x16x32_bf16 v[98:101], v[152:155], v[194:197], v[98:101]
	v_mfma_f32_16x16x32_bf16 v[126:129], v[136:139], v[174:177], v[126:129]
	v_mfma_f32_16x16x32_bf16 v[122:125], v[158:161], v[174:177], v[122:125]
	v_mfma_f32_16x16x32_bf16 v[118:121], v[136:139], v[182:185], v[118:121]
	v_mfma_f32_16x16x32_bf16 v[114:117], v[158:161], v[182:185], v[114:117]
	v_mfma_f32_16x16x32_bf16 v[110:113], v[136:139], v[190:193], v[110:113]
	v_mfma_f32_16x16x32_bf16 v[106:109], v[158:161], v[190:193], v[106:109]
	v_mfma_f32_16x16x32_bf16 v[102:105], v[136:139], v[198:201], v[102:105]
	v_mfma_f32_16x16x32_bf16 v[98:101], v[158:161], v[198:201], v[98:101]
	s_barrier
	ds_read_b128 v[166:169], v165
	ds_read_b128 v[202:205], v165 offset:1024
	ds_read_b128 v[206:209], v165 offset:2048
	ds_read_b128 v[162:165], v165 offset:3072
	s_barrier
	s_waitcnt lgkmcnt(0)
	s_waitcnt lgkmcnt(0)
	v_mfma_f32_16x16x32_bf16 v[94:97], v[166:169], v[170:173], v[94:97]
	v_mfma_f32_16x16x32_bf16 v[90:93], v[206:209], v[170:173], v[90:93]
	v_mfma_f32_16x16x32_bf16 v[86:89], v[166:169], v[178:181], v[86:89]
	v_mfma_f32_16x16x32_bf16 v[82:85], v[206:209], v[178:181], v[82:85]
	v_mfma_f32_16x16x32_bf16 v[78:81], v[166:169], v[186:189], v[78:81]
	v_mfma_f32_16x16x32_bf16 v[74:77], v[206:209], v[186:189], v[74:77]
	v_mfma_f32_16x16x32_bf16 v[70:73], v[166:169], v[194:197], v[70:73]
	v_mfma_f32_16x16x32_bf16 v[66:69], v[206:209], v[194:197], v[66:69]
	v_mfma_f32_16x16x32_bf16 v[94:97], v[202:205], v[174:177], v[94:97]
	v_mfma_f32_16x16x32_bf16 v[90:93], v[162:165], v[174:177], v[90:93]
	v_mfma_f32_16x16x32_bf16 v[86:89], v[202:205], v[182:185], v[86:89]
	v_mfma_f32_16x16x32_bf16 v[82:85], v[162:165], v[182:185], v[82:85]
	v_mfma_f32_16x16x32_bf16 v[78:81], v[202:205], v[190:193], v[78:81]
	v_mfma_f32_16x16x32_bf16 v[74:77], v[162:165], v[190:193], v[74:77]
	v_mfma_f32_16x16x32_bf16 v[70:73], v[202:205], v[198:201], v[70:73]
	v_mfma_f32_16x16x32_bf16 v[66:69], v[162:165], v[198:201], v[66:69]
	s_barrier
; #define LDA(dst, b, h) _Pragma("unroll") for (int m = 0; m < 4; ++m) _Pragma("unroll") for (int k = 0; k < 2; ++k) \
;     dst[m][k] = *(const bf16x8*)(lds + SA_(b, h) + lds_byte(wr * 64 + m * 16 + fr, k * 32 + fq * 8));
; #define LDB(dst, b, h) _Pragma("unroll") for (int n = 0; n < 2; ++n) _Pragma("unroll") for (int k = 0; k < 2; ++k) \
;     dst[n][k] = *(const bf16x8*)(lds + SB_(b, h) + lds_byte(wc * 32 + n * 16 + fr, k * 32 + fq * 8));
; #define MMA(ai, bj, At_, Bt_) { __builtin_amdgcn_s_setprio(1); \
;     _Pragma("unroll") for (int m = 0; m < 4; ++m) _Pragma("unroll") for (int n = 0; n < 2; ++n) _Pragma("unroll") for (int k = 0; k < 2; ++k) \
;       acc[ai][bj][m][n] = MFMA16(Bt_[n][k], At_[m][k], acc[ai][bj][m][n]); \
;     __builtin_amdgcn_s_setprio(0); }
; #define WAIT_V(n) asm volatile("s_waitcnt vmcnt(" #n ")" ::: "memory");
; #define WAIT_L(n) asm volatile("s_waitcnt lgkmcnt(" #n ")" ::: "memory");
; #define BAR __builtin_amdgcn_s_barrier();
; DI void gemm256(const u16* __restrict__ A, int lda, const u16* __restrict__ B0, const u16* __restrict__ B1, int ldb, int nt, acc_t& acc, char* lds) {
;     ...
;     LDA(At, 0, 1) WAIT_V(4) BAR WAIT_L(0) MMA(1, 0, At, Bq0) MMA(1, 1, At, Bq1) BAR }
;   { LDB(Bq0, 1, 0) LDA(At, 1, 0) WAIT_V(2) BAR WAIT_L(0) MMA(0, 0, At, Bq0) BAR
;     LDB(Bq1, 1, 1) WAIT_V(0) BAR WAIT_L(0) MMA(0, 1, At, Bq1) BAR
	ds_read_b128 v[170:173], v148 offset:16384
	ds_read_b128 v[174:177], v148 offset:17408
	ds_read_b128 v[178:181], v147 offset:16384
	ds_read_b128 v[182:185], v147 offset:17408
	ds_read_b128 v[186:189], v146 offset:16384
	ds_read_b128 v[190:193], v146 offset:17408
	ds_read_b128 v[194:197], v141 offset:16384
	ds_read_b128 v[198:201], v141 offset:17408
	s_waitcnt vmcnt(4)
	s_barrier
	s_waitcnt lgkmcnt(0)
	s_waitcnt lgkmcnt(0)
	v_mfma_f32_16x16x32_bf16 v[60:63], v[132:135], v[170:173], v[60:63]
	v_mfma_f32_16x16x32_bf16 v[52:55], v[132:135], v[178:181], v[52:55]
	v_mfma_f32_16x16x32_bf16 v[44:47], v[132:135], v[186:189], v[44:47]
	v_mfma_f32_16x16x32_bf16 v[36:39], v[132:135], v[194:197], v[36:39]
	v_mfma_f32_16x16x32_bf16 v[32:35], v[152:155], v[194:197], v[32:35]
	v_mfma_f32_16x16x32_bf16 v[60:63], v[136:139], v[174:177], v[60:63]
	v_mfma_f32_16x16x32_bf16 v[56:59], v[152:155], v[170:173], v[56:59]
	v_mfma_f32_16x16x32_bf16 v[210:213], v[136:139], v[182:185], v[52:55]
	v_mfma_f32_16x16x32_bf16 v[48:51], v[152:155], v[178:181], v[48:51]
	v_mfma_f32_16x16x32_bf16 v[230:233], v[136:139], v[190:193], v[44:47]
	v_mfma_f32_16x16x32_bf16 v[40:43], v[152:155], v[186:189], v[40:43]
	v_mfma_f32_16x16x32_bf16 v[130:133], v[136:139], v[198:201], v[36:39]
	v_mfma_f32_16x16x32_bf16 v[134:137], v[158:161], v[198:201], v[32:35]
	v_mfma_f32_16x16x32_bf16 v[56:59], v[158:161], v[174:177], v[56:59]
	v_mfma_f32_16x16x32_bf16 v[226:229], v[158:161], v[182:185], v[48:51]
	v_mfma_f32_16x16x32_bf16 v[234:237], v[158:161], v[190:193], v[40:43]
	v_mfma_f32_16x16x32_bf16 v[28:31], v[166:169], v[170:173], v[28:31]
	v_mfma_f32_16x16x32_bf16 v[24:27], v[206:209], v[170:173], v[24:27]
	v_mfma_f32_16x16x32_bf16 v[20:23], v[166:169], v[178:181], v[20:23]
	v_mfma_f32_16x16x32_bf16 v[16:19], v[206:209], v[178:181], v[16:19]
	v_mfma_f32_16x16x32_bf16 v[12:15], v[166:169], v[186:189], v[12:15]
	v_mfma_f32_16x16x32_bf16 v[8:11], v[206:209], v[186:189], v[8:11]
	v_mfma_f32_16x16x32_bf16 v[4:7], v[166:169], v[194:197], v[4:7]
	v_mfma_f32_16x16x32_bf16 v[0:3], v[206:209], v[194:197], v[0:3]
	v_mfma_f32_16x16x32_bf16 v[152:155], v[202:205], v[174:177], v[28:31]
	v_mfma_f32_16x16x32_bf16 v[158:161], v[162:165], v[174:177], v[24:27]
	v_mfma_f32_16x16x32_bf16 v[170:173], v[202:205], v[182:185], v[20:23]
	v_mfma_f32_16x16x32_bf16 v[174:177], v[162:165], v[182:185], v[16:19]
	v_mfma_f32_16x16x32_bf16 v[178:181], v[202:205], v[190:193], v[12:15]
	v_mfma_f32_16x16x32_bf16 v[182:185], v[162:165], v[190:193], v[8:11]
	v_mfma_f32_16x16x32_bf16 v[166:169], v[202:205], v[198:201], v[4:7]
	v_mfma_f32_16x16x32_bf16 v[162:165], v[162:165], v[198:201], v[0:3]
	s_barrier
	ds_read_b128 v[186:189], v156
	ds_read_b128 v[190:193], v156 offset:1024
	ds_read_b128 v[194:197], v156 offset:2048
	ds_read_b128 v[198:201], v156 offset:3072
	ds_read_b128 v[32:35], v148 offset:32768
	ds_read_b128 v[36:39], v148 offset:33792
	ds_read_b128 v[44:47], v147 offset:32768
	ds_read_b128 v[202:205], v147 offset:33792
	ds_read_b128 v[206:209], v146 offset:32768
	ds_read_b128 v[238:241], v146 offset:33792
	ds_read_b128 v[242:245], v141 offset:32768
	ds_read_b128 v[246:249], v141 offset:33792
	s_waitcnt vmcnt(2)
	s_barrier
	s_waitcnt lgkmcnt(0)
	s_waitcnt lgkmcnt(0)
	v_mfma_f32_16x16x32_bf16 v[0:3], v[186:189], v[32:35], v[126:129]
	v_mfma_f32_16x16x32_bf16 v[28:31], v[190:193], v[36:39], v[0:3]
	v_mfma_f32_16x16x32_bf16 v[0:3], v[194:197], v[32:35], v[122:125]
	v_mfma_f32_16x16x32_bf16 v[24:27], v[198:201], v[36:39], v[0:3]
	v_mfma_f32_16x16x32_bf16 v[0:3], v[186:189], v[44:47], v[118:121]
	v_mfma_f32_16x16x32_bf16 v[16:19], v[190:193], v[202:205], v[0:3]
	v_mfma_f32_16x16x32_bf16 v[0:3], v[194:197], v[44:47], v[114:117]
	v_mfma_f32_16x16x32_bf16 v[20:23], v[198:201], v[202:205], v[0:3]
	v_mfma_f32_16x16x32_bf16 v[0:3], v[186:189], v[206:209], v[110:113]
	v_mfma_f32_16x16x32_bf16 v[8:11], v[190:193], v[238:241], v[0:3]
	v_mfma_f32_16x16x32_bf16 v[0:3], v[194:197], v[206:209], v[106:109]
	v_mfma_f32_16x16x32_bf16 v[12:15], v[198:201], v[238:241], v[0:3]
	v_mfma_f32_16x16x32_bf16 v[0:3], v[186:189], v[242:245], v[102:105]
	v_mfma_f32_16x16x32_bf16 v[4:7], v[194:197], v[242:245], v[98:101]
	v_mfma_f32_16x16x32_bf16 v[0:3], v[190:193], v[246:249], v[0:3]
	v_mfma_f32_16x16x32_bf16 v[4:7], v[198:201], v[246:249], v[4:7]
	s_barrier
; #define LDA(dst, b, h) _Pragma("unroll") for (int m = 0; m < 4; ++m) _Pragma("unroll") for (int k = 0; k < 2; ++k) \
;     dst[m][k] = *(const bf16x8*)(lds + SA_(b, h) + lds_byte(wr * 64 + m * 16 + fr, k * 32 + fq * 8));
; #define LDB(dst, b, h) _Pragma("unroll") for (int n = 0; n < 2; ++n) _Pragma("unroll") for (int k = 0; k < 2; ++k) \
;     dst[n][k] = *(const bf16x8*)(lds + SB_(b, h) + lds_byte(wc * 32 + n * 16 + fr, k * 32 + fq * 8));
; #define MMA(ai, bj, At_, Bt_) { __builtin_amdgcn_s_setprio(1); \
;     _Pragma("unroll") for (int m = 0; m < 4; ++m) _Pragma("unroll") for (int n = 0; n < 2; ++n) _Pragma("unroll") for (int k = 0; k < 2; ++k) \
;       acc[ai][bj][m][n] = MFMA16(Bt_[n][k], At_[m][k], acc[ai][bj][m][n]); \
;     __builtin_amdgcn_s_setprio(0); }
; #define WAIT_V(n) asm volatile("s_waitcnt vmcnt(" #n ")" ::: "memory");
; #define WAIT_L(n) asm volatile("s_waitcnt lgkmcnt(" #n ")" ::: "memory");
; #define BAR __builtin_amdgcn_s_barrier();
; DI void gemm256(const u16* __restrict__ A, int lda, const u16* __restrict__ B0, const u16* __restrict__ B1, int ldb, int nt, acc_t& acc, char* lds) {
;     ...
;   { LDB(Bq0, 1, 0) LDA(At, 1, 0) WAIT_V(2) BAR WAIT_L(0) MMA(0, 0, At, Bq0) BAR
;     LDB(Bq1, 1, 1) WAIT_V(0) BAR WAIT_L(0) MMA(0, 1, At, Bq1) BAR
;     LDA(At, 1, 1) BAR WAIT_L(0) MMA(1, 0, At, Bq0) MMA(1, 1, At, Bq1) BAR }
;   if (wr == 0) BAR
;   __syncthreads();
	ds_read_b128 v[106:109], v151
	ds_read_b128 v[110:113], v151 offset:1024
	ds_read_b128 v[142:145], v151 offset:2048
	ds_read_b128 v[216:219], v151 offset:3072
	s_waitcnt vmcnt(0)
	s_barrier
	s_waitcnt lgkmcnt(0)
	s_waitcnt lgkmcnt(0)
	v_mfma_f32_16x16x32_bf16 v[40:43], v[106:109], v[32:35], v[94:97]
	v_mfma_f32_16x16x32_bf16 v[32:35], v[142:145], v[32:35], v[90:93]
	v_mfma_f32_16x16x32_bf16 v[52:55], v[216:219], v[36:39], v[32:35]
	v_mfma_f32_16x16x32_bf16 v[32:35], v[106:109], v[44:47], v[86:89]
	v_mfma_f32_16x16x32_bf16 v[48:51], v[110:113], v[36:39], v[40:43]
	v_mfma_f32_16x16x32_bf16 v[40:43], v[110:113], v[202:205], v[32:35]
	v_mfma_f32_16x16x32_bf16 v[32:35], v[142:145], v[44:47], v[82:85]
	v_mfma_f32_16x16x32_bf16 v[44:47], v[216:219], v[202:205], v[32:35]
	v_mfma_f32_16x16x32_bf16 v[32:35], v[106:109], v[206:209], v[78:81]
	v_mfma_f32_16x16x32_bf16 v[36:39], v[110:113], v[238:241], v[32:35]
	v_mfma_f32_16x16x32_bf16 v[32:35], v[142:145], v[206:209], v[74:77]
	v_mfma_f32_16x16x32_bf16 v[78:81], v[216:219], v[238:241], v[32:35]
	v_mfma_f32_16x16x32_bf16 v[32:35], v[106:109], v[242:245], v[70:73]
	v_mfma_f32_16x16x32_bf16 v[66:69], v[142:145], v[242:245], v[66:69]
	v_mfma_f32_16x16x32_bf16 v[32:35], v[110:113], v[246:249], v[32:35]
	v_mfma_f32_16x16x32_bf16 v[66:69], v[216:219], v[246:249], v[66:69]
	s_barrier
	ds_read_b128 v[114:117], v148 offset:49152
	ds_read_b128 v[118:121], v148 offset:50176
	ds_read_b128 v[126:129], v147 offset:49152
	ds_read_b128 v[148:151], v147 offset:50176
	ds_read_b128 v[202:205], v146 offset:49152
	ds_read_b128 v[206:209], v146 offset:50176
	ds_read_b128 v[238:241], v141 offset:49152
	ds_read_b128 v[242:245], v141 offset:50176
	s_barrier
	s_waitcnt lgkmcnt(0)
	s_waitcnt lgkmcnt(0)
	v_mfma_f32_16x16x32_bf16 v[56:59], v[194:197], v[114:117], v[56:59]
	v_mfma_f32_16x16x32_bf16 v[102:105], v[198:201], v[118:121], v[56:59]
	v_mfma_f32_16x16x32_bf16 v[56:59], v[186:189], v[126:129], v[210:213]
	v_mfma_f32_16x16x32_bf16 v[90:93], v[190:193], v[148:151], v[56:59]
	v_mfma_f32_16x16x32_bf16 v[56:59], v[194:197], v[126:129], v[226:229]
	v_mfma_f32_16x16x32_bf16 v[94:97], v[198:201], v[148:151], v[56:59]
	v_mfma_f32_16x16x32_bf16 v[56:59], v[186:189], v[202:205], v[230:233]
	v_mfma_f32_16x16x32_bf16 v[82:85], v[190:193], v[206:209], v[56:59]
	v_mfma_f32_16x16x32_bf16 v[56:59], v[194:197], v[202:205], v[234:237]
	v_mfma_f32_16x16x32_bf16 v[86:89], v[198:201], v[206:209], v[56:59]
	v_mfma_f32_16x16x32_bf16 v[56:59], v[186:189], v[238:241], v[130:133]
	v_mfma_f32_16x16x32_bf16 v[60:63], v[186:189], v[114:117], v[60:63]
	v_mfma_f32_16x16x32_bf16 v[70:73], v[190:193], v[242:245], v[56:59]
	v_mfma_f32_16x16x32_bf16 v[56:59], v[194:197], v[238:241], v[134:137]
	v_mfma_f32_16x16x32_bf16 v[98:101], v[190:193], v[118:121], v[60:63]
	v_mfma_f32_16x16x32_bf16 v[74:77], v[198:201], v[242:245], v[56:59]
	v_mfma_f32_16x16x32_bf16 v[56:59], v[106:109], v[114:117], v[152:155]
	v_mfma_f32_16x16x32_bf16 v[130:133], v[110:113], v[118:121], v[56:59]
	v_mfma_f32_16x16x32_bf16 v[56:59], v[142:145], v[114:117], v[158:161]
	v_mfma_f32_16x16x32_bf16 v[134:137], v[216:219], v[118:121], v[56:59]
	v_mfma_f32_16x16x32_bf16 v[56:59], v[106:109], v[126:129], v[170:173]
	v_mfma_f32_16x16x32_bf16 v[122:125], v[110:113], v[148:151], v[56:59]
	v_mfma_f32_16x16x32_bf16 v[56:59], v[142:145], v[126:129], v[174:177]
	v_mfma_f32_16x16x32_bf16 v[126:129], v[216:219], v[148:151], v[56:59]
	v_mfma_f32_16x16x32_bf16 v[56:59], v[106:109], v[202:205], v[178:181]
	v_mfma_f32_16x16x32_bf16 v[114:117], v[110:113], v[206:209], v[56:59]
	v_mfma_f32_16x16x32_bf16 v[56:59], v[142:145], v[202:205], v[182:185]
	v_mfma_f32_16x16x32_bf16 v[118:121], v[216:219], v[206:209], v[56:59]
	v_mfma_f32_16x16x32_bf16 v[56:59], v[106:109], v[238:241], v[166:169]
	v_mfma_f32_16x16x32_bf16 v[106:109], v[110:113], v[242:245], v[56:59]
	v_mfma_f32_16x16x32_bf16 v[56:59], v[142:145], v[238:241], v[162:165]
	v_mfma_f32_16x16x32_bf16 v[110:113], v[216:219], v[242:245], v[56:59]
	s_movk_i32 s2, 0x100
	v_cmp_gt_u32_e32 vcc, s2, v140
	s_barrier
	s_and_saveexec_b64 s[8:9], vcc
	s_mov_b32 s69, 0x800000
	s_mov_b32 s75, 0x3f317217
	s_mov_b32 s92, 0x7f800000
	s_cbranch_execz .LBB0_567
	s_barrier

; #define STAGE_A(b, h, kt) { const u16* ap_ = A + (size_t)((h) * ahalf + (unsigned)(kt) * 64u); glds16(ap_ + ao0, l0 + SA_(b, h)); glds16(ap_ + ao1, l0 + SA_(b, h) + 8192); }
; #define STAGE_B(b, h, kt) { const u16* bp_ = ((h) ? B1 : B0) + (unsigned)(kt) * 64u; glds16(bp_ + bo0, l0 + SB_(b, h)); glds16(bp_ + bo1, l0 + SB_(b, h) + 8192); }
; #define LDA(dst, b, h) _Pragma("unroll") for (int m = 0; m < 4; ++m) _Pragma("unroll") for (int k = 0; k < 2; ++k) \
;     dst[m][k] = *(const bf16x8*)(lds + SA_(b, h) + lds_byte(wr * 64 + m * 16 + fr, k * 32 + fq * 8));
; #define LDB(dst, b, h) _Pragma("unroll") for (int n = 0; n < 2; ++n) _Pragma("unroll") for (int k = 0; k < 2; ++k) \
;     dst[n][k] = *(const bf16x8*)(lds + SB_(b, h) + lds_byte(wc * 32 + n * 16 + fr, k * 32 + fq * 8));
; #define MMA(ai, bj, At_, Bt_) { __builtin_amdgcn_s_setprio(1); \
;     _Pragma("unroll") for (int m = 0; m < 4; ++m) _Pragma("unroll") for (int n = 0; n < 2; ++n) _Pragma("unroll") for (int k = 0; k < 2; ++k) \
;       acc[ai][bj][m][n] = MFMA16(Bt_[n][k], At_[m][k], acc[ai][bj][m][n]); \
;     __builtin_amdgcn_s_setprio(0); }
; #define WAIT_V(n) asm volatile("s_waitcnt vmcnt(" #n ")" ::: "memory");
; #define WAIT_L(n) asm volatile("s_waitcnt lgkmcnt(" #n ")" ::: "memory");
; #define BAR __builtin_amdgcn_s_barrier();
; #define SCHED __builtin_amdgcn_sched_barrier(0);
; DI void gemm256(const u16* __restrict__ A, int lda, const u16* __restrict__ B0, const u16* __restrict__ B1, int ldb, int nt, acc_t& acc, char* lds) {
;     ...
;   for (int t = 0; t < nt - 2; t += 2) {
;     LDB(Bq0, 0, 0) SCHED LDA(At, 0, 0) STAGE_A(1, 1, t + 1)
;     WAIT_L(8) BAR WAIT_L(0) MMA(0, 0, At, Bq0) BAR SCHED
;     LDB(Bq1, 0, 1) STAGE_B(0, 0, t + 2)
;     BAR WAIT_L(0) MMA(0, 1, At, Bq1) BAR
;     LDA(At, 0, 1) STAGE_A(0, 0, t + 2)
;     BAR WAIT_L(0) MMA(1, 0, At, Bq0) BAR SCHED
;     STAGE_B(0, 1, t + 2)
;     WAIT_V(6) BAR MMA(1, 1, At, Bq1) BAR
;     LDB(Bq0, 1, 0) SCHED LDA(At, 1, 0) STAGE_A(0, 1, t + 2)
;     WAIT_L(8) BAR WAIT_L(0) MMA(0, 0, At, Bq0) BAR SCHED
.LBB0_973:
	ds_read_b128 v[142:145], v166
	ds_read_b128 v[170:173], v166 offset:1024
	ds_read_b128 v[174:177], v166 offset:2048
	ds_read_b128 v[178:181], v166 offset:3072
	v_add_u32_e32 v167, 0xc000, v149
	v_lshl_add_u64 v[222:223], s[22:23], 0, v[136:137]
	v_readfirstlane_b32 s19, v167
	v_lshl_add_u64 v[168:169], v[222:223], 0, s[0:1]
	s_mov_b32 m0, s19
	ds_read_b128 v[182:185], v148
	ds_read_b128 v[186:189], v148 offset:1024
	ds_read_b128 v[190:193], v147
	ds_read_b128 v[194:197], v147 offset:1024
	ds_read_b128 v[198:201], v146
	ds_read_b128 v[202:205], v146 offset:1024
	ds_read_b128 v[206:209], v141
	ds_read_b128 v[210:213], v141 offset:1024
	global_load_lds_dwordx4 v[168:169], off
	v_add_u32_e32 v168, 0xe000, v149
	v_lshl_add_u64 v[224:225], s[22:23], 0, v[138:139]
	v_readfirstlane_b32 s19, v168
	v_lshl_add_u64 v[216:217], v[224:225], 0, s[0:1]
	s_mov_b32 m0, s19
	s_nop 0
	global_load_lds_dwordx4 v[216:217], off
	s_waitcnt lgkmcnt(8)
	s_barrier
	s_waitcnt lgkmcnt(0)
	s_waitcnt lgkmcnt(0)
	v_mfma_f32_16x16x32_bf16 v[126:129], v[142:145], v[182:185], v[126:129]
	v_mfma_f32_16x16x32_bf16 v[122:125], v[174:177], v[182:185], v[122:125]
	v_mfma_f32_16x16x32_bf16 v[118:121], v[142:145], v[190:193], v[118:121]
	v_mfma_f32_16x16x32_bf16 v[114:117], v[174:177], v[190:193], v[114:117]
	v_mfma_f32_16x16x32_bf16 v[110:113], v[142:145], v[198:201], v[110:113]
	v_mfma_f32_16x16x32_bf16 v[106:109], v[174:177], v[198:201], v[106:109]
	v_mfma_f32_16x16x32_bf16 v[102:105], v[142:145], v[206:209], v[102:105]
	v_mfma_f32_16x16x32_bf16 v[98:101], v[174:177], v[206:209], v[98:101]
	v_mfma_f32_16x16x32_bf16 v[126:129], v[170:173], v[186:189], v[126:129]
	v_mfma_f32_16x16x32_bf16 v[122:125], v[178:181], v[186:189], v[122:125]
	v_mfma_f32_16x16x32_bf16 v[118:121], v[170:173], v[194:197], v[118:121]
	v_mfma_f32_16x16x32_bf16 v[114:117], v[178:181], v[194:197], v[114:117]
	v_mfma_f32_16x16x32_bf16 v[110:113], v[170:173], v[202:205], v[110:113]
	v_mfma_f32_16x16x32_bf16 v[106:109], v[178:181], v[202:205], v[106:109]
	v_mfma_f32_16x16x32_bf16 v[102:105], v[170:173], v[210:213], v[102:105]
	v_mfma_f32_16x16x32_bf16 v[98:101], v[178:181], v[210:213], v[98:101]
	s_barrier
	v_lshl_add_u64 v[238:239], s[22:23], 0, v[132:133]
	v_readfirstlane_b32 s19, v150
	v_lshl_add_u64 v[240:241], v[238:239], 0, s[28:29]
	s_mov_b32 m0, s19
	ds_read_b128 v[216:219], v165
	ds_read_b128 v[226:229], v165 offset:1024
	ds_read_b128 v[230:233], v165 offset:2048
	ds_read_b128 v[234:237], v165 offset:3072
	global_load_lds_dwordx4 v[240:241], off
	v_lshl_add_u64 v[240:241], s[22:23], 0, v[134:135]
	v_readfirstlane_b32 s19, v151
	v_lshl_add_u64 v[242:243], v[240:241], 0, s[28:29]
	s_mov_b32 m0, s19
	s_nop 0
	global_load_lds_dwordx4 v[242:243], off
	s_barrier
	s_waitcnt lgkmcnt(0)
	s_waitcnt lgkmcnt(0)
	v_mfma_f32_16x16x32_bf16 v[94:97], v[216:219], v[182:185], v[94:97]
	v_mfma_f32_16x16x32_bf16 v[90:93], v[230:233], v[182:185], v[90:93]
	v_mfma_f32_16x16x32_bf16 v[86:89], v[216:219], v[190:193], v[86:89]
	v_mfma_f32_16x16x32_bf16 v[82:85], v[230:233], v[190:193], v[82:85]
	v_mfma_f32_16x16x32_bf16 v[78:81], v[216:219], v[198:201], v[78:81]
	v_mfma_f32_16x16x32_bf16 v[74:77], v[230:233], v[198:201], v[74:77]
	v_mfma_f32_16x16x32_bf16 v[70:73], v[216:219], v[206:209], v[70:73]
	v_mfma_f32_16x16x32_bf16 v[66:69], v[230:233], v[206:209], v[66:69]
	v_mfma_f32_16x16x32_bf16 v[94:97], v[226:229], v[186:189], v[94:97]
	v_mfma_f32_16x16x32_bf16 v[90:93], v[234:237], v[186:189], v[90:93]
	v_mfma_f32_16x16x32_bf16 v[86:89], v[226:229], v[194:197], v[86:89]
	v_mfma_f32_16x16x32_bf16 v[82:85], v[234:237], v[194:197], v[82:85]
	v_mfma_f32_16x16x32_bf16 v[78:81], v[226:229], v[202:205], v[78:81]
	v_mfma_f32_16x16x32_bf16 v[74:77], v[234:237], v[202:205], v[74:77]
	v_mfma_f32_16x16x32_bf16 v[70:73], v[226:229], v[210:213], v[70:73]
	v_mfma_f32_16x16x32_bf16 v[66:69], v[234:237], v[210:213], v[66:69]
	v_readfirstlane_b32 s19, v149
	v_lshl_add_u64 v[242:243], v[222:223], 0, s[20:21]
	s_mov_b32 m0, s19
	v_readfirstlane_b32 s19, v153
	s_barrier
	ds_read_b128 v[182:185], v148 offset:16384
	ds_read_b128 v[186:189], v148 offset:17408
	ds_read_b128 v[190:193], v147 offset:16384
	ds_read_b128 v[194:197], v147 offset:17408
	ds_read_b128 v[198:201], v146 offset:16384
	ds_read_b128 v[202:205], v146 offset:17408
	ds_read_b128 v[206:209], v141 offset:16384
	ds_read_b128 v[210:213], v141 offset:17408
	global_load_lds_dwordx4 v[242:243], off
	v_lshl_add_u64 v[242:243], v[224:225], 0, s[20:21]
	s_mov_b32 m0, s19
	s_nop 0
	global_load_lds_dwordx4 v[242:243], off
	s_barrier
	s_waitcnt lgkmcnt(0)
	s_waitcnt lgkmcnt(0)
	v_mfma_f32_16x16x32_bf16 v[60:63], v[142:145], v[182:185], v[60:63]
	v_mfma_f32_16x16x32_bf16 v[56:59], v[174:177], v[182:185], v[56:59]
	v_mfma_f32_16x16x32_bf16 v[52:55], v[142:145], v[190:193], v[52:55]
	v_mfma_f32_16x16x32_bf16 v[48:51], v[174:177], v[190:193], v[48:51]
	v_mfma_f32_16x16x32_bf16 v[44:47], v[142:145], v[198:201], v[44:47]
	v_mfma_f32_16x16x32_bf16 v[40:43], v[174:177], v[198:201], v[40:43]
	v_mfma_f32_16x16x32_bf16 v[36:39], v[142:145], v[206:209], v[36:39]
	v_mfma_f32_16x16x32_bf16 v[32:35], v[174:177], v[206:209], v[32:35]
	v_mfma_f32_16x16x32_bf16 v[60:63], v[170:173], v[186:189], v[60:63]
	v_mfma_f32_16x16x32_bf16 v[56:59], v[178:181], v[186:189], v[56:59]
	v_mfma_f32_16x16x32_bf16 v[52:55], v[170:173], v[194:197], v[52:55]
	v_mfma_f32_16x16x32_bf16 v[48:51], v[178:181], v[194:197], v[48:51]
	v_mfma_f32_16x16x32_bf16 v[44:47], v[170:173], v[202:205], v[44:47]
	v_mfma_f32_16x16x32_bf16 v[40:43], v[178:181], v[202:205], v[40:43]
	v_mfma_f32_16x16x32_bf16 v[36:39], v[170:173], v[210:213], v[36:39]
	v_mfma_f32_16x16x32_bf16 v[32:35], v[178:181], v[210:213], v[32:35]
	s_barrier
; #define STAGE_A(b, h, kt) { const u16* ap_ = A + (size_t)((h) * ahalf + (unsigned)(kt) * 64u); glds16(ap_ + ao0, l0 + SA_(b, h)); glds16(ap_ + ao1, l0 + SA_(b, h) + 8192); }
; #define STAGE_B(b, h, kt) { const u16* bp_ = ((h) ? B1 : B0) + (unsigned)(kt) * 64u; glds16(bp_ + bo0, l0 + SB_(b, h)); glds16(bp_ + bo1, l0 + SB_(b, h) + 8192); }
; #define LDA(dst, b, h) _Pragma("unroll") for (int m = 0; m < 4; ++m) _Pragma("unroll") for (int k = 0; k < 2; ++k) \
;     dst[m][k] = *(const bf16x8*)(lds + SA_(b, h) + lds_byte(wr * 64 + m * 16 + fr, k * 32 + fq * 8));
; #define LDB(dst, b, h) _Pragma("unroll") for (int n = 0; n < 2; ++n) _Pragma("unroll") for (int k = 0; k < 2; ++k) \
;     dst[n][k] = *(const bf16x8*)(lds + SB_(b, h) + lds_byte(wc * 32 + n * 16 + fr, k * 32 + fq * 8));
; #define MMA(ai, bj, At_, Bt_) { __builtin_amdgcn_s_setprio(1); \
;     _Pragma("unroll") for (int m = 0; m < 4; ++m) _Pragma("unroll") for (int n = 0; n < 2; ++n) _Pragma("unroll") for (int k = 0; k < 2; ++k) \
;       acc[ai][bj][m][n] = MFMA16(Bt_[n][k], At_[m][k], acc[ai][bj][m][n]); \
;     __builtin_amdgcn_s_setprio(0); }
; #define WAIT_V(n) asm volatile("s_waitcnt vmcnt(" #n ")" ::: "memory");
; #define WAIT_L(n) asm volatile("s_waitcnt lgkmcnt(" #n ")" ::: "memory");
; #define BAR __builtin_amdgcn_s_barrier();
; #define SCHED __builtin_amdgcn_sched_barrier(0);
; DI void gemm256(const u16* __restrict__ A, int lda, const u16* __restrict__ B0, const u16* __restrict__ B1, int ldb, int nt, acc_t& acc, char* lds) {
;     ...
;     WAIT_V(6) BAR MMA(1, 1, At, Bq1) BAR
;     LDB(Bq0, 1, 0) SCHED LDA(At, 1, 0) STAGE_A(0, 1, t + 2)
;     WAIT_L(8) BAR WAIT_L(0) MMA(0, 0, At, Bq0) BAR SCHED
;     LDB(Bq1, 1, 1) STAGE_B(1, 0, t + 3)
;     BAR WAIT_L(0) MMA(0, 1, At, Bq1) BAR
;     LDA(At, 1, 1) STAGE_A(1, 0, t + 3)
;     BAR WAIT_L(0) MMA(1, 0, At, Bq0) BAR SCHED
;     STAGE_B(1, 1, t + 3)
;     WAIT_V(6) BAR MMA(1, 1, At, Bq1) BAR
	v_readfirstlane_b32 s19, v154
	v_lshl_add_u64 v[142:143], v[238:239], 0, s[44:45]
	s_mov_b32 m0, s19
	v_readfirstlane_b32 s19, v155
	global_load_lds_dwordx4 v[142:143], off
	v_lshl_add_u64 v[142:143], v[240:241], 0, s[44:45]
	s_mov_b32 m0, s19
	s_nop 0
	global_load_lds_dwordx4 v[142:143], off
	s_waitcnt vmcnt(6)
	s_barrier
	v_mfma_f32_16x16x32_bf16 v[28:31], v[216:219], v[182:185], v[28:31]
	v_mfma_f32_16x16x32_bf16 v[24:27], v[230:233], v[182:185], v[24:27]
	v_mfma_f32_16x16x32_bf16 v[20:23], v[216:219], v[190:193], v[20:23]
	v_mfma_f32_16x16x32_bf16 v[16:19], v[230:233], v[190:193], v[16:19]
	v_mfma_f32_16x16x32_bf16 v[12:15], v[216:219], v[198:201], v[12:15]
	v_mfma_f32_16x16x32_bf16 v[8:11], v[230:233], v[198:201], v[8:11]
	v_mfma_f32_16x16x32_bf16 v[4:7], v[216:219], v[206:209], v[4:7]
	v_mfma_f32_16x16x32_bf16 v[0:3], v[230:233], v[206:209], v[0:3]
	v_mfma_f32_16x16x32_bf16 v[28:31], v[226:229], v[186:189], v[28:31]
	v_mfma_f32_16x16x32_bf16 v[24:27], v[234:237], v[186:189], v[24:27]
	v_mfma_f32_16x16x32_bf16 v[20:23], v[226:229], v[194:197], v[20:23]
	v_mfma_f32_16x16x32_bf16 v[16:19], v[234:237], v[194:197], v[16:19]
	v_mfma_f32_16x16x32_bf16 v[12:15], v[226:229], v[202:205], v[12:15]
	v_mfma_f32_16x16x32_bf16 v[8:11], v[234:237], v[202:205], v[8:11]
	v_mfma_f32_16x16x32_bf16 v[4:7], v[226:229], v[210:213], v[4:7]
	v_mfma_f32_16x16x32_bf16 v[0:3], v[234:237], v[210:213], v[0:3]
	s_barrier
	ds_read_b128 v[142:145], v156
	ds_read_b128 v[170:173], v156 offset:1024
	ds_read_b128 v[174:177], v156 offset:2048
	ds_read_b128 v[178:181], v156 offset:3072
	v_readfirstlane_b32 s19, v157
	v_lshl_add_u64 v[216:217], v[222:223], 0, s[24:25]
	s_mov_b32 m0, s19
	v_readfirstlane_b32 s19, v158
	ds_read_b128 v[182:185], v148 offset:32768
	ds_read_b128 v[186:189], v148 offset:33792
	ds_read_b128 v[190:193], v147 offset:32768
	ds_read_b128 v[194:197], v147 offset:33792
	ds_read_b128 v[198:201], v146 offset:32768
	ds_read_b128 v[202:205], v146 offset:33792
	ds_read_b128 v[206:209], v141 offset:32768
	ds_read_b128 v[210:213], v141 offset:33792
	global_load_lds_dwordx4 v[216:217], off
	v_lshl_add_u64 v[216:217], v[224:225], 0, s[24:25]
	s_mov_b32 m0, s19
	s_nop 0
	global_load_lds_dwordx4 v[216:217], off
	s_waitcnt lgkmcnt(8)
	s_barrier
	s_waitcnt lgkmcnt(0)
	s_waitcnt lgkmcnt(0)
	v_mfma_f32_16x16x32_bf16 v[126:129], v[142:145], v[182:185], v[126:129]
	v_mfma_f32_16x16x32_bf16 v[122:125], v[174:177], v[182:185], v[122:125]
	v_mfma_f32_16x16x32_bf16 v[118:121], v[142:145], v[190:193], v[118:121]
	v_mfma_f32_16x16x32_bf16 v[114:117], v[174:177], v[190:193], v[114:117]
	v_mfma_f32_16x16x32_bf16 v[110:113], v[142:145], v[198:201], v[110:113]
	v_mfma_f32_16x16x32_bf16 v[106:109], v[174:177], v[198:201], v[106:109]
	v_mfma_f32_16x16x32_bf16 v[102:105], v[142:145], v[206:209], v[102:105]
	v_mfma_f32_16x16x32_bf16 v[98:101], v[174:177], v[206:209], v[98:101]
	v_mfma_f32_16x16x32_bf16 v[126:129], v[170:173], v[186:189], v[126:129]
	v_mfma_f32_16x16x32_bf16 v[122:125], v[178:181], v[186:189], v[122:125]
	v_mfma_f32_16x16x32_bf16 v[118:121], v[170:173], v[194:197], v[118:121]
	v_mfma_f32_16x16x32_bf16 v[114:117], v[178:181], v[194:197], v[114:117]
	v_mfma_f32_16x16x32_bf16 v[110:113], v[170:173], v[202:205], v[110:113]
	v_mfma_f32_16x16x32_bf16 v[106:109], v[178:181], v[202:205], v[106:109]
	v_mfma_f32_16x16x32_bf16 v[102:105], v[170:173], v[210:213], v[102:105]
	v_mfma_f32_16x16x32_bf16 v[98:101], v[178:181], v[210:213], v[98:101]
	s_barrier
	v_readfirstlane_b32 s19, v159
	v_lshl_add_u64 v[242:243], v[238:239], 0, s[48:49]
	s_mov_b32 m0, s19
	v_readfirstlane_b32 s19, v160
	ds_read_b128 v[216:219], v152
	ds_read_b128 v[226:229], v152 offset:1024
	ds_read_b128 v[230:233], v152 offset:2048
	ds_read_b128 v[234:237], v152 offset:3072
	global_load_lds_dwordx4 v[242:243], off
	v_lshl_add_u64 v[242:243], v[240:241], 0, s[48:49]
	s_mov_b32 m0, s19
	s_nop 0
	global_load_lds_dwordx4 v[242:243], off
	s_barrier
	s_waitcnt lgkmcnt(0)
	s_waitcnt lgkmcnt(0)
	v_mfma_f32_16x16x32_bf16 v[94:97], v[216:219], v[182:185], v[94:97]
	v_mfma_f32_16x16x32_bf16 v[90:93], v[230:233], v[182:185], v[90:93]
	v_mfma_f32_16x16x32_bf16 v[86:89], v[216:219], v[190:193], v[86:89]
	v_mfma_f32_16x16x32_bf16 v[82:85], v[230:233], v[190:193], v[82:85]
	v_mfma_f32_16x16x32_bf16 v[78:81], v[216:219], v[198:201], v[78:81]
	v_mfma_f32_16x16x32_bf16 v[74:77], v[230:233], v[198:201], v[74:77]
	v_mfma_f32_16x16x32_bf16 v[70:73], v[216:219], v[206:209], v[70:73]
	v_mfma_f32_16x16x32_bf16 v[66:69], v[230:233], v[206:209], v[66:69]
	v_mfma_f32_16x16x32_bf16 v[94:97], v[226:229], v[186:189], v[94:97]
	v_mfma_f32_16x16x32_bf16 v[90:93], v[234:237], v[186:189], v[90:93]
	v_mfma_f32_16x16x32_bf16 v[86:89], v[226:229], v[194:197], v[86:89]
	v_mfma_f32_16x16x32_bf16 v[82:85], v[234:237], v[194:197], v[82:85]
	v_mfma_f32_16x16x32_bf16 v[78:81], v[226:229], v[202:205], v[78:81]
	v_mfma_f32_16x16x32_bf16 v[74:77], v[234:237], v[202:205], v[74:77]
	v_mfma_f32_16x16x32_bf16 v[70:73], v[226:229], v[210:213], v[70:73]
	v_mfma_f32_16x16x32_bf16 v[66:69], v[234:237], v[210:213], v[66:69]
	v_readfirstlane_b32 s19, v161
	v_lshl_add_u64 v[222:223], v[222:223], 0, s[34:35]
	s_mov_b32 m0, s19
	v_readfirstlane_b32 s19, v162
	s_barrier
	ds_read_b128 v[182:185], v148 offset:49152
	ds_read_b128 v[186:189], v148 offset:50176
	ds_read_b128 v[190:193], v147 offset:49152
	ds_read_b128 v[194:197], v147 offset:50176
	ds_read_b128 v[198:201], v146 offset:49152
	ds_read_b128 v[202:205], v146 offset:50176
	ds_read_b128 v[206:209], v141 offset:49152
	ds_read_b128 v[210:213], v141 offset:50176
	global_load_lds_dwordx4 v[222:223], off
	v_lshl_add_u64 v[222:223], v[224:225], 0, s[34:35]
	s_mov_b32 m0, s19
	s_nop 0
	global_load_lds_dwordx4 v[222:223], off
	s_barrier
; #define STAGE_A(b, h, kt) { const u16* ap_ = A + (size_t)((h) * ahalf + (unsigned)(kt) * 64u); glds16(ap_ + ao0, l0 + SA_(b, h)); glds16(ap_ + ao1, l0 + SA_(b, h) + 8192); }
; #define STAGE_B(b, h, kt) { const u16* bp_ = ((h) ? B1 : B0) + (unsigned)(kt) * 64u; glds16(bp_ + bo0, l0 + SB_(b, h)); glds16(bp_ + bo1, l0 + SB_(b, h) + 8192); }
; #define LDA(dst, b, h) _Pragma("unroll") for (int m = 0; m < 4; ++m) _Pragma("unroll") for (int k = 0; k < 2; ++k) \
;     dst[m][k] = *(const bf16x8*)(lds + SA_(b, h) + lds_byte(wr * 64 + m * 16 + fr, k * 32 + fq * 8));
; #define LDB(dst, b, h) _Pragma("unroll") for (int n = 0; n < 2; ++n) _Pragma("unroll") for (int k = 0; k < 2; ++k) \
;     dst[n][k] = *(const bf16x8*)(lds + SB_(b, h) + lds_byte(wc * 32 + n * 16 + fr, k * 32 + fq * 8));
; #define MMA(ai, bj, At_, Bt_) { __builtin_amdgcn_s_setprio(1); \
;     _Pragma("unroll") for (int m = 0; m < 4; ++m) _Pragma("unroll") for (int n = 0; n < 2; ++n) _Pragma("unroll") for (int k = 0; k < 2; ++k) \
;       acc[ai][bj][m][n] = MFMA16(Bt_[n][k], At_[m][k], acc[ai][bj][m][n]); \
;     __builtin_amdgcn_s_setprio(0); }
; #define WAIT_V(n) asm volatile("s_waitcnt vmcnt(" #n ")" ::: "memory");
; #define WAIT_L(n) asm volatile("s_waitcnt lgkmcnt(" #n ")" ::: "memory");
; #define BAR __builtin_amdgcn_s_barrier();
; #define SCHED __builtin_amdgcn_sched_barrier(0);
; DI void gemm256(const u16* __restrict__ A, int lda, const u16* __restrict__ B0, const u16* __restrict__ B1, int ldb, int nt, acc_t& acc, char* lds) {
;     ...
;     LDA(At, 1, 1) STAGE_A(1, 0, t + 3)
;     BAR WAIT_L(0) MMA(1, 0, At, Bq0) BAR SCHED
;     STAGE_B(1, 1, t + 3)
;     WAIT_V(6) BAR MMA(1, 1, At, Bq1) BAR
;   }
;   { LDB(Bq0, 0, 0) LDA(At, 0, 0) STAGE_A(1, 1, nt - 1)
;     BAR WAIT_L(0) MMA(0, 0, At, Bq0) BAR
;     LDB(Bq1, 0, 1) BAR WAIT_L(0) MMA(0, 1, At, Bq1) BAR
	s_waitcnt lgkmcnt(0)
	s_waitcnt lgkmcnt(0)
	v_mfma_f32_16x16x32_bf16 v[60:63], v[142:145], v[182:185], v[60:63]
	v_mfma_f32_16x16x32_bf16 v[56:59], v[174:177], v[182:185], v[56:59]
	v_mfma_f32_16x16x32_bf16 v[52:55], v[142:145], v[190:193], v[52:55]
	v_mfma_f32_16x16x32_bf16 v[48:51], v[174:177], v[190:193], v[48:51]
	v_mfma_f32_16x16x32_bf16 v[44:47], v[142:145], v[198:201], v[44:47]
	v_mfma_f32_16x16x32_bf16 v[40:43], v[174:177], v[198:201], v[40:43]
	v_mfma_f32_16x16x32_bf16 v[36:39], v[142:145], v[206:209], v[36:39]
	v_mfma_f32_16x16x32_bf16 v[32:35], v[174:177], v[206:209], v[32:35]
	v_mfma_f32_16x16x32_bf16 v[60:63], v[170:173], v[186:189], v[60:63]
	v_mfma_f32_16x16x32_bf16 v[56:59], v[178:181], v[186:189], v[56:59]
	v_mfma_f32_16x16x32_bf16 v[52:55], v[170:173], v[194:197], v[52:55]
	v_mfma_f32_16x16x32_bf16 v[48:51], v[178:181], v[194:197], v[48:51]
	v_mfma_f32_16x16x32_bf16 v[44:47], v[170:173], v[202:205], v[44:47]
	v_mfma_f32_16x16x32_bf16 v[40:43], v[178:181], v[202:205], v[40:43]
	v_mfma_f32_16x16x32_bf16 v[36:39], v[170:173], v[210:213], v[36:39]
	v_mfma_f32_16x16x32_bf16 v[32:35], v[178:181], v[210:213], v[32:35]
	s_barrier
	v_readfirstlane_b32 s19, v163
	v_lshl_add_u64 v[142:143], v[238:239], 0, s[54:55]
	s_mov_b32 m0, s19
	v_readfirstlane_b32 s19, v164
	global_load_lds_dwordx4 v[142:143], off
	v_lshl_add_u64 v[142:143], v[240:241], 0, s[54:55]
	s_mov_b32 m0, s19
	s_nop 0
	global_load_lds_dwordx4 v[142:143], off
	s_waitcnt vmcnt(6)
	s_barrier
	v_mfma_f32_16x16x32_bf16 v[28:31], v[216:219], v[182:185], v[28:31]
	v_mfma_f32_16x16x32_bf16 v[24:27], v[230:233], v[182:185], v[24:27]
	v_mfma_f32_16x16x32_bf16 v[20:23], v[216:219], v[190:193], v[20:23]
	v_mfma_f32_16x16x32_bf16 v[16:19], v[230:233], v[190:193], v[16:19]
	v_mfma_f32_16x16x32_bf16 v[12:15], v[216:219], v[198:201], v[12:15]
	v_mfma_f32_16x16x32_bf16 v[8:11], v[230:233], v[198:201], v[8:11]
	v_mfma_f32_16x16x32_bf16 v[4:7], v[216:219], v[206:209], v[4:7]
	v_mfma_f32_16x16x32_bf16 v[0:3], v[230:233], v[206:209], v[0:3]
	v_mfma_f32_16x16x32_bf16 v[28:31], v[226:229], v[186:189], v[28:31]
	v_mfma_f32_16x16x32_bf16 v[24:27], v[234:237], v[186:189], v[24:27]
	v_mfma_f32_16x16x32_bf16 v[20:23], v[226:229], v[194:197], v[20:23]
	v_mfma_f32_16x16x32_bf16 v[16:19], v[234:237], v[194:197], v[16:19]
	v_mfma_f32_16x16x32_bf16 v[12:15], v[226:229], v[202:205], v[12:15]
	v_mfma_f32_16x16x32_bf16 v[8:11], v[234:237], v[202:205], v[8:11]
	v_mfma_f32_16x16x32_bf16 v[4:7], v[226:229], v[210:213], v[4:7]
	v_mfma_f32_16x16x32_bf16 v[0:3], v[234:237], v[210:213], v[0:3]
	s_add_i32 s7, s7, 2
	s_add_u32 s22, s22, 0x100
	s_addc_u32 s23, s23, 0
	s_cmp_lt_u32 s7, 12
	s_barrier
	s_cbranch_scc1 .LBB0_973
	s_add_u32 s54, s50, 0x40780
	s_addc_u32 s55, s51, 0
	v_readfirstlane_b32 s7, v167
	v_lshl_add_u64 v[150:151], v[64:65], 1, s[54:55]
	s_mov_b32 m0, s7
	v_readfirstlane_b32 s7, v168
	ds_read_b128 v[132:135], v166
	ds_read_b128 v[136:139], v166 offset:1024
	ds_read_b128 v[142:145], v166 offset:2048
	ds_read_b128 v[158:161], v166 offset:3072
	ds_read_b128 v[170:173], v148
	ds_read_b128 v[174:177], v148 offset:1024
	ds_read_b128 v[178:181], v147
	ds_read_b128 v[182:185], v147 offset:1024
	ds_read_b128 v[186:189], v146
	ds_read_b128 v[190:193], v146 offset:1024
	ds_read_b128 v[194:197], v141
	ds_read_b128 v[198:201], v141 offset:1024
	global_load_lds_dwordx4 v[150:151], off
	v_lshl_add_u64 v[130:131], v[130:131], 1, s[54:55]
	s_mov_b32 m0, s7
	s_nop 0
	global_load_lds_dwordx4 v[130:131], off
	s_barrier
	s_waitcnt lgkmcnt(0)
	s_waitcnt lgkmcnt(0)
	v_mfma_f32_16x16x32_bf16 v[126:129], v[132:135], v[170:173], v[126:129]
	v_mfma_f32_16x16x32_bf16 v[122:125], v[142:145], v[170:173], v[122:125]
	v_mfma_f32_16x16x32_bf16 v[118:121], v[132:135], v[178:181], v[118:121]
	v_mfma_f32_16x16x32_bf16 v[114:117], v[142:145], v[178:181], v[114:117]
	v_mfma_f32_16x16x32_bf16 v[102:105], v[132:135], v[194:197], v[102:105]
	v_mfma_f32_16x16x32_bf16 v[98:101], v[142:145], v[194:197], v[98:101]
	v_mfma_f32_16x16x32_bf16 v[126:129], v[136:139], v[174:177], v[126:129]
	v_mfma_f32_16x16x32_bf16 v[122:125], v[158:161], v[174:177], v[122:125]
	v_mfma_f32_16x16x32_bf16 v[118:121], v[136:139], v[182:185], v[118:121]
	v_mfma_f32_16x16x32_bf16 v[114:117], v[158:161], v[182:185], v[114:117]
	v_mfma_f32_16x16x32_bf16 v[110:113], v[132:135], v[186:189], v[110:113]
	v_mfma_f32_16x16x32_bf16 v[106:109], v[142:145], v[186:189], v[106:109]
	v_mfma_f32_16x16x32_bf16 v[102:105], v[136:139], v[198:201], v[102:105]
	v_mfma_f32_16x16x32_bf16 v[98:101], v[158:161], v[198:201], v[98:101]
	v_mfma_f32_16x16x32_bf16 v[166:169], v[136:139], v[190:193], v[110:113]
	v_mfma_f32_16x16x32_bf16 v[202:205], v[158:161], v[190:193], v[106:109]
	s_barrier
	s_nop 1
	ds_read_b128 v[106:109], v165
	ds_read_b128 v[110:113], v165 offset:1024
	ds_read_b128 v[206:209], v165 offset:2048
	ds_read_b128 v[162:165], v165 offset:3072
	s_barrier
	s_waitcnt lgkmcnt(0)
	s_waitcnt lgkmcnt(0)
	v_mfma_f32_16x16x32_bf16 v[86:89], v[106:109], v[178:181], v[86:89]
	v_mfma_f32_16x16x32_bf16 v[82:85], v[206:209], v[178:181], v[82:85]
	v_mfma_f32_16x16x32_bf16 v[70:73], v[106:109], v[194:197], v[70:73]
	v_mfma_f32_16x16x32_bf16 v[66:69], v[206:209], v[194:197], v[66:69]
	v_mfma_f32_16x16x32_bf16 v[94:97], v[106:109], v[170:173], v[94:97]
	v_mfma_f32_16x16x32_bf16 v[90:93], v[206:209], v[170:173], v[90:93]
	v_mfma_f32_16x16x32_bf16 v[86:89], v[110:113], v[182:185], v[86:89]
	v_mfma_f32_16x16x32_bf16 v[82:85], v[162:165], v[182:185], v[82:85]
	v_mfma_f32_16x16x32_bf16 v[78:81], v[106:109], v[186:189], v[78:81]
	v_mfma_f32_16x16x32_bf16 v[74:77], v[206:209], v[186:189], v[74:77]
	v_mfma_f32_16x16x32_bf16 v[70:73], v[110:113], v[198:201], v[70:73]
	v_mfma_f32_16x16x32_bf16 v[66:69], v[162:165], v[198:201], v[66:69]
	v_mfma_f32_16x16x32_bf16 v[210:213], v[110:113], v[174:177], v[94:97]
	v_mfma_f32_16x16x32_bf16 v[170:173], v[162:165], v[174:177], v[90:93]
	v_mfma_f32_16x16x32_bf16 v[174:177], v[110:113], v[190:193], v[78:81]
	v_mfma_f32_16x16x32_bf16 v[178:181], v[162:165], v[190:193], v[74:77]
	s_barrier
; #define LDA(dst, b, h) _Pragma("unroll") for (int m = 0; m < 4; ++m) _Pragma("unroll") for (int k = 0; k < 2; ++k) \
;     dst[m][k] = *(const bf16x8*)(lds + SA_(b, h) + lds_byte(wr * 64 + m * 16 + fr, k * 32 + fq * 8));
; #define LDB(dst, b, h) _Pragma("unroll") for (int n = 0; n < 2; ++n) _Pragma("unroll") for (int k = 0; k < 2; ++k) \
;     dst[n][k] = *(const bf16x8*)(lds + SB_(b, h) + lds_byte(wc * 32 + n * 16 + fr, k * 32 + fq * 8));
; #define MMA(ai, bj, At_, Bt_) { __builtin_amdgcn_s_setprio(1); \
;     _Pragma("unroll") for (int m = 0; m < 4; ++m) _Pragma("unroll") for (int n = 0; n < 2; ++n) _Pragma("unroll") for (int k = 0; k < 2; ++k) \
;       acc[ai][bj][m][n] = MFMA16(Bt_[n][k], At_[m][k], acc[ai][bj][m][n]); \
;     __builtin_amdgcn_s_setprio(0); }
; #define WAIT_V(n) asm volatile("s_waitcnt vmcnt(" #n ")" ::: "memory");
; #define WAIT_L(n) asm volatile("s_waitcnt lgkmcnt(" #n ")" ::: "memory");
; #define BAR __builtin_amdgcn_s_barrier();
; DI void gemm256(const u16* __restrict__ A, int lda, const u16* __restrict__ B0, const u16* __restrict__ B1, int ldb, int nt, acc_t& acc, char* lds) {
;     ...
;     BAR WAIT_L(0) MMA(0, 0, At, Bq0) BAR
;     LDB(Bq1, 0, 1) BAR WAIT_L(0) MMA(0, 1, At, Bq1) BAR
;     LDA(At, 0, 1) WAIT_V(4) BAR WAIT_L(0) MMA(1, 0, At, Bq0) MMA(1, 1, At, Bq1) BAR }
;   { LDB(Bq0, 1, 0) LDA(At, 1, 0) WAIT_V(2) BAR WAIT_L(0) MMA(0, 0, At, Bq0) BAR
;     LDB(Bq1, 1, 1) WAIT_V(0) BAR WAIT_L(0) MMA(0, 1, At, Bq1) BAR
	s_nop 0
	ds_read_b128 v[74:77], v148 offset:16384
	ds_read_b128 v[78:81], v148 offset:17408
	ds_read_b128 v[90:93], v147 offset:16384
	ds_read_b128 v[94:97], v147 offset:17408
	ds_read_b128 v[182:185], v146 offset:16384
	ds_read_b128 v[186:189], v146 offset:17408
	ds_read_b128 v[190:193], v141 offset:16384
	ds_read_b128 v[194:197], v141 offset:17408
	s_waitcnt vmcnt(4)
	s_barrier
	s_waitcnt lgkmcnt(0)
	s_waitcnt lgkmcnt(0)
	v_mfma_f32_16x16x32_bf16 v[60:63], v[132:135], v[74:77], v[60:63]
	v_mfma_f32_16x16x32_bf16 v[56:59], v[142:145], v[74:77], v[56:59]
	v_mfma_f32_16x16x32_bf16 v[52:55], v[132:135], v[90:93], v[52:55]
	v_mfma_f32_16x16x32_bf16 v[48:51], v[142:145], v[90:93], v[48:51]
	v_mfma_f32_16x16x32_bf16 v[36:39], v[132:135], v[190:193], v[36:39]
	v_mfma_f32_16x16x32_bf16 v[32:35], v[142:145], v[190:193], v[32:35]
	v_mfma_f32_16x16x32_bf16 v[60:63], v[136:139], v[78:81], v[60:63]
	v_mfma_f32_16x16x32_bf16 v[56:59], v[158:161], v[78:81], v[56:59]
	v_mfma_f32_16x16x32_bf16 v[52:55], v[136:139], v[94:97], v[52:55]
	v_mfma_f32_16x16x32_bf16 v[48:51], v[158:161], v[94:97], v[48:51]
	v_mfma_f32_16x16x32_bf16 v[44:47], v[132:135], v[182:185], v[44:47]
	v_mfma_f32_16x16x32_bf16 v[40:43], v[142:145], v[182:185], v[40:43]
	v_mfma_f32_16x16x32_bf16 v[36:39], v[136:139], v[194:197], v[36:39]
	v_mfma_f32_16x16x32_bf16 v[32:35], v[158:161], v[194:197], v[32:35]
	v_mfma_f32_16x16x32_bf16 v[198:201], v[136:139], v[186:189], v[44:47]
	v_mfma_f32_16x16x32_bf16 v[216:219], v[158:161], v[186:189], v[40:43]
	v_mfma_f32_16x16x32_bf16 v[20:23], v[106:109], v[90:93], v[20:23]
	v_mfma_f32_16x16x32_bf16 v[16:19], v[206:209], v[90:93], v[16:19]
	v_mfma_f32_16x16x32_bf16 v[4:7], v[106:109], v[190:193], v[4:7]
	v_mfma_f32_16x16x32_bf16 v[0:3], v[206:209], v[190:193], v[0:3]
	v_mfma_f32_16x16x32_bf16 v[28:31], v[106:109], v[74:77], v[28:31]
	v_mfma_f32_16x16x32_bf16 v[24:27], v[206:209], v[74:77], v[24:27]
	v_mfma_f32_16x16x32_bf16 v[20:23], v[110:113], v[94:97], v[20:23]
	v_mfma_f32_16x16x32_bf16 v[16:19], v[162:165], v[94:97], v[16:19]
	v_mfma_f32_16x16x32_bf16 v[12:15], v[106:109], v[182:185], v[12:15]
	v_mfma_f32_16x16x32_bf16 v[8:11], v[206:209], v[182:185], v[8:11]
	v_mfma_f32_16x16x32_bf16 v[4:7], v[110:113], v[194:197], v[4:7]
	v_mfma_f32_16x16x32_bf16 v[0:3], v[162:165], v[194:197], v[0:3]
	v_mfma_f32_16x16x32_bf16 v[130:133], v[110:113], v[78:81], v[28:31]
	v_mfma_f32_16x16x32_bf16 v[134:137], v[162:165], v[78:81], v[24:27]
	v_mfma_f32_16x16x32_bf16 v[142:145], v[110:113], v[186:189], v[12:15]
	v_mfma_f32_16x16x32_bf16 v[158:161], v[162:165], v[186:189], v[8:11]
	s_barrier
	s_nop 0
	ds_read_b128 v[8:11], v156
	ds_read_b128 v[12:15], v156 offset:1024
	ds_read_b128 v[162:165], v156 offset:2048
	ds_read_b128 v[154:157], v156 offset:3072
	ds_read_b128 v[24:27], v148 offset:32768
	ds_read_b128 v[28:31], v148 offset:33792
	ds_read_b128 v[40:43], v147 offset:32768
	ds_read_b128 v[44:47], v147 offset:33792
	ds_read_b128 v[182:185], v146 offset:32768
	ds_read_b128 v[186:189], v146 offset:33792
	ds_read_b128 v[190:193], v141 offset:32768
	ds_read_b128 v[194:197], v141 offset:33792
	s_waitcnt vmcnt(2)
	s_barrier
	s_waitcnt lgkmcnt(0)
	s_waitcnt lgkmcnt(0)
	v_mfma_f32_16x16x32_bf16 v[74:77], v[8:11], v[24:27], v[126:129]
	v_mfma_f32_16x16x32_bf16 v[126:129], v[12:15], v[28:31], v[74:77]
	v_mfma_f32_16x16x32_bf16 v[74:77], v[162:165], v[24:27], v[122:125]
	v_mfma_f32_16x16x32_bf16 v[122:125], v[154:157], v[28:31], v[74:77]
	v_mfma_f32_16x16x32_bf16 v[74:77], v[8:11], v[40:43], v[118:121]
	v_mfma_f32_16x16x32_bf16 v[110:113], v[12:15], v[44:47], v[74:77]
	v_mfma_f32_16x16x32_bf16 v[74:77], v[162:165], v[40:43], v[114:117]
	v_mfma_f32_16x16x32_bf16 v[106:109], v[154:157], v[44:47], v[74:77]
	v_mfma_f32_16x16x32_bf16 v[74:77], v[8:11], v[182:185], v[166:169]
	v_mfma_f32_16x16x32_bf16 v[94:97], v[12:15], v[186:189], v[74:77]
	v_mfma_f32_16x16x32_bf16 v[74:77], v[162:165], v[182:185], v[202:205]
	v_mfma_f32_16x16x32_bf16 v[90:93], v[154:157], v[186:189], v[74:77]
	v_mfma_f32_16x16x32_bf16 v[74:77], v[8:11], v[190:193], v[102:105]
	v_mfma_f32_16x16x32_bf16 v[78:81], v[12:15], v[194:197], v[74:77]
	v_mfma_f32_16x16x32_bf16 v[74:77], v[162:165], v[190:193], v[98:101]
	v_mfma_f32_16x16x32_bf16 v[74:77], v[154:157], v[194:197], v[74:77]
	s_barrier
; #define LDA(dst, b, h) _Pragma("unroll") for (int m = 0; m < 4; ++m) _Pragma("unroll") for (int k = 0; k < 2; ++k) \
;     dst[m][k] = *(const bf16x8*)(lds + SA_(b, h) + lds_byte(wr * 64 + m * 16 + fr, k * 32 + fq * 8));
; #define LDB(dst, b, h) _Pragma("unroll") for (int n = 0; n < 2; ++n) _Pragma("unroll") for (int k = 0; k < 2; ++k) \
;     dst[n][k] = *(const bf16x8*)(lds + SB_(b, h) + lds_byte(wc * 32 + n * 16 + fr, k * 32 + fq * 8));
; #define MMA(ai, bj, At_, Bt_) { __builtin_amdgcn_s_setprio(1); \
;     _Pragma("unroll") for (int m = 0; m < 4; ++m) _Pragma("unroll") for (int n = 0; n < 2; ++n) _Pragma("unroll") for (int k = 0; k < 2; ++k) \
;       acc[ai][bj][m][n] = MFMA16(Bt_[n][k], At_[m][k], acc[ai][bj][m][n]); \
;     __builtin_amdgcn_s_setprio(0); }
; #define WAIT_V(n) asm volatile("s_waitcnt vmcnt(" #n ")" ::: "memory");
; #define WAIT_L(n) asm volatile("s_waitcnt lgkmcnt(" #n ")" ::: "memory");
; #define BAR __builtin_amdgcn_s_barrier();
; DI void gemm256(const u16* __restrict__ A, int lda, const u16* __restrict__ B0, const u16* __restrict__ B1, int ldb, int nt, acc_t& acc, char* lds) {
;     ...
;   { LDB(Bq0, 1, 0) LDA(At, 1, 0) WAIT_V(2) BAR WAIT_L(0) MMA(0, 0, At, Bq0) BAR
;     LDB(Bq1, 1, 1) WAIT_V(0) BAR WAIT_L(0) MMA(0, 1, At, Bq1) BAR
;     LDA(At, 1, 1) BAR WAIT_L(0) MMA(1, 0, At, Bq0) MMA(1, 1, At, Bq1) BAR }
;   if (wr == 0) BAR
;   __syncthreads();
	ds_read_b128 v[166:169], v152
	ds_read_b128 v[202:205], v152 offset:1024
	ds_read_b128 v[206:209], v152 offset:2048
	ds_read_b128 v[150:153], v152 offset:3072
	s_waitcnt vmcnt(0)
	s_barrier
	s_waitcnt lgkmcnt(0)
	s_waitcnt lgkmcnt(0)
	v_mfma_f32_16x16x32_bf16 v[98:101], v[166:169], v[24:27], v[210:213]
	v_mfma_f32_16x16x32_bf16 v[24:27], v[206:209], v[24:27], v[170:173]
	v_mfma_f32_16x16x32_bf16 v[114:117], v[150:153], v[28:31], v[24:27]
	v_mfma_f32_16x16x32_bf16 v[24:27], v[166:169], v[40:43], v[86:89]
	v_mfma_f32_16x16x32_bf16 v[102:105], v[202:205], v[44:47], v[24:27]
	v_mfma_f32_16x16x32_bf16 v[24:27], v[206:209], v[40:43], v[82:85]
	v_mfma_f32_16x16x32_bf16 v[118:121], v[202:205], v[28:31], v[98:101]
	v_mfma_f32_16x16x32_bf16 v[98:101], v[150:153], v[44:47], v[24:27]
	v_mfma_f32_16x16x32_bf16 v[24:27], v[166:169], v[182:185], v[174:177]
	v_mfma_f32_16x16x32_bf16 v[86:89], v[202:205], v[186:189], v[24:27]
	v_mfma_f32_16x16x32_bf16 v[24:27], v[206:209], v[182:185], v[178:181]
	v_mfma_f32_16x16x32_bf16 v[82:85], v[150:153], v[186:189], v[24:27]
	v_mfma_f32_16x16x32_bf16 v[24:27], v[166:169], v[190:193], v[70:73]
	v_mfma_f32_16x16x32_bf16 v[70:73], v[202:205], v[194:197], v[24:27]
	v_mfma_f32_16x16x32_bf16 v[24:27], v[206:209], v[190:193], v[66:69]
	v_mfma_f32_16x16x32_bf16 v[66:69], v[150:153], v[194:197], v[24:27]
	s_barrier
	ds_read_b128 v[170:173], v148 offset:49152
	ds_read_b128 v[174:177], v148 offset:50176
	ds_read_b128 v[178:181], v147 offset:49152
	ds_read_b128 v[182:185], v147 offset:50176
	ds_read_b128 v[186:189], v146 offset:49152
	ds_read_b128 v[146:149], v146 offset:50176
	ds_read_b128 v[190:193], v141 offset:49152
	ds_read_b128 v[194:197], v141 offset:50176
	s_barrier
	s_waitcnt lgkmcnt(0)
	s_waitcnt lgkmcnt(0)
	v_mfma_f32_16x16x32_bf16 v[24:27], v[8:11], v[170:173], v[60:63]
	v_mfma_f32_16x16x32_bf16 v[60:63], v[12:15], v[174:177], v[24:27]
	v_mfma_f32_16x16x32_bf16 v[24:27], v[162:165], v[170:173], v[56:59]
	v_mfma_f32_16x16x32_bf16 v[56:59], v[154:157], v[174:177], v[24:27]
	v_mfma_f32_16x16x32_bf16 v[24:27], v[8:11], v[178:181], v[52:55]
	v_mfma_f32_16x16x32_bf16 v[44:47], v[12:15], v[182:185], v[24:27]
	v_mfma_f32_16x16x32_bf16 v[24:27], v[162:165], v[178:181], v[48:51]
	v_mfma_f32_16x16x32_bf16 v[40:43], v[154:157], v[182:185], v[24:27]
	v_mfma_f32_16x16x32_bf16 v[24:27], v[8:11], v[186:189], v[198:201]
	v_mfma_f32_16x16x32_bf16 v[8:11], v[8:11], v[190:193], v[36:39]
	v_mfma_f32_16x16x32_bf16 v[28:31], v[12:15], v[146:149], v[24:27]
	v_mfma_f32_16x16x32_bf16 v[24:27], v[162:165], v[186:189], v[216:219]
	v_mfma_f32_16x16x32_bf16 v[12:15], v[12:15], v[194:197], v[8:11]
	v_mfma_f32_16x16x32_bf16 v[8:11], v[162:165], v[190:193], v[32:35]
	v_mfma_f32_16x16x32_bf16 v[24:27], v[154:157], v[146:149], v[24:27]
	v_mfma_f32_16x16x32_bf16 v[8:11], v[154:157], v[194:197], v[8:11]
	v_mfma_f32_16x16x32_bf16 v[32:35], v[166:169], v[170:173], v[130:133]
	v_mfma_f32_16x16x32_bf16 v[52:55], v[202:205], v[174:177], v[32:35]
	v_mfma_f32_16x16x32_bf16 v[32:35], v[206:209], v[170:173], v[134:137]
	v_mfma_f32_16x16x32_bf16 v[16:19], v[206:209], v[178:181], v[16:19]
	v_mfma_f32_16x16x32_bf16 v[48:51], v[150:153], v[174:177], v[32:35]
	v_mfma_f32_16x16x32_bf16 v[20:23], v[166:169], v[178:181], v[20:23]
	v_mfma_f32_16x16x32_bf16 v[32:35], v[150:153], v[182:185], v[16:19]
	v_mfma_f32_16x16x32_bf16 v[16:19], v[166:169], v[186:189], v[142:145]
	v_mfma_f32_16x16x32_bf16 v[36:39], v[202:205], v[182:185], v[20:23]
	v_mfma_f32_16x16x32_bf16 v[20:23], v[202:205], v[146:149], v[16:19]
	v_mfma_f32_16x16x32_bf16 v[16:19], v[206:209], v[186:189], v[158:161]
	v_mfma_f32_16x16x32_bf16 v[4:7], v[166:169], v[190:193], v[4:7]
	v_mfma_f32_16x16x32_bf16 v[0:3], v[206:209], v[190:193], v[0:3]
	v_mfma_f32_16x16x32_bf16 v[16:19], v[150:153], v[146:149], v[16:19]
	v_mfma_f32_16x16x32_bf16 v[4:7], v[202:205], v[194:197], v[4:7]
	v_mfma_f32_16x16x32_bf16 v[0:3], v[150:153], v[194:197], v[0:3]
	s_movk_i32 s7, 0x100
	v_cmp_gt_u32_e32 vcc, s7, v140
	s_barrier
	s_and_saveexec_b64 s[22:23], vcc
	s_cbranch_execz .LBB0_976
	s_barrier

; #define STAGE_A(b, h, kt) { const u16* ap_ = A + (size_t)((h) * ahalf + (unsigned)(kt) * 64u); glds16(ap_ + ao0, l0 + SA_(b, h)); glds16(ap_ + ao1, l0 + SA_(b, h) + 8192); }
; #define STAGE_B(b, h, kt) { const u16* bp_ = ((h) ? B1 : B0) + (unsigned)(kt) * 64u; glds16(bp_ + bo0, l0 + SB_(b, h)); glds16(bp_ + bo1, l0 + SB_(b, h) + 8192); }
; #define LDA(dst, b, h) _Pragma("unroll") for (int m = 0; m < 4; ++m) _Pragma("unroll") for (int k = 0; k < 2; ++k) \
;     dst[m][k] = *(const bf16x8*)(lds + SA_(b, h) + lds_byte(wr * 64 + m * 16 + fr, k * 32 + fq * 8));
; #define LDB(dst, b, h) _Pragma("unroll") for (int n = 0; n < 2; ++n) _Pragma("unroll") for (int k = 0; k < 2; ++k) \
;     dst[n][k] = *(const bf16x8*)(lds + SB_(b, h) + lds_byte(wc * 32 + n * 16 + fr, k * 32 + fq * 8));
; #define MMA(ai, bj, At_, Bt_) { __builtin_amdgcn_s_setprio(1); \
;     _Pragma("unroll") for (int m = 0; m < 4; ++m) _Pragma("unroll") for (int n = 0; n < 2; ++n) _Pragma("unroll") for (int k = 0; k < 2; ++k) \
;       acc[ai][bj][m][n] = MFMA16(Bt_[n][k], At_[m][k], acc[ai][bj][m][n]); \
;     __builtin_amdgcn_s_setprio(0); }
; #define WAIT_V(n) asm volatile("s_waitcnt vmcnt(" #n ")" ::: "memory");
; #define WAIT_L(n) asm volatile("s_waitcnt lgkmcnt(" #n ")" ::: "memory");
; #define BAR __builtin_amdgcn_s_barrier();
; #define SCHED __builtin_amdgcn_sched_barrier(0);
; DI void gemm256(const u16* __restrict__ A, int lda, const u16* __restrict__ B0, const u16* __restrict__ B1, int ldb, int nt, acc_t& acc, char* lds) {
;     ...
;   for (int t = 0; t < nt - 2; t += 2) {
;     LDB(Bq0, 0, 0) SCHED LDA(At, 0, 0) STAGE_A(1, 1, t + 1)
;     WAIT_L(8) BAR WAIT_L(0) MMA(0, 0, At, Bq0) BAR SCHED
;     LDB(Bq1, 0, 1) STAGE_B(0, 0, t + 2)
;     BAR WAIT_L(0) MMA(0, 1, At, Bq1) BAR
;     LDA(At, 0, 1) STAGE_A(0, 0, t + 2)
;     BAR WAIT_L(0) MMA(1, 0, At, Bq0) BAR SCHED
;     STAGE_B(0, 1, t + 2)
;     WAIT_V(6) BAR MMA(1, 1, At, Bq1) BAR
;     LDB(Bq0, 1, 0) SCHED LDA(At, 1, 0) STAGE_A(0, 1, t + 2)
;     WAIT_L(8) BAR WAIT_L(0) MMA(0, 0, At, Bq0) BAR SCHED
.LBB0_979:
	ds_read_b128 v[142:145], v166
	ds_read_b128 v[170:173], v166 offset:1024
	ds_read_b128 v[174:177], v166 offset:2048
	ds_read_b128 v[178:181], v166 offset:3072
	v_add_u32_e32 v167, 0xc000, v149
	v_lshl_add_u64 v[222:223], s[8:9], 0, v[136:137]
	v_readfirstlane_b32 s3, v167
	v_lshl_add_u64 v[168:169], v[222:223], 0, s[76:77]
	s_mov_b32 m0, s3
	ds_read_b128 v[182:185], v148
	ds_read_b128 v[186:189], v148 offset:1024
	ds_read_b128 v[190:193], v147
	ds_read_b128 v[194:197], v147 offset:1024
	ds_read_b128 v[198:201], v146
	ds_read_b128 v[202:205], v146 offset:1024
	ds_read_b128 v[206:209], v141
	ds_read_b128 v[210:213], v141 offset:1024
	global_load_lds_dwordx4 v[168:169], off
	v_add_u32_e32 v168, 0xe000, v149
	v_lshl_add_u64 v[224:225], s[8:9], 0, v[138:139]
	v_readfirstlane_b32 s3, v168
	v_lshl_add_u64 v[216:217], v[224:225], 0, s[76:77]
	s_mov_b32 m0, s3
	s_nop 0
	global_load_lds_dwordx4 v[216:217], off
	s_waitcnt lgkmcnt(8)
	s_barrier
	s_waitcnt lgkmcnt(0)
	s_waitcnt lgkmcnt(0)
	v_mfma_f32_16x16x32_bf16 v[126:129], v[142:145], v[182:185], v[126:129]
	v_mfma_f32_16x16x32_bf16 v[122:125], v[174:177], v[182:185], v[122:125]
	v_mfma_f32_16x16x32_bf16 v[118:121], v[142:145], v[190:193], v[118:121]
	v_mfma_f32_16x16x32_bf16 v[114:117], v[174:177], v[190:193], v[114:117]
	v_mfma_f32_16x16x32_bf16 v[110:113], v[142:145], v[198:201], v[110:113]
	v_mfma_f32_16x16x32_bf16 v[106:109], v[174:177], v[198:201], v[106:109]
	v_mfma_f32_16x16x32_bf16 v[102:105], v[142:145], v[206:209], v[102:105]
	v_mfma_f32_16x16x32_bf16 v[98:101], v[174:177], v[206:209], v[98:101]
	v_mfma_f32_16x16x32_bf16 v[126:129], v[170:173], v[186:189], v[126:129]
	v_mfma_f32_16x16x32_bf16 v[122:125], v[178:181], v[186:189], v[122:125]
	v_mfma_f32_16x16x32_bf16 v[118:121], v[170:173], v[194:197], v[118:121]
	v_mfma_f32_16x16x32_bf16 v[114:117], v[178:181], v[194:197], v[114:117]
	v_mfma_f32_16x16x32_bf16 v[110:113], v[170:173], v[202:205], v[110:113]
	v_mfma_f32_16x16x32_bf16 v[106:109], v[178:181], v[202:205], v[106:109]
	v_mfma_f32_16x16x32_bf16 v[102:105], v[170:173], v[210:213], v[102:105]
	v_mfma_f32_16x16x32_bf16 v[98:101], v[178:181], v[210:213], v[98:101]
	s_barrier
	v_lshl_add_u64 v[238:239], s[8:9], 0, v[132:133]
	v_readfirstlane_b32 s3, v150
	v_lshl_add_u64 v[240:241], v[238:239], 0, s[22:23]
	s_mov_b32 m0, s3
	ds_read_b128 v[216:219], v165
	ds_read_b128 v[226:229], v165 offset:1024
	ds_read_b128 v[230:233], v165 offset:2048
	ds_read_b128 v[234:237], v165 offset:3072
	global_load_lds_dwordx4 v[240:241], off
	v_lshl_add_u64 v[240:241], s[8:9], 0, v[134:135]
	v_readfirstlane_b32 s3, v152
	v_lshl_add_u64 v[242:243], v[240:241], 0, s[22:23]
	s_mov_b32 m0, s3
	s_nop 0
	global_load_lds_dwordx4 v[242:243], off
	s_barrier
	s_waitcnt lgkmcnt(0)
	s_waitcnt lgkmcnt(0)
	v_mfma_f32_16x16x32_bf16 v[94:97], v[216:219], v[182:185], v[94:97]
	v_mfma_f32_16x16x32_bf16 v[90:93], v[230:233], v[182:185], v[90:93]
	v_mfma_f32_16x16x32_bf16 v[86:89], v[216:219], v[190:193], v[86:89]
	v_mfma_f32_16x16x32_bf16 v[82:85], v[230:233], v[190:193], v[82:85]
	v_mfma_f32_16x16x32_bf16 v[78:81], v[216:219], v[198:201], v[78:81]
	v_mfma_f32_16x16x32_bf16 v[74:77], v[230:233], v[198:201], v[74:77]
	v_mfma_f32_16x16x32_bf16 v[70:73], v[216:219], v[206:209], v[70:73]
	v_mfma_f32_16x16x32_bf16 v[66:69], v[230:233], v[206:209], v[66:69]
	v_mfma_f32_16x16x32_bf16 v[94:97], v[226:229], v[186:189], v[94:97]
	v_mfma_f32_16x16x32_bf16 v[90:93], v[234:237], v[186:189], v[90:93]
	v_mfma_f32_16x16x32_bf16 v[86:89], v[226:229], v[194:197], v[86:89]
	v_mfma_f32_16x16x32_bf16 v[82:85], v[234:237], v[194:197], v[82:85]
	v_mfma_f32_16x16x32_bf16 v[78:81], v[226:229], v[202:205], v[78:81]
	v_mfma_f32_16x16x32_bf16 v[74:77], v[234:237], v[202:205], v[74:77]
	v_mfma_f32_16x16x32_bf16 v[70:73], v[226:229], v[210:213], v[70:73]
	v_mfma_f32_16x16x32_bf16 v[66:69], v[234:237], v[210:213], v[66:69]
	v_readfirstlane_b32 s3, v149
	v_lshl_add_u64 v[242:243], v[222:223], 0, s[80:81]
	s_mov_b32 m0, s3
	v_readfirstlane_b32 s3, v153
	s_barrier
	ds_read_b128 v[182:185], v148 offset:16384
	ds_read_b128 v[186:189], v148 offset:17408
	ds_read_b128 v[190:193], v147 offset:16384
	ds_read_b128 v[194:197], v147 offset:17408
	ds_read_b128 v[198:201], v146 offset:16384
	ds_read_b128 v[202:205], v146 offset:17408
	ds_read_b128 v[206:209], v141 offset:16384
	ds_read_b128 v[210:213], v141 offset:17408
	global_load_lds_dwordx4 v[242:243], off
	v_lshl_add_u64 v[242:243], v[224:225], 0, s[80:81]
	s_mov_b32 m0, s3
	s_nop 0
	global_load_lds_dwordx4 v[242:243], off
	s_barrier
	s_waitcnt lgkmcnt(0)
	s_waitcnt lgkmcnt(0)
	v_mfma_f32_16x16x32_bf16 v[60:63], v[142:145], v[182:185], v[60:63]
	v_mfma_f32_16x16x32_bf16 v[56:59], v[174:177], v[182:185], v[56:59]
	v_mfma_f32_16x16x32_bf16 v[52:55], v[142:145], v[190:193], v[52:55]
	v_mfma_f32_16x16x32_bf16 v[48:51], v[174:177], v[190:193], v[48:51]
	v_mfma_f32_16x16x32_bf16 v[44:47], v[142:145], v[198:201], v[44:47]
	v_mfma_f32_16x16x32_bf16 v[40:43], v[174:177], v[198:201], v[40:43]
	v_mfma_f32_16x16x32_bf16 v[36:39], v[142:145], v[206:209], v[36:39]
	v_mfma_f32_16x16x32_bf16 v[32:35], v[174:177], v[206:209], v[32:35]
	v_mfma_f32_16x16x32_bf16 v[60:63], v[170:173], v[186:189], v[60:63]
	v_mfma_f32_16x16x32_bf16 v[56:59], v[178:181], v[186:189], v[56:59]
	v_mfma_f32_16x16x32_bf16 v[52:55], v[170:173], v[194:197], v[52:55]
	v_mfma_f32_16x16x32_bf16 v[48:51], v[178:181], v[194:197], v[48:51]
	v_mfma_f32_16x16x32_bf16 v[44:47], v[170:173], v[202:205], v[44:47]
	v_mfma_f32_16x16x32_bf16 v[40:43], v[178:181], v[202:205], v[40:43]
	v_mfma_f32_16x16x32_bf16 v[36:39], v[170:173], v[210:213], v[36:39]
	v_mfma_f32_16x16x32_bf16 v[32:35], v[178:181], v[210:213], v[32:35]
	s_barrier
; #define STAGE_A(b, h, kt) { const u16* ap_ = A + (size_t)((h) * ahalf + (unsigned)(kt) * 64u); glds16(ap_ + ao0, l0 + SA_(b, h)); glds16(ap_ + ao1, l0 + SA_(b, h) + 8192); }
; #define STAGE_B(b, h, kt) { const u16* bp_ = ((h) ? B1 : B0) + (unsigned)(kt) * 64u; glds16(bp_ + bo0, l0 + SB_(b, h)); glds16(bp_ + bo1, l0 + SB_(b, h) + 8192); }
; #define LDA(dst, b, h) _Pragma("unroll") for (int m = 0; m < 4; ++m) _Pragma("unroll") for (int k = 0; k < 2; ++k) \
;     dst[m][k] = *(const bf16x8*)(lds + SA_(b, h) + lds_byte(wr * 64 + m * 16 + fr, k * 32 + fq * 8));
; #define LDB(dst, b, h) _Pragma("unroll") for (int n = 0; n < 2; ++n) _Pragma("unroll") for (int k = 0; k < 2; ++k) \
;     dst[n][k] = *(const bf16x8*)(lds + SB_(b, h) + lds_byte(wc * 32 + n * 16 + fr, k * 32 + fq * 8));
; #define MMA(ai, bj, At_, Bt_) { __builtin_amdgcn_s_setprio(1); \
;     _Pragma("unroll") for (int m = 0; m < 4; ++m) _Pragma("unroll") for (int n = 0; n < 2; ++n) _Pragma("unroll") for (int k = 0; k < 2; ++k) \
;       acc[ai][bj][m][n] = MFMA16(Bt_[n][k], At_[m][k], acc[ai][bj][m][n]); \
;     __builtin_amdgcn_s_setprio(0); }
; #define WAIT_V(n) asm volatile("s_waitcnt vmcnt(" #n ")" ::: "memory");
; #define WAIT_L(n) asm volatile("s_waitcnt lgkmcnt(" #n ")" ::: "memory");
; #define BAR __builtin_amdgcn_s_barrier();
; #define SCHED __builtin_amdgcn_sched_barrier(0);
; DI void gemm256(const u16* __restrict__ A, int lda, const u16* __restrict__ B0, const u16* __restrict__ B1, int ldb, int nt, acc_t& acc, char* lds) {
;     ...
;     LDA(At, 0, 1) STAGE_A(0, 0, t + 2)
;     BAR WAIT_L(0) MMA(1, 0, At, Bq0) BAR SCHED
;     STAGE_B(0, 1, t + 2)
;     WAIT_V(6) BAR MMA(1, 1, At, Bq1) BAR
;     LDB(Bq0, 1, 0) SCHED LDA(At, 1, 0) STAGE_A(0, 1, t + 2)
;     WAIT_L(8) BAR WAIT_L(0) MMA(0, 0, At, Bq0) BAR SCHED
;     LDB(Bq1, 1, 1) STAGE_B(1, 0, t + 3)
;     BAR WAIT_L(0) MMA(0, 1, At, Bq1) BAR
;     LDA(At, 1, 1) STAGE_A(1, 0, t + 3)
;     BAR WAIT_L(0) MMA(1, 0, At, Bq0) BAR SCHED
;     STAGE_B(1, 1, t + 3)
	v_readfirstlane_b32 s3, v154
	v_lshl_add_u64 v[142:143], v[238:239], 0, s[28:29]
	s_mov_b32 m0, s3
	v_readfirstlane_b32 s3, v155
	global_load_lds_dwordx4 v[142:143], off
	v_lshl_add_u64 v[142:143], v[240:241], 0, s[28:29]
	s_mov_b32 m0, s3
	s_nop 0
	global_load_lds_dwordx4 v[142:143], off
	s_waitcnt vmcnt(6)
	s_barrier
	v_mfma_f32_16x16x32_bf16 v[28:31], v[216:219], v[182:185], v[28:31]
	v_mfma_f32_16x16x32_bf16 v[24:27], v[230:233], v[182:185], v[24:27]
	v_mfma_f32_16x16x32_bf16 v[20:23], v[216:219], v[190:193], v[20:23]
	v_mfma_f32_16x16x32_bf16 v[16:19], v[230:233], v[190:193], v[16:19]
	v_mfma_f32_16x16x32_bf16 v[12:15], v[216:219], v[198:201], v[12:15]
	v_mfma_f32_16x16x32_bf16 v[8:11], v[230:233], v[198:201], v[8:11]
	v_mfma_f32_16x16x32_bf16 v[4:7], v[216:219], v[206:209], v[4:7]
	v_mfma_f32_16x16x32_bf16 v[0:3], v[230:233], v[206:209], v[0:3]
	v_mfma_f32_16x16x32_bf16 v[28:31], v[226:229], v[186:189], v[28:31]
	v_mfma_f32_16x16x32_bf16 v[24:27], v[234:237], v[186:189], v[24:27]
	v_mfma_f32_16x16x32_bf16 v[20:23], v[226:229], v[194:197], v[20:23]
	v_mfma_f32_16x16x32_bf16 v[16:19], v[234:237], v[194:197], v[16:19]
	v_mfma_f32_16x16x32_bf16 v[12:15], v[226:229], v[202:205], v[12:15]
	v_mfma_f32_16x16x32_bf16 v[8:11], v[234:237], v[202:205], v[8:11]
	v_mfma_f32_16x16x32_bf16 v[4:7], v[226:229], v[210:213], v[4:7]
	v_mfma_f32_16x16x32_bf16 v[0:3], v[234:237], v[210:213], v[0:3]
	s_barrier
	ds_read_b128 v[142:145], v156
	ds_read_b128 v[170:173], v156 offset:1024
	ds_read_b128 v[174:177], v156 offset:2048
	ds_read_b128 v[178:181], v156 offset:3072
	v_readfirstlane_b32 s3, v157
	v_lshl_add_u64 v[216:217], v[222:223], 0, s[4:5]
	s_mov_b32 m0, s3
	v_readfirstlane_b32 s3, v158
	ds_read_b128 v[182:185], v148 offset:32768
	ds_read_b128 v[186:189], v148 offset:33792
	ds_read_b128 v[190:193], v147 offset:32768
	ds_read_b128 v[194:197], v147 offset:33792
	ds_read_b128 v[198:201], v146 offset:32768
	ds_read_b128 v[202:205], v146 offset:33792
	ds_read_b128 v[206:209], v141 offset:32768
	ds_read_b128 v[210:213], v141 offset:33792
	global_load_lds_dwordx4 v[216:217], off
	v_lshl_add_u64 v[216:217], v[224:225], 0, s[4:5]
	s_mov_b32 m0, s3
	s_nop 0
	global_load_lds_dwordx4 v[216:217], off
	s_waitcnt lgkmcnt(8)
	s_barrier
	s_waitcnt lgkmcnt(0)
	s_waitcnt lgkmcnt(0)
	v_mfma_f32_16x16x32_bf16 v[126:129], v[142:145], v[182:185], v[126:129]
	v_mfma_f32_16x16x32_bf16 v[122:125], v[174:177], v[182:185], v[122:125]
	v_mfma_f32_16x16x32_bf16 v[118:121], v[142:145], v[190:193], v[118:121]
	v_mfma_f32_16x16x32_bf16 v[114:117], v[174:177], v[190:193], v[114:117]
	v_mfma_f32_16x16x32_bf16 v[110:113], v[142:145], v[198:201], v[110:113]
	v_mfma_f32_16x16x32_bf16 v[106:109], v[174:177], v[198:201], v[106:109]
	v_mfma_f32_16x16x32_bf16 v[102:105], v[142:145], v[206:209], v[102:105]
	v_mfma_f32_16x16x32_bf16 v[98:101], v[174:177], v[206:209], v[98:101]
	v_mfma_f32_16x16x32_bf16 v[126:129], v[170:173], v[186:189], v[126:129]
	v_mfma_f32_16x16x32_bf16 v[122:125], v[178:181], v[186:189], v[122:125]
	v_mfma_f32_16x16x32_bf16 v[118:121], v[170:173], v[194:197], v[118:121]
	v_mfma_f32_16x16x32_bf16 v[114:117], v[178:181], v[194:197], v[114:117]
	v_mfma_f32_16x16x32_bf16 v[110:113], v[170:173], v[202:205], v[110:113]
	v_mfma_f32_16x16x32_bf16 v[106:109], v[178:181], v[202:205], v[106:109]
	v_mfma_f32_16x16x32_bf16 v[102:105], v[170:173], v[210:213], v[102:105]
	v_mfma_f32_16x16x32_bf16 v[98:101], v[178:181], v[210:213], v[98:101]
	s_barrier
	v_readfirstlane_b32 s3, v159
	v_lshl_add_u64 v[242:243], v[238:239], 0, s[64:65]
	s_mov_b32 m0, s3
	v_readfirstlane_b32 s3, v160
	ds_read_b128 v[216:219], v151
	ds_read_b128 v[226:229], v151 offset:1024
	ds_read_b128 v[230:233], v151 offset:2048
	ds_read_b128 v[234:237], v151 offset:3072
	global_load_lds_dwordx4 v[242:243], off
	v_lshl_add_u64 v[242:243], v[240:241], 0, s[64:65]
	s_mov_b32 m0, s3
	s_nop 0
	global_load_lds_dwordx4 v[242:243], off
	s_barrier
	s_waitcnt lgkmcnt(0)
	s_waitcnt lgkmcnt(0)
	v_mfma_f32_16x16x32_bf16 v[94:97], v[216:219], v[182:185], v[94:97]
	v_mfma_f32_16x16x32_bf16 v[90:93], v[230:233], v[182:185], v[90:93]
	v_mfma_f32_16x16x32_bf16 v[86:89], v[216:219], v[190:193], v[86:89]
	v_mfma_f32_16x16x32_bf16 v[82:85], v[230:233], v[190:193], v[82:85]
	v_mfma_f32_16x16x32_bf16 v[78:81], v[216:219], v[198:201], v[78:81]
	v_mfma_f32_16x16x32_bf16 v[74:77], v[230:233], v[198:201], v[74:77]
	v_mfma_f32_16x16x32_bf16 v[70:73], v[216:219], v[206:209], v[70:73]
	v_mfma_f32_16x16x32_bf16 v[66:69], v[230:233], v[206:209], v[66:69]
	v_mfma_f32_16x16x32_bf16 v[94:97], v[226:229], v[186:189], v[94:97]
	v_mfma_f32_16x16x32_bf16 v[90:93], v[234:237], v[186:189], v[90:93]
	v_mfma_f32_16x16x32_bf16 v[86:89], v[226:229], v[194:197], v[86:89]
	v_mfma_f32_16x16x32_bf16 v[82:85], v[234:237], v[194:197], v[82:85]
	v_mfma_f32_16x16x32_bf16 v[78:81], v[226:229], v[202:205], v[78:81]
	v_mfma_f32_16x16x32_bf16 v[74:77], v[234:237], v[202:205], v[74:77]
	v_mfma_f32_16x16x32_bf16 v[70:73], v[226:229], v[210:213], v[70:73]
	v_mfma_f32_16x16x32_bf16 v[66:69], v[234:237], v[210:213], v[66:69]
	v_readfirstlane_b32 s3, v161
	v_lshl_add_u64 v[222:223], v[222:223], 0, s[30:31]
	s_mov_b32 m0, s3
	v_readfirstlane_b32 s3, v162
	s_barrier
	ds_read_b128 v[182:185], v148 offset:49152
	ds_read_b128 v[186:189], v148 offset:50176
	ds_read_b128 v[190:193], v147 offset:49152
	ds_read_b128 v[194:197], v147 offset:50176
	ds_read_b128 v[198:201], v146 offset:49152
	ds_read_b128 v[202:205], v146 offset:50176
	ds_read_b128 v[206:209], v141 offset:49152
	ds_read_b128 v[210:213], v141 offset:50176
	global_load_lds_dwordx4 v[222:223], off
	v_lshl_add_u64 v[222:223], v[224:225], 0, s[30:31]
	s_mov_b32 m0, s3
	s_nop 0
	global_load_lds_dwordx4 v[222:223], off
	s_barrier
; #define STAGE_A(b, h, kt) { const u16* ap_ = A + (size_t)((h) * ahalf + (unsigned)(kt) * 64u); glds16(ap_ + ao0, l0 + SA_(b, h)); glds16(ap_ + ao1, l0 + SA_(b, h) + 8192); }
; #define STAGE_B(b, h, kt) { const u16* bp_ = ((h) ? B1 : B0) + (unsigned)(kt) * 64u; glds16(bp_ + bo0, l0 + SB_(b, h)); glds16(bp_ + bo1, l0 + SB_(b, h) + 8192); }
; #define LDA(dst, b, h) _Pragma("unroll") for (int m = 0; m < 4; ++m) _Pragma("unroll") for (int k = 0; k < 2; ++k) \
;     dst[m][k] = *(const bf16x8*)(lds + SA_(b, h) + lds_byte(wr * 64 + m * 16 + fr, k * 32 + fq * 8));
; #define LDB(dst, b, h) _Pragma("unroll") for (int n = 0; n < 2; ++n) _Pragma("unroll") for (int k = 0; k < 2; ++k) \
;     dst[n][k] = *(const bf16x8*)(lds + SB_(b, h) + lds_byte(wc * 32 + n * 16 + fr, k * 32 + fq * 8));
; #define MMA(ai, bj, At_, Bt_) { __builtin_amdgcn_s_setprio(1); \
;     _Pragma("unroll") for (int m = 0; m < 4; ++m) _Pragma("unroll") for (int n = 0; n < 2; ++n) _Pragma("unroll") for (int k = 0; k < 2; ++k) \
;       acc[ai][bj][m][n] = MFMA16(Bt_[n][k], At_[m][k], acc[ai][bj][m][n]); \
;     __builtin_amdgcn_s_setprio(0); }
; #define WAIT_V(n) asm volatile("s_waitcnt vmcnt(" #n ")" ::: "memory");
; #define WAIT_L(n) asm volatile("s_waitcnt lgkmcnt(" #n ")" ::: "memory");
; #define BAR __builtin_amdgcn_s_barrier();
; #define SCHED __builtin_amdgcn_sched_barrier(0);
; DI void gemm256(const u16* __restrict__ A, int lda, const u16* __restrict__ B0, const u16* __restrict__ B1, int ldb, int nt, acc_t& acc, char* lds) {
;     ...
;     BAR WAIT_L(0) MMA(1, 0, At, Bq0) BAR SCHED
;     STAGE_B(1, 1, t + 3)
;     WAIT_V(6) BAR MMA(1, 1, At, Bq1) BAR
;   }
;   { LDB(Bq0, 0, 0) LDA(At, 0, 0) STAGE_A(1, 1, nt - 1)
;     BAR WAIT_L(0) MMA(0, 0, At, Bq0) BAR
;     LDB(Bq1, 0, 1) BAR WAIT_L(0) MMA(0, 1, At, Bq1) BAR
;     LDA(At, 0, 1) WAIT_V(4) BAR WAIT_L(0) MMA(1, 0, At, Bq0) MMA(1, 1, At, Bq1) BAR }
	s_waitcnt lgkmcnt(0)
	s_waitcnt lgkmcnt(0)
	v_mfma_f32_16x16x32_bf16 v[60:63], v[142:145], v[182:185], v[60:63]
	v_mfma_f32_16x16x32_bf16 v[56:59], v[174:177], v[182:185], v[56:59]
	v_mfma_f32_16x16x32_bf16 v[52:55], v[142:145], v[190:193], v[52:55]
	v_mfma_f32_16x16x32_bf16 v[48:51], v[174:177], v[190:193], v[48:51]
	v_mfma_f32_16x16x32_bf16 v[44:47], v[142:145], v[198:201], v[44:47]
	v_mfma_f32_16x16x32_bf16 v[40:43], v[174:177], v[198:201], v[40:43]
	v_mfma_f32_16x16x32_bf16 v[36:39], v[142:145], v[206:209], v[36:39]
	v_mfma_f32_16x16x32_bf16 v[32:35], v[174:177], v[206:209], v[32:35]
	v_mfma_f32_16x16x32_bf16 v[60:63], v[170:173], v[186:189], v[60:63]
	v_mfma_f32_16x16x32_bf16 v[56:59], v[178:181], v[186:189], v[56:59]
	v_mfma_f32_16x16x32_bf16 v[52:55], v[170:173], v[194:197], v[52:55]
	v_mfma_f32_16x16x32_bf16 v[48:51], v[178:181], v[194:197], v[48:51]
	v_mfma_f32_16x16x32_bf16 v[44:47], v[170:173], v[202:205], v[44:47]
	v_mfma_f32_16x16x32_bf16 v[40:43], v[178:181], v[202:205], v[40:43]
	v_mfma_f32_16x16x32_bf16 v[36:39], v[170:173], v[210:213], v[36:39]
	v_mfma_f32_16x16x32_bf16 v[32:35], v[178:181], v[210:213], v[32:35]
	s_barrier
	v_readfirstlane_b32 s3, v163
	v_lshl_add_u64 v[142:143], v[238:239], 0, s[66:67]
	s_mov_b32 m0, s3
	v_readfirstlane_b32 s3, v164
	global_load_lds_dwordx4 v[142:143], off
	v_lshl_add_u64 v[142:143], v[240:241], 0, s[66:67]
	s_mov_b32 m0, s3
	s_nop 0
	global_load_lds_dwordx4 v[142:143], off
	s_waitcnt vmcnt(6)
	s_barrier
	v_mfma_f32_16x16x32_bf16 v[28:31], v[216:219], v[182:185], v[28:31]
	v_mfma_f32_16x16x32_bf16 v[24:27], v[230:233], v[182:185], v[24:27]
	v_mfma_f32_16x16x32_bf16 v[20:23], v[216:219], v[190:193], v[20:23]
	v_mfma_f32_16x16x32_bf16 v[16:19], v[230:233], v[190:193], v[16:19]
	v_mfma_f32_16x16x32_bf16 v[12:15], v[216:219], v[198:201], v[12:15]
	v_mfma_f32_16x16x32_bf16 v[8:11], v[230:233], v[198:201], v[8:11]
	v_mfma_f32_16x16x32_bf16 v[4:7], v[216:219], v[206:209], v[4:7]
	v_mfma_f32_16x16x32_bf16 v[0:3], v[230:233], v[206:209], v[0:3]
	v_mfma_f32_16x16x32_bf16 v[28:31], v[226:229], v[186:189], v[28:31]
	v_mfma_f32_16x16x32_bf16 v[24:27], v[234:237], v[186:189], v[24:27]
	v_mfma_f32_16x16x32_bf16 v[20:23], v[226:229], v[194:197], v[20:23]
	v_mfma_f32_16x16x32_bf16 v[16:19], v[234:237], v[194:197], v[16:19]
	v_mfma_f32_16x16x32_bf16 v[12:15], v[226:229], v[202:205], v[12:15]
	v_mfma_f32_16x16x32_bf16 v[8:11], v[234:237], v[202:205], v[8:11]
	v_mfma_f32_16x16x32_bf16 v[4:7], v[226:229], v[210:213], v[4:7]
	v_mfma_f32_16x16x32_bf16 v[0:3], v[234:237], v[210:213], v[0:3]
	s_add_i32 s2, s2, 2
	s_add_u32 s8, s8, 0x100
	s_addc_u32 s9, s9, 0
	s_cmp_lt_u32 s2, 4
	s_barrier
	s_cbranch_scc1 .LBB0_979
	s_add_u32 s2, s44, 0x40380
	s_addc_u32 s3, s45, 0
	v_readfirstlane_b32 s7, v167
	v_lshl_add_u64 v[162:163], v[64:65], 1, s[2:3]
	s_mov_b32 m0, s7
	v_lshl_add_u64 v[130:131], v[130:131], 1, s[2:3]
	v_readfirstlane_b32 s2, v168
	ds_read_b128 v[132:135], v166
	ds_read_b128 v[136:139], v166 offset:1024
	ds_read_b128 v[142:145], v166 offset:2048
	ds_read_b128 v[152:155], v166 offset:3072
	ds_read_b128 v[158:161], v148
	ds_read_b128 v[170:173], v148 offset:1024
	ds_read_b128 v[174:177], v147
	ds_read_b128 v[178:181], v147 offset:1024
	ds_read_b128 v[182:185], v146
	ds_read_b128 v[186:189], v146 offset:1024
	ds_read_b128 v[190:193], v141
	ds_read_b128 v[194:197], v141 offset:1024
	global_load_lds_dwordx4 v[162:163], off
	s_mov_b32 m0, s2
	s_nop 0
	global_load_lds_dwordx4 v[130:131], off
	s_barrier
	s_waitcnt lgkmcnt(0)
	s_waitcnt lgkmcnt(0)
	v_mfma_f32_16x16x32_bf16 v[126:129], v[132:135], v[158:161], v[126:129]
	v_mfma_f32_16x16x32_bf16 v[122:125], v[142:145], v[158:161], v[122:125]
	v_mfma_f32_16x16x32_bf16 v[118:121], v[132:135], v[174:177], v[118:121]
	v_mfma_f32_16x16x32_bf16 v[114:117], v[142:145], v[174:177], v[114:117]
	v_mfma_f32_16x16x32_bf16 v[106:109], v[142:145], v[182:185], v[106:109]
	v_mfma_f32_16x16x32_bf16 v[98:101], v[142:145], v[190:193], v[98:101]
	v_mfma_f32_16x16x32_bf16 v[126:129], v[136:139], v[170:173], v[126:129]
	v_mfma_f32_16x16x32_bf16 v[122:125], v[152:155], v[170:173], v[122:125]
	v_mfma_f32_16x16x32_bf16 v[118:121], v[136:139], v[178:181], v[118:121]
	v_mfma_f32_16x16x32_bf16 v[114:117], v[152:155], v[178:181], v[114:117]
	v_mfma_f32_16x16x32_bf16 v[110:113], v[132:135], v[182:185], v[110:113]
	v_mfma_f32_16x16x32_bf16 v[106:109], v[152:155], v[186:189], v[106:109]
	v_mfma_f32_16x16x32_bf16 v[102:105], v[132:135], v[190:193], v[102:105]
	v_mfma_f32_16x16x32_bf16 v[98:101], v[152:155], v[194:197], v[98:101]
	v_mfma_f32_16x16x32_bf16 v[166:169], v[136:139], v[186:189], v[110:113]
	v_mfma_f32_16x16x32_bf16 v[198:201], v[136:139], v[194:197], v[102:105]
	s_barrier
	s_nop 2
	ds_read_b128 v[102:105], v165
	ds_read_b128 v[110:113], v165 offset:1024
	ds_read_b128 v[202:205], v165 offset:2048
	ds_read_b128 v[162:165], v165 offset:3072
	s_barrier
	s_waitcnt lgkmcnt(0)
	s_waitcnt lgkmcnt(0)
	v_mfma_f32_16x16x32_bf16 v[90:93], v[202:205], v[158:161], v[90:93]
	v_mfma_f32_16x16x32_bf16 v[82:85], v[202:205], v[174:177], v[82:85]
	v_mfma_f32_16x16x32_bf16 v[74:77], v[202:205], v[182:185], v[74:77]
	v_mfma_f32_16x16x32_bf16 v[66:69], v[202:205], v[190:193], v[66:69]
	v_mfma_f32_16x16x32_bf16 v[94:97], v[102:105], v[158:161], v[94:97]
	v_mfma_f32_16x16x32_bf16 v[90:93], v[162:165], v[170:173], v[90:93]
	v_mfma_f32_16x16x32_bf16 v[86:89], v[102:105], v[174:177], v[86:89]
	v_mfma_f32_16x16x32_bf16 v[82:85], v[162:165], v[178:181], v[82:85]
	v_mfma_f32_16x16x32_bf16 v[78:81], v[102:105], v[182:185], v[78:81]
	v_mfma_f32_16x16x32_bf16 v[74:77], v[162:165], v[186:189], v[74:77]
	v_mfma_f32_16x16x32_bf16 v[70:73], v[102:105], v[190:193], v[70:73]
	v_mfma_f32_16x16x32_bf16 v[66:69], v[162:165], v[194:197], v[66:69]
	v_mfma_f32_16x16x32_bf16 v[206:209], v[110:113], v[170:173], v[94:97]
	v_mfma_f32_16x16x32_bf16 v[158:161], v[110:113], v[178:181], v[86:89]
	v_mfma_f32_16x16x32_bf16 v[170:173], v[110:113], v[186:189], v[78:81]
	v_mfma_f32_16x16x32_bf16 v[174:177], v[110:113], v[194:197], v[70:73]
	s_barrier
; #define LDA(dst, b, h) _Pragma("unroll") for (int m = 0; m < 4; ++m) _Pragma("unroll") for (int k = 0; k < 2; ++k) \
;     dst[m][k] = *(const bf16x8*)(lds + SA_(b, h) + lds_byte(wr * 64 + m * 16 + fr, k * 32 + fq * 8));
; #define LDB(dst, b, h) _Pragma("unroll") for (int n = 0; n < 2; ++n) _Pragma("unroll") for (int k = 0; k < 2; ++k) \
;     dst[n][k] = *(const bf16x8*)(lds + SB_(b, h) + lds_byte(wc * 32 + n * 16 + fr, k * 32 + fq * 8));
; #define MMA(ai, bj, At_, Bt_) { __builtin_amdgcn_s_setprio(1); \
;     _Pragma("unroll") for (int m = 0; m < 4; ++m) _Pragma("unroll") for (int n = 0; n < 2; ++n) _Pragma("unroll") for (int k = 0; k < 2; ++k) \
;       acc[ai][bj][m][n] = MFMA16(Bt_[n][k], At_[m][k], acc[ai][bj][m][n]); \
;     __builtin_amdgcn_s_setprio(0); }
; #define WAIT_V(n) asm volatile("s_waitcnt vmcnt(" #n ")" ::: "memory");
; #define WAIT_L(n) asm volatile("s_waitcnt lgkmcnt(" #n ")" ::: "memory");
; #define BAR __builtin_amdgcn_s_barrier();
; DI void gemm256(const u16* __restrict__ A, int lda, const u16* __restrict__ B0, const u16* __restrict__ B1, int ldb, int nt, acc_t& acc, char* lds) {
;     ...
;     BAR WAIT_L(0) MMA(0, 0, At, Bq0) BAR
;     LDB(Bq1, 0, 1) BAR WAIT_L(0) MMA(0, 1, At, Bq1) BAR
;     LDA(At, 0, 1) WAIT_V(4) BAR WAIT_L(0) MMA(1, 0, At, Bq0) MMA(1, 1, At, Bq1) BAR }
;   { LDB(Bq0, 1, 0) LDA(At, 1, 0) WAIT_V(2) BAR WAIT_L(0) MMA(0, 0, At, Bq0) BAR
	s_nop 0
	ds_read_b128 v[70:73], v148 offset:16384
	ds_read_b128 v[78:81], v148 offset:17408
	ds_read_b128 v[86:89], v147 offset:16384
	ds_read_b128 v[94:97], v147 offset:17408
	ds_read_b128 v[178:181], v146 offset:16384
	ds_read_b128 v[182:185], v146 offset:17408
	ds_read_b128 v[186:189], v141 offset:16384
	ds_read_b128 v[190:193], v141 offset:17408
	s_waitcnt vmcnt(4)
	s_barrier
	s_waitcnt lgkmcnt(0)
	s_waitcnt lgkmcnt(0)
	v_mfma_f32_16x16x32_bf16 v[60:63], v[132:135], v[70:73], v[60:63]
	v_mfma_f32_16x16x32_bf16 v[56:59], v[142:145], v[70:73], v[56:59]
	v_mfma_f32_16x16x32_bf16 v[52:55], v[132:135], v[86:89], v[52:55]
	v_mfma_f32_16x16x32_bf16 v[48:51], v[142:145], v[86:89], v[48:51]
	v_mfma_f32_16x16x32_bf16 v[36:39], v[132:135], v[186:189], v[36:39]
	v_mfma_f32_16x16x32_bf16 v[32:35], v[142:145], v[186:189], v[32:35]
	v_mfma_f32_16x16x32_bf16 v[60:63], v[136:139], v[78:81], v[60:63]
	v_mfma_f32_16x16x32_bf16 v[56:59], v[152:155], v[78:81], v[56:59]
	v_mfma_f32_16x16x32_bf16 v[52:55], v[136:139], v[94:97], v[52:55]
	v_mfma_f32_16x16x32_bf16 v[48:51], v[152:155], v[94:97], v[48:51]
	v_mfma_f32_16x16x32_bf16 v[44:47], v[132:135], v[178:181], v[44:47]
	v_mfma_f32_16x16x32_bf16 v[40:43], v[142:145], v[178:181], v[40:43]
	v_mfma_f32_16x16x32_bf16 v[36:39], v[136:139], v[190:193], v[36:39]
	v_mfma_f32_16x16x32_bf16 v[32:35], v[152:155], v[190:193], v[32:35]
	v_mfma_f32_16x16x32_bf16 v[194:197], v[136:139], v[182:185], v[44:47]
	v_mfma_f32_16x16x32_bf16 v[210:213], v[152:155], v[182:185], v[40:43]
	v_mfma_f32_16x16x32_bf16 v[20:23], v[102:105], v[86:89], v[20:23]
	v_mfma_f32_16x16x32_bf16 v[16:19], v[202:205], v[86:89], v[16:19]
	v_mfma_f32_16x16x32_bf16 v[4:7], v[102:105], v[186:189], v[4:7]
	v_mfma_f32_16x16x32_bf16 v[0:3], v[202:205], v[186:189], v[0:3]
	v_mfma_f32_16x16x32_bf16 v[28:31], v[102:105], v[70:73], v[28:31]
	v_mfma_f32_16x16x32_bf16 v[24:27], v[202:205], v[70:73], v[24:27]
	v_mfma_f32_16x16x32_bf16 v[20:23], v[110:113], v[94:97], v[20:23]
	v_mfma_f32_16x16x32_bf16 v[16:19], v[162:165], v[94:97], v[16:19]
	v_mfma_f32_16x16x32_bf16 v[12:15], v[102:105], v[178:181], v[12:15]
	v_mfma_f32_16x16x32_bf16 v[8:11], v[202:205], v[178:181], v[8:11]
	v_mfma_f32_16x16x32_bf16 v[4:7], v[110:113], v[190:193], v[4:7]
	v_mfma_f32_16x16x32_bf16 v[0:3], v[162:165], v[190:193], v[0:3]
	v_mfma_f32_16x16x32_bf16 v[130:133], v[110:113], v[78:81], v[28:31]
	v_mfma_f32_16x16x32_bf16 v[134:137], v[162:165], v[78:81], v[24:27]
	v_mfma_f32_16x16x32_bf16 v[142:145], v[110:113], v[182:185], v[12:15]
	v_mfma_f32_16x16x32_bf16 v[152:155], v[162:165], v[182:185], v[8:11]
	s_barrier
	s_nop 0
	ds_read_b128 v[8:11], v156
	ds_read_b128 v[12:15], v156 offset:1024
	ds_read_b128 v[162:165], v156 offset:2048
	ds_read_b128 v[178:181], v156 offset:3072
	ds_read_b128 v[24:27], v148 offset:32768
	ds_read_b128 v[28:31], v148 offset:33792
	ds_read_b128 v[40:43], v147 offset:32768
	ds_read_b128 v[44:47], v147 offset:33792
	ds_read_b128 v[182:185], v146 offset:32768
	ds_read_b128 v[186:189], v146 offset:33792
	ds_read_b128 v[190:193], v141 offset:32768
	ds_read_b128 v[202:205], v141 offset:33792
	s_waitcnt vmcnt(2)
	s_barrier
	s_waitcnt lgkmcnt(0)
	s_waitcnt lgkmcnt(0)
	v_mfma_f32_16x16x32_bf16 v[70:73], v[8:11], v[24:27], v[126:129]
	v_mfma_f32_16x16x32_bf16 v[126:129], v[12:15], v[28:31], v[70:73]
	v_mfma_f32_16x16x32_bf16 v[70:73], v[162:165], v[24:27], v[122:125]
	v_mfma_f32_16x16x32_bf16 v[122:125], v[178:181], v[28:31], v[70:73]
	v_mfma_f32_16x16x32_bf16 v[70:73], v[8:11], v[40:43], v[118:121]
	v_mfma_f32_16x16x32_bf16 v[110:113], v[12:15], v[44:47], v[70:73]
	v_mfma_f32_16x16x32_bf16 v[70:73], v[162:165], v[40:43], v[114:117]
	v_mfma_f32_16x16x32_bf16 v[102:105], v[178:181], v[44:47], v[70:73]
	v_mfma_f32_16x16x32_bf16 v[70:73], v[8:11], v[182:185], v[166:169]
	v_mfma_f32_16x16x32_bf16 v[94:97], v[12:15], v[186:189], v[70:73]
	v_mfma_f32_16x16x32_bf16 v[70:73], v[162:165], v[182:185], v[106:109]
	v_mfma_f32_16x16x32_bf16 v[86:89], v[178:181], v[186:189], v[70:73]
	v_mfma_f32_16x16x32_bf16 v[70:73], v[8:11], v[190:193], v[198:201]
	v_mfma_f32_16x16x32_bf16 v[78:81], v[12:15], v[202:205], v[70:73]
	v_mfma_f32_16x16x32_bf16 v[70:73], v[162:165], v[190:193], v[98:101]
	v_mfma_f32_16x16x32_bf16 v[70:73], v[178:181], v[202:205], v[70:73]
	s_barrier
; #define LDA(dst, b, h) _Pragma("unroll") for (int m = 0; m < 4; ++m) _Pragma("unroll") for (int k = 0; k < 2; ++k) \
;     dst[m][k] = *(const bf16x8*)(lds + SA_(b, h) + lds_byte(wr * 64 + m * 16 + fr, k * 32 + fq * 8));
; #define LDB(dst, b, h) _Pragma("unroll") for (int n = 0; n < 2; ++n) _Pragma("unroll") for (int k = 0; k < 2; ++k) \
;     dst[n][k] = *(const bf16x8*)(lds + SB_(b, h) + lds_byte(wc * 32 + n * 16 + fr, k * 32 + fq * 8));
; #define MMA(ai, bj, At_, Bt_) { __builtin_amdgcn_s_setprio(1); \
;     _Pragma("unroll") for (int m = 0; m < 4; ++m) _Pragma("unroll") for (int n = 0; n < 2; ++n) _Pragma("unroll") for (int k = 0; k < 2; ++k) \
;       acc[ai][bj][m][n] = MFMA16(Bt_[n][k], At_[m][k], acc[ai][bj][m][n]); \
;     __builtin_amdgcn_s_setprio(0); }
; #define WAIT_V(n) asm volatile("s_waitcnt vmcnt(" #n ")" ::: "memory");
; #define WAIT_L(n) asm volatile("s_waitcnt lgkmcnt(" #n ")" ::: "memory");
; #define BAR __builtin_amdgcn_s_barrier();
; DI void gemm256(const u16* __restrict__ A, int lda, const u16* __restrict__ B0, const u16* __restrict__ B1, int ldb, int nt, acc_t& acc, char* lds) {
;     ...
;   { LDB(Bq0, 1, 0) LDA(At, 1, 0) WAIT_V(2) BAR WAIT_L(0) MMA(0, 0, At, Bq0) BAR
;     LDB(Bq1, 1, 1) WAIT_V(0) BAR WAIT_L(0) MMA(0, 1, At, Bq1) BAR
;     LDA(At, 1, 1) BAR WAIT_L(0) MMA(1, 0, At, Bq0) MMA(1, 1, At, Bq1) BAR }
;   if (wr == 0) BAR
;   __syncthreads();
	ds_read_b128 v[166:169], v151
	ds_read_b128 v[198:201], v151 offset:1024
	ds_read_b128 v[216:219], v151 offset:2048
	ds_read_b128 v[226:229], v151 offset:3072
	s_waitcnt vmcnt(0)
	s_barrier
	s_waitcnt lgkmcnt(0)
	s_waitcnt lgkmcnt(0)
	v_mfma_f32_16x16x32_bf16 v[98:101], v[166:169], v[24:27], v[206:209]
	v_mfma_f32_16x16x32_bf16 v[24:27], v[216:219], v[24:27], v[90:93]
	v_mfma_f32_16x16x32_bf16 v[114:117], v[226:229], v[28:31], v[24:27]
	v_mfma_f32_16x16x32_bf16 v[24:27], v[166:169], v[40:43], v[158:161]
	v_mfma_f32_16x16x32_bf16 v[106:109], v[198:201], v[44:47], v[24:27]
	v_mfma_f32_16x16x32_bf16 v[24:27], v[216:219], v[40:43], v[82:85]
	v_mfma_f32_16x16x32_bf16 v[118:121], v[198:201], v[28:31], v[98:101]
	v_mfma_f32_16x16x32_bf16 v[98:101], v[226:229], v[44:47], v[24:27]
	v_mfma_f32_16x16x32_bf16 v[24:27], v[166:169], v[182:185], v[170:173]
	v_mfma_f32_16x16x32_bf16 v[90:93], v[198:201], v[186:189], v[24:27]
	v_mfma_f32_16x16x32_bf16 v[24:27], v[216:219], v[182:185], v[74:77]
	v_mfma_f32_16x16x32_bf16 v[82:85], v[226:229], v[186:189], v[24:27]
	v_mfma_f32_16x16x32_bf16 v[24:27], v[166:169], v[190:193], v[174:177]
	v_mfma_f32_16x16x32_bf16 v[74:77], v[198:201], v[202:205], v[24:27]
	v_mfma_f32_16x16x32_bf16 v[24:27], v[216:219], v[190:193], v[66:69]
	v_mfma_f32_16x16x32_bf16 v[66:69], v[226:229], v[202:205], v[24:27]
	s_barrier
	ds_read_b128 v[156:159], v148 offset:49152
	ds_read_b128 v[148:151], v148 offset:50176
	ds_read_b128 v[170:173], v147 offset:49152
	ds_read_b128 v[174:177], v147 offset:50176
	ds_read_b128 v[182:185], v146 offset:49152
	ds_read_b128 v[186:189], v146 offset:50176
	ds_read_b128 v[190:193], v141 offset:49152
	ds_read_b128 v[202:205], v141 offset:50176
	s_barrier
	s_waitcnt lgkmcnt(0)
	s_waitcnt lgkmcnt(0)
	v_mfma_f32_16x16x32_bf16 v[24:27], v[8:11], v[156:159], v[60:63]
	v_mfma_f32_16x16x32_bf16 v[60:63], v[12:15], v[148:151], v[24:27]
	v_mfma_f32_16x16x32_bf16 v[24:27], v[162:165], v[156:159], v[56:59]
	v_mfma_f32_16x16x32_bf16 v[56:59], v[178:181], v[148:151], v[24:27]
	v_mfma_f32_16x16x32_bf16 v[24:27], v[8:11], v[170:173], v[52:55]
	v_mfma_f32_16x16x32_bf16 v[44:47], v[12:15], v[174:177], v[24:27]
	v_mfma_f32_16x16x32_bf16 v[24:27], v[162:165], v[170:173], v[48:51]
	v_mfma_f32_16x16x32_bf16 v[40:43], v[178:181], v[174:177], v[24:27]
	v_mfma_f32_16x16x32_bf16 v[24:27], v[8:11], v[182:185], v[194:197]
	v_mfma_f32_16x16x32_bf16 v[8:11], v[8:11], v[190:193], v[36:39]
	v_mfma_f32_16x16x32_bf16 v[28:31], v[12:15], v[186:189], v[24:27]
	v_mfma_f32_16x16x32_bf16 v[24:27], v[162:165], v[182:185], v[210:213]
	v_mfma_f32_16x16x32_bf16 v[12:15], v[12:15], v[202:205], v[8:11]
	v_mfma_f32_16x16x32_bf16 v[8:11], v[162:165], v[190:193], v[32:35]
	v_mfma_f32_16x16x32_bf16 v[24:27], v[178:181], v[186:189], v[24:27]
	v_mfma_f32_16x16x32_bf16 v[8:11], v[178:181], v[202:205], v[8:11]
	v_mfma_f32_16x16x32_bf16 v[32:35], v[166:169], v[156:159], v[130:133]
	v_mfma_f32_16x16x32_bf16 v[52:55], v[198:201], v[148:151], v[32:35]
	v_mfma_f32_16x16x32_bf16 v[32:35], v[216:219], v[156:159], v[134:137]
	v_mfma_f32_16x16x32_bf16 v[16:19], v[216:219], v[170:173], v[16:19]
	v_mfma_f32_16x16x32_bf16 v[48:51], v[226:229], v[148:151], v[32:35]
	v_mfma_f32_16x16x32_bf16 v[20:23], v[166:169], v[170:173], v[20:23]
	v_mfma_f32_16x16x32_bf16 v[32:35], v[226:229], v[174:177], v[16:19]
	v_mfma_f32_16x16x32_bf16 v[16:19], v[166:169], v[182:185], v[142:145]
	v_mfma_f32_16x16x32_bf16 v[36:39], v[198:201], v[174:177], v[20:23]
	v_mfma_f32_16x16x32_bf16 v[20:23], v[198:201], v[186:189], v[16:19]
	v_mfma_f32_16x16x32_bf16 v[16:19], v[216:219], v[182:185], v[152:155]
	v_mfma_f32_16x16x32_bf16 v[4:7], v[166:169], v[190:193], v[4:7]
	v_mfma_f32_16x16x32_bf16 v[0:3], v[216:219], v[190:193], v[0:3]
	v_mfma_f32_16x16x32_bf16 v[16:19], v[226:229], v[186:189], v[16:19]
	v_mfma_f32_16x16x32_bf16 v[4:7], v[198:201], v[202:205], v[4:7]
	v_mfma_f32_16x16x32_bf16 v[0:3], v[226:229], v[202:205], v[0:3]
	s_movk_i32 s2, 0x100
	v_cmp_gt_u32_e32 vcc, s2, v140
	s_barrier
	s_and_saveexec_b64 s[8:9], vcc
	s_cbranch_execz .LBB0_982
	s_barrier

; #define STAGE_A(b, h, kt) { const u16* ap_ = A + (size_t)((h) * ahalf + (unsigned)(kt) * 64u); glds16(ap_ + ao0, l0 + SA_(b, h)); glds16(ap_ + ao1, l0 + SA_(b, h) + 8192); }
; #define STAGE_B(b, h, kt) { const u16* bp_ = ((h) ? B1 : B0) + (unsigned)(kt) * 64u; glds16(bp_ + bo0, l0 + SB_(b, h)); glds16(bp_ + bo1, l0 + SB_(b, h) + 8192); }
; #define LDA(dst, b, h) _Pragma("unroll") for (int m = 0; m < 4; ++m) _Pragma("unroll") for (int k = 0; k < 2; ++k) \
;     dst[m][k] = *(const bf16x8*)(lds + SA_(b, h) + lds_byte(wr * 64 + m * 16 + fr, k * 32 + fq * 8));
; #define LDB(dst, b, h) _Pragma("unroll") for (int n = 0; n < 2; ++n) _Pragma("unroll") for (int k = 0; k < 2; ++k) \
;     dst[n][k] = *(const bf16x8*)(lds + SB_(b, h) + lds_byte(wc * 32 + n * 16 + fr, k * 32 + fq * 8));
; #define MMA(ai, bj, At_, Bt_) { __builtin_amdgcn_s_setprio(1); \
;     _Pragma("unroll") for (int m = 0; m < 4; ++m) _Pragma("unroll") for (int n = 0; n < 2; ++n) _Pragma("unroll") for (int k = 0; k < 2; ++k) \
;       acc[ai][bj][m][n] = MFMA16(Bt_[n][k], At_[m][k], acc[ai][bj][m][n]); \
;     __builtin_amdgcn_s_setprio(0); }
; #define WAIT_V(n) asm volatile("s_waitcnt vmcnt(" #n ")" ::: "memory");
; #define WAIT_L(n) asm volatile("s_waitcnt lgkmcnt(" #n ")" ::: "memory");
; #define BAR __builtin_amdgcn_s_barrier();
; #define SCHED __builtin_amdgcn_sched_barrier(0);
; DI void gemm256(const u16* __restrict__ A, int lda, const u16* __restrict__ B0, const u16* __restrict__ B1, int ldb, int nt, acc_t& acc, char* lds) {
;     ...
;   for (int t = 0; t < nt - 2; t += 2) {
;     LDB(Bq0, 0, 0) SCHED LDA(At, 0, 0) STAGE_A(1, 1, t + 1)
;     WAIT_L(8) BAR WAIT_L(0) MMA(0, 0, At, Bq0) BAR SCHED
;     LDB(Bq1, 0, 1) STAGE_B(0, 0, t + 2)
;     BAR WAIT_L(0) MMA(0, 1, At, Bq1) BAR
;     LDA(At, 0, 1) STAGE_A(0, 0, t + 2)
;     BAR WAIT_L(0) MMA(1, 0, At, Bq0) BAR SCHED
;     STAGE_B(0, 1, t + 2)
;     WAIT_V(6) BAR MMA(1, 1, At, Bq1) BAR
;     LDB(Bq0, 1, 0) SCHED LDA(At, 1, 0) STAGE_A(0, 1, t + 2)
;     WAIT_L(8) BAR WAIT_L(0) MMA(0, 0, At, Bq0) BAR SCHED
.LBB0_985:
	ds_read_b128 v[142:145], v166
	ds_read_b128 v[170:173], v166 offset:1024
	ds_read_b128 v[174:177], v166 offset:2048
	ds_read_b128 v[178:181], v166 offset:3072
	v_add_u32_e32 v167, 0xc000, v150
	v_lshl_add_u64 v[222:223], s[8:9], 0, v[136:137]
	v_readfirstlane_b32 s3, v167
	v_lshl_add_u64 v[168:169], v[222:223], 0, s[0:1]
	s_mov_b32 m0, s3
	ds_read_b128 v[182:185], v148
	ds_read_b128 v[186:189], v148 offset:1024
	ds_read_b128 v[190:193], v147
	ds_read_b128 v[194:197], v147 offset:1024
	ds_read_b128 v[198:201], v146
	ds_read_b128 v[202:205], v146 offset:1024
	ds_read_b128 v[206:209], v141
	ds_read_b128 v[210:213], v141 offset:1024
	global_load_lds_dwordx4 v[168:169], off
	v_add_u32_e32 v168, 0xe000, v150
	v_lshl_add_u64 v[224:225], s[8:9], 0, v[138:139]
	v_readfirstlane_b32 s3, v168
	v_lshl_add_u64 v[216:217], v[224:225], 0, s[0:1]
	s_mov_b32 m0, s3
	s_nop 0
	global_load_lds_dwordx4 v[216:217], off
	s_waitcnt lgkmcnt(8)
	s_barrier
	s_waitcnt lgkmcnt(0)
	s_waitcnt lgkmcnt(0)
	v_mfma_f32_16x16x32_bf16 v[126:129], v[142:145], v[182:185], v[126:129]
	v_mfma_f32_16x16x32_bf16 v[122:125], v[174:177], v[182:185], v[122:125]
	v_mfma_f32_16x16x32_bf16 v[118:121], v[142:145], v[190:193], v[118:121]
	v_mfma_f32_16x16x32_bf16 v[114:117], v[174:177], v[190:193], v[114:117]
	v_mfma_f32_16x16x32_bf16 v[110:113], v[142:145], v[198:201], v[110:113]
	v_mfma_f32_16x16x32_bf16 v[106:109], v[174:177], v[198:201], v[106:109]
	v_mfma_f32_16x16x32_bf16 v[102:105], v[142:145], v[206:209], v[102:105]
	v_mfma_f32_16x16x32_bf16 v[98:101], v[174:177], v[206:209], v[98:101]
	v_mfma_f32_16x16x32_bf16 v[126:129], v[170:173], v[186:189], v[126:129]
	v_mfma_f32_16x16x32_bf16 v[122:125], v[178:181], v[186:189], v[122:125]
	v_mfma_f32_16x16x32_bf16 v[118:121], v[170:173], v[194:197], v[118:121]
	v_mfma_f32_16x16x32_bf16 v[114:117], v[178:181], v[194:197], v[114:117]
	v_mfma_f32_16x16x32_bf16 v[110:113], v[170:173], v[202:205], v[110:113]
	v_mfma_f32_16x16x32_bf16 v[106:109], v[178:181], v[202:205], v[106:109]
	v_mfma_f32_16x16x32_bf16 v[102:105], v[170:173], v[210:213], v[102:105]
	v_mfma_f32_16x16x32_bf16 v[98:101], v[178:181], v[210:213], v[98:101]
	s_barrier
	v_lshl_add_u64 v[238:239], s[8:9], 0, v[132:133]
	v_readfirstlane_b32 s3, v151
	v_lshl_add_u64 v[240:241], v[238:239], 0, s[22:23]
	s_mov_b32 m0, s3
	ds_read_b128 v[216:219], v165
	ds_read_b128 v[226:229], v165 offset:1024
	ds_read_b128 v[230:233], v165 offset:2048
	ds_read_b128 v[234:237], v165 offset:3072
	global_load_lds_dwordx4 v[240:241], off
	v_lshl_add_u64 v[240:241], s[8:9], 0, v[134:135]
	v_readfirstlane_b32 s3, v152
	v_lshl_add_u64 v[242:243], v[240:241], 0, s[22:23]
	s_mov_b32 m0, s3
	s_nop 0
	global_load_lds_dwordx4 v[242:243], off
	s_barrier
	s_waitcnt lgkmcnt(0)
	s_waitcnt lgkmcnt(0)
	v_mfma_f32_16x16x32_bf16 v[94:97], v[216:219], v[182:185], v[94:97]
	v_mfma_f32_16x16x32_bf16 v[90:93], v[230:233], v[182:185], v[90:93]
	v_mfma_f32_16x16x32_bf16 v[86:89], v[216:219], v[190:193], v[86:89]
	v_mfma_f32_16x16x32_bf16 v[82:85], v[230:233], v[190:193], v[82:85]
	v_mfma_f32_16x16x32_bf16 v[78:81], v[216:219], v[198:201], v[78:81]
	v_mfma_f32_16x16x32_bf16 v[74:77], v[230:233], v[198:201], v[74:77]
	v_mfma_f32_16x16x32_bf16 v[70:73], v[216:219], v[206:209], v[70:73]
	v_mfma_f32_16x16x32_bf16 v[66:69], v[230:233], v[206:209], v[66:69]
	v_mfma_f32_16x16x32_bf16 v[94:97], v[226:229], v[186:189], v[94:97]
	v_mfma_f32_16x16x32_bf16 v[90:93], v[234:237], v[186:189], v[90:93]
	v_mfma_f32_16x16x32_bf16 v[86:89], v[226:229], v[194:197], v[86:89]
	v_mfma_f32_16x16x32_bf16 v[82:85], v[234:237], v[194:197], v[82:85]
	v_mfma_f32_16x16x32_bf16 v[78:81], v[226:229], v[202:205], v[78:81]
	v_mfma_f32_16x16x32_bf16 v[74:77], v[234:237], v[202:205], v[74:77]
	v_mfma_f32_16x16x32_bf16 v[70:73], v[226:229], v[210:213], v[70:73]
	v_mfma_f32_16x16x32_bf16 v[66:69], v[234:237], v[210:213], v[66:69]
	v_readfirstlane_b32 s3, v150
	v_lshl_add_u64 v[242:243], v[222:223], 0, s[20:21]
	s_mov_b32 m0, s3
	v_readfirstlane_b32 s3, v153
	s_barrier
	ds_read_b128 v[182:185], v148 offset:16384
	ds_read_b128 v[186:189], v148 offset:17408
	ds_read_b128 v[190:193], v147 offset:16384
	ds_read_b128 v[194:197], v147 offset:17408
	ds_read_b128 v[198:201], v146 offset:16384
	ds_read_b128 v[202:205], v146 offset:17408
	ds_read_b128 v[206:209], v141 offset:16384
	ds_read_b128 v[210:213], v141 offset:17408
	global_load_lds_dwordx4 v[242:243], off
	v_lshl_add_u64 v[242:243], v[224:225], 0, s[20:21]
	s_mov_b32 m0, s3
	s_nop 0
	global_load_lds_dwordx4 v[242:243], off
	s_barrier
	s_waitcnt lgkmcnt(0)
	s_waitcnt lgkmcnt(0)
	v_mfma_f32_16x16x32_bf16 v[60:63], v[142:145], v[182:185], v[60:63]
	v_mfma_f32_16x16x32_bf16 v[56:59], v[174:177], v[182:185], v[56:59]
	v_mfma_f32_16x16x32_bf16 v[52:55], v[142:145], v[190:193], v[52:55]
	v_mfma_f32_16x16x32_bf16 v[48:51], v[174:177], v[190:193], v[48:51]
	v_mfma_f32_16x16x32_bf16 v[44:47], v[142:145], v[198:201], v[44:47]
	v_mfma_f32_16x16x32_bf16 v[40:43], v[174:177], v[198:201], v[40:43]
	v_mfma_f32_16x16x32_bf16 v[36:39], v[142:145], v[206:209], v[36:39]
	v_mfma_f32_16x16x32_bf16 v[32:35], v[174:177], v[206:209], v[32:35]
	v_mfma_f32_16x16x32_bf16 v[60:63], v[170:173], v[186:189], v[60:63]
	v_mfma_f32_16x16x32_bf16 v[56:59], v[178:181], v[186:189], v[56:59]
	v_mfma_f32_16x16x32_bf16 v[52:55], v[170:173], v[194:197], v[52:55]
	v_mfma_f32_16x16x32_bf16 v[48:51], v[178:181], v[194:197], v[48:51]
	v_mfma_f32_16x16x32_bf16 v[44:47], v[170:173], v[202:205], v[44:47]
	v_mfma_f32_16x16x32_bf16 v[40:43], v[178:181], v[202:205], v[40:43]
	v_mfma_f32_16x16x32_bf16 v[36:39], v[170:173], v[210:213], v[36:39]
	v_mfma_f32_16x16x32_bf16 v[32:35], v[178:181], v[210:213], v[32:35]
	s_barrier
; #define STAGE_A(b, h, kt) { const u16* ap_ = A + (size_t)((h) * ahalf + (unsigned)(kt) * 64u); glds16(ap_ + ao0, l0 + SA_(b, h)); glds16(ap_ + ao1, l0 + SA_(b, h) + 8192); }
; #define STAGE_B(b, h, kt) { const u16* bp_ = ((h) ? B1 : B0) + (unsigned)(kt) * 64u; glds16(bp_ + bo0, l0 + SB_(b, h)); glds16(bp_ + bo1, l0 + SB_(b, h) + 8192); }
; #define LDA(dst, b, h) _Pragma("unroll") for (int m = 0; m < 4; ++m) _Pragma("unroll") for (int k = 0; k < 2; ++k) \
;     dst[m][k] = *(const bf16x8*)(lds + SA_(b, h) + lds_byte(wr * 64 + m * 16 + fr, k * 32 + fq * 8));
; #define LDB(dst, b, h) _Pragma("unroll") for (int n = 0; n < 2; ++n) _Pragma("unroll") for (int k = 0; k < 2; ++k) \
;     dst[n][k] = *(const bf16x8*)(lds + SB_(b, h) + lds_byte(wc * 32 + n * 16 + fr, k * 32 + fq * 8));
; #define MMA(ai, bj, At_, Bt_) { __builtin_amdgcn_s_setprio(1); \
;     _Pragma("unroll") for (int m = 0; m < 4; ++m) _Pragma("unroll") for (int n = 0; n < 2; ++n) _Pragma("unroll") for (int k = 0; k < 2; ++k) \
;       acc[ai][bj][m][n] = MFMA16(Bt_[n][k], At_[m][k], acc[ai][bj][m][n]); \
;     __builtin_amdgcn_s_setprio(0); }
; #define WAIT_V(n) asm volatile("s_waitcnt vmcnt(" #n ")" ::: "memory");
; #define WAIT_L(n) asm volatile("s_waitcnt lgkmcnt(" #n ")" ::: "memory");
; #define BAR __builtin_amdgcn_s_barrier();
; #define SCHED __builtin_amdgcn_sched_barrier(0);
; DI void gemm256(const u16* __restrict__ A, int lda, const u16* __restrict__ B0, const u16* __restrict__ B1, int ldb, int nt, acc_t& acc, char* lds) {
;     ...
;     LDA(At, 0, 1) STAGE_A(0, 0, t + 2)
;     BAR WAIT_L(0) MMA(1, 0, At, Bq0) BAR SCHED
;     STAGE_B(0, 1, t + 2)
;     WAIT_V(6) BAR MMA(1, 1, At, Bq1) BAR
;     LDB(Bq0, 1, 0) SCHED LDA(At, 1, 0) STAGE_A(0, 1, t + 2)
;     WAIT_L(8) BAR WAIT_L(0) MMA(0, 0, At, Bq0) BAR SCHED
;     LDB(Bq1, 1, 1) STAGE_B(1, 0, t + 3)
;     BAR WAIT_L(0) MMA(0, 1, At, Bq1) BAR
;     LDA(At, 1, 1) STAGE_A(1, 0, t + 3)
;     BAR WAIT_L(0) MMA(1, 0, At, Bq0) BAR SCHED
;     STAGE_B(1, 1, t + 3)
	v_readfirstlane_b32 s3, v155
	v_lshl_add_u64 v[142:143], v[238:239], 0, s[28:29]
	s_mov_b32 m0, s3
	v_readfirstlane_b32 s3, v156
	global_load_lds_dwordx4 v[142:143], off
	v_lshl_add_u64 v[142:143], v[240:241], 0, s[28:29]
	s_mov_b32 m0, s3
	s_nop 0
	global_load_lds_dwordx4 v[142:143], off
	s_waitcnt vmcnt(6)
	s_barrier
	v_mfma_f32_16x16x32_bf16 v[28:31], v[216:219], v[182:185], v[28:31]
	v_mfma_f32_16x16x32_bf16 v[24:27], v[230:233], v[182:185], v[24:27]
	v_mfma_f32_16x16x32_bf16 v[20:23], v[216:219], v[190:193], v[20:23]
	v_mfma_f32_16x16x32_bf16 v[16:19], v[230:233], v[190:193], v[16:19]
	v_mfma_f32_16x16x32_bf16 v[12:15], v[216:219], v[198:201], v[12:15]
	v_mfma_f32_16x16x32_bf16 v[8:11], v[230:233], v[198:201], v[8:11]
	v_mfma_f32_16x16x32_bf16 v[4:7], v[216:219], v[206:209], v[4:7]
	v_mfma_f32_16x16x32_bf16 v[0:3], v[230:233], v[206:209], v[0:3]
	v_mfma_f32_16x16x32_bf16 v[28:31], v[226:229], v[186:189], v[28:31]
	v_mfma_f32_16x16x32_bf16 v[24:27], v[234:237], v[186:189], v[24:27]
	v_mfma_f32_16x16x32_bf16 v[20:23], v[226:229], v[194:197], v[20:23]
	v_mfma_f32_16x16x32_bf16 v[16:19], v[234:237], v[194:197], v[16:19]
	v_mfma_f32_16x16x32_bf16 v[12:15], v[226:229], v[202:205], v[12:15]
	v_mfma_f32_16x16x32_bf16 v[8:11], v[234:237], v[202:205], v[8:11]
	v_mfma_f32_16x16x32_bf16 v[4:7], v[226:229], v[210:213], v[4:7]
	v_mfma_f32_16x16x32_bf16 v[0:3], v[234:237], v[210:213], v[0:3]
	s_barrier
	ds_read_b128 v[142:145], v154
	ds_read_b128 v[170:173], v154 offset:1024
	ds_read_b128 v[174:177], v154 offset:2048
	ds_read_b128 v[178:181], v154 offset:3072
	v_readfirstlane_b32 s3, v157
	v_lshl_add_u64 v[216:217], v[222:223], 0, s[24:25]
	s_mov_b32 m0, s3
	v_readfirstlane_b32 s3, v158
	ds_read_b128 v[182:185], v148 offset:32768
	ds_read_b128 v[186:189], v148 offset:33792
	ds_read_b128 v[190:193], v147 offset:32768
	ds_read_b128 v[194:197], v147 offset:33792
	ds_read_b128 v[198:201], v146 offset:32768
	ds_read_b128 v[202:205], v146 offset:33792
	ds_read_b128 v[206:209], v141 offset:32768
	ds_read_b128 v[210:213], v141 offset:33792
	global_load_lds_dwordx4 v[216:217], off
	v_lshl_add_u64 v[216:217], v[224:225], 0, s[24:25]
	s_mov_b32 m0, s3
	s_nop 0
	global_load_lds_dwordx4 v[216:217], off
	s_waitcnt lgkmcnt(8)
	s_barrier
	s_waitcnt lgkmcnt(0)
	s_waitcnt lgkmcnt(0)
	v_mfma_f32_16x16x32_bf16 v[126:129], v[142:145], v[182:185], v[126:129]
	v_mfma_f32_16x16x32_bf16 v[122:125], v[174:177], v[182:185], v[122:125]
	v_mfma_f32_16x16x32_bf16 v[118:121], v[142:145], v[190:193], v[118:121]
	v_mfma_f32_16x16x32_bf16 v[114:117], v[174:177], v[190:193], v[114:117]
	v_mfma_f32_16x16x32_bf16 v[110:113], v[142:145], v[198:201], v[110:113]
	v_mfma_f32_16x16x32_bf16 v[106:109], v[174:177], v[198:201], v[106:109]
	v_mfma_f32_16x16x32_bf16 v[102:105], v[142:145], v[206:209], v[102:105]
	v_mfma_f32_16x16x32_bf16 v[98:101], v[174:177], v[206:209], v[98:101]
	v_mfma_f32_16x16x32_bf16 v[126:129], v[170:173], v[186:189], v[126:129]
	v_mfma_f32_16x16x32_bf16 v[122:125], v[178:181], v[186:189], v[122:125]
	v_mfma_f32_16x16x32_bf16 v[118:121], v[170:173], v[194:197], v[118:121]
	v_mfma_f32_16x16x32_bf16 v[114:117], v[178:181], v[194:197], v[114:117]
	v_mfma_f32_16x16x32_bf16 v[110:113], v[170:173], v[202:205], v[110:113]
	v_mfma_f32_16x16x32_bf16 v[106:109], v[178:181], v[202:205], v[106:109]
	v_mfma_f32_16x16x32_bf16 v[102:105], v[170:173], v[210:213], v[102:105]
	v_mfma_f32_16x16x32_bf16 v[98:101], v[178:181], v[210:213], v[98:101]
	s_barrier
	v_readfirstlane_b32 s3, v159
	v_lshl_add_u64 v[242:243], v[238:239], 0, s[46:47]
	s_mov_b32 m0, s3
	v_readfirstlane_b32 s3, v160
	ds_read_b128 v[216:219], v149
	ds_read_b128 v[226:229], v149 offset:1024
	ds_read_b128 v[230:233], v149 offset:2048
	ds_read_b128 v[234:237], v149 offset:3072
	global_load_lds_dwordx4 v[242:243], off
	v_lshl_add_u64 v[242:243], v[240:241], 0, s[46:47]
	s_mov_b32 m0, s3
	s_nop 0
	global_load_lds_dwordx4 v[242:243], off
	s_barrier
	s_waitcnt lgkmcnt(0)
	s_waitcnt lgkmcnt(0)
	v_mfma_f32_16x16x32_bf16 v[94:97], v[216:219], v[182:185], v[94:97]
	v_mfma_f32_16x16x32_bf16 v[90:93], v[230:233], v[182:185], v[90:93]
	v_mfma_f32_16x16x32_bf16 v[86:89], v[216:219], v[190:193], v[86:89]
	v_mfma_f32_16x16x32_bf16 v[82:85], v[230:233], v[190:193], v[82:85]
	v_mfma_f32_16x16x32_bf16 v[78:81], v[216:219], v[198:201], v[78:81]
	v_mfma_f32_16x16x32_bf16 v[74:77], v[230:233], v[198:201], v[74:77]
	v_mfma_f32_16x16x32_bf16 v[70:73], v[216:219], v[206:209], v[70:73]
	v_mfma_f32_16x16x32_bf16 v[66:69], v[230:233], v[206:209], v[66:69]
	v_mfma_f32_16x16x32_bf16 v[94:97], v[226:229], v[186:189], v[94:97]
	v_mfma_f32_16x16x32_bf16 v[90:93], v[234:237], v[186:189], v[90:93]
	v_mfma_f32_16x16x32_bf16 v[86:89], v[226:229], v[194:197], v[86:89]
	v_mfma_f32_16x16x32_bf16 v[82:85], v[234:237], v[194:197], v[82:85]
	v_mfma_f32_16x16x32_bf16 v[78:81], v[226:229], v[202:205], v[78:81]
	v_mfma_f32_16x16x32_bf16 v[74:77], v[234:237], v[202:205], v[74:77]
	v_mfma_f32_16x16x32_bf16 v[70:73], v[226:229], v[210:213], v[70:73]
	v_mfma_f32_16x16x32_bf16 v[66:69], v[234:237], v[210:213], v[66:69]
	v_readfirstlane_b32 s3, v161
	v_lshl_add_u64 v[222:223], v[222:223], 0, s[34:35]
	s_mov_b32 m0, s3
	v_readfirstlane_b32 s3, v162
	s_barrier
	ds_read_b128 v[182:185], v148 offset:49152
	ds_read_b128 v[186:189], v148 offset:50176
	ds_read_b128 v[190:193], v147 offset:49152
	ds_read_b128 v[194:197], v147 offset:50176
	ds_read_b128 v[198:201], v146 offset:49152
	ds_read_b128 v[202:205], v146 offset:50176
	ds_read_b128 v[206:209], v141 offset:49152
	ds_read_b128 v[210:213], v141 offset:50176
	global_load_lds_dwordx4 v[222:223], off
	v_lshl_add_u64 v[222:223], v[224:225], 0, s[34:35]
	s_mov_b32 m0, s3
	s_nop 0
	global_load_lds_dwordx4 v[222:223], off
	s_barrier
; #define STAGE_A(b, h, kt) { const u16* ap_ = A + (size_t)((h) * ahalf + (unsigned)(kt) * 64u); glds16(ap_ + ao0, l0 + SA_(b, h)); glds16(ap_ + ao1, l0 + SA_(b, h) + 8192); }
; #define STAGE_B(b, h, kt) { const u16* bp_ = ((h) ? B1 : B0) + (unsigned)(kt) * 64u; glds16(bp_ + bo0, l0 + SB_(b, h)); glds16(bp_ + bo1, l0 + SB_(b, h) + 8192); }
; #define LDA(dst, b, h) _Pragma("unroll") for (int m = 0; m < 4; ++m) _Pragma("unroll") for (int k = 0; k < 2; ++k) \
;     dst[m][k] = *(const bf16x8*)(lds + SA_(b, h) + lds_byte(wr * 64 + m * 16 + fr, k * 32 + fq * 8));
; #define LDB(dst, b, h) _Pragma("unroll") for (int n = 0; n < 2; ++n) _Pragma("unroll") for (int k = 0; k < 2; ++k) \
;     dst[n][k] = *(const bf16x8*)(lds + SB_(b, h) + lds_byte(wc * 32 + n * 16 + fr, k * 32 + fq * 8));
; #define MMA(ai, bj, At_, Bt_) { __builtin_amdgcn_s_setprio(1); \
;     _Pragma("unroll") for (int m = 0; m < 4; ++m) _Pragma("unroll") for (int n = 0; n < 2; ++n) _Pragma("unroll") for (int k = 0; k < 2; ++k) \
;       acc[ai][bj][m][n] = MFMA16(Bt_[n][k], At_[m][k], acc[ai][bj][m][n]); \
;     __builtin_amdgcn_s_setprio(0); }
; #define WAIT_V(n) asm volatile("s_waitcnt vmcnt(" #n ")" ::: "memory");
; #define WAIT_L(n) asm volatile("s_waitcnt lgkmcnt(" #n ")" ::: "memory");
; #define BAR __builtin_amdgcn_s_barrier();
; #define SCHED __builtin_amdgcn_sched_barrier(0);
; DI void gemm256(const u16* __restrict__ A, int lda, const u16* __restrict__ B0, const u16* __restrict__ B1, int ldb, int nt, acc_t& acc, char* lds) {
;     ...
;     BAR WAIT_L(0) MMA(1, 0, At, Bq0) BAR SCHED
;     STAGE_B(1, 1, t + 3)
;     WAIT_V(6) BAR MMA(1, 1, At, Bq1) BAR
;   }
;   { LDB(Bq0, 0, 0) LDA(At, 0, 0) STAGE_A(1, 1, nt - 1)
;     BAR WAIT_L(0) MMA(0, 0, At, Bq0) BAR
;     LDB(Bq1, 0, 1) BAR WAIT_L(0) MMA(0, 1, At, Bq1) BAR
;     LDA(At, 0, 1) WAIT_V(4) BAR WAIT_L(0) MMA(1, 0, At, Bq0) MMA(1, 1, At, Bq1) BAR }
	s_waitcnt lgkmcnt(0)
	s_waitcnt lgkmcnt(0)
	v_mfma_f32_16x16x32_bf16 v[60:63], v[142:145], v[182:185], v[60:63]
	v_mfma_f32_16x16x32_bf16 v[56:59], v[174:177], v[182:185], v[56:59]
	v_mfma_f32_16x16x32_bf16 v[52:55], v[142:145], v[190:193], v[52:55]
	v_mfma_f32_16x16x32_bf16 v[48:51], v[174:177], v[190:193], v[48:51]
	v_mfma_f32_16x16x32_bf16 v[44:47], v[142:145], v[198:201], v[44:47]
	v_mfma_f32_16x16x32_bf16 v[40:43], v[174:177], v[198:201], v[40:43]
	v_mfma_f32_16x16x32_bf16 v[36:39], v[142:145], v[206:209], v[36:39]
	v_mfma_f32_16x16x32_bf16 v[32:35], v[174:177], v[206:209], v[32:35]
	v_mfma_f32_16x16x32_bf16 v[60:63], v[170:173], v[186:189], v[60:63]
	v_mfma_f32_16x16x32_bf16 v[56:59], v[178:181], v[186:189], v[56:59]
	v_mfma_f32_16x16x32_bf16 v[52:55], v[170:173], v[194:197], v[52:55]
	v_mfma_f32_16x16x32_bf16 v[48:51], v[178:181], v[194:197], v[48:51]
	v_mfma_f32_16x16x32_bf16 v[44:47], v[170:173], v[202:205], v[44:47]
	v_mfma_f32_16x16x32_bf16 v[40:43], v[178:181], v[202:205], v[40:43]
	v_mfma_f32_16x16x32_bf16 v[36:39], v[170:173], v[210:213], v[36:39]
	v_mfma_f32_16x16x32_bf16 v[32:35], v[178:181], v[210:213], v[32:35]
	s_barrier
	v_readfirstlane_b32 s3, v163
	v_lshl_add_u64 v[142:143], v[238:239], 0, s[50:51]
	s_mov_b32 m0, s3
	v_readfirstlane_b32 s3, v164
	global_load_lds_dwordx4 v[142:143], off
	v_lshl_add_u64 v[142:143], v[240:241], 0, s[50:51]
	s_mov_b32 m0, s3
	s_nop 0
	global_load_lds_dwordx4 v[142:143], off
	s_waitcnt vmcnt(6)
	s_barrier
	v_mfma_f32_16x16x32_bf16 v[28:31], v[216:219], v[182:185], v[28:31]
	v_mfma_f32_16x16x32_bf16 v[24:27], v[230:233], v[182:185], v[24:27]
	v_mfma_f32_16x16x32_bf16 v[20:23], v[216:219], v[190:193], v[20:23]
	v_mfma_f32_16x16x32_bf16 v[16:19], v[230:233], v[190:193], v[16:19]
	v_mfma_f32_16x16x32_bf16 v[12:15], v[216:219], v[198:201], v[12:15]
	v_mfma_f32_16x16x32_bf16 v[8:11], v[230:233], v[198:201], v[8:11]
	v_mfma_f32_16x16x32_bf16 v[4:7], v[216:219], v[206:209], v[4:7]
	v_mfma_f32_16x16x32_bf16 v[0:3], v[230:233], v[206:209], v[0:3]
	v_mfma_f32_16x16x32_bf16 v[28:31], v[226:229], v[186:189], v[28:31]
	v_mfma_f32_16x16x32_bf16 v[24:27], v[234:237], v[186:189], v[24:27]
	v_mfma_f32_16x16x32_bf16 v[20:23], v[226:229], v[194:197], v[20:23]
	v_mfma_f32_16x16x32_bf16 v[16:19], v[234:237], v[194:197], v[16:19]
	v_mfma_f32_16x16x32_bf16 v[12:15], v[226:229], v[202:205], v[12:15]
	v_mfma_f32_16x16x32_bf16 v[8:11], v[234:237], v[202:205], v[8:11]
	v_mfma_f32_16x16x32_bf16 v[4:7], v[226:229], v[210:213], v[4:7]
	v_mfma_f32_16x16x32_bf16 v[0:3], v[234:237], v[210:213], v[0:3]
	s_add_i32 s2, s2, 2
	s_add_u32 s8, s8, 0x100
	s_addc_u32 s9, s9, 0
	s_cmp_lt_u32 s2, 12
	s_barrier
	s_cbranch_scc1 .LBB0_985
	v_readfirstlane_b32 s2, v167
	v_lshl_add_u64 v[194:195], v[64:65], 1, s[54:55]
	s_mov_b32 m0, s2
	v_readfirstlane_b32 s2, v168
	ds_read_b128 v[132:135], v166
	ds_read_b128 v[136:139], v166 offset:1024
	ds_read_b128 v[142:145], v166 offset:2048
	ds_read_b128 v[150:153], v166 offset:3072
	ds_read_b128 v[156:159], v148
	ds_read_b128 v[160:163], v148 offset:1024
	ds_read_b128 v[170:173], v147
	ds_read_b128 v[174:177], v147 offset:1024
	ds_read_b128 v[178:181], v146
	ds_read_b128 v[182:185], v146 offset:1024
	ds_read_b128 v[186:189], v141
	ds_read_b128 v[190:193], v141 offset:1024
	global_load_lds_dwordx4 v[194:195], off
	v_lshl_add_u64 v[130:131], v[130:131], 1, s[54:55]
	s_mov_b32 m0, s2
	s_nop 0
	global_load_lds_dwordx4 v[130:131], off
	s_barrier
	s_waitcnt lgkmcnt(0)
	s_waitcnt lgkmcnt(0)
	v_mfma_f32_16x16x32_bf16 v[126:129], v[132:135], v[156:159], v[126:129]
	v_mfma_f32_16x16x32_bf16 v[122:125], v[142:145], v[156:159], v[122:125]
	v_mfma_f32_16x16x32_bf16 v[118:121], v[132:135], v[170:173], v[118:121]
	v_mfma_f32_16x16x32_bf16 v[114:117], v[142:145], v[170:173], v[114:117]
	v_mfma_f32_16x16x32_bf16 v[102:105], v[132:135], v[186:189], v[102:105]
	v_mfma_f32_16x16x32_bf16 v[98:101], v[142:145], v[186:189], v[98:101]
	v_mfma_f32_16x16x32_bf16 v[126:129], v[136:139], v[160:163], v[126:129]
	v_mfma_f32_16x16x32_bf16 v[122:125], v[150:153], v[160:163], v[122:125]
	v_mfma_f32_16x16x32_bf16 v[118:121], v[136:139], v[174:177], v[118:121]
	v_mfma_f32_16x16x32_bf16 v[114:117], v[150:153], v[174:177], v[114:117]
	v_mfma_f32_16x16x32_bf16 v[110:113], v[132:135], v[178:181], v[110:113]
	v_mfma_f32_16x16x32_bf16 v[106:109], v[142:145], v[178:181], v[106:109]
	v_mfma_f32_16x16x32_bf16 v[102:105], v[136:139], v[190:193], v[102:105]
	v_mfma_f32_16x16x32_bf16 v[98:101], v[150:153], v[190:193], v[98:101]
	v_mfma_f32_16x16x32_bf16 v[166:169], v[136:139], v[182:185], v[110:113]
	v_mfma_f32_16x16x32_bf16 v[194:197], v[150:153], v[182:185], v[106:109]
	s_barrier
	s_nop 1
	ds_read_b128 v[106:109], v165
	ds_read_b128 v[110:113], v165 offset:1024
	ds_read_b128 v[198:201], v165 offset:2048
	ds_read_b128 v[202:205], v165 offset:3072
	s_barrier
	s_waitcnt lgkmcnt(0)
	s_waitcnt lgkmcnt(0)
	v_mfma_f32_16x16x32_bf16 v[86:89], v[106:109], v[170:173], v[86:89]
	v_mfma_f32_16x16x32_bf16 v[82:85], v[198:201], v[170:173], v[82:85]
	v_mfma_f32_16x16x32_bf16 v[70:73], v[106:109], v[186:189], v[70:73]
	v_mfma_f32_16x16x32_bf16 v[66:69], v[198:201], v[186:189], v[66:69]
	v_mfma_f32_16x16x32_bf16 v[94:97], v[106:109], v[156:159], v[94:97]
	v_mfma_f32_16x16x32_bf16 v[90:93], v[198:201], v[156:159], v[90:93]
	v_mfma_f32_16x16x32_bf16 v[86:89], v[110:113], v[174:177], v[86:89]
	v_mfma_f32_16x16x32_bf16 v[82:85], v[202:205], v[174:177], v[82:85]
	v_mfma_f32_16x16x32_bf16 v[78:81], v[106:109], v[178:181], v[78:81]
	v_mfma_f32_16x16x32_bf16 v[74:77], v[198:201], v[178:181], v[74:77]
	v_mfma_f32_16x16x32_bf16 v[70:73], v[110:113], v[190:193], v[70:73]
	v_mfma_f32_16x16x32_bf16 v[66:69], v[202:205], v[190:193], v[66:69]
	v_mfma_f32_16x16x32_bf16 v[206:209], v[110:113], v[160:163], v[94:97]
	v_mfma_f32_16x16x32_bf16 v[156:159], v[202:205], v[160:163], v[90:93]
	v_mfma_f32_16x16x32_bf16 v[160:163], v[110:113], v[182:185], v[78:81]
	v_mfma_f32_16x16x32_bf16 v[170:173], v[202:205], v[182:185], v[74:77]
	s_barrier
; #define LDA(dst, b, h) _Pragma("unroll") for (int m = 0; m < 4; ++m) _Pragma("unroll") for (int k = 0; k < 2; ++k) \
;     dst[m][k] = *(const bf16x8*)(lds + SA_(b, h) + lds_byte(wr * 64 + m * 16 + fr, k * 32 + fq * 8));
; #define LDB(dst, b, h) _Pragma("unroll") for (int n = 0; n < 2; ++n) _Pragma("unroll") for (int k = 0; k < 2; ++k) \
;     dst[n][k] = *(const bf16x8*)(lds + SB_(b, h) + lds_byte(wc * 32 + n * 16 + fr, k * 32 + fq * 8));
; #define MMA(ai, bj, At_, Bt_) { __builtin_amdgcn_s_setprio(1); \
;     _Pragma("unroll") for (int m = 0; m < 4; ++m) _Pragma("unroll") for (int n = 0; n < 2; ++n) _Pragma("unroll") for (int k = 0; k < 2; ++k) \
;       acc[ai][bj][m][n] = MFMA16(Bt_[n][k], At_[m][k], acc[ai][bj][m][n]); \
;     __builtin_amdgcn_s_setprio(0); }
; #define WAIT_V(n) asm volatile("s_waitcnt vmcnt(" #n ")" ::: "memory");
; #define WAIT_L(n) asm volatile("s_waitcnt lgkmcnt(" #n ")" ::: "memory");
; #define BAR __builtin_amdgcn_s_barrier();
; DI void gemm256(const u16* __restrict__ A, int lda, const u16* __restrict__ B0, const u16* __restrict__ B1, int ldb, int nt, acc_t& acc, char* lds) {
;     ...
;     BAR WAIT_L(0) MMA(0, 0, At, Bq0) BAR
;     LDB(Bq1, 0, 1) BAR WAIT_L(0) MMA(0, 1, At, Bq1) BAR
;     LDA(At, 0, 1) WAIT_V(4) BAR WAIT_L(0) MMA(1, 0, At, Bq0) MMA(1, 1, At, Bq1) BAR }
;   { LDB(Bq0, 1, 0) LDA(At, 1, 0) WAIT_V(2) BAR WAIT_L(0) MMA(0, 0, At, Bq0) BAR
	s_nop 0
	ds_read_b128 v[74:77], v148 offset:16384
	ds_read_b128 v[78:81], v148 offset:17408
	ds_read_b128 v[90:93], v147 offset:16384
	ds_read_b128 v[94:97], v147 offset:17408
	ds_read_b128 v[174:177], v146 offset:16384
	ds_read_b128 v[178:181], v146 offset:17408
	ds_read_b128 v[182:185], v141 offset:16384
	ds_read_b128 v[186:189], v141 offset:17408
	s_waitcnt vmcnt(4)
	s_barrier
	s_waitcnt lgkmcnt(0)
	s_waitcnt lgkmcnt(0)
	v_mfma_f32_16x16x32_bf16 v[60:63], v[132:135], v[74:77], v[60:63]
	v_mfma_f32_16x16x32_bf16 v[56:59], v[142:145], v[74:77], v[56:59]
	v_mfma_f32_16x16x32_bf16 v[52:55], v[132:135], v[90:93], v[52:55]
	v_mfma_f32_16x16x32_bf16 v[48:51], v[142:145], v[90:93], v[48:51]
	v_mfma_f32_16x16x32_bf16 v[36:39], v[132:135], v[182:185], v[36:39]
	v_mfma_f32_16x16x32_bf16 v[32:35], v[142:145], v[182:185], v[32:35]
	v_mfma_f32_16x16x32_bf16 v[60:63], v[136:139], v[78:81], v[60:63]
	v_mfma_f32_16x16x32_bf16 v[56:59], v[150:153], v[78:81], v[56:59]
	v_mfma_f32_16x16x32_bf16 v[52:55], v[136:139], v[94:97], v[52:55]
	v_mfma_f32_16x16x32_bf16 v[48:51], v[150:153], v[94:97], v[48:51]
	v_mfma_f32_16x16x32_bf16 v[44:47], v[132:135], v[174:177], v[44:47]
	v_mfma_f32_16x16x32_bf16 v[40:43], v[142:145], v[174:177], v[40:43]
	v_mfma_f32_16x16x32_bf16 v[36:39], v[136:139], v[186:189], v[36:39]
	v_mfma_f32_16x16x32_bf16 v[32:35], v[150:153], v[186:189], v[32:35]
	v_mfma_f32_16x16x32_bf16 v[190:193], v[136:139], v[178:181], v[44:47]
	v_mfma_f32_16x16x32_bf16 v[210:213], v[150:153], v[178:181], v[40:43]
	v_mfma_f32_16x16x32_bf16 v[20:23], v[106:109], v[90:93], v[20:23]
	v_mfma_f32_16x16x32_bf16 v[16:19], v[198:201], v[90:93], v[16:19]
	v_mfma_f32_16x16x32_bf16 v[4:7], v[106:109], v[182:185], v[4:7]
	v_mfma_f32_16x16x32_bf16 v[0:3], v[198:201], v[182:185], v[0:3]
	v_mfma_f32_16x16x32_bf16 v[28:31], v[106:109], v[74:77], v[28:31]
	v_mfma_f32_16x16x32_bf16 v[24:27], v[198:201], v[74:77], v[24:27]
	v_mfma_f32_16x16x32_bf16 v[20:23], v[110:113], v[94:97], v[20:23]
	v_mfma_f32_16x16x32_bf16 v[16:19], v[202:205], v[94:97], v[16:19]
	v_mfma_f32_16x16x32_bf16 v[12:15], v[106:109], v[174:177], v[12:15]
	v_mfma_f32_16x16x32_bf16 v[8:11], v[198:201], v[174:177], v[8:11]
	v_mfma_f32_16x16x32_bf16 v[4:7], v[110:113], v[186:189], v[4:7]
	v_mfma_f32_16x16x32_bf16 v[0:3], v[202:205], v[186:189], v[0:3]
	v_mfma_f32_16x16x32_bf16 v[130:133], v[110:113], v[78:81], v[28:31]
	v_mfma_f32_16x16x32_bf16 v[134:137], v[202:205], v[78:81], v[24:27]
	v_mfma_f32_16x16x32_bf16 v[142:145], v[110:113], v[178:181], v[12:15]
	v_mfma_f32_16x16x32_bf16 v[150:153], v[202:205], v[178:181], v[8:11]
	s_barrier
	s_nop 0
	ds_read_b128 v[8:11], v154
	ds_read_b128 v[12:15], v154 offset:1024
	ds_read_b128 v[174:177], v154 offset:2048
	ds_read_b128 v[178:181], v154 offset:3072
	ds_read_b128 v[24:27], v148 offset:32768
	ds_read_b128 v[28:31], v148 offset:33792
	ds_read_b128 v[40:43], v147 offset:32768
	ds_read_b128 v[44:47], v147 offset:33792
	ds_read_b128 v[182:185], v146 offset:32768
	ds_read_b128 v[186:189], v146 offset:33792
	ds_read_b128 v[198:201], v141 offset:32768
	ds_read_b128 v[202:205], v141 offset:33792
	s_waitcnt vmcnt(2)
	s_barrier
	s_waitcnt lgkmcnt(0)
	s_waitcnt lgkmcnt(0)
	v_mfma_f32_16x16x32_bf16 v[74:77], v[8:11], v[24:27], v[126:129]
	v_mfma_f32_16x16x32_bf16 v[126:129], v[12:15], v[28:31], v[74:77]
	v_mfma_f32_16x16x32_bf16 v[74:77], v[174:177], v[24:27], v[122:125]
	v_mfma_f32_16x16x32_bf16 v[122:125], v[178:181], v[28:31], v[74:77]
	v_mfma_f32_16x16x32_bf16 v[74:77], v[8:11], v[40:43], v[118:121]
	v_mfma_f32_16x16x32_bf16 v[110:113], v[12:15], v[44:47], v[74:77]
	v_mfma_f32_16x16x32_bf16 v[74:77], v[174:177], v[40:43], v[114:117]
	v_mfma_f32_16x16x32_bf16 v[106:109], v[178:181], v[44:47], v[74:77]
	v_mfma_f32_16x16x32_bf16 v[74:77], v[8:11], v[182:185], v[166:169]
	v_mfma_f32_16x16x32_bf16 v[94:97], v[12:15], v[186:189], v[74:77]
	v_mfma_f32_16x16x32_bf16 v[74:77], v[174:177], v[182:185], v[194:197]
	v_mfma_f32_16x16x32_bf16 v[90:93], v[178:181], v[186:189], v[74:77]
	v_mfma_f32_16x16x32_bf16 v[74:77], v[8:11], v[198:201], v[102:105]
	v_mfma_f32_16x16x32_bf16 v[78:81], v[12:15], v[202:205], v[74:77]
	v_mfma_f32_16x16x32_bf16 v[74:77], v[174:177], v[198:201], v[98:101]
	v_mfma_f32_16x16x32_bf16 v[74:77], v[178:181], v[202:205], v[74:77]
	s_barrier
; #define LDA(dst, b, h) _Pragma("unroll") for (int m = 0; m < 4; ++m) _Pragma("unroll") for (int k = 0; k < 2; ++k) \
;     dst[m][k] = *(const bf16x8*)(lds + SA_(b, h) + lds_byte(wr * 64 + m * 16 + fr, k * 32 + fq * 8));
; #define LDB(dst, b, h) _Pragma("unroll") for (int n = 0; n < 2; ++n) _Pragma("unroll") for (int k = 0; k < 2; ++k) \
;     dst[n][k] = *(const bf16x8*)(lds + SB_(b, h) + lds_byte(wc * 32 + n * 16 + fr, k * 32 + fq * 8));
; #define MMA(ai, bj, At_, Bt_) { __builtin_amdgcn_s_setprio(1); \
;     _Pragma("unroll") for (int m = 0; m < 4; ++m) _Pragma("unroll") for (int n = 0; n < 2; ++n) _Pragma("unroll") for (int k = 0; k < 2; ++k) \
;       acc[ai][bj][m][n] = MFMA16(Bt_[n][k], At_[m][k], acc[ai][bj][m][n]); \
;     __builtin_amdgcn_s_setprio(0); }
; #define WAIT_V(n) asm volatile("s_waitcnt vmcnt(" #n ")" ::: "memory");
; #define WAIT_L(n) asm volatile("s_waitcnt lgkmcnt(" #n ")" ::: "memory");
; #define BAR __builtin_amdgcn_s_barrier();
; DI void gemm256(const u16* __restrict__ A, int lda, const u16* __restrict__ B0, const u16* __restrict__ B1, int ldb, int nt, acc_t& acc, char* lds) {
;     ...
;   { LDB(Bq0, 1, 0) LDA(At, 1, 0) WAIT_V(2) BAR WAIT_L(0) MMA(0, 0, At, Bq0) BAR
;     LDB(Bq1, 1, 1) WAIT_V(0) BAR WAIT_L(0) MMA(0, 1, At, Bq1) BAR
;     LDA(At, 1, 1) BAR WAIT_L(0) MMA(1, 0, At, Bq0) MMA(1, 1, At, Bq1) BAR }
;   if (wr == 0) BAR
;   __syncthreads();
	ds_read_b128 v[164:167], v149
	ds_read_b128 v[194:197], v149 offset:1024
	ds_read_b128 v[216:219], v149 offset:2048
	ds_read_b128 v[226:229], v149 offset:3072
	s_waitcnt vmcnt(0)
	s_barrier
	s_waitcnt lgkmcnt(0)
	s_waitcnt lgkmcnt(0)
	v_mfma_f32_16x16x32_bf16 v[98:101], v[164:167], v[24:27], v[206:209]
	v_mfma_f32_16x16x32_bf16 v[24:27], v[216:219], v[24:27], v[156:159]
	v_mfma_f32_16x16x32_bf16 v[114:117], v[226:229], v[28:31], v[24:27]
	v_mfma_f32_16x16x32_bf16 v[24:27], v[164:167], v[40:43], v[86:89]
	v_mfma_f32_16x16x32_bf16 v[102:105], v[194:197], v[44:47], v[24:27]
	v_mfma_f32_16x16x32_bf16 v[24:27], v[216:219], v[40:43], v[82:85]
	v_mfma_f32_16x16x32_bf16 v[118:121], v[194:197], v[28:31], v[98:101]
	v_mfma_f32_16x16x32_bf16 v[98:101], v[226:229], v[44:47], v[24:27]
	v_mfma_f32_16x16x32_bf16 v[24:27], v[164:167], v[182:185], v[160:163]
	v_mfma_f32_16x16x32_bf16 v[86:89], v[194:197], v[186:189], v[24:27]
	v_mfma_f32_16x16x32_bf16 v[24:27], v[216:219], v[182:185], v[170:173]
	v_mfma_f32_16x16x32_bf16 v[82:85], v[226:229], v[186:189], v[24:27]
	v_mfma_f32_16x16x32_bf16 v[24:27], v[164:167], v[198:201], v[70:73]
	v_mfma_f32_16x16x32_bf16 v[70:73], v[194:197], v[202:205], v[24:27]
	v_mfma_f32_16x16x32_bf16 v[24:27], v[216:219], v[198:201], v[66:69]
	v_mfma_f32_16x16x32_bf16 v[66:69], v[226:229], v[202:205], v[24:27]
	s_barrier
	ds_read_b128 v[154:157], v148 offset:49152
	ds_read_b128 v[158:161], v148 offset:50176
	ds_read_b128 v[168:171], v147 offset:49152
	ds_read_b128 v[182:185], v147 offset:50176
	ds_read_b128 v[186:189], v146 offset:49152
	ds_read_b128 v[146:149], v146 offset:50176
	ds_read_b128 v[198:201], v141 offset:49152
	ds_read_b128 v[202:205], v141 offset:50176
	s_barrier
	s_waitcnt lgkmcnt(0)
	s_waitcnt lgkmcnt(0)
	v_mfma_f32_16x16x32_bf16 v[24:27], v[8:11], v[154:157], v[60:63]
	v_mfma_f32_16x16x32_bf16 v[60:63], v[12:15], v[158:161], v[24:27]
	v_mfma_f32_16x16x32_bf16 v[24:27], v[174:177], v[154:157], v[56:59]
	v_mfma_f32_16x16x32_bf16 v[56:59], v[178:181], v[158:161], v[24:27]
	v_mfma_f32_16x16x32_bf16 v[24:27], v[8:11], v[168:171], v[52:55]
	v_mfma_f32_16x16x32_bf16 v[44:47], v[12:15], v[182:185], v[24:27]
	v_mfma_f32_16x16x32_bf16 v[24:27], v[174:177], v[168:171], v[48:51]
	v_mfma_f32_16x16x32_bf16 v[40:43], v[178:181], v[182:185], v[24:27]
	v_mfma_f32_16x16x32_bf16 v[24:27], v[8:11], v[186:189], v[190:193]
	v_mfma_f32_16x16x32_bf16 v[8:11], v[8:11], v[198:201], v[36:39]
	v_mfma_f32_16x16x32_bf16 v[28:31], v[12:15], v[146:149], v[24:27]
	v_mfma_f32_16x16x32_bf16 v[24:27], v[174:177], v[186:189], v[210:213]
	v_mfma_f32_16x16x32_bf16 v[12:15], v[12:15], v[202:205], v[8:11]
	v_mfma_f32_16x16x32_bf16 v[8:11], v[174:177], v[198:201], v[32:35]
	v_mfma_f32_16x16x32_bf16 v[24:27], v[178:181], v[146:149], v[24:27]
	v_mfma_f32_16x16x32_bf16 v[8:11], v[178:181], v[202:205], v[8:11]
	v_mfma_f32_16x16x32_bf16 v[32:35], v[164:167], v[154:157], v[130:133]
	v_mfma_f32_16x16x32_bf16 v[52:55], v[194:197], v[158:161], v[32:35]
	v_mfma_f32_16x16x32_bf16 v[32:35], v[216:219], v[154:157], v[134:137]
	v_mfma_f32_16x16x32_bf16 v[16:19], v[216:219], v[168:171], v[16:19]
	v_mfma_f32_16x16x32_bf16 v[48:51], v[226:229], v[158:161], v[32:35]
	v_mfma_f32_16x16x32_bf16 v[20:23], v[164:167], v[168:171], v[20:23]
	v_mfma_f32_16x16x32_bf16 v[32:35], v[226:229], v[182:185], v[16:19]
	v_mfma_f32_16x16x32_bf16 v[16:19], v[164:167], v[186:189], v[142:145]
	v_mfma_f32_16x16x32_bf16 v[36:39], v[194:197], v[182:185], v[20:23]
	v_mfma_f32_16x16x32_bf16 v[20:23], v[194:197], v[146:149], v[16:19]
	v_mfma_f32_16x16x32_bf16 v[16:19], v[216:219], v[186:189], v[150:153]
	v_mfma_f32_16x16x32_bf16 v[4:7], v[164:167], v[198:201], v[4:7]
	v_mfma_f32_16x16x32_bf16 v[0:3], v[216:219], v[198:201], v[0:3]
	v_mfma_f32_16x16x32_bf16 v[16:19], v[226:229], v[146:149], v[16:19]
	v_mfma_f32_16x16x32_bf16 v[4:7], v[194:197], v[202:205], v[4:7]
	v_mfma_f32_16x16x32_bf16 v[0:3], v[226:229], v[202:205], v[0:3]
	s_movk_i32 s2, 0x100
	v_cmp_gt_u32_e32 vcc, s2, v140
	s_barrier
	s_and_saveexec_b64 s[8:9], vcc
	s_cbranch_execz .LBB0_988
	s_barrier

; #define STAGE_A(b, h, kt) { const u16* ap_ = A + (size_t)((h) * ahalf + (unsigned)(kt) * 64u); glds16(ap_ + ao0, l0 + SA_(b, h)); glds16(ap_ + ao1, l0 + SA_(b, h) + 8192); }
; #define STAGE_B(b, h, kt) { const u16* bp_ = ((h) ? B1 : B0) + (unsigned)(kt) * 64u; glds16(bp_ + bo0, l0 + SB_(b, h)); glds16(bp_ + bo1, l0 + SB_(b, h) + 8192); }
; #define LDA(dst, b, h) _Pragma("unroll") for (int m = 0; m < 4; ++m) _Pragma("unroll") for (int k = 0; k < 2; ++k) \
;     dst[m][k] = *(const bf16x8*)(lds + SA_(b, h) + lds_byte(wr * 64 + m * 16 + fr, k * 32 + fq * 8));
; #define LDB(dst, b, h) _Pragma("unroll") for (int n = 0; n < 2; ++n) _Pragma("unroll") for (int k = 0; k < 2; ++k) \
;     dst[n][k] = *(const bf16x8*)(lds + SB_(b, h) + lds_byte(wc * 32 + n * 16 + fr, k * 32 + fq * 8));
; #define MMA(ai, bj, At_, Bt_) { __builtin_amdgcn_s_setprio(1); \
;     _Pragma("unroll") for (int m = 0; m < 4; ++m) _Pragma("unroll") for (int n = 0; n < 2; ++n) _Pragma("unroll") for (int k = 0; k < 2; ++k) \
;       acc[ai][bj][m][n] = MFMA16(Bt_[n][k], At_[m][k], acc[ai][bj][m][n]); \
;     __builtin_amdgcn_s_setprio(0); }
; #define WAIT_V(n) asm volatile("s_waitcnt vmcnt(" #n ")" ::: "memory");
; #define WAIT_L(n) asm volatile("s_waitcnt lgkmcnt(" #n ")" ::: "memory");
; #define BAR __builtin_amdgcn_s_barrier();
; #define SCHED __builtin_amdgcn_sched_barrier(0);
; DI void gemm256(const u16* __restrict__ A, int lda, const u16* __restrict__ B0, const u16* __restrict__ B1, int ldb, int nt, acc_t& acc, char* lds) {
;     ...
;   for (int t = 0; t < nt - 2; t += 2) {
;     LDB(Bq0, 0, 0) SCHED LDA(At, 0, 0) STAGE_A(1, 1, t + 1)
;     WAIT_L(8) BAR WAIT_L(0) MMA(0, 0, At, Bq0) BAR SCHED
;     LDB(Bq1, 0, 1) STAGE_B(0, 0, t + 2)
;     BAR WAIT_L(0) MMA(0, 1, At, Bq1) BAR
;     LDA(At, 0, 1) STAGE_A(0, 0, t + 2)
;     BAR WAIT_L(0) MMA(1, 0, At, Bq0) BAR SCHED
;     STAGE_B(0, 1, t + 2)
;     WAIT_V(6) BAR MMA(1, 1, At, Bq1) BAR
;     LDB(Bq0, 1, 0) SCHED LDA(At, 1, 0) STAGE_A(0, 1, t + 2)
;     WAIT_L(8) BAR WAIT_L(0) MMA(0, 0, At, Bq0) BAR SCHED
.LBB0_991:
	ds_read_b128 v[142:145], v166
	ds_read_b128 v[170:173], v166 offset:1024
	ds_read_b128 v[174:177], v166 offset:2048
	ds_read_b128 v[178:181], v166 offset:3072
	v_add_u32_e32 v167, 0xc000, v149
	v_lshl_add_u64 v[222:223], s[8:9], 0, v[134:135]
	v_readfirstlane_b32 s3, v167
	v_lshl_add_u64 v[168:169], v[222:223], 0, s[22:23]
	s_mov_b32 m0, s3
	ds_read_b128 v[182:185], v148
	ds_read_b128 v[186:189], v148 offset:1024
	ds_read_b128 v[190:193], v147
	ds_read_b128 v[194:197], v147 offset:1024
	ds_read_b128 v[198:201], v146
	ds_read_b128 v[202:205], v146 offset:1024
	ds_read_b128 v[206:209], v141
	ds_read_b128 v[210:213], v141 offset:1024
	global_load_lds_dwordx4 v[168:169], off
	v_add_u32_e32 v168, 0xe000, v149
	v_lshl_add_u64 v[224:225], s[8:9], 0, v[132:133]
	v_readfirstlane_b32 s3, v168
	v_lshl_add_u64 v[216:217], v[224:225], 0, s[22:23]
	s_mov_b32 m0, s3
	s_nop 0
	global_load_lds_dwordx4 v[216:217], off
	s_waitcnt lgkmcnt(8)
	s_barrier
	s_waitcnt lgkmcnt(0)
	s_waitcnt lgkmcnt(0)
	v_mfma_f32_16x16x32_bf16 v[126:129], v[142:145], v[182:185], v[126:129]
	v_mfma_f32_16x16x32_bf16 v[122:125], v[174:177], v[182:185], v[122:125]
	v_mfma_f32_16x16x32_bf16 v[118:121], v[142:145], v[190:193], v[118:121]
	v_mfma_f32_16x16x32_bf16 v[114:117], v[174:177], v[190:193], v[114:117]
	v_mfma_f32_16x16x32_bf16 v[110:113], v[142:145], v[198:201], v[110:113]
	v_mfma_f32_16x16x32_bf16 v[106:109], v[174:177], v[198:201], v[106:109]
	v_mfma_f32_16x16x32_bf16 v[102:105], v[142:145], v[206:209], v[102:105]
	v_mfma_f32_16x16x32_bf16 v[98:101], v[174:177], v[206:209], v[98:101]
	v_mfma_f32_16x16x32_bf16 v[126:129], v[170:173], v[186:189], v[126:129]
	v_mfma_f32_16x16x32_bf16 v[122:125], v[178:181], v[186:189], v[122:125]
	v_mfma_f32_16x16x32_bf16 v[118:121], v[170:173], v[194:197], v[118:121]
	v_mfma_f32_16x16x32_bf16 v[114:117], v[178:181], v[194:197], v[114:117]
	v_mfma_f32_16x16x32_bf16 v[110:113], v[170:173], v[202:205], v[110:113]
	v_mfma_f32_16x16x32_bf16 v[106:109], v[178:181], v[202:205], v[106:109]
	v_mfma_f32_16x16x32_bf16 v[102:105], v[170:173], v[210:213], v[102:105]
	v_mfma_f32_16x16x32_bf16 v[98:101], v[178:181], v[210:213], v[98:101]
	s_barrier
	v_lshl_add_u64 v[238:239], s[8:9], 0, v[136:137]
	v_readfirstlane_b32 s3, v150
	v_lshl_add_u64 v[240:241], v[238:239], 0, s[28:29]
	s_mov_b32 m0, s3
	ds_read_b128 v[216:219], v165
	ds_read_b128 v[226:229], v165 offset:1024
	ds_read_b128 v[230:233], v165 offset:2048
	ds_read_b128 v[234:237], v165 offset:3072
	global_load_lds_dwordx4 v[240:241], off
	v_lshl_add_u64 v[240:241], s[8:9], 0, v[138:139]
	v_readfirstlane_b32 s3, v152
	v_lshl_add_u64 v[242:243], v[240:241], 0, s[28:29]
	s_mov_b32 m0, s3
	s_nop 0
	global_load_lds_dwordx4 v[242:243], off
	s_barrier
	s_waitcnt lgkmcnt(0)
	s_waitcnt lgkmcnt(0)
	v_mfma_f32_16x16x32_bf16 v[94:97], v[216:219], v[182:185], v[94:97]
	v_mfma_f32_16x16x32_bf16 v[90:93], v[230:233], v[182:185], v[90:93]
	v_mfma_f32_16x16x32_bf16 v[86:89], v[216:219], v[190:193], v[86:89]
	v_mfma_f32_16x16x32_bf16 v[82:85], v[230:233], v[190:193], v[82:85]
	v_mfma_f32_16x16x32_bf16 v[78:81], v[216:219], v[198:201], v[78:81]
	v_mfma_f32_16x16x32_bf16 v[74:77], v[230:233], v[198:201], v[74:77]
	v_mfma_f32_16x16x32_bf16 v[70:73], v[216:219], v[206:209], v[70:73]
	v_mfma_f32_16x16x32_bf16 v[66:69], v[230:233], v[206:209], v[66:69]
	v_mfma_f32_16x16x32_bf16 v[94:97], v[226:229], v[186:189], v[94:97]
	v_mfma_f32_16x16x32_bf16 v[90:93], v[234:237], v[186:189], v[90:93]
	v_mfma_f32_16x16x32_bf16 v[86:89], v[226:229], v[194:197], v[86:89]
	v_mfma_f32_16x16x32_bf16 v[82:85], v[234:237], v[194:197], v[82:85]
	v_mfma_f32_16x16x32_bf16 v[78:81], v[226:229], v[202:205], v[78:81]
	v_mfma_f32_16x16x32_bf16 v[74:77], v[234:237], v[202:205], v[74:77]
	v_mfma_f32_16x16x32_bf16 v[70:73], v[226:229], v[210:213], v[70:73]
	v_mfma_f32_16x16x32_bf16 v[66:69], v[234:237], v[210:213], v[66:69]
	v_readfirstlane_b32 s3, v149
	v_lshl_add_u64 v[242:243], v[222:223], 0, s[42:43]
	s_mov_b32 m0, s3
	v_readfirstlane_b32 s3, v153
	s_barrier
	ds_read_b128 v[182:185], v148 offset:16384
	ds_read_b128 v[186:189], v148 offset:17408
	ds_read_b128 v[190:193], v147 offset:16384
	ds_read_b128 v[194:197], v147 offset:17408
	ds_read_b128 v[198:201], v146 offset:16384
	ds_read_b128 v[202:205], v146 offset:17408
	ds_read_b128 v[206:209], v141 offset:16384
	ds_read_b128 v[210:213], v141 offset:17408
	global_load_lds_dwordx4 v[242:243], off
	v_lshl_add_u64 v[242:243], v[224:225], 0, s[42:43]
	s_mov_b32 m0, s3
	s_nop 0
	global_load_lds_dwordx4 v[242:243], off
	s_barrier
	s_waitcnt lgkmcnt(0)
	s_waitcnt lgkmcnt(0)
	v_mfma_f32_16x16x32_bf16 v[60:63], v[142:145], v[182:185], v[60:63]
	v_mfma_f32_16x16x32_bf16 v[56:59], v[174:177], v[182:185], v[56:59]
	v_mfma_f32_16x16x32_bf16 v[52:55], v[142:145], v[190:193], v[52:55]
	v_mfma_f32_16x16x32_bf16 v[48:51], v[174:177], v[190:193], v[48:51]
	v_mfma_f32_16x16x32_bf16 v[44:47], v[142:145], v[198:201], v[44:47]
	v_mfma_f32_16x16x32_bf16 v[40:43], v[174:177], v[198:201], v[40:43]
	v_mfma_f32_16x16x32_bf16 v[36:39], v[142:145], v[206:209], v[36:39]
	v_mfma_f32_16x16x32_bf16 v[32:35], v[174:177], v[206:209], v[32:35]
	v_mfma_f32_16x16x32_bf16 v[60:63], v[170:173], v[186:189], v[60:63]
	v_mfma_f32_16x16x32_bf16 v[56:59], v[178:181], v[186:189], v[56:59]
	v_mfma_f32_16x16x32_bf16 v[52:55], v[170:173], v[194:197], v[52:55]
	v_mfma_f32_16x16x32_bf16 v[48:51], v[178:181], v[194:197], v[48:51]
	v_mfma_f32_16x16x32_bf16 v[44:47], v[170:173], v[202:205], v[44:47]
	v_mfma_f32_16x16x32_bf16 v[40:43], v[178:181], v[202:205], v[40:43]
	v_mfma_f32_16x16x32_bf16 v[36:39], v[170:173], v[210:213], v[36:39]
	v_mfma_f32_16x16x32_bf16 v[32:35], v[178:181], v[210:213], v[32:35]
	s_barrier
; #define STAGE_A(b, h, kt) { const u16* ap_ = A + (size_t)((h) * ahalf + (unsigned)(kt) * 64u); glds16(ap_ + ao0, l0 + SA_(b, h)); glds16(ap_ + ao1, l0 + SA_(b, h) + 8192); }
; #define STAGE_B(b, h, kt) { const u16* bp_ = ((h) ? B1 : B0) + (unsigned)(kt) * 64u; glds16(bp_ + bo0, l0 + SB_(b, h)); glds16(bp_ + bo1, l0 + SB_(b, h) + 8192); }
; #define LDA(dst, b, h) _Pragma("unroll") for (int m = 0; m < 4; ++m) _Pragma("unroll") for (int k = 0; k < 2; ++k) \
;     dst[m][k] = *(const bf16x8*)(lds + SA_(b, h) + lds_byte(wr * 64 + m * 16 + fr, k * 32 + fq * 8));
; #define LDB(dst, b, h) _Pragma("unroll") for (int n = 0; n < 2; ++n) _Pragma("unroll") for (int k = 0; k < 2; ++k) \
;     dst[n][k] = *(const bf16x8*)(lds + SB_(b, h) + lds_byte(wc * 32 + n * 16 + fr, k * 32 + fq * 8));
; #define MMA(ai, bj, At_, Bt_) { __builtin_amdgcn_s_setprio(1); \
;     _Pragma("unroll") for (int m = 0; m < 4; ++m) _Pragma("unroll") for (int n = 0; n < 2; ++n) _Pragma("unroll") for (int k = 0; k < 2; ++k) \
;       acc[ai][bj][m][n] = MFMA16(Bt_[n][k], At_[m][k], acc[ai][bj][m][n]); \
;     __builtin_amdgcn_s_setprio(0); }
; #define WAIT_V(n) asm volatile("s_waitcnt vmcnt(" #n ")" ::: "memory");
; #define WAIT_L(n) asm volatile("s_waitcnt lgkmcnt(" #n ")" ::: "memory");
; #define BAR __builtin_amdgcn_s_barrier();
; #define SCHED __builtin_amdgcn_sched_barrier(0);
; DI void gemm256(const u16* __restrict__ A, int lda, const u16* __restrict__ B0, const u16* __restrict__ B1, int ldb, int nt, acc_t& acc, char* lds) {
;     ...
;     LDA(At, 0, 1) STAGE_A(0, 0, t + 2)
;     BAR WAIT_L(0) MMA(1, 0, At, Bq0) BAR SCHED
;     STAGE_B(0, 1, t + 2)
;     WAIT_V(6) BAR MMA(1, 1, At, Bq1) BAR
;     LDB(Bq0, 1, 0) SCHED LDA(At, 1, 0) STAGE_A(0, 1, t + 2)
;     WAIT_L(8) BAR WAIT_L(0) MMA(0, 0, At, Bq0) BAR SCHED
;     LDB(Bq1, 1, 1) STAGE_B(1, 0, t + 3)
;     BAR WAIT_L(0) MMA(0, 1, At, Bq1) BAR
;     LDA(At, 1, 1) STAGE_A(1, 0, t + 3)
;     BAR WAIT_L(0) MMA(1, 0, At, Bq0) BAR SCHED
;     STAGE_B(1, 1, t + 3)
	v_readfirstlane_b32 s3, v154
	v_lshl_add_u64 v[142:143], v[238:239], 0, s[46:47]
	s_mov_b32 m0, s3
	v_readfirstlane_b32 s3, v156
	global_load_lds_dwordx4 v[142:143], off
	v_lshl_add_u64 v[142:143], v[240:241], 0, s[46:47]
	s_mov_b32 m0, s3
	s_nop 0
	global_load_lds_dwordx4 v[142:143], off
	s_waitcnt vmcnt(6)
	s_barrier
	v_mfma_f32_16x16x32_bf16 v[28:31], v[216:219], v[182:185], v[28:31]
	v_mfma_f32_16x16x32_bf16 v[24:27], v[230:233], v[182:185], v[24:27]
	v_mfma_f32_16x16x32_bf16 v[20:23], v[216:219], v[190:193], v[20:23]
	v_mfma_f32_16x16x32_bf16 v[16:19], v[230:233], v[190:193], v[16:19]
	v_mfma_f32_16x16x32_bf16 v[12:15], v[216:219], v[198:201], v[12:15]
	v_mfma_f32_16x16x32_bf16 v[8:11], v[230:233], v[198:201], v[8:11]
	v_mfma_f32_16x16x32_bf16 v[4:7], v[216:219], v[206:209], v[4:7]
	v_mfma_f32_16x16x32_bf16 v[0:3], v[230:233], v[206:209], v[0:3]
	v_mfma_f32_16x16x32_bf16 v[28:31], v[226:229], v[186:189], v[28:31]
	v_mfma_f32_16x16x32_bf16 v[24:27], v[234:237], v[186:189], v[24:27]
	v_mfma_f32_16x16x32_bf16 v[20:23], v[226:229], v[194:197], v[20:23]
	v_mfma_f32_16x16x32_bf16 v[16:19], v[234:237], v[194:197], v[16:19]
	v_mfma_f32_16x16x32_bf16 v[12:15], v[226:229], v[202:205], v[12:15]
	v_mfma_f32_16x16x32_bf16 v[8:11], v[234:237], v[202:205], v[8:11]
	v_mfma_f32_16x16x32_bf16 v[4:7], v[226:229], v[210:213], v[4:7]
	v_mfma_f32_16x16x32_bf16 v[0:3], v[234:237], v[210:213], v[0:3]
	s_barrier
	ds_read_b128 v[142:145], v155
	ds_read_b128 v[170:173], v155 offset:1024
	ds_read_b128 v[174:177], v155 offset:2048
	ds_read_b128 v[178:181], v155 offset:3072
	v_readfirstlane_b32 s3, v157
	v_lshl_add_u64 v[216:217], v[222:223], 0, s[48:49]
	s_mov_b32 m0, s3
	v_readfirstlane_b32 s3, v158
	ds_read_b128 v[182:185], v148 offset:32768
	ds_read_b128 v[186:189], v148 offset:33792
	ds_read_b128 v[190:193], v147 offset:32768
	ds_read_b128 v[194:197], v147 offset:33792
	ds_read_b128 v[198:201], v146 offset:32768
	ds_read_b128 v[202:205], v146 offset:33792
	ds_read_b128 v[206:209], v141 offset:32768
	ds_read_b128 v[210:213], v141 offset:33792
	global_load_lds_dwordx4 v[216:217], off
	v_lshl_add_u64 v[216:217], v[224:225], 0, s[48:49]
	s_mov_b32 m0, s3
	s_nop 0
	global_load_lds_dwordx4 v[216:217], off
	s_waitcnt lgkmcnt(8)
	s_barrier
	s_waitcnt lgkmcnt(0)
	s_waitcnt lgkmcnt(0)
	v_mfma_f32_16x16x32_bf16 v[126:129], v[142:145], v[182:185], v[126:129]
	v_mfma_f32_16x16x32_bf16 v[122:125], v[174:177], v[182:185], v[122:125]
	v_mfma_f32_16x16x32_bf16 v[118:121], v[142:145], v[190:193], v[118:121]
	v_mfma_f32_16x16x32_bf16 v[114:117], v[174:177], v[190:193], v[114:117]
	v_mfma_f32_16x16x32_bf16 v[110:113], v[142:145], v[198:201], v[110:113]
	v_mfma_f32_16x16x32_bf16 v[106:109], v[174:177], v[198:201], v[106:109]
	v_mfma_f32_16x16x32_bf16 v[102:105], v[142:145], v[206:209], v[102:105]
	v_mfma_f32_16x16x32_bf16 v[98:101], v[174:177], v[206:209], v[98:101]
	v_mfma_f32_16x16x32_bf16 v[126:129], v[170:173], v[186:189], v[126:129]
	v_mfma_f32_16x16x32_bf16 v[122:125], v[178:181], v[186:189], v[122:125]
	v_mfma_f32_16x16x32_bf16 v[118:121], v[170:173], v[194:197], v[118:121]
	v_mfma_f32_16x16x32_bf16 v[114:117], v[178:181], v[194:197], v[114:117]
	v_mfma_f32_16x16x32_bf16 v[110:113], v[170:173], v[202:205], v[110:113]
	v_mfma_f32_16x16x32_bf16 v[106:109], v[178:181], v[202:205], v[106:109]
	v_mfma_f32_16x16x32_bf16 v[102:105], v[170:173], v[210:213], v[102:105]
	v_mfma_f32_16x16x32_bf16 v[98:101], v[178:181], v[210:213], v[98:101]
	s_barrier
	v_readfirstlane_b32 s3, v159
	v_lshl_add_u64 v[242:243], v[238:239], 0, s[50:51]
	s_mov_b32 m0, s3
	v_readfirstlane_b32 s3, v160
	ds_read_b128 v[216:219], v151
	ds_read_b128 v[226:229], v151 offset:1024
	ds_read_b128 v[230:233], v151 offset:2048
	ds_read_b128 v[234:237], v151 offset:3072
	global_load_lds_dwordx4 v[242:243], off
	v_lshl_add_u64 v[242:243], v[240:241], 0, s[50:51]
	s_mov_b32 m0, s3
	s_nop 0
	global_load_lds_dwordx4 v[242:243], off
	s_barrier
	s_waitcnt lgkmcnt(0)
	s_waitcnt lgkmcnt(0)
	v_mfma_f32_16x16x32_bf16 v[94:97], v[216:219], v[182:185], v[94:97]
	v_mfma_f32_16x16x32_bf16 v[90:93], v[230:233], v[182:185], v[90:93]
	v_mfma_f32_16x16x32_bf16 v[86:89], v[216:219], v[190:193], v[86:89]
	v_mfma_f32_16x16x32_bf16 v[82:85], v[230:233], v[190:193], v[82:85]
	v_mfma_f32_16x16x32_bf16 v[78:81], v[216:219], v[198:201], v[78:81]
	v_mfma_f32_16x16x32_bf16 v[74:77], v[230:233], v[198:201], v[74:77]
	v_mfma_f32_16x16x32_bf16 v[70:73], v[216:219], v[206:209], v[70:73]
	v_mfma_f32_16x16x32_bf16 v[66:69], v[230:233], v[206:209], v[66:69]
	v_mfma_f32_16x16x32_bf16 v[94:97], v[226:229], v[186:189], v[94:97]
	v_mfma_f32_16x16x32_bf16 v[90:93], v[234:237], v[186:189], v[90:93]
	v_mfma_f32_16x16x32_bf16 v[86:89], v[226:229], v[194:197], v[86:89]
	v_mfma_f32_16x16x32_bf16 v[82:85], v[234:237], v[194:197], v[82:85]
	v_mfma_f32_16x16x32_bf16 v[78:81], v[226:229], v[202:205], v[78:81]
	v_mfma_f32_16x16x32_bf16 v[74:77], v[234:237], v[202:205], v[74:77]
	v_mfma_f32_16x16x32_bf16 v[70:73], v[226:229], v[210:213], v[70:73]
	v_mfma_f32_16x16x32_bf16 v[66:69], v[234:237], v[210:213], v[66:69]
	v_readfirstlane_b32 s3, v161
	v_lshl_add_u64 v[222:223], v[222:223], 0, s[52:53]
	s_mov_b32 m0, s3
	v_readfirstlane_b32 s3, v162
	s_barrier
	ds_read_b128 v[182:185], v148 offset:49152
	ds_read_b128 v[186:189], v148 offset:50176
	ds_read_b128 v[190:193], v147 offset:49152
	ds_read_b128 v[194:197], v147 offset:50176
	ds_read_b128 v[198:201], v146 offset:49152
	ds_read_b128 v[202:205], v146 offset:50176
	ds_read_b128 v[206:209], v141 offset:49152
	ds_read_b128 v[210:213], v141 offset:50176
	global_load_lds_dwordx4 v[222:223], off
	v_lshl_add_u64 v[222:223], v[224:225], 0, s[52:53]
	s_mov_b32 m0, s3
	s_nop 0
	global_load_lds_dwordx4 v[222:223], off
	s_barrier
; #define STAGE_A(b, h, kt) { const u16* ap_ = A + (size_t)((h) * ahalf + (unsigned)(kt) * 64u); glds16(ap_ + ao0, l0 + SA_(b, h)); glds16(ap_ + ao1, l0 + SA_(b, h) + 8192); }
; #define STAGE_B(b, h, kt) { const u16* bp_ = ((h) ? B1 : B0) + (unsigned)(kt) * 64u; glds16(bp_ + bo0, l0 + SB_(b, h)); glds16(bp_ + bo1, l0 + SB_(b, h) + 8192); }
; #define LDA(dst, b, h) _Pragma("unroll") for (int m = 0; m < 4; ++m) _Pragma("unroll") for (int k = 0; k < 2; ++k) \
;     dst[m][k] = *(const bf16x8*)(lds + SA_(b, h) + lds_byte(wr * 64 + m * 16 + fr, k * 32 + fq * 8));
; #define LDB(dst, b, h) _Pragma("unroll") for (int n = 0; n < 2; ++n) _Pragma("unroll") for (int k = 0; k < 2; ++k) \
;     dst[n][k] = *(const bf16x8*)(lds + SB_(b, h) + lds_byte(wc * 32 + n * 16 + fr, k * 32 + fq * 8));
; #define MMA(ai, bj, At_, Bt_) { __builtin_amdgcn_s_setprio(1); \
;     _Pragma("unroll") for (int m = 0; m < 4; ++m) _Pragma("unroll") for (int n = 0; n < 2; ++n) _Pragma("unroll") for (int k = 0; k < 2; ++k) \
;       acc[ai][bj][m][n] = MFMA16(Bt_[n][k], At_[m][k], acc[ai][bj][m][n]); \
;     __builtin_amdgcn_s_setprio(0); }
; #define WAIT_V(n) asm volatile("s_waitcnt vmcnt(" #n ")" ::: "memory");
; #define WAIT_L(n) asm volatile("s_waitcnt lgkmcnt(" #n ")" ::: "memory");
; #define BAR __builtin_amdgcn_s_barrier();
; #define SCHED __builtin_amdgcn_sched_barrier(0);
; DI void gemm256(const u16* __restrict__ A, int lda, const u16* __restrict__ B0, const u16* __restrict__ B1, int ldb, int nt, acc_t& acc, char* lds) {
;     ...
;     BAR WAIT_L(0) MMA(1, 0, At, Bq0) BAR SCHED
;     STAGE_B(1, 1, t + 3)
;     WAIT_V(6) BAR MMA(1, 1, At, Bq1) BAR
;   }
;   { LDB(Bq0, 0, 0) LDA(At, 0, 0) STAGE_A(1, 1, nt - 1)
;     BAR WAIT_L(0) MMA(0, 0, At, Bq0) BAR
;     LDB(Bq1, 0, 1) BAR WAIT_L(0) MMA(0, 1, At, Bq1) BAR
;     LDA(At, 0, 1) WAIT_V(4) BAR WAIT_L(0) MMA(1, 0, At, Bq0) MMA(1, 1, At, Bq1) BAR }
	s_waitcnt lgkmcnt(0)
	s_waitcnt lgkmcnt(0)
	v_mfma_f32_16x16x32_bf16 v[60:63], v[142:145], v[182:185], v[60:63]
	v_mfma_f32_16x16x32_bf16 v[56:59], v[174:177], v[182:185], v[56:59]
	v_mfma_f32_16x16x32_bf16 v[52:55], v[142:145], v[190:193], v[52:55]
	v_mfma_f32_16x16x32_bf16 v[48:51], v[174:177], v[190:193], v[48:51]
	v_mfma_f32_16x16x32_bf16 v[44:47], v[142:145], v[198:201], v[44:47]
	v_mfma_f32_16x16x32_bf16 v[40:43], v[174:177], v[198:201], v[40:43]
	v_mfma_f32_16x16x32_bf16 v[36:39], v[142:145], v[206:209], v[36:39]
	v_mfma_f32_16x16x32_bf16 v[32:35], v[174:177], v[206:209], v[32:35]
	v_mfma_f32_16x16x32_bf16 v[60:63], v[170:173], v[186:189], v[60:63]
	v_mfma_f32_16x16x32_bf16 v[56:59], v[178:181], v[186:189], v[56:59]
	v_mfma_f32_16x16x32_bf16 v[52:55], v[170:173], v[194:197], v[52:55]
	v_mfma_f32_16x16x32_bf16 v[48:51], v[178:181], v[194:197], v[48:51]
	v_mfma_f32_16x16x32_bf16 v[44:47], v[170:173], v[202:205], v[44:47]
	v_mfma_f32_16x16x32_bf16 v[40:43], v[178:181], v[202:205], v[40:43]
	v_mfma_f32_16x16x32_bf16 v[36:39], v[170:173], v[210:213], v[36:39]
	v_mfma_f32_16x16x32_bf16 v[32:35], v[178:181], v[210:213], v[32:35]
	s_barrier
	v_readfirstlane_b32 s3, v163
	v_lshl_add_u64 v[142:143], v[238:239], 0, s[54:55]
	s_mov_b32 m0, s3
	v_readfirstlane_b32 s3, v164
	global_load_lds_dwordx4 v[142:143], off
	v_lshl_add_u64 v[142:143], v[240:241], 0, s[54:55]
	s_mov_b32 m0, s3
	s_nop 0
	global_load_lds_dwordx4 v[142:143], off
	s_waitcnt vmcnt(6)
	s_barrier
	v_mfma_f32_16x16x32_bf16 v[28:31], v[216:219], v[182:185], v[28:31]
	v_mfma_f32_16x16x32_bf16 v[24:27], v[230:233], v[182:185], v[24:27]
	v_mfma_f32_16x16x32_bf16 v[20:23], v[216:219], v[190:193], v[20:23]
	v_mfma_f32_16x16x32_bf16 v[16:19], v[230:233], v[190:193], v[16:19]
	v_mfma_f32_16x16x32_bf16 v[12:15], v[216:219], v[198:201], v[12:15]
	v_mfma_f32_16x16x32_bf16 v[8:11], v[230:233], v[198:201], v[8:11]
	v_mfma_f32_16x16x32_bf16 v[4:7], v[216:219], v[206:209], v[4:7]
	v_mfma_f32_16x16x32_bf16 v[0:3], v[230:233], v[206:209], v[0:3]
	v_mfma_f32_16x16x32_bf16 v[28:31], v[226:229], v[186:189], v[28:31]
	v_mfma_f32_16x16x32_bf16 v[24:27], v[234:237], v[186:189], v[24:27]
	v_mfma_f32_16x16x32_bf16 v[20:23], v[226:229], v[194:197], v[20:23]
	v_mfma_f32_16x16x32_bf16 v[16:19], v[234:237], v[194:197], v[16:19]
	v_mfma_f32_16x16x32_bf16 v[12:15], v[226:229], v[202:205], v[12:15]
	v_mfma_f32_16x16x32_bf16 v[8:11], v[234:237], v[202:205], v[8:11]
	v_mfma_f32_16x16x32_bf16 v[4:7], v[226:229], v[210:213], v[4:7]
	v_mfma_f32_16x16x32_bf16 v[0:3], v[234:237], v[210:213], v[0:3]
	s_add_i32 s2, s2, 2
	s_add_u32 s8, s8, 0x100
	s_addc_u32 s9, s9, 0
	s_cmp_lt_u32 s2, 4
	s_barrier
	s_cbranch_scc1 .LBB0_991
	s_add_u32 s2, s44, 0x40780
	s_addc_u32 s3, s45, 0
	v_readfirstlane_b32 s7, v167
	v_lshl_add_u64 v[152:153], v[64:65], 1, s[2:3]
	s_mov_b32 m0, s7
	v_lshl_add_u64 v[130:131], v[130:131], 1, s[2:3]
	v_readfirstlane_b32 s2, v168
	ds_read_b128 v[132:135], v166
	ds_read_b128 v[136:139], v166 offset:1024
	ds_read_b128 v[142:145], v166 offset:2048
	ds_read_b128 v[156:159], v166 offset:3072
	ds_read_b128 v[160:163], v148
	ds_read_b128 v[170:173], v148 offset:1024
	ds_read_b128 v[174:177], v147
	ds_read_b128 v[178:181], v147 offset:1024
	ds_read_b128 v[182:185], v146
	ds_read_b128 v[186:189], v146 offset:1024
	ds_read_b128 v[190:193], v141
	ds_read_b128 v[194:197], v141 offset:1024
	global_load_lds_dwordx4 v[152:153], off
	s_mov_b32 m0, s2
	s_nop 0
	global_load_lds_dwordx4 v[130:131], off
	s_barrier
	s_waitcnt lgkmcnt(0)
	s_waitcnt lgkmcnt(0)
	v_mfma_f32_16x16x32_bf16 v[126:129], v[132:135], v[160:163], v[126:129]
	v_mfma_f32_16x16x32_bf16 v[122:125], v[142:145], v[160:163], v[122:125]
	v_mfma_f32_16x16x32_bf16 v[118:121], v[132:135], v[174:177], v[118:121]
	v_mfma_f32_16x16x32_bf16 v[114:117], v[142:145], v[174:177], v[114:117]
	v_mfma_f32_16x16x32_bf16 v[102:105], v[132:135], v[190:193], v[102:105]
	v_mfma_f32_16x16x32_bf16 v[98:101], v[142:145], v[190:193], v[98:101]
	v_mfma_f32_16x16x32_bf16 v[126:129], v[136:139], v[170:173], v[126:129]
	v_mfma_f32_16x16x32_bf16 v[122:125], v[156:159], v[170:173], v[122:125]
	v_mfma_f32_16x16x32_bf16 v[118:121], v[136:139], v[178:181], v[118:121]
	v_mfma_f32_16x16x32_bf16 v[114:117], v[156:159], v[178:181], v[114:117]
	v_mfma_f32_16x16x32_bf16 v[110:113], v[132:135], v[182:185], v[110:113]
	v_mfma_f32_16x16x32_bf16 v[106:109], v[142:145], v[182:185], v[106:109]
	v_mfma_f32_16x16x32_bf16 v[102:105], v[136:139], v[194:197], v[102:105]
	v_mfma_f32_16x16x32_bf16 v[98:101], v[156:159], v[194:197], v[98:101]
	v_mfma_f32_16x16x32_bf16 v[166:169], v[136:139], v[186:189], v[110:113]
	v_mfma_f32_16x16x32_bf16 v[198:201], v[156:159], v[186:189], v[106:109]
	s_barrier
	s_nop 1
	ds_read_b128 v[106:109], v165
	ds_read_b128 v[110:113], v165 offset:1024
	ds_read_b128 v[202:205], v165 offset:2048
	ds_read_b128 v[206:209], v165 offset:3072
	s_barrier
	s_waitcnt lgkmcnt(0)
	s_waitcnt lgkmcnt(0)
	v_mfma_f32_16x16x32_bf16 v[86:89], v[106:109], v[174:177], v[86:89]
	v_mfma_f32_16x16x32_bf16 v[82:85], v[202:205], v[174:177], v[82:85]
	v_mfma_f32_16x16x32_bf16 v[70:73], v[106:109], v[190:193], v[70:73]
	v_mfma_f32_16x16x32_bf16 v[66:69], v[202:205], v[190:193], v[66:69]
	v_mfma_f32_16x16x32_bf16 v[94:97], v[106:109], v[160:163], v[94:97]
	v_mfma_f32_16x16x32_bf16 v[90:93], v[202:205], v[160:163], v[90:93]
	v_mfma_f32_16x16x32_bf16 v[86:89], v[110:113], v[178:181], v[86:89]
	v_mfma_f32_16x16x32_bf16 v[82:85], v[206:209], v[178:181], v[82:85]
	v_mfma_f32_16x16x32_bf16 v[78:81], v[106:109], v[182:185], v[78:81]
	v_mfma_f32_16x16x32_bf16 v[74:77], v[202:205], v[182:185], v[74:77]
	v_mfma_f32_16x16x32_bf16 v[70:73], v[110:113], v[194:197], v[70:73]
	v_mfma_f32_16x16x32_bf16 v[66:69], v[206:209], v[194:197], v[66:69]
	v_mfma_f32_16x16x32_bf16 v[210:213], v[110:113], v[170:173], v[94:97]
	v_mfma_f32_16x16x32_bf16 v[160:163], v[206:209], v[170:173], v[90:93]
	v_mfma_f32_16x16x32_bf16 v[170:173], v[110:113], v[186:189], v[78:81]
	v_mfma_f32_16x16x32_bf16 v[174:177], v[206:209], v[186:189], v[74:77]
	s_barrier
; #define LDA(dst, b, h) _Pragma("unroll") for (int m = 0; m < 4; ++m) _Pragma("unroll") for (int k = 0; k < 2; ++k) \
;     dst[m][k] = *(const bf16x8*)(lds + SA_(b, h) + lds_byte(wr * 64 + m * 16 + fr, k * 32 + fq * 8));
; #define LDB(dst, b, h) _Pragma("unroll") for (int n = 0; n < 2; ++n) _Pragma("unroll") for (int k = 0; k < 2; ++k) \
;     dst[n][k] = *(const bf16x8*)(lds + SB_(b, h) + lds_byte(wc * 32 + n * 16 + fr, k * 32 + fq * 8));
; #define MMA(ai, bj, At_, Bt_) { __builtin_amdgcn_s_setprio(1); \
;     _Pragma("unroll") for (int m = 0; m < 4; ++m) _Pragma("unroll") for (int n = 0; n < 2; ++n) _Pragma("unroll") for (int k = 0; k < 2; ++k) \
;       acc[ai][bj][m][n] = MFMA16(Bt_[n][k], At_[m][k], acc[ai][bj][m][n]); \
;     __builtin_amdgcn_s_setprio(0); }
; #define WAIT_V(n) asm volatile("s_waitcnt vmcnt(" #n ")" ::: "memory");
; #define WAIT_L(n) asm volatile("s_waitcnt lgkmcnt(" #n ")" ::: "memory");
; #define BAR __builtin_amdgcn_s_barrier();
; DI void gemm256(const u16* __restrict__ A, int lda, const u16* __restrict__ B0, const u16* __restrict__ B1, int ldb, int nt, acc_t& acc, char* lds) {
;     ...
;     BAR WAIT_L(0) MMA(0, 0, At, Bq0) BAR
;     LDB(Bq1, 0, 1) BAR WAIT_L(0) MMA(0, 1, At, Bq1) BAR
;     LDA(At, 0, 1) WAIT_V(4) BAR WAIT_L(0) MMA(1, 0, At, Bq0) MMA(1, 1, At, Bq1) BAR }
;   { LDB(Bq0, 1, 0) LDA(At, 1, 0) WAIT_V(2) BAR WAIT_L(0) MMA(0, 0, At, Bq0) BAR
	s_nop 0
	ds_read_b128 v[74:77], v148 offset:16384
	ds_read_b128 v[78:81], v148 offset:17408
	ds_read_b128 v[90:93], v147 offset:16384
	ds_read_b128 v[94:97], v147 offset:17408
	ds_read_b128 v[178:181], v146 offset:16384
	ds_read_b128 v[182:185], v146 offset:17408
	ds_read_b128 v[186:189], v141 offset:16384
	ds_read_b128 v[190:193], v141 offset:17408
	s_waitcnt vmcnt(4)
	s_barrier
	s_waitcnt lgkmcnt(0)
	s_waitcnt lgkmcnt(0)
	v_mfma_f32_16x16x32_bf16 v[60:63], v[132:135], v[74:77], v[60:63]
	v_mfma_f32_16x16x32_bf16 v[56:59], v[142:145], v[74:77], v[56:59]
	v_mfma_f32_16x16x32_bf16 v[52:55], v[132:135], v[90:93], v[52:55]
	v_mfma_f32_16x16x32_bf16 v[48:51], v[142:145], v[90:93], v[48:51]
	v_mfma_f32_16x16x32_bf16 v[36:39], v[132:135], v[186:189], v[36:39]
	v_mfma_f32_16x16x32_bf16 v[32:35], v[142:145], v[186:189], v[32:35]
	v_mfma_f32_16x16x32_bf16 v[60:63], v[136:139], v[78:81], v[60:63]
	v_mfma_f32_16x16x32_bf16 v[56:59], v[156:159], v[78:81], v[56:59]
	v_mfma_f32_16x16x32_bf16 v[52:55], v[136:139], v[94:97], v[52:55]
	v_mfma_f32_16x16x32_bf16 v[48:51], v[156:159], v[94:97], v[48:51]
	v_mfma_f32_16x16x32_bf16 v[44:47], v[132:135], v[178:181], v[44:47]
	v_mfma_f32_16x16x32_bf16 v[40:43], v[142:145], v[178:181], v[40:43]
	v_mfma_f32_16x16x32_bf16 v[36:39], v[136:139], v[190:193], v[36:39]
	v_mfma_f32_16x16x32_bf16 v[32:35], v[156:159], v[190:193], v[32:35]
	v_mfma_f32_16x16x32_bf16 v[194:197], v[136:139], v[182:185], v[44:47]
	v_mfma_f32_16x16x32_bf16 v[216:219], v[156:159], v[182:185], v[40:43]
	v_mfma_f32_16x16x32_bf16 v[20:23], v[106:109], v[90:93], v[20:23]
	v_mfma_f32_16x16x32_bf16 v[16:19], v[202:205], v[90:93], v[16:19]
	v_mfma_f32_16x16x32_bf16 v[4:7], v[106:109], v[186:189], v[4:7]
	v_mfma_f32_16x16x32_bf16 v[0:3], v[202:205], v[186:189], v[0:3]
	v_mfma_f32_16x16x32_bf16 v[28:31], v[106:109], v[74:77], v[28:31]
	v_mfma_f32_16x16x32_bf16 v[24:27], v[202:205], v[74:77], v[24:27]
	v_mfma_f32_16x16x32_bf16 v[20:23], v[110:113], v[94:97], v[20:23]
	v_mfma_f32_16x16x32_bf16 v[16:19], v[206:209], v[94:97], v[16:19]
	v_mfma_f32_16x16x32_bf16 v[12:15], v[106:109], v[178:181], v[12:15]
	v_mfma_f32_16x16x32_bf16 v[8:11], v[202:205], v[178:181], v[8:11]
	v_mfma_f32_16x16x32_bf16 v[4:7], v[110:113], v[190:193], v[4:7]
	v_mfma_f32_16x16x32_bf16 v[0:3], v[206:209], v[190:193], v[0:3]
	v_mfma_f32_16x16x32_bf16 v[130:133], v[110:113], v[78:81], v[28:31]
	v_mfma_f32_16x16x32_bf16 v[134:137], v[206:209], v[78:81], v[24:27]
	v_mfma_f32_16x16x32_bf16 v[142:145], v[110:113], v[182:185], v[12:15]
	v_mfma_f32_16x16x32_bf16 v[156:159], v[206:209], v[182:185], v[8:11]
	s_barrier
	s_nop 0
	ds_read_b128 v[8:11], v155
	ds_read_b128 v[12:15], v155 offset:1024
	ds_read_b128 v[178:181], v155 offset:2048
	ds_read_b128 v[152:155], v155 offset:3072
	ds_read_b128 v[24:27], v148 offset:32768
	ds_read_b128 v[28:31], v148 offset:33792
	ds_read_b128 v[40:43], v147 offset:32768
	ds_read_b128 v[44:47], v147 offset:33792
	ds_read_b128 v[182:185], v146 offset:32768
	ds_read_b128 v[186:189], v146 offset:33792
	ds_read_b128 v[190:193], v141 offset:32768
	ds_read_b128 v[202:205], v141 offset:33792
	s_waitcnt vmcnt(2)
	s_barrier
	s_waitcnt lgkmcnt(0)
	s_waitcnt lgkmcnt(0)
	v_mfma_f32_16x16x32_bf16 v[74:77], v[8:11], v[24:27], v[126:129]
	v_mfma_f32_16x16x32_bf16 v[126:129], v[12:15], v[28:31], v[74:77]
	v_mfma_f32_16x16x32_bf16 v[74:77], v[178:181], v[24:27], v[122:125]
	v_mfma_f32_16x16x32_bf16 v[122:125], v[152:155], v[28:31], v[74:77]
	v_mfma_f32_16x16x32_bf16 v[74:77], v[8:11], v[40:43], v[118:121]
	v_mfma_f32_16x16x32_bf16 v[110:113], v[12:15], v[44:47], v[74:77]
	v_mfma_f32_16x16x32_bf16 v[74:77], v[178:181], v[40:43], v[114:117]
	v_mfma_f32_16x16x32_bf16 v[106:109], v[152:155], v[44:47], v[74:77]
	v_mfma_f32_16x16x32_bf16 v[74:77], v[8:11], v[182:185], v[166:169]
	v_mfma_f32_16x16x32_bf16 v[94:97], v[12:15], v[186:189], v[74:77]
	v_mfma_f32_16x16x32_bf16 v[74:77], v[178:181], v[182:185], v[198:201]
	v_mfma_f32_16x16x32_bf16 v[90:93], v[152:155], v[186:189], v[74:77]
	v_mfma_f32_16x16x32_bf16 v[74:77], v[8:11], v[190:193], v[102:105]
	v_mfma_f32_16x16x32_bf16 v[78:81], v[12:15], v[202:205], v[74:77]
	v_mfma_f32_16x16x32_bf16 v[74:77], v[178:181], v[190:193], v[98:101]
	v_mfma_f32_16x16x32_bf16 v[74:77], v[152:155], v[202:205], v[74:77]
	s_barrier
; #define LDA(dst, b, h) _Pragma("unroll") for (int m = 0; m < 4; ++m) _Pragma("unroll") for (int k = 0; k < 2; ++k) \
;     dst[m][k] = *(const bf16x8*)(lds + SA_(b, h) + lds_byte(wr * 64 + m * 16 + fr, k * 32 + fq * 8));
; #define LDB(dst, b, h) _Pragma("unroll") for (int n = 0; n < 2; ++n) _Pragma("unroll") for (int k = 0; k < 2; ++k) \
;     dst[n][k] = *(const bf16x8*)(lds + SB_(b, h) + lds_byte(wc * 32 + n * 16 + fr, k * 32 + fq * 8));
; #define MMA(ai, bj, At_, Bt_) { __builtin_amdgcn_s_setprio(1); \
;     _Pragma("unroll") for (int m = 0; m < 4; ++m) _Pragma("unroll") for (int n = 0; n < 2; ++n) _Pragma("unroll") for (int k = 0; k < 2; ++k) \
;       acc[ai][bj][m][n] = MFMA16(Bt_[n][k], At_[m][k], acc[ai][bj][m][n]); \
;     __builtin_amdgcn_s_setprio(0); }
; #define WAIT_V(n) asm volatile("s_waitcnt vmcnt(" #n ")" ::: "memory");
; #define WAIT_L(n) asm volatile("s_waitcnt lgkmcnt(" #n ")" ::: "memory");
; #define BAR __builtin_amdgcn_s_barrier();
; DI void gemm256(const u16* __restrict__ A, int lda, const u16* __restrict__ B0, const u16* __restrict__ B1, int ldb, int nt, acc_t& acc, char* lds) {
;     ...
;   { LDB(Bq0, 1, 0) LDA(At, 1, 0) WAIT_V(2) BAR WAIT_L(0) MMA(0, 0, At, Bq0) BAR
;     LDB(Bq1, 1, 1) WAIT_V(0) BAR WAIT_L(0) MMA(0, 1, At, Bq1) BAR
;     LDA(At, 1, 1) BAR WAIT_L(0) MMA(1, 0, At, Bq0) MMA(1, 1, At, Bq1) BAR }
;   if (wr == 0) BAR
;   __syncthreads();
	ds_read_b128 v[164:167], v151
	ds_read_b128 v[198:201], v151 offset:1024
	ds_read_b128 v[206:209], v151 offset:2048
	ds_read_b128 v[226:229], v151 offset:3072
	s_waitcnt vmcnt(0)
	s_barrier
	s_waitcnt lgkmcnt(0)
	s_waitcnt lgkmcnt(0)
	v_mfma_f32_16x16x32_bf16 v[98:101], v[164:167], v[24:27], v[210:213]
	v_mfma_f32_16x16x32_bf16 v[24:27], v[206:209], v[24:27], v[160:163]
	v_mfma_f32_16x16x32_bf16 v[114:117], v[226:229], v[28:31], v[24:27]
	v_mfma_f32_16x16x32_bf16 v[24:27], v[164:167], v[40:43], v[86:89]
	v_mfma_f32_16x16x32_bf16 v[102:105], v[198:201], v[44:47], v[24:27]
	v_mfma_f32_16x16x32_bf16 v[24:27], v[206:209], v[40:43], v[82:85]
	v_mfma_f32_16x16x32_bf16 v[118:121], v[198:201], v[28:31], v[98:101]
	v_mfma_f32_16x16x32_bf16 v[98:101], v[226:229], v[44:47], v[24:27]
	v_mfma_f32_16x16x32_bf16 v[24:27], v[164:167], v[182:185], v[170:173]
	v_mfma_f32_16x16x32_bf16 v[86:89], v[198:201], v[186:189], v[24:27]
	v_mfma_f32_16x16x32_bf16 v[24:27], v[206:209], v[182:185], v[174:177]
	v_mfma_f32_16x16x32_bf16 v[82:85], v[226:229], v[186:189], v[24:27]
	v_mfma_f32_16x16x32_bf16 v[24:27], v[164:167], v[190:193], v[70:73]
	v_mfma_f32_16x16x32_bf16 v[70:73], v[198:201], v[202:205], v[24:27]
	v_mfma_f32_16x16x32_bf16 v[24:27], v[206:209], v[190:193], v[66:69]
	v_mfma_f32_16x16x32_bf16 v[66:69], v[226:229], v[202:205], v[24:27]
	s_barrier
	ds_read_b128 v[160:163], v148 offset:49152
	ds_read_b128 v[148:151], v148 offset:50176
	ds_read_b128 v[168:171], v147 offset:49152
	ds_read_b128 v[172:175], v147 offset:50176
	ds_read_b128 v[182:185], v146 offset:49152
	ds_read_b128 v[186:189], v146 offset:50176
	ds_read_b128 v[190:193], v141 offset:49152
	ds_read_b128 v[202:205], v141 offset:50176
	s_barrier
	s_waitcnt lgkmcnt(0)
	s_waitcnt lgkmcnt(0)
	v_mfma_f32_16x16x32_bf16 v[24:27], v[8:11], v[160:163], v[60:63]
	v_mfma_f32_16x16x32_bf16 v[60:63], v[12:15], v[148:151], v[24:27]
	v_mfma_f32_16x16x32_bf16 v[24:27], v[178:181], v[160:163], v[56:59]
	v_mfma_f32_16x16x32_bf16 v[56:59], v[152:155], v[148:151], v[24:27]
	v_mfma_f32_16x16x32_bf16 v[24:27], v[8:11], v[168:171], v[52:55]
	v_mfma_f32_16x16x32_bf16 v[44:47], v[12:15], v[172:175], v[24:27]
	v_mfma_f32_16x16x32_bf16 v[24:27], v[178:181], v[168:171], v[48:51]
	v_mfma_f32_16x16x32_bf16 v[40:43], v[152:155], v[172:175], v[24:27]
	v_mfma_f32_16x16x32_bf16 v[24:27], v[8:11], v[182:185], v[194:197]
	v_mfma_f32_16x16x32_bf16 v[8:11], v[8:11], v[190:193], v[36:39]
	v_mfma_f32_16x16x32_bf16 v[28:31], v[12:15], v[186:189], v[24:27]
	v_mfma_f32_16x16x32_bf16 v[24:27], v[178:181], v[182:185], v[216:219]
	v_mfma_f32_16x16x32_bf16 v[12:15], v[12:15], v[202:205], v[8:11]
	v_mfma_f32_16x16x32_bf16 v[8:11], v[178:181], v[190:193], v[32:35]
	v_mfma_f32_16x16x32_bf16 v[24:27], v[152:155], v[186:189], v[24:27]
	v_mfma_f32_16x16x32_bf16 v[8:11], v[152:155], v[202:205], v[8:11]
	v_mfma_f32_16x16x32_bf16 v[32:35], v[164:167], v[160:163], v[130:133]
	v_mfma_f32_16x16x32_bf16 v[52:55], v[198:201], v[148:151], v[32:35]
	v_mfma_f32_16x16x32_bf16 v[32:35], v[206:209], v[160:163], v[134:137]
	v_mfma_f32_16x16x32_bf16 v[16:19], v[206:209], v[168:171], v[16:19]
	v_mfma_f32_16x16x32_bf16 v[48:51], v[226:229], v[148:151], v[32:35]
	v_mfma_f32_16x16x32_bf16 v[20:23], v[164:167], v[168:171], v[20:23]
	v_mfma_f32_16x16x32_bf16 v[32:35], v[226:229], v[172:175], v[16:19]
	v_mfma_f32_16x16x32_bf16 v[16:19], v[164:167], v[182:185], v[142:145]
	v_mfma_f32_16x16x32_bf16 v[36:39], v[198:201], v[172:175], v[20:23]
	v_mfma_f32_16x16x32_bf16 v[20:23], v[198:201], v[186:189], v[16:19]
	v_mfma_f32_16x16x32_bf16 v[16:19], v[206:209], v[182:185], v[156:159]
	v_mfma_f32_16x16x32_bf16 v[4:7], v[164:167], v[190:193], v[4:7]
	v_mfma_f32_16x16x32_bf16 v[0:3], v[206:209], v[190:193], v[0:3]
	v_mfma_f32_16x16x32_bf16 v[16:19], v[226:229], v[186:189], v[16:19]
	v_mfma_f32_16x16x32_bf16 v[4:7], v[198:201], v[202:205], v[4:7]
	v_mfma_f32_16x16x32_bf16 v[0:3], v[226:229], v[202:205], v[0:3]
	s_movk_i32 s2, 0x100
	v_cmp_gt_u32_e32 vcc, s2, v140
	s_barrier
	s_and_saveexec_b64 s[8:9], vcc
	s_cbranch_execz .LBB0_969
	s_barrier
	s_branch .LBB0_969

; #define STAGE_A(b, h, kt) { const u16* ap_ = A + (size_t)((h) * ahalf + (unsigned)(kt) * 64u); glds16(ap_ + ao0, l0 + SA_(b, h)); glds16(ap_ + ao1, l0 + SA_(b, h) + 8192); }
; #define STAGE_B(b, h, kt) { const u16* bp_ = ((h) ? B1 : B0) + (unsigned)(kt) * 64u; glds16(bp_ + bo0, l0 + SB_(b, h)); glds16(bp_ + bo1, l0 + SB_(b, h) + 8192); }
; #define LDA(dst, b, h) _Pragma("unroll") for (int m = 0; m < 4; ++m) _Pragma("unroll") for (int k = 0; k < 2; ++k) \
;     dst[m][k] = *(const bf16x8*)(lds + SA_(b, h) + lds_byte(wr * 64 + m * 16 + fr, k * 32 + fq * 8));
; #define LDB(dst, b, h) _Pragma("unroll") for (int n = 0; n < 2; ++n) _Pragma("unroll") for (int k = 0; k < 2; ++k) \
;     dst[n][k] = *(const bf16x8*)(lds + SB_(b, h) + lds_byte(wc * 32 + n * 16 + fr, k * 32 + fq * 8));
; #define MMA(ai, bj, At_, Bt_) { __builtin_amdgcn_s_setprio(1); \
;     _Pragma("unroll") for (int m = 0; m < 4; ++m) _Pragma("unroll") for (int n = 0; n < 2; ++n) _Pragma("unroll") for (int k = 0; k < 2; ++k) \
;       acc[ai][bj][m][n] = MFMA16(Bt_[n][k], At_[m][k], acc[ai][bj][m][n]); \
;     __builtin_amdgcn_s_setprio(0); }
; #define WAIT_V(n) asm volatile("s_waitcnt vmcnt(" #n ")" ::: "memory");
; #define WAIT_L(n) asm volatile("s_waitcnt lgkmcnt(" #n ")" ::: "memory");
; #define BAR __builtin_amdgcn_s_barrier();
; #define SCHED __builtin_amdgcn_sched_barrier(0);
; DI void gemm256(const u16* __restrict__ A, int lda, const u16* __restrict__ B0, const u16* __restrict__ B1, int ldb, int nt, acc_t& acc, char* lds) {
;     ...
;   for (int t = 0; t < nt - 2; t += 2) {
;     LDB(Bq0, 0, 0) SCHED LDA(At, 0, 0) STAGE_A(1, 1, t + 1)
;     WAIT_L(8) BAR WAIT_L(0) MMA(0, 0, At, Bq0) BAR SCHED
;     LDB(Bq1, 0, 1) STAGE_B(0, 0, t + 2)
;     BAR WAIT_L(0) MMA(0, 1, At, Bq1) BAR
;     LDA(At, 0, 1) STAGE_A(0, 0, t + 2)
;     BAR WAIT_L(0) MMA(1, 0, At, Bq0) BAR SCHED
;     STAGE_B(0, 1, t + 2)
;     WAIT_V(6) BAR MMA(1, 1, At, Bq1) BAR
;     LDB(Bq0, 1, 0) SCHED LDA(At, 1, 0) STAGE_A(0, 1, t + 2)
;     WAIT_L(8) BAR WAIT_L(0) MMA(0, 0, At, Bq0) BAR SCHED
.LBB0_1053:
	ds_read_b128 v[142:145], v166
	ds_read_b128 v[170:173], v166 offset:1024
	ds_read_b128 v[174:177], v166 offset:2048
	ds_read_b128 v[178:181], v166 offset:3072
	v_add_u32_e32 v167, 0xc000, v149
	v_lshl_add_u64 v[222:223], s[36:37], 0, v[136:137]
	v_readfirstlane_b32 s7, v167
	v_lshl_add_u64 v[168:169], v[222:223], 0, s[38:39]
	s_mov_b32 m0, s7
	ds_read_b128 v[182:185], v148
	ds_read_b128 v[186:189], v148 offset:1024
	ds_read_b128 v[190:193], v147
	ds_read_b128 v[194:197], v147 offset:1024
	ds_read_b128 v[198:201], v146
	ds_read_b128 v[202:205], v146 offset:1024
	ds_read_b128 v[206:209], v141
	ds_read_b128 v[210:213], v141 offset:1024
	global_load_lds_dwordx4 v[168:169], off
	v_add_u32_e32 v168, 0xe000, v149
	v_lshl_add_u64 v[224:225], s[36:37], 0, v[138:139]
	v_readfirstlane_b32 s7, v168
	v_lshl_add_u64 v[216:217], v[224:225], 0, s[38:39]
	s_mov_b32 m0, s7
	s_nop 0
	global_load_lds_dwordx4 v[216:217], off
	s_waitcnt lgkmcnt(8)
	s_barrier
	s_waitcnt lgkmcnt(0)
	s_waitcnt lgkmcnt(0)
	v_mfma_f32_16x16x32_bf16 v[126:129], v[142:145], v[182:185], v[126:129]
	v_mfma_f32_16x16x32_bf16 v[122:125], v[174:177], v[182:185], v[122:125]
	v_mfma_f32_16x16x32_bf16 v[118:121], v[142:145], v[190:193], v[118:121]
	v_mfma_f32_16x16x32_bf16 v[114:117], v[174:177], v[190:193], v[114:117]
	v_mfma_f32_16x16x32_bf16 v[110:113], v[142:145], v[198:201], v[110:113]
	v_mfma_f32_16x16x32_bf16 v[106:109], v[174:177], v[198:201], v[106:109]
	v_mfma_f32_16x16x32_bf16 v[102:105], v[142:145], v[206:209], v[102:105]
	v_mfma_f32_16x16x32_bf16 v[98:101], v[174:177], v[206:209], v[98:101]
	v_mfma_f32_16x16x32_bf16 v[126:129], v[170:173], v[186:189], v[126:129]
	v_mfma_f32_16x16x32_bf16 v[122:125], v[178:181], v[186:189], v[122:125]
	v_mfma_f32_16x16x32_bf16 v[118:121], v[170:173], v[194:197], v[118:121]
	v_mfma_f32_16x16x32_bf16 v[114:117], v[178:181], v[194:197], v[114:117]
	v_mfma_f32_16x16x32_bf16 v[110:113], v[170:173], v[202:205], v[110:113]
	v_mfma_f32_16x16x32_bf16 v[106:109], v[178:181], v[202:205], v[106:109]
	v_mfma_f32_16x16x32_bf16 v[102:105], v[170:173], v[210:213], v[102:105]
	v_mfma_f32_16x16x32_bf16 v[98:101], v[178:181], v[210:213], v[98:101]
	s_barrier
	v_lshl_add_u64 v[238:239], s[36:37], 0, v[132:133]
	v_readfirstlane_b32 s7, v150
	v_lshl_add_u64 v[240:241], v[238:239], 0, s[40:41]
	s_mov_b32 m0, s7
	ds_read_b128 v[216:219], v165
	ds_read_b128 v[226:229], v165 offset:1024
	ds_read_b128 v[230:233], v165 offset:2048
	ds_read_b128 v[234:237], v165 offset:3072
	global_load_lds_dwordx4 v[240:241], off
	v_lshl_add_u64 v[240:241], s[36:37], 0, v[134:135]
	v_readfirstlane_b32 s7, v152
	v_lshl_add_u64 v[242:243], v[240:241], 0, s[40:41]
	s_mov_b32 m0, s7
	s_nop 0
	global_load_lds_dwordx4 v[242:243], off
	s_barrier
	s_waitcnt lgkmcnt(0)
	s_waitcnt lgkmcnt(0)
	v_mfma_f32_16x16x32_bf16 v[94:97], v[216:219], v[182:185], v[94:97]
	v_mfma_f32_16x16x32_bf16 v[90:93], v[230:233], v[182:185], v[90:93]
	v_mfma_f32_16x16x32_bf16 v[86:89], v[216:219], v[190:193], v[86:89]
	v_mfma_f32_16x16x32_bf16 v[82:85], v[230:233], v[190:193], v[82:85]
	v_mfma_f32_16x16x32_bf16 v[78:81], v[216:219], v[198:201], v[78:81]
	v_mfma_f32_16x16x32_bf16 v[74:77], v[230:233], v[198:201], v[74:77]
	v_mfma_f32_16x16x32_bf16 v[70:73], v[216:219], v[206:209], v[70:73]
	v_mfma_f32_16x16x32_bf16 v[66:69], v[230:233], v[206:209], v[66:69]
	v_mfma_f32_16x16x32_bf16 v[94:97], v[226:229], v[186:189], v[94:97]
	v_mfma_f32_16x16x32_bf16 v[90:93], v[234:237], v[186:189], v[90:93]
	v_mfma_f32_16x16x32_bf16 v[86:89], v[226:229], v[194:197], v[86:89]
	v_mfma_f32_16x16x32_bf16 v[82:85], v[234:237], v[194:197], v[82:85]
	v_mfma_f32_16x16x32_bf16 v[78:81], v[226:229], v[202:205], v[78:81]
	v_mfma_f32_16x16x32_bf16 v[74:77], v[234:237], v[202:205], v[74:77]
	v_mfma_f32_16x16x32_bf16 v[70:73], v[226:229], v[210:213], v[70:73]
	v_mfma_f32_16x16x32_bf16 v[66:69], v[234:237], v[210:213], v[66:69]
	v_readfirstlane_b32 s7, v149
	v_lshl_add_u64 v[242:243], v[222:223], 0, s[70:71]
	s_mov_b32 m0, s7
	v_readfirstlane_b32 s7, v153
	s_barrier
	ds_read_b128 v[182:185], v148 offset:16384
	ds_read_b128 v[186:189], v148 offset:17408
	ds_read_b128 v[190:193], v147 offset:16384
	ds_read_b128 v[194:197], v147 offset:17408
	ds_read_b128 v[198:201], v146 offset:16384
	ds_read_b128 v[202:205], v146 offset:17408
	ds_read_b128 v[206:209], v141 offset:16384
	ds_read_b128 v[210:213], v141 offset:17408
	global_load_lds_dwordx4 v[242:243], off
	v_lshl_add_u64 v[242:243], v[224:225], 0, s[70:71]
	s_mov_b32 m0, s7
	s_nop 0
	global_load_lds_dwordx4 v[242:243], off
	s_barrier
	s_waitcnt lgkmcnt(0)
	s_waitcnt lgkmcnt(0)
	v_mfma_f32_16x16x32_bf16 v[60:63], v[142:145], v[182:185], v[60:63]
	v_mfma_f32_16x16x32_bf16 v[56:59], v[174:177], v[182:185], v[56:59]
	v_mfma_f32_16x16x32_bf16 v[52:55], v[142:145], v[190:193], v[52:55]
	v_mfma_f32_16x16x32_bf16 v[48:51], v[174:177], v[190:193], v[48:51]
	v_mfma_f32_16x16x32_bf16 v[44:47], v[142:145], v[198:201], v[44:47]
	v_mfma_f32_16x16x32_bf16 v[40:43], v[174:177], v[198:201], v[40:43]
	v_mfma_f32_16x16x32_bf16 v[36:39], v[142:145], v[206:209], v[36:39]
	v_mfma_f32_16x16x32_bf16 v[32:35], v[174:177], v[206:209], v[32:35]
	v_mfma_f32_16x16x32_bf16 v[60:63], v[170:173], v[186:189], v[60:63]
	v_mfma_f32_16x16x32_bf16 v[56:59], v[178:181], v[186:189], v[56:59]
	v_mfma_f32_16x16x32_bf16 v[52:55], v[170:173], v[194:197], v[52:55]
	v_mfma_f32_16x16x32_bf16 v[48:51], v[178:181], v[194:197], v[48:51]
	v_mfma_f32_16x16x32_bf16 v[44:47], v[170:173], v[202:205], v[44:47]
	v_mfma_f32_16x16x32_bf16 v[40:43], v[178:181], v[202:205], v[40:43]
	v_mfma_f32_16x16x32_bf16 v[36:39], v[170:173], v[210:213], v[36:39]
	v_mfma_f32_16x16x32_bf16 v[32:35], v[178:181], v[210:213], v[32:35]
	s_barrier
; #define STAGE_A(b, h, kt) { const u16* ap_ = A + (size_t)((h) * ahalf + (unsigned)(kt) * 64u); glds16(ap_ + ao0, l0 + SA_(b, h)); glds16(ap_ + ao1, l0 + SA_(b, h) + 8192); }
; #define STAGE_B(b, h, kt) { const u16* bp_ = ((h) ? B1 : B0) + (unsigned)(kt) * 64u; glds16(bp_ + bo0, l0 + SB_(b, h)); glds16(bp_ + bo1, l0 + SB_(b, h) + 8192); }
; #define LDA(dst, b, h) _Pragma("unroll") for (int m = 0; m < 4; ++m) _Pragma("unroll") for (int k = 0; k < 2; ++k) \
;     dst[m][k] = *(const bf16x8*)(lds + SA_(b, h) + lds_byte(wr * 64 + m * 16 + fr, k * 32 + fq * 8));
; #define LDB(dst, b, h) _Pragma("unroll") for (int n = 0; n < 2; ++n) _Pragma("unroll") for (int k = 0; k < 2; ++k) \
;     dst[n][k] = *(const bf16x8*)(lds + SB_(b, h) + lds_byte(wc * 32 + n * 16 + fr, k * 32 + fq * 8));
; #define MMA(ai, bj, At_, Bt_) { __builtin_amdgcn_s_setprio(1); \
;     _Pragma("unroll") for (int m = 0; m < 4; ++m) _Pragma("unroll") for (int n = 0; n < 2; ++n) _Pragma("unroll") for (int k = 0; k < 2; ++k) \
;       acc[ai][bj][m][n] = MFMA16(Bt_[n][k], At_[m][k], acc[ai][bj][m][n]); \
;     __builtin_amdgcn_s_setprio(0); }
; #define WAIT_V(n) asm volatile("s_waitcnt vmcnt(" #n ")" ::: "memory");
; #define WAIT_L(n) asm volatile("s_waitcnt lgkmcnt(" #n ")" ::: "memory");
; #define BAR __builtin_amdgcn_s_barrier();
; #define SCHED __builtin_amdgcn_sched_barrier(0);
; DI void gemm256(const u16* __restrict__ A, int lda, const u16* __restrict__ B0, const u16* __restrict__ B1, int ldb, int nt, acc_t& acc, char* lds) {
;     ...
;     LDA(At, 0, 1) STAGE_A(0, 0, t + 2)
;     BAR WAIT_L(0) MMA(1, 0, At, Bq0) BAR SCHED
;     STAGE_B(0, 1, t + 2)
;     WAIT_V(6) BAR MMA(1, 1, At, Bq1) BAR
;     LDB(Bq0, 1, 0) SCHED LDA(At, 1, 0) STAGE_A(0, 1, t + 2)
;     WAIT_L(8) BAR WAIT_L(0) MMA(0, 0, At, Bq0) BAR SCHED
;     LDB(Bq1, 1, 1) STAGE_B(1, 0, t + 3)
;     BAR WAIT_L(0) MMA(0, 1, At, Bq1) BAR
;     LDA(At, 1, 1) STAGE_A(1, 0, t + 3)
;     BAR WAIT_L(0) MMA(1, 0, At, Bq0) BAR SCHED
;     STAGE_B(1, 1, t + 3)
	v_readfirstlane_b32 s7, v154
	v_lshl_add_u64 v[142:143], v[238:239], 0, s[42:43]
	s_mov_b32 m0, s7
	v_readfirstlane_b32 s7, v155
	global_load_lds_dwordx4 v[142:143], off
	v_lshl_add_u64 v[142:143], v[240:241], 0, s[42:43]
	s_mov_b32 m0, s7
	s_nop 0
	global_load_lds_dwordx4 v[142:143], off
	s_waitcnt vmcnt(6)
	s_barrier
	v_mfma_f32_16x16x32_bf16 v[28:31], v[216:219], v[182:185], v[28:31]
	v_mfma_f32_16x16x32_bf16 v[24:27], v[230:233], v[182:185], v[24:27]
	v_mfma_f32_16x16x32_bf16 v[20:23], v[216:219], v[190:193], v[20:23]
	v_mfma_f32_16x16x32_bf16 v[16:19], v[230:233], v[190:193], v[16:19]
	v_mfma_f32_16x16x32_bf16 v[12:15], v[216:219], v[198:201], v[12:15]
	v_mfma_f32_16x16x32_bf16 v[8:11], v[230:233], v[198:201], v[8:11]
	v_mfma_f32_16x16x32_bf16 v[4:7], v[216:219], v[206:209], v[4:7]
	v_mfma_f32_16x16x32_bf16 v[0:3], v[230:233], v[206:209], v[0:3]
	v_mfma_f32_16x16x32_bf16 v[28:31], v[226:229], v[186:189], v[28:31]
	v_mfma_f32_16x16x32_bf16 v[24:27], v[234:237], v[186:189], v[24:27]
	v_mfma_f32_16x16x32_bf16 v[20:23], v[226:229], v[194:197], v[20:23]
	v_mfma_f32_16x16x32_bf16 v[16:19], v[234:237], v[194:197], v[16:19]
	v_mfma_f32_16x16x32_bf16 v[12:15], v[226:229], v[202:205], v[12:15]
	v_mfma_f32_16x16x32_bf16 v[8:11], v[234:237], v[202:205], v[8:11]
	v_mfma_f32_16x16x32_bf16 v[4:7], v[226:229], v[210:213], v[4:7]
	v_mfma_f32_16x16x32_bf16 v[0:3], v[234:237], v[210:213], v[0:3]
	s_barrier
	ds_read_b128 v[142:145], v156
	ds_read_b128 v[170:173], v156 offset:1024
	ds_read_b128 v[174:177], v156 offset:2048
	ds_read_b128 v[178:181], v156 offset:3072
	v_readfirstlane_b32 s7, v157
	v_lshl_add_u64 v[216:217], v[222:223], 0, s[44:45]
	s_mov_b32 m0, s7
	v_readfirstlane_b32 s7, v158
	ds_read_b128 v[182:185], v148 offset:32768
	ds_read_b128 v[186:189], v148 offset:33792
	ds_read_b128 v[190:193], v147 offset:32768
	ds_read_b128 v[194:197], v147 offset:33792
	ds_read_b128 v[198:201], v146 offset:32768
	ds_read_b128 v[202:205], v146 offset:33792
	ds_read_b128 v[206:209], v141 offset:32768
	ds_read_b128 v[210:213], v141 offset:33792
	global_load_lds_dwordx4 v[216:217], off
	v_lshl_add_u64 v[216:217], v[224:225], 0, s[44:45]
	s_mov_b32 m0, s7
	s_nop 0
	global_load_lds_dwordx4 v[216:217], off
	s_waitcnt lgkmcnt(8)
	s_barrier
	s_waitcnt lgkmcnt(0)
	s_waitcnt lgkmcnt(0)
	v_mfma_f32_16x16x32_bf16 v[126:129], v[142:145], v[182:185], v[126:129]
	v_mfma_f32_16x16x32_bf16 v[122:125], v[174:177], v[182:185], v[122:125]
	v_mfma_f32_16x16x32_bf16 v[118:121], v[142:145], v[190:193], v[118:121]
	v_mfma_f32_16x16x32_bf16 v[114:117], v[174:177], v[190:193], v[114:117]
	v_mfma_f32_16x16x32_bf16 v[110:113], v[142:145], v[198:201], v[110:113]
	v_mfma_f32_16x16x32_bf16 v[106:109], v[174:177], v[198:201], v[106:109]
	v_mfma_f32_16x16x32_bf16 v[102:105], v[142:145], v[206:209], v[102:105]
	v_mfma_f32_16x16x32_bf16 v[98:101], v[174:177], v[206:209], v[98:101]
	v_mfma_f32_16x16x32_bf16 v[126:129], v[170:173], v[186:189], v[126:129]
	v_mfma_f32_16x16x32_bf16 v[122:125], v[178:181], v[186:189], v[122:125]
	v_mfma_f32_16x16x32_bf16 v[118:121], v[170:173], v[194:197], v[118:121]
	v_mfma_f32_16x16x32_bf16 v[114:117], v[178:181], v[194:197], v[114:117]
	v_mfma_f32_16x16x32_bf16 v[110:113], v[170:173], v[202:205], v[110:113]
	v_mfma_f32_16x16x32_bf16 v[106:109], v[178:181], v[202:205], v[106:109]
	v_mfma_f32_16x16x32_bf16 v[102:105], v[170:173], v[210:213], v[102:105]
	v_mfma_f32_16x16x32_bf16 v[98:101], v[178:181], v[210:213], v[98:101]
	s_barrier
	v_readfirstlane_b32 s7, v159
	v_lshl_add_u64 v[242:243], v[238:239], 0, s[46:47]
	s_mov_b32 m0, s7
	v_readfirstlane_b32 s7, v160
	ds_read_b128 v[216:219], v151
	ds_read_b128 v[226:229], v151 offset:1024
	ds_read_b128 v[230:233], v151 offset:2048
	ds_read_b128 v[234:237], v151 offset:3072
	global_load_lds_dwordx4 v[242:243], off
	v_lshl_add_u64 v[242:243], v[240:241], 0, s[46:47]
	s_mov_b32 m0, s7
	s_nop 0
	global_load_lds_dwordx4 v[242:243], off
	s_barrier
	s_waitcnt lgkmcnt(0)
	s_waitcnt lgkmcnt(0)
	v_mfma_f32_16x16x32_bf16 v[94:97], v[216:219], v[182:185], v[94:97]
	v_mfma_f32_16x16x32_bf16 v[90:93], v[230:233], v[182:185], v[90:93]
	v_mfma_f32_16x16x32_bf16 v[86:89], v[216:219], v[190:193], v[86:89]
	v_mfma_f32_16x16x32_bf16 v[82:85], v[230:233], v[190:193], v[82:85]
	v_mfma_f32_16x16x32_bf16 v[78:81], v[216:219], v[198:201], v[78:81]
	v_mfma_f32_16x16x32_bf16 v[74:77], v[230:233], v[198:201], v[74:77]
	v_mfma_f32_16x16x32_bf16 v[70:73], v[216:219], v[206:209], v[70:73]
	v_mfma_f32_16x16x32_bf16 v[66:69], v[230:233], v[206:209], v[66:69]
	v_mfma_f32_16x16x32_bf16 v[94:97], v[226:229], v[186:189], v[94:97]
	v_mfma_f32_16x16x32_bf16 v[90:93], v[234:237], v[186:189], v[90:93]
	v_mfma_f32_16x16x32_bf16 v[86:89], v[226:229], v[194:197], v[86:89]
	v_mfma_f32_16x16x32_bf16 v[82:85], v[234:237], v[194:197], v[82:85]
	v_mfma_f32_16x16x32_bf16 v[78:81], v[226:229], v[202:205], v[78:81]
	v_mfma_f32_16x16x32_bf16 v[74:77], v[234:237], v[202:205], v[74:77]
	v_mfma_f32_16x16x32_bf16 v[70:73], v[226:229], v[210:213], v[70:73]
	v_mfma_f32_16x16x32_bf16 v[66:69], v[234:237], v[210:213], v[66:69]
	v_readfirstlane_b32 s7, v161
	v_lshl_add_u64 v[222:223], v[222:223], 0, s[72:73]
	s_mov_b32 m0, s7
	v_readfirstlane_b32 s7, v162
	s_barrier
	ds_read_b128 v[182:185], v148 offset:49152
	ds_read_b128 v[186:189], v148 offset:50176
	ds_read_b128 v[190:193], v147 offset:49152
	ds_read_b128 v[194:197], v147 offset:50176
	ds_read_b128 v[198:201], v146 offset:49152
	ds_read_b128 v[202:205], v146 offset:50176
	ds_read_b128 v[206:209], v141 offset:49152
	ds_read_b128 v[210:213], v141 offset:50176
	global_load_lds_dwordx4 v[222:223], off
	v_lshl_add_u64 v[222:223], v[224:225], 0, s[72:73]
	s_mov_b32 m0, s7
	s_nop 0
	global_load_lds_dwordx4 v[222:223], off
	s_barrier
; #define STAGE_A(b, h, kt) { const u16* ap_ = A + (size_t)((h) * ahalf + (unsigned)(kt) * 64u); glds16(ap_ + ao0, l0 + SA_(b, h)); glds16(ap_ + ao1, l0 + SA_(b, h) + 8192); }
; #define STAGE_B(b, h, kt) { const u16* bp_ = ((h) ? B1 : B0) + (unsigned)(kt) * 64u; glds16(bp_ + bo0, l0 + SB_(b, h)); glds16(bp_ + bo1, l0 + SB_(b, h) + 8192); }
; #define LDA(dst, b, h) _Pragma("unroll") for (int m = 0; m < 4; ++m) _Pragma("unroll") for (int k = 0; k < 2; ++k) \
;     dst[m][k] = *(const bf16x8*)(lds + SA_(b, h) + lds_byte(wr * 64 + m * 16 + fr, k * 32 + fq * 8));
; #define LDB(dst, b, h) _Pragma("unroll") for (int n = 0; n < 2; ++n) _Pragma("unroll") for (int k = 0; k < 2; ++k) \
;     dst[n][k] = *(const bf16x8*)(lds + SB_(b, h) + lds_byte(wc * 32 + n * 16 + fr, k * 32 + fq * 8));
; #define MMA(ai, bj, At_, Bt_) { __builtin_amdgcn_s_setprio(1); \
;     _Pragma("unroll") for (int m = 0; m < 4; ++m) _Pragma("unroll") for (int n = 0; n < 2; ++n) _Pragma("unroll") for (int k = 0; k < 2; ++k) \
;       acc[ai][bj][m][n] = MFMA16(Bt_[n][k], At_[m][k], acc[ai][bj][m][n]); \
;     __builtin_amdgcn_s_setprio(0); }
; #define WAIT_V(n) asm volatile("s_waitcnt vmcnt(" #n ")" ::: "memory");
; #define WAIT_L(n) asm volatile("s_waitcnt lgkmcnt(" #n ")" ::: "memory");
; #define BAR __builtin_amdgcn_s_barrier();
; #define SCHED __builtin_amdgcn_sched_barrier(0);
; DI void gemm256(const u16* __restrict__ A, int lda, const u16* __restrict__ B0, const u16* __restrict__ B1, int ldb, int nt, acc_t& acc, char* lds) {
;     ...
;     BAR WAIT_L(0) MMA(1, 0, At, Bq0) BAR SCHED
;     STAGE_B(1, 1, t + 3)
;     WAIT_V(6) BAR MMA(1, 1, At, Bq1) BAR
;   }
;   { LDB(Bq0, 0, 0) LDA(At, 0, 0) STAGE_A(1, 1, nt - 1)
;     BAR WAIT_L(0) MMA(0, 0, At, Bq0) BAR
;     LDB(Bq1, 0, 1) BAR WAIT_L(0) MMA(0, 1, At, Bq1) BAR
;     LDA(At, 0, 1) WAIT_V(4) BAR WAIT_L(0) MMA(1, 0, At, Bq0) MMA(1, 1, At, Bq1) BAR }
	s_waitcnt lgkmcnt(0)
	s_waitcnt lgkmcnt(0)
	v_mfma_f32_16x16x32_bf16 v[60:63], v[142:145], v[182:185], v[60:63]
	v_mfma_f32_16x16x32_bf16 v[56:59], v[174:177], v[182:185], v[56:59]
	v_mfma_f32_16x16x32_bf16 v[52:55], v[142:145], v[190:193], v[52:55]
	v_mfma_f32_16x16x32_bf16 v[48:51], v[174:177], v[190:193], v[48:51]
	v_mfma_f32_16x16x32_bf16 v[44:47], v[142:145], v[198:201], v[44:47]
	v_mfma_f32_16x16x32_bf16 v[40:43], v[174:177], v[198:201], v[40:43]
	v_mfma_f32_16x16x32_bf16 v[36:39], v[142:145], v[206:209], v[36:39]
	v_mfma_f32_16x16x32_bf16 v[32:35], v[174:177], v[206:209], v[32:35]
	v_mfma_f32_16x16x32_bf16 v[60:63], v[170:173], v[186:189], v[60:63]
	v_mfma_f32_16x16x32_bf16 v[56:59], v[178:181], v[186:189], v[56:59]
	v_mfma_f32_16x16x32_bf16 v[52:55], v[170:173], v[194:197], v[52:55]
	v_mfma_f32_16x16x32_bf16 v[48:51], v[178:181], v[194:197], v[48:51]
	v_mfma_f32_16x16x32_bf16 v[44:47], v[170:173], v[202:205], v[44:47]
	v_mfma_f32_16x16x32_bf16 v[40:43], v[178:181], v[202:205], v[40:43]
	v_mfma_f32_16x16x32_bf16 v[36:39], v[170:173], v[210:213], v[36:39]
	v_mfma_f32_16x16x32_bf16 v[32:35], v[178:181], v[210:213], v[32:35]
	s_barrier
	v_readfirstlane_b32 s7, v163
	v_lshl_add_u64 v[142:143], v[238:239], 0, s[48:49]
	s_mov_b32 m0, s7
	v_readfirstlane_b32 s7, v164
	global_load_lds_dwordx4 v[142:143], off
	v_lshl_add_u64 v[142:143], v[240:241], 0, s[48:49]
	s_mov_b32 m0, s7
	s_nop 0
	global_load_lds_dwordx4 v[142:143], off
	s_waitcnt vmcnt(6)
	s_barrier
	v_mfma_f32_16x16x32_bf16 v[28:31], v[216:219], v[182:185], v[28:31]
	v_mfma_f32_16x16x32_bf16 v[24:27], v[230:233], v[182:185], v[24:27]
	v_mfma_f32_16x16x32_bf16 v[20:23], v[216:219], v[190:193], v[20:23]
	v_mfma_f32_16x16x32_bf16 v[16:19], v[230:233], v[190:193], v[16:19]
	v_mfma_f32_16x16x32_bf16 v[12:15], v[216:219], v[198:201], v[12:15]
	v_mfma_f32_16x16x32_bf16 v[8:11], v[230:233], v[198:201], v[8:11]
	v_mfma_f32_16x16x32_bf16 v[4:7], v[216:219], v[206:209], v[4:7]
	v_mfma_f32_16x16x32_bf16 v[0:3], v[230:233], v[206:209], v[0:3]
	v_mfma_f32_16x16x32_bf16 v[28:31], v[226:229], v[186:189], v[28:31]
	v_mfma_f32_16x16x32_bf16 v[24:27], v[234:237], v[186:189], v[24:27]
	v_mfma_f32_16x16x32_bf16 v[20:23], v[226:229], v[194:197], v[20:23]
	v_mfma_f32_16x16x32_bf16 v[16:19], v[234:237], v[194:197], v[16:19]
	v_mfma_f32_16x16x32_bf16 v[12:15], v[226:229], v[202:205], v[12:15]
	v_mfma_f32_16x16x32_bf16 v[8:11], v[234:237], v[202:205], v[8:11]
	v_mfma_f32_16x16x32_bf16 v[4:7], v[226:229], v[210:213], v[4:7]
	v_mfma_f32_16x16x32_bf16 v[0:3], v[234:237], v[210:213], v[0:3]
	s_add_i32 s3, s3, 2
	s_add_u32 s36, s36, 0x100
	s_addc_u32 s37, s37, 0
	s_cmp_lt_u32 s3, 12
	s_barrier
	s_cbranch_scc1 .LBB0_1053
	s_add_u32 s28, s28, 0x40780
	s_addc_u32 s29, s29, 0
	v_readfirstlane_b32 s3, v167
	v_lshl_add_u64 v[162:163], v[64:65], 1, s[28:29]
	s_mov_b32 m0, s3
	v_readfirstlane_b32 s3, v168
	ds_read_b128 v[132:135], v166
	ds_read_b128 v[136:139], v166 offset:1024
	ds_read_b128 v[142:145], v166 offset:2048
	ds_read_b128 v[152:155], v166 offset:3072
	ds_read_b128 v[158:161], v148
	ds_read_b128 v[170:173], v148 offset:1024
	ds_read_b128 v[174:177], v147
	ds_read_b128 v[178:181], v147 offset:1024
	ds_read_b128 v[182:185], v146
	ds_read_b128 v[186:189], v146 offset:1024
	ds_read_b128 v[190:193], v141
	ds_read_b128 v[194:197], v141 offset:1024
	global_load_lds_dwordx4 v[162:163], off
	v_lshl_add_u64 v[130:131], v[130:131], 1, s[28:29]
	s_mov_b32 m0, s3
	s_nop 0
	global_load_lds_dwordx4 v[130:131], off
	s_barrier
	s_waitcnt lgkmcnt(0)
	s_waitcnt lgkmcnt(0)
	v_mfma_f32_16x16x32_bf16 v[126:129], v[132:135], v[158:161], v[126:129]
	v_mfma_f32_16x16x32_bf16 v[118:121], v[132:135], v[174:177], v[118:121]
	v_mfma_f32_16x16x32_bf16 v[114:117], v[142:145], v[174:177], v[114:117]
	v_mfma_f32_16x16x32_bf16 v[102:105], v[132:135], v[190:193], v[102:105]
	v_mfma_f32_16x16x32_bf16 v[98:101], v[142:145], v[190:193], v[98:101]
	v_mfma_f32_16x16x32_bf16 v[126:129], v[136:139], v[170:173], v[126:129]
	v_mfma_f32_16x16x32_bf16 v[122:125], v[142:145], v[158:161], v[122:125]
	v_mfma_f32_16x16x32_bf16 v[118:121], v[136:139], v[178:181], v[118:121]
	v_mfma_f32_16x16x32_bf16 v[114:117], v[152:155], v[178:181], v[114:117]
	v_mfma_f32_16x16x32_bf16 v[110:113], v[132:135], v[182:185], v[110:113]
	v_mfma_f32_16x16x32_bf16 v[106:109], v[142:145], v[182:185], v[106:109]
	v_mfma_f32_16x16x32_bf16 v[102:105], v[136:139], v[194:197], v[102:105]
	v_mfma_f32_16x16x32_bf16 v[98:101], v[152:155], v[194:197], v[98:101]
	v_mfma_f32_16x16x32_bf16 v[122:125], v[152:155], v[170:173], v[122:125]
	v_mfma_f32_16x16x32_bf16 v[166:169], v[136:139], v[186:189], v[110:113]
	v_mfma_f32_16x16x32_bf16 v[198:201], v[152:155], v[186:189], v[106:109]
	s_barrier
	s_nop 0
	ds_read_b128 v[106:109], v165
	ds_read_b128 v[110:113], v165 offset:1024
	ds_read_b128 v[202:205], v165 offset:2048
	ds_read_b128 v[162:165], v165 offset:3072
	s_barrier
	s_waitcnt lgkmcnt(0)
	s_waitcnt lgkmcnt(0)
	v_mfma_f32_16x16x32_bf16 v[86:89], v[106:109], v[174:177], v[86:89]
	v_mfma_f32_16x16x32_bf16 v[82:85], v[202:205], v[174:177], v[82:85]
	v_mfma_f32_16x16x32_bf16 v[70:73], v[106:109], v[190:193], v[70:73]
	v_mfma_f32_16x16x32_bf16 v[66:69], v[202:205], v[190:193], v[66:69]
	v_mfma_f32_16x16x32_bf16 v[94:97], v[106:109], v[158:161], v[94:97]
	v_mfma_f32_16x16x32_bf16 v[90:93], v[202:205], v[158:161], v[90:93]
	v_mfma_f32_16x16x32_bf16 v[86:89], v[110:113], v[178:181], v[86:89]
	v_mfma_f32_16x16x32_bf16 v[82:85], v[162:165], v[178:181], v[82:85]
	v_mfma_f32_16x16x32_bf16 v[78:81], v[106:109], v[182:185], v[78:81]
	v_mfma_f32_16x16x32_bf16 v[74:77], v[202:205], v[182:185], v[74:77]
	v_mfma_f32_16x16x32_bf16 v[70:73], v[110:113], v[194:197], v[70:73]
	v_mfma_f32_16x16x32_bf16 v[66:69], v[162:165], v[194:197], v[66:69]
	v_mfma_f32_16x16x32_bf16 v[206:209], v[110:113], v[170:173], v[94:97]
	v_mfma_f32_16x16x32_bf16 v[158:161], v[162:165], v[170:173], v[90:93]
	v_mfma_f32_16x16x32_bf16 v[170:173], v[110:113], v[186:189], v[78:81]
	v_mfma_f32_16x16x32_bf16 v[174:177], v[162:165], v[186:189], v[74:77]
	s_barrier
; #define LDA(dst, b, h) _Pragma("unroll") for (int m = 0; m < 4; ++m) _Pragma("unroll") for (int k = 0; k < 2; ++k) \
;     dst[m][k] = *(const bf16x8*)(lds + SA_(b, h) + lds_byte(wr * 64 + m * 16 + fr, k * 32 + fq * 8));
; #define LDB(dst, b, h) _Pragma("unroll") for (int n = 0; n < 2; ++n) _Pragma("unroll") for (int k = 0; k < 2; ++k) \
;     dst[n][k] = *(const bf16x8*)(lds + SB_(b, h) + lds_byte(wc * 32 + n * 16 + fr, k * 32 + fq * 8));
; #define MMA(ai, bj, At_, Bt_) { __builtin_amdgcn_s_setprio(1); \
;     _Pragma("unroll") for (int m = 0; m < 4; ++m) _Pragma("unroll") for (int n = 0; n < 2; ++n) _Pragma("unroll") for (int k = 0; k < 2; ++k) \
;       acc[ai][bj][m][n] = MFMA16(Bt_[n][k], At_[m][k], acc[ai][bj][m][n]); \
;     __builtin_amdgcn_s_setprio(0); }
; #define WAIT_V(n) asm volatile("s_waitcnt vmcnt(" #n ")" ::: "memory");
; #define WAIT_L(n) asm volatile("s_waitcnt lgkmcnt(" #n ")" ::: "memory");
; #define BAR __builtin_amdgcn_s_barrier();
; DI void gemm256(const u16* __restrict__ A, int lda, const u16* __restrict__ B0, const u16* __restrict__ B1, int ldb, int nt, acc_t& acc, char* lds) {
;     ...
;     BAR WAIT_L(0) MMA(0, 0, At, Bq0) BAR
;     LDB(Bq1, 0, 1) BAR WAIT_L(0) MMA(0, 1, At, Bq1) BAR
;     LDA(At, 0, 1) WAIT_V(4) BAR WAIT_L(0) MMA(1, 0, At, Bq0) MMA(1, 1, At, Bq1) BAR }
;   { LDB(Bq0, 1, 0) LDA(At, 1, 0) WAIT_V(2) BAR WAIT_L(0) MMA(0, 0, At, Bq0) BAR
	s_nop 0
	ds_read_b128 v[74:77], v148 offset:16384
	ds_read_b128 v[78:81], v148 offset:17408
	ds_read_b128 v[90:93], v147 offset:16384
	ds_read_b128 v[94:97], v147 offset:17408
	ds_read_b128 v[178:181], v146 offset:16384
	ds_read_b128 v[182:185], v146 offset:17408
	ds_read_b128 v[186:189], v141 offset:16384
	ds_read_b128 v[190:193], v141 offset:17408
	s_waitcnt vmcnt(4)
	s_barrier
	s_waitcnt lgkmcnt(0)
	s_waitcnt lgkmcnt(0)
	v_mfma_f32_16x16x32_bf16 v[60:63], v[132:135], v[74:77], v[60:63]
	v_mfma_f32_16x16x32_bf16 v[56:59], v[142:145], v[74:77], v[56:59]
	v_mfma_f32_16x16x32_bf16 v[52:55], v[132:135], v[90:93], v[52:55]
	v_mfma_f32_16x16x32_bf16 v[48:51], v[142:145], v[90:93], v[48:51]
	v_mfma_f32_16x16x32_bf16 v[36:39], v[132:135], v[186:189], v[36:39]
	v_mfma_f32_16x16x32_bf16 v[32:35], v[142:145], v[186:189], v[32:35]
	v_mfma_f32_16x16x32_bf16 v[60:63], v[136:139], v[78:81], v[60:63]
	v_mfma_f32_16x16x32_bf16 v[56:59], v[152:155], v[78:81], v[56:59]
	v_mfma_f32_16x16x32_bf16 v[52:55], v[136:139], v[94:97], v[52:55]
	v_mfma_f32_16x16x32_bf16 v[48:51], v[152:155], v[94:97], v[48:51]
	v_mfma_f32_16x16x32_bf16 v[44:47], v[132:135], v[178:181], v[44:47]
	v_mfma_f32_16x16x32_bf16 v[40:43], v[142:145], v[178:181], v[40:43]
	v_mfma_f32_16x16x32_bf16 v[36:39], v[136:139], v[190:193], v[36:39]
	v_mfma_f32_16x16x32_bf16 v[32:35], v[152:155], v[190:193], v[32:35]
	v_mfma_f32_16x16x32_bf16 v[194:197], v[136:139], v[182:185], v[44:47]
	v_mfma_f32_16x16x32_bf16 v[210:213], v[152:155], v[182:185], v[40:43]
	v_mfma_f32_16x16x32_bf16 v[20:23], v[106:109], v[90:93], v[20:23]
	v_mfma_f32_16x16x32_bf16 v[16:19], v[202:205], v[90:93], v[16:19]
	v_mfma_f32_16x16x32_bf16 v[4:7], v[106:109], v[186:189], v[4:7]
	v_mfma_f32_16x16x32_bf16 v[0:3], v[202:205], v[186:189], v[0:3]
	v_mfma_f32_16x16x32_bf16 v[28:31], v[106:109], v[74:77], v[28:31]
	v_mfma_f32_16x16x32_bf16 v[24:27], v[202:205], v[74:77], v[24:27]
	v_mfma_f32_16x16x32_bf16 v[20:23], v[110:113], v[94:97], v[20:23]
	v_mfma_f32_16x16x32_bf16 v[16:19], v[162:165], v[94:97], v[16:19]
	v_mfma_f32_16x16x32_bf16 v[12:15], v[106:109], v[178:181], v[12:15]
	v_mfma_f32_16x16x32_bf16 v[8:11], v[202:205], v[178:181], v[8:11]
	v_mfma_f32_16x16x32_bf16 v[4:7], v[110:113], v[190:193], v[4:7]
	v_mfma_f32_16x16x32_bf16 v[0:3], v[162:165], v[190:193], v[0:3]
	v_mfma_f32_16x16x32_bf16 v[134:137], v[110:113], v[78:81], v[28:31]
	v_mfma_f32_16x16x32_bf16 v[142:145], v[162:165], v[78:81], v[24:27]
	v_mfma_f32_16x16x32_bf16 v[152:155], v[110:113], v[182:185], v[12:15]
	v_mfma_f32_16x16x32_bf16 v[178:181], v[162:165], v[182:185], v[8:11]
	s_barrier
	s_nop 0
	ds_read_b128 v[8:11], v156
	ds_read_b128 v[12:15], v156 offset:1024
	ds_read_b128 v[162:165], v156 offset:2048
	ds_read_b128 v[182:185], v156 offset:3072
	ds_read_b128 v[24:27], v148 offset:32768
	ds_read_b128 v[28:31], v148 offset:33792
	ds_read_b128 v[40:43], v147 offset:32768
	ds_read_b128 v[44:47], v147 offset:33792
	ds_read_b128 v[186:189], v146 offset:32768
	ds_read_b128 v[190:193], v146 offset:33792
	ds_read_b128 v[202:205], v141 offset:32768
	ds_read_b128 v[216:219], v141 offset:33792
	s_waitcnt vmcnt(2)
	s_barrier
	s_waitcnt lgkmcnt(0)
	s_waitcnt lgkmcnt(0)
	v_mfma_f32_16x16x32_bf16 v[74:77], v[8:11], v[24:27], v[126:129]
	v_mfma_f32_16x16x32_bf16 v[126:129], v[12:15], v[28:31], v[74:77]
	v_mfma_f32_16x16x32_bf16 v[74:77], v[162:165], v[24:27], v[122:125]
	v_mfma_f32_16x16x32_bf16 v[130:133], v[182:185], v[28:31], v[74:77]
	v_mfma_f32_16x16x32_bf16 v[74:77], v[8:11], v[40:43], v[118:121]
	v_mfma_f32_16x16x32_bf16 v[110:113], v[12:15], v[44:47], v[74:77]
	v_mfma_f32_16x16x32_bf16 v[74:77], v[162:165], v[40:43], v[114:117]
	v_mfma_f32_16x16x32_bf16 v[106:109], v[182:185], v[44:47], v[74:77]
	v_mfma_f32_16x16x32_bf16 v[74:77], v[8:11], v[186:189], v[166:169]
	v_mfma_f32_16x16x32_bf16 v[94:97], v[12:15], v[190:193], v[74:77]
	v_mfma_f32_16x16x32_bf16 v[74:77], v[162:165], v[186:189], v[198:201]
	v_mfma_f32_16x16x32_bf16 v[90:93], v[182:185], v[190:193], v[74:77]
	v_mfma_f32_16x16x32_bf16 v[74:77], v[8:11], v[202:205], v[102:105]
	v_mfma_f32_16x16x32_bf16 v[78:81], v[12:15], v[216:219], v[74:77]
	v_mfma_f32_16x16x32_bf16 v[74:77], v[162:165], v[202:205], v[98:101]
	v_mfma_f32_16x16x32_bf16 v[74:77], v[182:185], v[216:219], v[74:77]
	s_barrier
; #define LDA(dst, b, h) _Pragma("unroll") for (int m = 0; m < 4; ++m) _Pragma("unroll") for (int k = 0; k < 2; ++k) \
;     dst[m][k] = *(const bf16x8*)(lds + SA_(b, h) + lds_byte(wr * 64 + m * 16 + fr, k * 32 + fq * 8));
; #define LDB(dst, b, h) _Pragma("unroll") for (int n = 0; n < 2; ++n) _Pragma("unroll") for (int k = 0; k < 2; ++k) \
;     dst[n][k] = *(const bf16x8*)(lds + SB_(b, h) + lds_byte(wc * 32 + n * 16 + fr, k * 32 + fq * 8));
; #define MMA(ai, bj, At_, Bt_) { __builtin_amdgcn_s_setprio(1); \
;     _Pragma("unroll") for (int m = 0; m < 4; ++m) _Pragma("unroll") for (int n = 0; n < 2; ++n) _Pragma("unroll") for (int k = 0; k < 2; ++k) \
;       acc[ai][bj][m][n] = MFMA16(Bt_[n][k], At_[m][k], acc[ai][bj][m][n]); \
;     __builtin_amdgcn_s_setprio(0); }
; #define WAIT_V(n) asm volatile("s_waitcnt vmcnt(" #n ")" ::: "memory");
; #define WAIT_L(n) asm volatile("s_waitcnt lgkmcnt(" #n ")" ::: "memory");
; #define BAR __builtin_amdgcn_s_barrier();
; DI void gemm256(const u16* __restrict__ A, int lda, const u16* __restrict__ B0, const u16* __restrict__ B1, int ldb, int nt, acc_t& acc, char* lds) {
;     ...
;   { LDB(Bq0, 1, 0) LDA(At, 1, 0) WAIT_V(2) BAR WAIT_L(0) MMA(0, 0, At, Bq0) BAR
;     LDB(Bq1, 1, 1) WAIT_V(0) BAR WAIT_L(0) MMA(0, 1, At, Bq1) BAR
;     LDA(At, 1, 1) BAR WAIT_L(0) MMA(1, 0, At, Bq0) MMA(1, 1, At, Bq1) BAR }
;   if (wr == 0) BAR
;   __syncthreads();
	ds_read_b128 v[122:125], v151
	ds_read_b128 v[166:169], v151 offset:1024
	ds_read_b128 v[198:201], v151 offset:2048
	ds_read_b128 v[226:229], v151 offset:3072
	s_waitcnt vmcnt(0)
	s_barrier
	s_waitcnt lgkmcnt(0)
	s_waitcnt lgkmcnt(0)
	v_mfma_f32_16x16x32_bf16 v[98:101], v[122:125], v[24:27], v[206:209]
	v_mfma_f32_16x16x32_bf16 v[24:27], v[198:201], v[24:27], v[158:161]
	v_mfma_f32_16x16x32_bf16 v[114:117], v[226:229], v[28:31], v[24:27]
	v_mfma_f32_16x16x32_bf16 v[24:27], v[122:125], v[40:43], v[86:89]
	v_mfma_f32_16x16x32_bf16 v[102:105], v[166:169], v[44:47], v[24:27]
	v_mfma_f32_16x16x32_bf16 v[24:27], v[198:201], v[40:43], v[82:85]
	v_mfma_f32_16x16x32_bf16 v[118:121], v[166:169], v[28:31], v[98:101]
	v_mfma_f32_16x16x32_bf16 v[98:101], v[226:229], v[44:47], v[24:27]
	v_mfma_f32_16x16x32_bf16 v[24:27], v[122:125], v[186:189], v[170:173]
	v_mfma_f32_16x16x32_bf16 v[86:89], v[166:169], v[190:193], v[24:27]
	v_mfma_f32_16x16x32_bf16 v[24:27], v[198:201], v[186:189], v[174:177]
	v_mfma_f32_16x16x32_bf16 v[82:85], v[226:229], v[190:193], v[24:27]
	v_mfma_f32_16x16x32_bf16 v[24:27], v[122:125], v[202:205], v[70:73]
	v_mfma_f32_16x16x32_bf16 v[70:73], v[166:169], v[216:219], v[24:27]
	v_mfma_f32_16x16x32_bf16 v[24:27], v[198:201], v[202:205], v[66:69]
	v_mfma_f32_16x16x32_bf16 v[66:69], v[226:229], v[216:219], v[24:27]
	s_barrier
	ds_read_b128 v[156:159], v148 offset:49152
	ds_read_b128 v[148:151], v148 offset:50176
	ds_read_b128 v[170:173], v147 offset:49152
	ds_read_b128 v[174:177], v147 offset:50176
	ds_read_b128 v[186:189], v146 offset:49152
	ds_read_b128 v[190:193], v146 offset:50176
	ds_read_b128 v[202:205], v141 offset:49152
	ds_read_b128 v[206:209], v141 offset:50176
	s_barrier
	s_waitcnt lgkmcnt(0)
	s_waitcnt lgkmcnt(0)
	v_mfma_f32_16x16x32_bf16 v[24:27], v[8:11], v[156:159], v[60:63]
	v_mfma_f32_16x16x32_bf16 v[60:63], v[12:15], v[148:151], v[24:27]
	v_mfma_f32_16x16x32_bf16 v[24:27], v[162:165], v[156:159], v[56:59]
	v_mfma_f32_16x16x32_bf16 v[56:59], v[182:185], v[148:151], v[24:27]
	v_mfma_f32_16x16x32_bf16 v[24:27], v[8:11], v[170:173], v[52:55]
	v_mfma_f32_16x16x32_bf16 v[44:47], v[12:15], v[174:177], v[24:27]
	v_mfma_f32_16x16x32_bf16 v[24:27], v[162:165], v[170:173], v[48:51]
	v_mfma_f32_16x16x32_bf16 v[40:43], v[182:185], v[174:177], v[24:27]
	v_mfma_f32_16x16x32_bf16 v[24:27], v[8:11], v[186:189], v[194:197]
	v_mfma_f32_16x16x32_bf16 v[8:11], v[8:11], v[202:205], v[36:39]
	v_mfma_f32_16x16x32_bf16 v[28:31], v[12:15], v[190:193], v[24:27]
	v_mfma_f32_16x16x32_bf16 v[24:27], v[162:165], v[186:189], v[210:213]
	v_mfma_f32_16x16x32_bf16 v[12:15], v[12:15], v[206:209], v[8:11]
	v_mfma_f32_16x16x32_bf16 v[8:11], v[162:165], v[202:205], v[32:35]
	v_mfma_f32_16x16x32_bf16 v[24:27], v[182:185], v[190:193], v[24:27]
	v_mfma_f32_16x16x32_bf16 v[8:11], v[182:185], v[206:209], v[8:11]
	v_mfma_f32_16x16x32_bf16 v[32:35], v[122:125], v[156:159], v[134:137]
	v_mfma_f32_16x16x32_bf16 v[52:55], v[166:169], v[148:151], v[32:35]
	v_mfma_f32_16x16x32_bf16 v[32:35], v[198:201], v[156:159], v[142:145]
	v_mfma_f32_16x16x32_bf16 v[16:19], v[198:201], v[170:173], v[16:19]
	v_mfma_f32_16x16x32_bf16 v[48:51], v[226:229], v[148:151], v[32:35]
	v_mfma_f32_16x16x32_bf16 v[20:23], v[122:125], v[170:173], v[20:23]
	v_mfma_f32_16x16x32_bf16 v[32:35], v[226:229], v[174:177], v[16:19]
	v_mfma_f32_16x16x32_bf16 v[16:19], v[122:125], v[186:189], v[152:155]
	v_mfma_f32_16x16x32_bf16 v[36:39], v[166:169], v[174:177], v[20:23]
	v_mfma_f32_16x16x32_bf16 v[20:23], v[166:169], v[190:193], v[16:19]
	v_mfma_f32_16x16x32_bf16 v[16:19], v[198:201], v[186:189], v[178:181]
	v_mfma_f32_16x16x32_bf16 v[4:7], v[122:125], v[202:205], v[4:7]
	v_mfma_f32_16x16x32_bf16 v[0:3], v[198:201], v[202:205], v[0:3]
	v_mfma_f32_16x16x32_bf16 v[16:19], v[226:229], v[190:193], v[16:19]
	v_mfma_f32_16x16x32_bf16 v[4:7], v[166:169], v[206:209], v[4:7]
	v_mfma_f32_16x16x32_bf16 v[0:3], v[226:229], v[206:209], v[0:3]
	s_movk_i32 s3, 0x100
	v_cmp_gt_u32_e32 vcc, s3, v140
	s_barrier
	s_and_saveexec_b64 s[28:29], vcc
	s_cbranch_execz .LBB0_1049
	s_barrier
	s_branch .LBB0_1049

; #define STAGE_A(b, h, kt) { const u16* ap_ = A + (size_t)((h) * ahalf + (unsigned)(kt) * 64u); glds16(ap_ + ao0, l0 + SA_(b, h)); glds16(ap_ + ao1, l0 + SA_(b, h) + 8192); }
; #define STAGE_B(b, h, kt) { const u16* bp_ = ((h) ? B1 : B0) + (unsigned)(kt) * 64u; glds16(bp_ + bo0, l0 + SB_(b, h)); glds16(bp_ + bo1, l0 + SB_(b, h) + 8192); }
; #define LDA(dst, b, h) _Pragma("unroll") for (int m = 0; m < 4; ++m) _Pragma("unroll") for (int k = 0; k < 2; ++k) \
;     dst[m][k] = *(const bf16x8*)(lds + SA_(b, h) + lds_byte(wr * 64 + m * 16 + fr, k * 32 + fq * 8));
; #define LDB(dst, b, h) _Pragma("unroll") for (int n = 0; n < 2; ++n) _Pragma("unroll") for (int k = 0; k < 2; ++k) \
;     dst[n][k] = *(const bf16x8*)(lds + SB_(b, h) + lds_byte(wc * 32 + n * 16 + fr, k * 32 + fq * 8));
; #define MMA(ai, bj, At_, Bt_) { __builtin_amdgcn_s_setprio(1); \
;     _Pragma("unroll") for (int m = 0; m < 4; ++m) _Pragma("unroll") for (int n = 0; n < 2; ++n) _Pragma("unroll") for (int k = 0; k < 2; ++k) \
;       acc[ai][bj][m][n] = MFMA16(Bt_[n][k], At_[m][k], acc[ai][bj][m][n]); \
;     __builtin_amdgcn_s_setprio(0); }
; #define WAIT_V(n) asm volatile("s_waitcnt vmcnt(" #n ")" ::: "memory");
; #define WAIT_L(n) asm volatile("s_waitcnt lgkmcnt(" #n ")" ::: "memory");
; #define BAR __builtin_amdgcn_s_barrier();
; #define SCHED __builtin_amdgcn_sched_barrier(0);
; DI void gemm256(const u16* __restrict__ A, int lda, const u16* __restrict__ B0, const u16* __restrict__ B1, int ldb, int nt, acc_t& acc, char* lds) {
;     ...
;   for (int t = 0; t < nt - 2; t += 2) {
;     LDB(Bq0, 0, 0) SCHED LDA(At, 0, 0) STAGE_A(1, 1, t + 1)
;     WAIT_L(8) BAR WAIT_L(0) MMA(0, 0, At, Bq0) BAR SCHED
;     LDB(Bq1, 0, 1) STAGE_B(0, 0, t + 2)
;     BAR WAIT_L(0) MMA(0, 1, At, Bq1) BAR
;     LDA(At, 0, 1) STAGE_A(0, 0, t + 2)
;     BAR WAIT_L(0) MMA(1, 0, At, Bq0) BAR SCHED
;     STAGE_B(0, 1, t + 2)
;     WAIT_V(6) BAR MMA(1, 1, At, Bq1) BAR
;     LDB(Bq0, 1, 0) SCHED LDA(At, 1, 0) STAGE_A(0, 1, t + 2)
;     WAIT_L(8) BAR WAIT_L(0) MMA(0, 0, At, Bq0) BAR SCHED
.LBB0_1172:
	ds_read_b128 v[142:145], v166
	ds_read_b128 v[170:173], v166 offset:1024
	ds_read_b128 v[174:177], v166 offset:2048
	ds_read_b128 v[178:181], v166 offset:3072
	v_add_u32_e32 v167, 0xc000, v149
	v_lshl_add_u64 v[222:223], s[36:37], 0, v[136:137]
	v_readfirstlane_b32 s9, v167
	v_lshl_add_u64 v[168:169], v[222:223], 0, s[76:77]
	s_mov_b32 m0, s9
	ds_read_b128 v[182:185], v148
	ds_read_b128 v[186:189], v148 offset:1024
	ds_read_b128 v[190:193], v147
	ds_read_b128 v[194:197], v147 offset:1024
	ds_read_b128 v[198:201], v146
	ds_read_b128 v[202:205], v146 offset:1024
	ds_read_b128 v[206:209], v141
	ds_read_b128 v[210:213], v141 offset:1024
	global_load_lds_dwordx4 v[168:169], off
	v_add_u32_e32 v168, 0xe000, v149
	v_lshl_add_u64 v[224:225], s[36:37], 0, v[138:139]
	v_readfirstlane_b32 s9, v168
	v_lshl_add_u64 v[216:217], v[224:225], 0, s[76:77]
	s_mov_b32 m0, s9
	s_nop 0
	global_load_lds_dwordx4 v[216:217], off
	s_waitcnt lgkmcnt(8)
	s_barrier
	s_waitcnt lgkmcnt(0)
	s_waitcnt lgkmcnt(0)
	v_mfma_f32_16x16x32_bf16 v[126:129], v[142:145], v[182:185], v[126:129]
	v_mfma_f32_16x16x32_bf16 v[122:125], v[174:177], v[182:185], v[122:125]
	v_mfma_f32_16x16x32_bf16 v[118:121], v[142:145], v[190:193], v[118:121]
	v_mfma_f32_16x16x32_bf16 v[114:117], v[174:177], v[190:193], v[114:117]
	v_mfma_f32_16x16x32_bf16 v[110:113], v[142:145], v[198:201], v[110:113]
	v_mfma_f32_16x16x32_bf16 v[106:109], v[174:177], v[198:201], v[106:109]
	v_mfma_f32_16x16x32_bf16 v[102:105], v[142:145], v[206:209], v[102:105]
	v_mfma_f32_16x16x32_bf16 v[98:101], v[174:177], v[206:209], v[98:101]
	v_mfma_f32_16x16x32_bf16 v[126:129], v[170:173], v[186:189], v[126:129]
	v_mfma_f32_16x16x32_bf16 v[122:125], v[178:181], v[186:189], v[122:125]
	v_mfma_f32_16x16x32_bf16 v[118:121], v[170:173], v[194:197], v[118:121]
	v_mfma_f32_16x16x32_bf16 v[114:117], v[178:181], v[194:197], v[114:117]
	v_mfma_f32_16x16x32_bf16 v[110:113], v[170:173], v[202:205], v[110:113]
	v_mfma_f32_16x16x32_bf16 v[106:109], v[178:181], v[202:205], v[106:109]
	v_mfma_f32_16x16x32_bf16 v[102:105], v[170:173], v[210:213], v[102:105]
	v_mfma_f32_16x16x32_bf16 v[98:101], v[178:181], v[210:213], v[98:101]
	s_barrier
	v_lshl_add_u64 v[238:239], s[36:37], 0, v[132:133]
	v_readfirstlane_b32 s9, v150
	v_lshl_add_u64 v[240:241], v[238:239], 0, s[42:43]
	s_mov_b32 m0, s9
	ds_read_b128 v[216:219], v165
	ds_read_b128 v[226:229], v165 offset:1024
	ds_read_b128 v[230:233], v165 offset:2048
	ds_read_b128 v[234:237], v165 offset:3072
	global_load_lds_dwordx4 v[240:241], off
	v_lshl_add_u64 v[240:241], s[36:37], 0, v[134:135]
	v_readfirstlane_b32 s9, v152
	v_lshl_add_u64 v[242:243], v[240:241], 0, s[42:43]
	s_mov_b32 m0, s9
	s_nop 0
	global_load_lds_dwordx4 v[242:243], off
	s_barrier
	s_waitcnt lgkmcnt(0)
	s_waitcnt lgkmcnt(0)
	v_mfma_f32_16x16x32_bf16 v[94:97], v[216:219], v[182:185], v[94:97]
	v_mfma_f32_16x16x32_bf16 v[90:93], v[230:233], v[182:185], v[90:93]
	v_mfma_f32_16x16x32_bf16 v[86:89], v[216:219], v[190:193], v[86:89]
	v_mfma_f32_16x16x32_bf16 v[82:85], v[230:233], v[190:193], v[82:85]
	v_mfma_f32_16x16x32_bf16 v[78:81], v[216:219], v[198:201], v[78:81]
	v_mfma_f32_16x16x32_bf16 v[74:77], v[230:233], v[198:201], v[74:77]
	v_mfma_f32_16x16x32_bf16 v[70:73], v[216:219], v[206:209], v[70:73]
	v_mfma_f32_16x16x32_bf16 v[66:69], v[230:233], v[206:209], v[66:69]
	v_mfma_f32_16x16x32_bf16 v[94:97], v[226:229], v[186:189], v[94:97]
	v_mfma_f32_16x16x32_bf16 v[90:93], v[234:237], v[186:189], v[90:93]
	v_mfma_f32_16x16x32_bf16 v[86:89], v[226:229], v[194:197], v[86:89]
	v_mfma_f32_16x16x32_bf16 v[82:85], v[234:237], v[194:197], v[82:85]
	v_mfma_f32_16x16x32_bf16 v[78:81], v[226:229], v[202:205], v[78:81]
	v_mfma_f32_16x16x32_bf16 v[74:77], v[234:237], v[202:205], v[74:77]
	v_mfma_f32_16x16x32_bf16 v[70:73], v[226:229], v[210:213], v[70:73]
	v_mfma_f32_16x16x32_bf16 v[66:69], v[234:237], v[210:213], v[66:69]
	v_readfirstlane_b32 s9, v149
	v_lshl_add_u64 v[242:243], v[222:223], 0, s[80:81]
	s_mov_b32 m0, s9
	v_readfirstlane_b32 s9, v153
	s_barrier
	ds_read_b128 v[182:185], v148 offset:16384
	ds_read_b128 v[186:189], v148 offset:17408
	ds_read_b128 v[190:193], v147 offset:16384
	ds_read_b128 v[194:197], v147 offset:17408
	ds_read_b128 v[198:201], v146 offset:16384
	ds_read_b128 v[202:205], v146 offset:17408
	ds_read_b128 v[206:209], v141 offset:16384
	ds_read_b128 v[210:213], v141 offset:17408
	global_load_lds_dwordx4 v[242:243], off
	v_lshl_add_u64 v[242:243], v[224:225], 0, s[80:81]
	s_mov_b32 m0, s9
	s_nop 0
	global_load_lds_dwordx4 v[242:243], off
	s_barrier
	s_waitcnt lgkmcnt(0)
	s_waitcnt lgkmcnt(0)
	v_mfma_f32_16x16x32_bf16 v[60:63], v[142:145], v[182:185], v[60:63]
	v_mfma_f32_16x16x32_bf16 v[56:59], v[174:177], v[182:185], v[56:59]
	v_mfma_f32_16x16x32_bf16 v[52:55], v[142:145], v[190:193], v[52:55]
	v_mfma_f32_16x16x32_bf16 v[48:51], v[174:177], v[190:193], v[48:51]
	v_mfma_f32_16x16x32_bf16 v[44:47], v[142:145], v[198:201], v[44:47]
	v_mfma_f32_16x16x32_bf16 v[40:43], v[174:177], v[198:201], v[40:43]
	v_mfma_f32_16x16x32_bf16 v[36:39], v[142:145], v[206:209], v[36:39]
	v_mfma_f32_16x16x32_bf16 v[32:35], v[174:177], v[206:209], v[32:35]
	v_mfma_f32_16x16x32_bf16 v[60:63], v[170:173], v[186:189], v[60:63]
	v_mfma_f32_16x16x32_bf16 v[56:59], v[178:181], v[186:189], v[56:59]
	v_mfma_f32_16x16x32_bf16 v[52:55], v[170:173], v[194:197], v[52:55]
	v_mfma_f32_16x16x32_bf16 v[48:51], v[178:181], v[194:197], v[48:51]
	v_mfma_f32_16x16x32_bf16 v[44:47], v[170:173], v[202:205], v[44:47]
	v_mfma_f32_16x16x32_bf16 v[40:43], v[178:181], v[202:205], v[40:43]
	v_mfma_f32_16x16x32_bf16 v[36:39], v[170:173], v[210:213], v[36:39]
	v_mfma_f32_16x16x32_bf16 v[32:35], v[178:181], v[210:213], v[32:35]
	s_barrier
; #define STAGE_A(b, h, kt) { const u16* ap_ = A + (size_t)((h) * ahalf + (unsigned)(kt) * 64u); glds16(ap_ + ao0, l0 + SA_(b, h)); glds16(ap_ + ao1, l0 + SA_(b, h) + 8192); }
; #define STAGE_B(b, h, kt) { const u16* bp_ = ((h) ? B1 : B0) + (unsigned)(kt) * 64u; glds16(bp_ + bo0, l0 + SB_(b, h)); glds16(bp_ + bo1, l0 + SB_(b, h) + 8192); }
; #define LDA(dst, b, h) _Pragma("unroll") for (int m = 0; m < 4; ++m) _Pragma("unroll") for (int k = 0; k < 2; ++k) \
;     dst[m][k] = *(const bf16x8*)(lds + SA_(b, h) + lds_byte(wr * 64 + m * 16 + fr, k * 32 + fq * 8));
; #define LDB(dst, b, h) _Pragma("unroll") for (int n = 0; n < 2; ++n) _Pragma("unroll") for (int k = 0; k < 2; ++k) \
;     dst[n][k] = *(const bf16x8*)(lds + SB_(b, h) + lds_byte(wc * 32 + n * 16 + fr, k * 32 + fq * 8));
; #define MMA(ai, bj, At_, Bt_) { __builtin_amdgcn_s_setprio(1); \
;     _Pragma("unroll") for (int m = 0; m < 4; ++m) _Pragma("unroll") for (int n = 0; n < 2; ++n) _Pragma("unroll") for (int k = 0; k < 2; ++k) \
;       acc[ai][bj][m][n] = MFMA16(Bt_[n][k], At_[m][k], acc[ai][bj][m][n]); \
;     __builtin_amdgcn_s_setprio(0); }
; #define WAIT_V(n) asm volatile("s_waitcnt vmcnt(" #n ")" ::: "memory");
; #define WAIT_L(n) asm volatile("s_waitcnt lgkmcnt(" #n ")" ::: "memory");
; #define BAR __builtin_amdgcn_s_barrier();
; #define SCHED __builtin_amdgcn_sched_barrier(0);
; DI void gemm256(const u16* __restrict__ A, int lda, const u16* __restrict__ B0, const u16* __restrict__ B1, int ldb, int nt, acc_t& acc, char* lds) {
;     ...
;     STAGE_B(0, 1, t + 2)
;     WAIT_V(6) BAR MMA(1, 1, At, Bq1) BAR
;     LDB(Bq0, 1, 0) SCHED LDA(At, 1, 0) STAGE_A(0, 1, t + 2)
;     WAIT_L(8) BAR WAIT_L(0) MMA(0, 0, At, Bq0) BAR SCHED
;     LDB(Bq1, 1, 1) STAGE_B(1, 0, t + 3)
;     BAR WAIT_L(0) MMA(0, 1, At, Bq1) BAR
;     LDA(At, 1, 1) STAGE_A(1, 0, t + 3)
	v_readfirstlane_b32 s9, v154
	v_lshl_add_u64 v[142:143], v[238:239], 0, s[44:45]
	s_mov_b32 m0, s9
	v_readfirstlane_b32 s9, v155
	global_load_lds_dwordx4 v[142:143], off
	v_lshl_add_u64 v[142:143], v[240:241], 0, s[44:45]
	s_mov_b32 m0, s9
	s_nop 0
	global_load_lds_dwordx4 v[142:143], off
	s_waitcnt vmcnt(6)
	s_barrier
	v_mfma_f32_16x16x32_bf16 v[28:31], v[216:219], v[182:185], v[28:31]
	v_mfma_f32_16x16x32_bf16 v[24:27], v[230:233], v[182:185], v[24:27]
	v_mfma_f32_16x16x32_bf16 v[20:23], v[216:219], v[190:193], v[20:23]
	v_mfma_f32_16x16x32_bf16 v[16:19], v[230:233], v[190:193], v[16:19]
	v_mfma_f32_16x16x32_bf16 v[12:15], v[216:219], v[198:201], v[12:15]
	v_mfma_f32_16x16x32_bf16 v[8:11], v[230:233], v[198:201], v[8:11]
	v_mfma_f32_16x16x32_bf16 v[4:7], v[216:219], v[206:209], v[4:7]
	v_mfma_f32_16x16x32_bf16 v[0:3], v[230:233], v[206:209], v[0:3]
	v_mfma_f32_16x16x32_bf16 v[28:31], v[226:229], v[186:189], v[28:31]
	v_mfma_f32_16x16x32_bf16 v[24:27], v[234:237], v[186:189], v[24:27]
	v_mfma_f32_16x16x32_bf16 v[20:23], v[226:229], v[194:197], v[20:23]
	v_mfma_f32_16x16x32_bf16 v[16:19], v[234:237], v[194:197], v[16:19]
	v_mfma_f32_16x16x32_bf16 v[12:15], v[226:229], v[202:205], v[12:15]
	v_mfma_f32_16x16x32_bf16 v[8:11], v[234:237], v[202:205], v[8:11]
	v_mfma_f32_16x16x32_bf16 v[4:7], v[226:229], v[210:213], v[4:7]
	v_mfma_f32_16x16x32_bf16 v[0:3], v[234:237], v[210:213], v[0:3]
	s_barrier
	ds_read_b128 v[142:145], v156
	ds_read_b128 v[170:173], v156 offset:1024
	ds_read_b128 v[174:177], v156 offset:2048
	ds_read_b128 v[178:181], v156 offset:3072
	v_readfirstlane_b32 s9, v157
	v_lshl_add_u64 v[216:217], v[222:223], 0, s[4:5]
	s_mov_b32 m0, s9
	v_readfirstlane_b32 s9, v158
	ds_read_b128 v[182:185], v148 offset:32768
	ds_read_b128 v[186:189], v148 offset:33792
	ds_read_b128 v[190:193], v147 offset:32768
	ds_read_b128 v[194:197], v147 offset:33792
	ds_read_b128 v[198:201], v146 offset:32768
	ds_read_b128 v[202:205], v146 offset:33792
	ds_read_b128 v[206:209], v141 offset:32768
	ds_read_b128 v[210:213], v141 offset:33792
	global_load_lds_dwordx4 v[216:217], off
	v_lshl_add_u64 v[216:217], v[224:225], 0, s[4:5]
	s_mov_b32 m0, s9
	s_nop 0
	global_load_lds_dwordx4 v[216:217], off
	s_waitcnt lgkmcnt(8)
	s_barrier
	s_waitcnt lgkmcnt(0)
	s_waitcnt lgkmcnt(0)
	v_mfma_f32_16x16x32_bf16 v[126:129], v[142:145], v[182:185], v[126:129]
	v_mfma_f32_16x16x32_bf16 v[122:125], v[174:177], v[182:185], v[122:125]
	v_mfma_f32_16x16x32_bf16 v[118:121], v[142:145], v[190:193], v[118:121]
	v_mfma_f32_16x16x32_bf16 v[114:117], v[174:177], v[190:193], v[114:117]
	v_mfma_f32_16x16x32_bf16 v[110:113], v[142:145], v[198:201], v[110:113]
	v_mfma_f32_16x16x32_bf16 v[106:109], v[174:177], v[198:201], v[106:109]
	v_mfma_f32_16x16x32_bf16 v[102:105], v[142:145], v[206:209], v[102:105]
	v_mfma_f32_16x16x32_bf16 v[98:101], v[174:177], v[206:209], v[98:101]
	v_mfma_f32_16x16x32_bf16 v[126:129], v[170:173], v[186:189], v[126:129]
	v_mfma_f32_16x16x32_bf16 v[122:125], v[178:181], v[186:189], v[122:125]
	v_mfma_f32_16x16x32_bf16 v[118:121], v[170:173], v[194:197], v[118:121]
	v_mfma_f32_16x16x32_bf16 v[114:117], v[178:181], v[194:197], v[114:117]
	v_mfma_f32_16x16x32_bf16 v[110:113], v[170:173], v[202:205], v[110:113]
	v_mfma_f32_16x16x32_bf16 v[106:109], v[178:181], v[202:205], v[106:109]
	v_mfma_f32_16x16x32_bf16 v[102:105], v[170:173], v[210:213], v[102:105]
	v_mfma_f32_16x16x32_bf16 v[98:101], v[178:181], v[210:213], v[98:101]
	s_barrier
	v_readfirstlane_b32 s9, v159
	v_lshl_add_u64 v[242:243], v[238:239], 0, s[46:47]
	s_mov_b32 m0, s9
	v_readfirstlane_b32 s9, v160
	ds_read_b128 v[216:219], v151
	ds_read_b128 v[226:229], v151 offset:1024
	ds_read_b128 v[230:233], v151 offset:2048
	ds_read_b128 v[234:237], v151 offset:3072
	global_load_lds_dwordx4 v[242:243], off
	v_lshl_add_u64 v[242:243], v[240:241], 0, s[46:47]
	s_mov_b32 m0, s9
	s_nop 0
	global_load_lds_dwordx4 v[242:243], off
	s_barrier
	s_waitcnt lgkmcnt(0)
	s_waitcnt lgkmcnt(0)
	v_mfma_f32_16x16x32_bf16 v[94:97], v[216:219], v[182:185], v[94:97]
	v_mfma_f32_16x16x32_bf16 v[90:93], v[230:233], v[182:185], v[90:93]
	v_mfma_f32_16x16x32_bf16 v[86:89], v[216:219], v[190:193], v[86:89]
	v_mfma_f32_16x16x32_bf16 v[82:85], v[230:233], v[190:193], v[82:85]
	v_mfma_f32_16x16x32_bf16 v[78:81], v[216:219], v[198:201], v[78:81]
	v_mfma_f32_16x16x32_bf16 v[74:77], v[230:233], v[198:201], v[74:77]
	v_mfma_f32_16x16x32_bf16 v[70:73], v[216:219], v[206:209], v[70:73]
	v_mfma_f32_16x16x32_bf16 v[66:69], v[230:233], v[206:209], v[66:69]
	v_mfma_f32_16x16x32_bf16 v[94:97], v[226:229], v[186:189], v[94:97]
	v_mfma_f32_16x16x32_bf16 v[90:93], v[234:237], v[186:189], v[90:93]
	v_mfma_f32_16x16x32_bf16 v[86:89], v[226:229], v[194:197], v[86:89]
	v_mfma_f32_16x16x32_bf16 v[82:85], v[234:237], v[194:197], v[82:85]
	v_mfma_f32_16x16x32_bf16 v[78:81], v[226:229], v[202:205], v[78:81]
	v_mfma_f32_16x16x32_bf16 v[74:77], v[234:237], v[202:205], v[74:77]
	v_mfma_f32_16x16x32_bf16 v[70:73], v[226:229], v[210:213], v[70:73]
	v_mfma_f32_16x16x32_bf16 v[66:69], v[234:237], v[210:213], v[66:69]
	v_readfirstlane_b32 s9, v161
	v_lshl_add_u64 v[222:223], v[222:223], 0, s[30:31]
	s_mov_b32 m0, s9
	v_readfirstlane_b32 s9, v162
	s_barrier
	ds_read_b128 v[182:185], v148 offset:49152
	ds_read_b128 v[186:189], v148 offset:50176
	ds_read_b128 v[190:193], v147 offset:49152
	ds_read_b128 v[194:197], v147 offset:50176
	ds_read_b128 v[198:201], v146 offset:49152
	ds_read_b128 v[202:205], v146 offset:50176
	ds_read_b128 v[206:209], v141 offset:49152
	ds_read_b128 v[210:213], v141 offset:50176
	global_load_lds_dwordx4 v[222:223], off
	v_lshl_add_u64 v[222:223], v[224:225], 0, s[30:31]
	s_mov_b32 m0, s9
	s_nop 0
	global_load_lds_dwordx4 v[222:223], off
	s_barrier
; #define STAGE_A(b, h, kt) { const u16* ap_ = A + (size_t)((h) * ahalf + (unsigned)(kt) * 64u); glds16(ap_ + ao0, l0 + SA_(b, h)); glds16(ap_ + ao1, l0 + SA_(b, h) + 8192); }
; #define STAGE_B(b, h, kt) { const u16* bp_ = ((h) ? B1 : B0) + (unsigned)(kt) * 64u; glds16(bp_ + bo0, l0 + SB_(b, h)); glds16(bp_ + bo1, l0 + SB_(b, h) + 8192); }
; #define LDA(dst, b, h) _Pragma("unroll") for (int m = 0; m < 4; ++m) _Pragma("unroll") for (int k = 0; k < 2; ++k) \
;     dst[m][k] = *(const bf16x8*)(lds + SA_(b, h) + lds_byte(wr * 64 + m * 16 + fr, k * 32 + fq * 8));
; #define LDB(dst, b, h) _Pragma("unroll") for (int n = 0; n < 2; ++n) _Pragma("unroll") for (int k = 0; k < 2; ++k) \
;     dst[n][k] = *(const bf16x8*)(lds + SB_(b, h) + lds_byte(wc * 32 + n * 16 + fr, k * 32 + fq * 8));
; #define MMA(ai, bj, At_, Bt_) { __builtin_amdgcn_s_setprio(1); \
;     _Pragma("unroll") for (int m = 0; m < 4; ++m) _Pragma("unroll") for (int n = 0; n < 2; ++n) _Pragma("unroll") for (int k = 0; k < 2; ++k) \
;       acc[ai][bj][m][n] = MFMA16(Bt_[n][k], At_[m][k], acc[ai][bj][m][n]); \
;     __builtin_amdgcn_s_setprio(0); }
; #define WAIT_V(n) asm volatile("s_waitcnt vmcnt(" #n ")" ::: "memory");
; #define WAIT_L(n) asm volatile("s_waitcnt lgkmcnt(" #n ")" ::: "memory");
; #define BAR __builtin_amdgcn_s_barrier();
; #define SCHED __builtin_amdgcn_sched_barrier(0);
; DI void gemm256(const u16* __restrict__ A, int lda, const u16* __restrict__ B0, const u16* __restrict__ B1, int ldb, int nt, acc_t& acc, char* lds) {
;     ...
;     BAR WAIT_L(0) MMA(1, 0, At, Bq0) BAR SCHED
;     STAGE_B(1, 1, t + 3)
;     WAIT_V(6) BAR MMA(1, 1, At, Bq1) BAR
;   }
;   { LDB(Bq0, 0, 0) LDA(At, 0, 0) STAGE_A(1, 1, nt - 1)
;     BAR WAIT_L(0) MMA(0, 0, At, Bq0) BAR
;     LDB(Bq1, 0, 1) BAR WAIT_L(0) MMA(0, 1, At, Bq1) BAR
	s_waitcnt lgkmcnt(0)
	s_waitcnt lgkmcnt(0)
	v_mfma_f32_16x16x32_bf16 v[60:63], v[142:145], v[182:185], v[60:63]
	v_mfma_f32_16x16x32_bf16 v[56:59], v[174:177], v[182:185], v[56:59]
	v_mfma_f32_16x16x32_bf16 v[52:55], v[142:145], v[190:193], v[52:55]
	v_mfma_f32_16x16x32_bf16 v[48:51], v[174:177], v[190:193], v[48:51]
	v_mfma_f32_16x16x32_bf16 v[44:47], v[142:145], v[198:201], v[44:47]
	v_mfma_f32_16x16x32_bf16 v[40:43], v[174:177], v[198:201], v[40:43]
	v_mfma_f32_16x16x32_bf16 v[36:39], v[142:145], v[206:209], v[36:39]
	v_mfma_f32_16x16x32_bf16 v[32:35], v[174:177], v[206:209], v[32:35]
	v_mfma_f32_16x16x32_bf16 v[60:63], v[170:173], v[186:189], v[60:63]
	v_mfma_f32_16x16x32_bf16 v[56:59], v[178:181], v[186:189], v[56:59]
	v_mfma_f32_16x16x32_bf16 v[52:55], v[170:173], v[194:197], v[52:55]
	v_mfma_f32_16x16x32_bf16 v[48:51], v[178:181], v[194:197], v[48:51]
	v_mfma_f32_16x16x32_bf16 v[44:47], v[170:173], v[202:205], v[44:47]
	v_mfma_f32_16x16x32_bf16 v[40:43], v[178:181], v[202:205], v[40:43]
	v_mfma_f32_16x16x32_bf16 v[36:39], v[170:173], v[210:213], v[36:39]
	v_mfma_f32_16x16x32_bf16 v[32:35], v[178:181], v[210:213], v[32:35]
	s_barrier
	v_readfirstlane_b32 s9, v163
	v_lshl_add_u64 v[142:143], v[238:239], 0, s[48:49]
	s_mov_b32 m0, s9
	v_readfirstlane_b32 s9, v164
	global_load_lds_dwordx4 v[142:143], off
	v_lshl_add_u64 v[142:143], v[240:241], 0, s[48:49]
	s_mov_b32 m0, s9
	s_nop 0
	global_load_lds_dwordx4 v[142:143], off
	s_waitcnt vmcnt(6)
	s_barrier
	v_mfma_f32_16x16x32_bf16 v[28:31], v[216:219], v[182:185], v[28:31]
	v_mfma_f32_16x16x32_bf16 v[24:27], v[230:233], v[182:185], v[24:27]
	v_mfma_f32_16x16x32_bf16 v[20:23], v[216:219], v[190:193], v[20:23]
	v_mfma_f32_16x16x32_bf16 v[16:19], v[230:233], v[190:193], v[16:19]
	v_mfma_f32_16x16x32_bf16 v[12:15], v[216:219], v[198:201], v[12:15]
	v_mfma_f32_16x16x32_bf16 v[8:11], v[230:233], v[198:201], v[8:11]
	v_mfma_f32_16x16x32_bf16 v[4:7], v[216:219], v[206:209], v[4:7]
	v_mfma_f32_16x16x32_bf16 v[0:3], v[230:233], v[206:209], v[0:3]
	v_mfma_f32_16x16x32_bf16 v[28:31], v[226:229], v[186:189], v[28:31]
	v_mfma_f32_16x16x32_bf16 v[24:27], v[234:237], v[186:189], v[24:27]
	v_mfma_f32_16x16x32_bf16 v[20:23], v[226:229], v[194:197], v[20:23]
	v_mfma_f32_16x16x32_bf16 v[16:19], v[234:237], v[194:197], v[16:19]
	v_mfma_f32_16x16x32_bf16 v[12:15], v[226:229], v[202:205], v[12:15]
	v_mfma_f32_16x16x32_bf16 v[8:11], v[234:237], v[202:205], v[8:11]
	v_mfma_f32_16x16x32_bf16 v[4:7], v[226:229], v[210:213], v[4:7]
	v_mfma_f32_16x16x32_bf16 v[0:3], v[234:237], v[210:213], v[0:3]
	s_add_i32 s7, s7, 2
	s_add_u32 s36, s36, 0x100
	s_addc_u32 s37, s37, 0
	s_cmp_lt_u32 s7, 12
	s_barrier
	s_cbranch_scc1 .LBB0_1172
	s_add_u32 s28, s28, 0x40780
	s_addc_u32 s29, s29, 0
	v_readfirstlane_b32 s7, v167
	v_lshl_add_u64 v[162:163], v[64:65], 1, s[28:29]
	s_mov_b32 m0, s7
	v_readfirstlane_b32 s7, v168
	ds_read_b128 v[132:135], v166
	ds_read_b128 v[136:139], v166 offset:1024
	ds_read_b128 v[142:145], v166 offset:2048
	ds_read_b128 v[152:155], v166 offset:3072
	ds_read_b128 v[158:161], v148
	ds_read_b128 v[170:173], v148 offset:1024
	ds_read_b128 v[174:177], v147
	ds_read_b128 v[178:181], v147 offset:1024
	ds_read_b128 v[182:185], v146
	ds_read_b128 v[186:189], v146 offset:1024
	ds_read_b128 v[190:193], v141
	ds_read_b128 v[194:197], v141 offset:1024
	global_load_lds_dwordx4 v[162:163], off
	v_lshl_add_u64 v[130:131], v[130:131], 1, s[28:29]
	s_mov_b32 m0, s7
	s_nop 0
	global_load_lds_dwordx4 v[130:131], off
	s_barrier
	s_waitcnt lgkmcnt(0)
	s_waitcnt lgkmcnt(0)
	v_mfma_f32_16x16x32_bf16 v[126:129], v[132:135], v[158:161], v[126:129]
	v_mfma_f32_16x16x32_bf16 v[122:125], v[142:145], v[158:161], v[122:125]
	v_mfma_f32_16x16x32_bf16 v[110:113], v[132:135], v[182:185], v[110:113]
	v_mfma_f32_16x16x32_bf16 v[106:109], v[142:145], v[182:185], v[106:109]
	v_mfma_f32_16x16x32_bf16 v[102:105], v[132:135], v[190:193], v[102:105]
	v_mfma_f32_16x16x32_bf16 v[98:101], v[142:145], v[190:193], v[98:101]
	v_mfma_f32_16x16x32_bf16 v[126:129], v[136:139], v[170:173], v[126:129]
	v_mfma_f32_16x16x32_bf16 v[122:125], v[152:155], v[170:173], v[122:125]
	v_mfma_f32_16x16x32_bf16 v[118:121], v[132:135], v[174:177], v[118:121]
	v_mfma_f32_16x16x32_bf16 v[114:117], v[142:145], v[174:177], v[114:117]
	v_mfma_f32_16x16x32_bf16 v[110:113], v[136:139], v[186:189], v[110:113]
	v_mfma_f32_16x16x32_bf16 v[106:109], v[152:155], v[186:189], v[106:109]
	v_mfma_f32_16x16x32_bf16 v[102:105], v[136:139], v[194:197], v[102:105]
	v_mfma_f32_16x16x32_bf16 v[98:101], v[152:155], v[194:197], v[98:101]
	v_mfma_f32_16x16x32_bf16 v[166:169], v[136:139], v[178:181], v[118:121]
	v_mfma_f32_16x16x32_bf16 v[198:201], v[152:155], v[178:181], v[114:117]
	s_barrier
	s_nop 0
	ds_read_b128 v[114:117], v165
	ds_read_b128 v[118:121], v165 offset:1024
	ds_read_b128 v[202:205], v165 offset:2048
	ds_read_b128 v[162:165], v165 offset:3072
	s_barrier
	s_waitcnt lgkmcnt(0)
	s_waitcnt lgkmcnt(0)
	v_mfma_f32_16x16x32_bf16 v[94:97], v[114:117], v[158:161], v[94:97]
	v_mfma_f32_16x16x32_bf16 v[90:93], v[202:205], v[158:161], v[90:93]
	v_mfma_f32_16x16x32_bf16 v[78:81], v[114:117], v[182:185], v[78:81]
	v_mfma_f32_16x16x32_bf16 v[74:77], v[202:205], v[182:185], v[74:77]
	v_mfma_f32_16x16x32_bf16 v[70:73], v[114:117], v[190:193], v[70:73]
	v_mfma_f32_16x16x32_bf16 v[66:69], v[202:205], v[190:193], v[66:69]
	v_mfma_f32_16x16x32_bf16 v[94:97], v[118:121], v[170:173], v[94:97]
	v_mfma_f32_16x16x32_bf16 v[90:93], v[162:165], v[170:173], v[90:93]
	v_mfma_f32_16x16x32_bf16 v[86:89], v[114:117], v[174:177], v[86:89]
	v_mfma_f32_16x16x32_bf16 v[82:85], v[202:205], v[174:177], v[82:85]
	v_mfma_f32_16x16x32_bf16 v[78:81], v[118:121], v[186:189], v[78:81]
	v_mfma_f32_16x16x32_bf16 v[74:77], v[162:165], v[186:189], v[74:77]
	v_mfma_f32_16x16x32_bf16 v[70:73], v[118:121], v[194:197], v[70:73]
	v_mfma_f32_16x16x32_bf16 v[66:69], v[162:165], v[194:197], v[66:69]
	v_mfma_f32_16x16x32_bf16 v[158:161], v[118:121], v[178:181], v[86:89]
	v_mfma_f32_16x16x32_bf16 v[170:173], v[162:165], v[178:181], v[82:85]
	s_barrier
; #define LDA(dst, b, h) _Pragma("unroll") for (int m = 0; m < 4; ++m) _Pragma("unroll") for (int k = 0; k < 2; ++k) \
;     dst[m][k] = *(const bf16x8*)(lds + SA_(b, h) + lds_byte(wr * 64 + m * 16 + fr, k * 32 + fq * 8));
; #define LDB(dst, b, h) _Pragma("unroll") for (int n = 0; n < 2; ++n) _Pragma("unroll") for (int k = 0; k < 2; ++k) \
;     dst[n][k] = *(const bf16x8*)(lds + SB_(b, h) + lds_byte(wc * 32 + n * 16 + fr, k * 32 + fq * 8));
; #define MMA(ai, bj, At_, Bt_) { __builtin_amdgcn_s_setprio(1); \
;     _Pragma("unroll") for (int m = 0; m < 4; ++m) _Pragma("unroll") for (int n = 0; n < 2; ++n) _Pragma("unroll") for (int k = 0; k < 2; ++k) \
;       acc[ai][bj][m][n] = MFMA16(Bt_[n][k], At_[m][k], acc[ai][bj][m][n]); \
;     __builtin_amdgcn_s_setprio(0); }
; #define WAIT_V(n) asm volatile("s_waitcnt vmcnt(" #n ")" ::: "memory");
; #define WAIT_L(n) asm volatile("s_waitcnt lgkmcnt(" #n ")" ::: "memory");
; #define BAR __builtin_amdgcn_s_barrier();
; DI void gemm256(const u16* __restrict__ A, int lda, const u16* __restrict__ B0, const u16* __restrict__ B1, int ldb, int nt, acc_t& acc, char* lds) {
;     ...
;     LDA(At, 0, 1) WAIT_V(4) BAR WAIT_L(0) MMA(1, 0, At, Bq0) MMA(1, 1, At, Bq1) BAR }
;   { LDB(Bq0, 1, 0) LDA(At, 1, 0) WAIT_V(2) BAR WAIT_L(0) MMA(0, 0, At, Bq0) BAR
	s_nop 0
	ds_read_b128 v[82:85], v148 offset:16384
	ds_read_b128 v[86:89], v148 offset:17408
	ds_read_b128 v[174:177], v147 offset:16384
	ds_read_b128 v[178:181], v147 offset:17408
	ds_read_b128 v[182:185], v146 offset:16384
	ds_read_b128 v[186:189], v146 offset:17408
	ds_read_b128 v[190:193], v141 offset:16384
	ds_read_b128 v[194:197], v141 offset:17408
	s_waitcnt vmcnt(4)
	s_barrier
	s_waitcnt lgkmcnt(0)
	s_waitcnt lgkmcnt(0)
	v_mfma_f32_16x16x32_bf16 v[36:39], v[132:135], v[190:193], v[36:39]
	v_mfma_f32_16x16x32_bf16 v[32:35], v[142:145], v[190:193], v[32:35]
	v_mfma_f32_16x16x32_bf16 v[60:63], v[132:135], v[82:85], v[60:63]
	v_mfma_f32_16x16x32_bf16 v[56:59], v[142:145], v[82:85], v[56:59]
	v_mfma_f32_16x16x32_bf16 v[52:55], v[132:135], v[174:177], v[52:55]
	v_mfma_f32_16x16x32_bf16 v[48:51], v[142:145], v[174:177], v[48:51]
	v_mfma_f32_16x16x32_bf16 v[44:47], v[132:135], v[182:185], v[44:47]
	v_mfma_f32_16x16x32_bf16 v[40:43], v[142:145], v[182:185], v[40:43]
	v_mfma_f32_16x16x32_bf16 v[36:39], v[136:139], v[194:197], v[36:39]
	v_mfma_f32_16x16x32_bf16 v[32:35], v[152:155], v[194:197], v[32:35]
	v_mfma_f32_16x16x32_bf16 v[206:209], v[136:139], v[86:89], v[60:63]
	v_mfma_f32_16x16x32_bf16 v[210:213], v[152:155], v[86:89], v[56:59]
	v_mfma_f32_16x16x32_bf16 v[216:219], v[136:139], v[178:181], v[52:55]
	v_mfma_f32_16x16x32_bf16 v[226:229], v[152:155], v[178:181], v[48:51]
	v_mfma_f32_16x16x32_bf16 v[230:233], v[136:139], v[186:189], v[44:47]
	v_mfma_f32_16x16x32_bf16 v[234:237], v[152:155], v[186:189], v[40:43]
	v_mfma_f32_16x16x32_bf16 v[12:15], v[114:117], v[182:185], v[12:15]
	v_mfma_f32_16x16x32_bf16 v[8:11], v[202:205], v[182:185], v[8:11]
	v_mfma_f32_16x16x32_bf16 v[28:31], v[114:117], v[82:85], v[28:31]
	v_mfma_f32_16x16x32_bf16 v[24:27], v[202:205], v[82:85], v[24:27]
	v_mfma_f32_16x16x32_bf16 v[20:23], v[114:117], v[174:177], v[20:23]
	v_mfma_f32_16x16x32_bf16 v[16:19], v[202:205], v[174:177], v[16:19]
	v_mfma_f32_16x16x32_bf16 v[12:15], v[118:121], v[186:189], v[12:15]
	v_mfma_f32_16x16x32_bf16 v[8:11], v[162:165], v[186:189], v[8:11]
	v_mfma_f32_16x16x32_bf16 v[4:7], v[114:117], v[190:193], v[4:7]
	v_mfma_f32_16x16x32_bf16 v[0:3], v[202:205], v[190:193], v[0:3]
	v_mfma_f32_16x16x32_bf16 v[130:133], v[118:121], v[86:89], v[28:31]
	v_mfma_f32_16x16x32_bf16 v[134:137], v[162:165], v[86:89], v[24:27]
	v_mfma_f32_16x16x32_bf16 v[142:145], v[118:121], v[178:181], v[20:23]
	v_mfma_f32_16x16x32_bf16 v[152:155], v[162:165], v[178:181], v[16:19]
	v_mfma_f32_16x16x32_bf16 v[174:177], v[118:121], v[194:197], v[4:7]
	v_mfma_f32_16x16x32_bf16 v[162:165], v[162:165], v[194:197], v[0:3]
	s_barrier
	s_nop 0
	ds_read_b128 v[0:3], v156
	ds_read_b128 v[4:7], v156 offset:1024
	ds_read_b128 v[178:181], v156 offset:2048
	ds_read_b128 v[182:185], v156 offset:3072
	ds_read_b128 v[16:19], v148 offset:32768
	ds_read_b128 v[20:23], v148 offset:33792
	ds_read_b128 v[40:43], v147 offset:32768
	ds_read_b128 v[44:47], v147 offset:33792
	ds_read_b128 v[56:59], v146 offset:32768
	ds_read_b128 v[60:63], v146 offset:33792
	ds_read_b128 v[186:189], v141 offset:32768
	ds_read_b128 v[190:193], v141 offset:33792
	s_waitcnt vmcnt(2)
	s_barrier
	s_waitcnt lgkmcnt(0)
	s_waitcnt lgkmcnt(0)
	v_mfma_f32_16x16x32_bf16 v[24:27], v[0:3], v[16:19], v[126:129]
	v_mfma_f32_16x16x32_bf16 v[114:117], v[4:7], v[20:23], v[24:27]
	v_mfma_f32_16x16x32_bf16 v[24:27], v[178:181], v[16:19], v[122:125]
	v_mfma_f32_16x16x32_bf16 v[118:121], v[182:185], v[20:23], v[24:27]
	v_mfma_f32_16x16x32_bf16 v[24:27], v[0:3], v[40:43], v[166:169]
	v_mfma_f32_16x16x32_bf16 v[82:85], v[4:7], v[44:47], v[24:27]
	v_mfma_f32_16x16x32_bf16 v[24:27], v[178:181], v[40:43], v[198:201]
	v_mfma_f32_16x16x32_bf16 v[86:89], v[182:185], v[44:47], v[24:27]
	v_mfma_f32_16x16x32_bf16 v[24:27], v[0:3], v[56:59], v[110:113]
	v_mfma_f32_16x16x32_bf16 v[48:51], v[4:7], v[60:63], v[24:27]
	v_mfma_f32_16x16x32_bf16 v[24:27], v[178:181], v[56:59], v[106:109]
	v_mfma_f32_16x16x32_bf16 v[52:55], v[182:185], v[60:63], v[24:27]
	v_mfma_f32_16x16x32_bf16 v[24:27], v[0:3], v[186:189], v[102:105]
	v_mfma_f32_16x16x32_bf16 v[28:31], v[178:181], v[186:189], v[98:101]
	v_mfma_f32_16x16x32_bf16 v[24:27], v[4:7], v[190:193], v[24:27]
	v_mfma_f32_16x16x32_bf16 v[28:31], v[182:185], v[190:193], v[28:31]
	s_barrier
; #define LDA(dst, b, h) _Pragma("unroll") for (int m = 0; m < 4; ++m) _Pragma("unroll") for (int k = 0; k < 2; ++k) \
;     dst[m][k] = *(const bf16x8*)(lds + SA_(b, h) + lds_byte(wr * 64 + m * 16 + fr, k * 32 + fq * 8));
; #define LDB(dst, b, h) _Pragma("unroll") for (int n = 0; n < 2; ++n) _Pragma("unroll") for (int k = 0; k < 2; ++k) \
;     dst[n][k] = *(const bf16x8*)(lds + SB_(b, h) + lds_byte(wc * 32 + n * 16 + fr, k * 32 + fq * 8));
; #define MMA(ai, bj, At_, Bt_) { __builtin_amdgcn_s_setprio(1); \
;     _Pragma("unroll") for (int m = 0; m < 4; ++m) _Pragma("unroll") for (int n = 0; n < 2; ++n) _Pragma("unroll") for (int k = 0; k < 2; ++k) \
;       acc[ai][bj][m][n] = MFMA16(Bt_[n][k], At_[m][k], acc[ai][bj][m][n]); \
;     __builtin_amdgcn_s_setprio(0); }
; #define WAIT_V(n) asm volatile("s_waitcnt vmcnt(" #n ")" ::: "memory");
; #define WAIT_L(n) asm volatile("s_waitcnt lgkmcnt(" #n ")" ::: "memory");
; #define BAR __builtin_amdgcn_s_barrier();
; DI void gemm256(const u16* __restrict__ A, int lda, const u16* __restrict__ B0, const u16* __restrict__ B1, int ldb, int nt, acc_t& acc, char* lds) {
;     ...
;     LDB(Bq1, 1, 1) WAIT_V(0) BAR WAIT_L(0) MMA(0, 1, At, Bq1) BAR
;     LDA(At, 1, 1) BAR WAIT_L(0) MMA(1, 0, At, Bq0) MMA(1, 1, At, Bq1) BAR }
;   if (wr == 0) BAR
	ds_read_b128 v[166:169], v151
	ds_read_b128 v[194:197], v151 offset:1024
	ds_read_b128 v[198:201], v151 offset:2048
	ds_read_b128 v[202:205], v151 offset:3072
	s_waitcnt vmcnt(0)
	s_barrier
	s_waitcnt lgkmcnt(0)
	s_waitcnt lgkmcnt(0)
	v_mfma_f32_16x16x32_bf16 v[94:97], v[166:169], v[16:19], v[94:97]
	v_mfma_f32_16x16x32_bf16 v[16:19], v[198:201], v[16:19], v[90:93]
	v_mfma_f32_16x16x32_bf16 v[126:129], v[202:205], v[20:23], v[16:19]
	v_mfma_f32_16x16x32_bf16 v[16:19], v[166:169], v[40:43], v[158:161]
	v_mfma_f32_16x16x32_bf16 v[106:109], v[194:197], v[44:47], v[16:19]
	v_mfma_f32_16x16x32_bf16 v[16:19], v[198:201], v[40:43], v[170:173]
	v_mfma_f32_16x16x32_bf16 v[110:113], v[202:205], v[44:47], v[16:19]
	v_mfma_f32_16x16x32_bf16 v[16:19], v[166:169], v[56:59], v[78:81]
	v_mfma_f32_16x16x32_bf16 v[90:93], v[194:197], v[60:63], v[16:19]
	v_mfma_f32_16x16x32_bf16 v[16:19], v[198:201], v[56:59], v[74:77]
	v_mfma_f32_16x16x32_bf16 v[122:125], v[194:197], v[20:23], v[94:97]
	v_mfma_f32_16x16x32_bf16 v[94:97], v[202:205], v[60:63], v[16:19]
	v_mfma_f32_16x16x32_bf16 v[16:19], v[166:169], v[186:189], v[70:73]
	v_mfma_f32_16x16x32_bf16 v[56:59], v[194:197], v[190:193], v[16:19]
	v_mfma_f32_16x16x32_bf16 v[16:19], v[198:201], v[186:189], v[66:69]
	v_mfma_f32_16x16x32_bf16 v[60:63], v[202:205], v[190:193], v[16:19]
	s_barrier
	ds_read_b128 v[66:69], v148 offset:49152
	ds_read_b128 v[70:73], v148 offset:50176
	ds_read_b128 v[148:151], v147 offset:49152
	ds_read_b128 v[156:159], v147 offset:50176
	ds_read_b128 v[170:173], v146 offset:49152
	ds_read_b128 v[186:189], v146 offset:50176
	ds_read_b128 v[190:193], v141 offset:49152
	ds_read_b128 v[238:241], v141 offset:50176
	s_barrier
	s_waitcnt lgkmcnt(0)
	s_waitcnt lgkmcnt(0)
	v_mfma_f32_16x16x32_bf16 v[16:19], v[0:3], v[66:69], v[206:209]
	v_mfma_f32_16x16x32_bf16 v[74:77], v[4:7], v[70:73], v[16:19]
	v_mfma_f32_16x16x32_bf16 v[16:19], v[178:181], v[66:69], v[210:213]
	v_mfma_f32_16x16x32_bf16 v[78:81], v[182:185], v[70:73], v[16:19]
	v_mfma_f32_16x16x32_bf16 v[16:19], v[0:3], v[148:151], v[216:219]
	v_mfma_f32_16x16x32_bf16 v[40:43], v[4:7], v[156:159], v[16:19]
	v_mfma_f32_16x16x32_bf16 v[16:19], v[178:181], v[148:151], v[226:229]
	v_mfma_f32_16x16x32_bf16 v[44:47], v[182:185], v[156:159], v[16:19]
	v_mfma_f32_16x16x32_bf16 v[16:19], v[0:3], v[170:173], v[230:233]
	v_mfma_f32_16x16x32_bf16 v[0:3], v[0:3], v[190:193], v[36:39]
	v_mfma_f32_16x16x32_bf16 v[16:19], v[4:7], v[186:189], v[16:19]
	v_mfma_f32_16x16x32_bf16 v[20:23], v[178:181], v[170:173], v[234:237]
	v_mfma_f32_16x16x32_bf16 v[0:3], v[4:7], v[238:241], v[0:3]
	v_mfma_f32_16x16x32_bf16 v[4:7], v[178:181], v[190:193], v[32:35]
	v_mfma_f32_16x16x32_bf16 v[20:23], v[182:185], v[186:189], v[20:23]
	v_mfma_f32_16x16x32_bf16 v[4:7], v[182:185], v[238:241], v[4:7]
	v_mfma_f32_16x16x32_bf16 v[32:35], v[166:169], v[66:69], v[130:133]
	v_mfma_f32_16x16x32_bf16 v[98:101], v[194:197], v[70:73], v[32:35]
	v_mfma_f32_16x16x32_bf16 v[32:35], v[198:201], v[66:69], v[134:137]
	v_mfma_f32_16x16x32_bf16 v[102:105], v[202:205], v[70:73], v[32:35]
	v_mfma_f32_16x16x32_bf16 v[32:35], v[166:169], v[148:151], v[142:145]
	v_mfma_f32_16x16x32_bf16 v[66:69], v[194:197], v[156:159], v[32:35]
	v_mfma_f32_16x16x32_bf16 v[32:35], v[198:201], v[148:151], v[152:155]
	v_mfma_f32_16x16x32_bf16 v[12:15], v[166:169], v[170:173], v[12:15]
	v_mfma_f32_16x16x32_bf16 v[8:11], v[198:201], v[170:173], v[8:11]
	v_mfma_f32_16x16x32_bf16 v[70:73], v[202:205], v[156:159], v[32:35]
	v_mfma_f32_16x16x32_bf16 v[32:35], v[194:197], v[186:189], v[12:15]
	v_mfma_f32_16x16x32_bf16 v[36:39], v[202:205], v[186:189], v[8:11]
	v_mfma_f32_16x16x32_bf16 v[8:11], v[166:169], v[190:193], v[174:177]
	v_mfma_f32_16x16x32_bf16 v[12:15], v[198:201], v[190:193], v[162:165]
	v_mfma_f32_16x16x32_bf16 v[8:11], v[194:197], v[238:241], v[8:11]
	v_mfma_f32_16x16x32_bf16 v[12:15], v[202:205], v[238:241], v[12:15]
	s_movk_i32 s7, 0x100
	v_cmp_gt_u32_e32 vcc, s7, v140
	s_barrier
	s_and_saveexec_b64 s[28:29], vcc
	s_cbranch_execz .LBB0_1175
	s_barrier

; #define STAGE_A(b, h, kt) { const u16* ap_ = A + (size_t)((h) * ahalf + (unsigned)(kt) * 64u); glds16(ap_ + ao0, l0 + SA_(b, h)); glds16(ap_ + ao1, l0 + SA_(b, h) + 8192); }
; #define STAGE_B(b, h, kt) { const u16* bp_ = ((h) ? B1 : B0) + (unsigned)(kt) * 64u; glds16(bp_ + bo0, l0 + SB_(b, h)); glds16(bp_ + bo1, l0 + SB_(b, h) + 8192); }
; #define LDA(dst, b, h) _Pragma("unroll") for (int m = 0; m < 4; ++m) _Pragma("unroll") for (int k = 0; k < 2; ++k) \
;     dst[m][k] = *(const bf16x8*)(lds + SA_(b, h) + lds_byte(wr * 64 + m * 16 + fr, k * 32 + fq * 8));
; #define LDB(dst, b, h) _Pragma("unroll") for (int n = 0; n < 2; ++n) _Pragma("unroll") for (int k = 0; k < 2; ++k) \
;     dst[n][k] = *(const bf16x8*)(lds + SB_(b, h) + lds_byte(wc * 32 + n * 16 + fr, k * 32 + fq * 8));
; #define MMA(ai, bj, At_, Bt_) { __builtin_amdgcn_s_setprio(1); \
;     _Pragma("unroll") for (int m = 0; m < 4; ++m) _Pragma("unroll") for (int n = 0; n < 2; ++n) _Pragma("unroll") for (int k = 0; k < 2; ++k) \
;       acc[ai][bj][m][n] = MFMA16(Bt_[n][k], At_[m][k], acc[ai][bj][m][n]); \
;     __builtin_amdgcn_s_setprio(0); }
; #define WAIT_V(n) asm volatile("s_waitcnt vmcnt(" #n ")" ::: "memory");
; #define WAIT_L(n) asm volatile("s_waitcnt lgkmcnt(" #n ")" ::: "memory");
; #define BAR __builtin_amdgcn_s_barrier();
; #define SCHED __builtin_amdgcn_sched_barrier(0);
; DI void gemm256(const u16* __restrict__ A, int lda, const u16* __restrict__ B0, const u16* __restrict__ B1, int ldb, int nt, acc_t& acc, char* lds) {
;     ...
;   WAIT_V(0)
;   STAGE_B(0, 0, 0) STAGE_A(0, 0, 0) STAGE_B(0, 1, 0) STAGE_A(0, 1, 0)
;   if (wr == 1) BAR
;   WAIT_V(4) BAR
;   STAGE_B(1, 0, 1) STAGE_A(1, 0, 1) STAGE_B(1, 1, 1)
;   WAIT_V(6) BAR
;   for (int t = 0; t < nt - 2; t += 2) {
;     LDB(Bq0, 0, 0) SCHED LDA(At, 0, 0) STAGE_A(1, 1, t + 1)
;     WAIT_L(8) BAR WAIT_L(0) MMA(0, 0, At, Bq0) BAR SCHED
;     LDB(Bq1, 0, 1) STAGE_B(0, 0, t + 2)
;     BAR WAIT_L(0) MMA(0, 1, At, Bq1) BAR
;     LDA(At, 0, 1) STAGE_A(0, 0, t + 2)
.LBB0_1255:
	s_or_b64 exec, exec, s[28:29]
	v_add_u32_e32 v29, 0x18000, v20
	s_mov_b64 s[48:49], 0x80
	v_readfirstlane_b32 s47, v29
	v_add_u32_e32 v29, 0x1a000, v20
	v_lshl_add_u64 v[26:27], v[12:13], 0, s[48:49]
	s_mov_b32 m0, s47
	v_readfirstlane_b32 s46, v29
	v_add_u32_e32 v29, 0x8000, v20
	s_waitcnt vmcnt(4)
	s_barrier
	global_load_lds_dwordx4 v[26:27], off
	v_lshl_add_u64 v[26:27], v[14:15], 0, s[48:49]
	s_mov_b32 m0, s46
	v_readfirstlane_b32 s44, v29
	v_add_u32_e32 v29, 0xa000, v20
	global_load_lds_dwordx4 v[26:27], off
	v_lshl_add_u64 v[26:27], v[8:9], 0, s[48:49]
	s_mov_b32 m0, s44
	v_readfirstlane_b32 s29, v29
	v_add_u32_e32 v29, 0x1c000, v20
	global_load_lds_dwordx4 v[26:27], off
	v_lshl_add_u64 v[26:27], v[10:11], 0, s[48:49]
	s_mov_b32 m0, s29
	v_readfirstlane_b32 s28, v29
	v_add_u32_e32 v29, 0x1e000, v20
	global_load_lds_dwordx4 v[26:27], off
	v_lshl_add_u64 v[26:27], v[4:5], 0, s[48:49]
	s_mov_b32 m0, s28
	v_readfirstlane_b32 s2, v29
	global_load_lds_dwordx4 v[26:27], off
	v_lshl_add_u64 v[26:27], v[6:7], 0, s[48:49]
	s_mov_b32 m0, s2
	v_and_b32_e32 v17, 15, v130
	global_load_lds_dwordx4 v[26:27], off
	v_lshlrev_b32_e32 v26, 2, v130
	v_and_b32_e32 v28, 48, v130
	v_lshlrev_b32_e32 v17, 6, v17
	v_and_b32_e32 v26, 32, v26
	v_lshlrev_b32_e32 v29, 6, v130
	v_bitop3_b32 v27, v17, v26, v28 bitop3:0x36
	s_add_i32 s48, 0, 0x10000
	v_and_b32_e32 v30, 0x3000, v29
	v_and_b32_e32 v29, 0x3c0, v29
	s_add_i32 s49, 0, 0x14000
	s_add_i32 s52, 0, 0x18000
	s_add_i32 s53, 0, 0x1c000
	v_add3_u32 v131, s48, v27, v30
	v_lshlrev_b32_e32 v16, 13, v16
	v_bitop3_b32 v26, v29, v26, v28 bitop3:0x36
	s_waitcnt vmcnt(6)
	s_barrier
	v_add3_u32 v17, 0, v27, v16
	v_add3_u32 v16, 0, v26, v16
	v_add3_u32 v212, s49, v27, v30
	v_add3_u32 v213, s52, v27, v30
	v_add3_u32 v222, s53, v27, v30
	ds_read_b128 v[26:29], v131
	ds_read_b128 v[30:33], v131 offset:1024
	ds_read_b128 v[34:37], v131 offset:2048
	ds_read_b128 v[38:41], v131 offset:3072
	v_add_u32_e32 v78, 0xe000, v20
	v_add_u32_e32 v64, 0xc000, v20
	s_add_u32 s56, s22, 0x10080
	s_addc_u32 s57, s23, 0
	v_readfirstlane_b32 s54, v64
	v_lshl_add_u64 v[62:63], s[56:57], 0, v[0:1]
	s_mov_b32 m0, s54
	v_readfirstlane_b32 s45, v78
	ds_read_b128 v[42:45], v17
	ds_read_b128 v[46:49], v17 offset:1024
	ds_read_b128 v[50:53], v16 offset:2048
	ds_read_b128 v[54:57], v16 offset:3072
	ds_read_b128 v[58:61], v16 offset:4096
	ds_read_b128 v[66:69], v16 offset:5120
	ds_read_b128 v[70:73], v16 offset:6144
	ds_read_b128 v[74:77], v16 offset:7168
	global_load_lds_dwordx4 v[62:63], off
	v_lshl_add_u64 v[62:63], s[56:57], 0, v[2:3]
	s_mov_b32 m0, s45
	s_nop 0
	global_load_lds_dwordx4 v[62:63], off
	s_waitcnt lgkmcnt(8)
	s_barrier
	s_waitcnt lgkmcnt(0)
	s_waitcnt lgkmcnt(0)
	v_mfma_f32_16x16x32_bf16 v[78:81], v[26:29], v[42:45], 0
	v_mfma_f32_16x16x32_bf16 v[82:85], v[34:37], v[42:45], 0
	v_mfma_f32_16x16x32_bf16 v[86:89], v[26:29], v[50:53], 0
	v_mfma_f32_16x16x32_bf16 v[90:93], v[34:37], v[50:53], 0
	v_mfma_f32_16x16x32_bf16 v[94:97], v[26:29], v[58:61], 0
	v_mfma_f32_16x16x32_bf16 v[98:101], v[34:37], v[58:61], 0
	v_mfma_f32_16x16x32_bf16 v[102:105], v[26:29], v[70:73], 0
	v_mfma_f32_16x16x32_bf16 v[106:109], v[34:37], v[70:73], 0
	v_mfma_f32_16x16x32_bf16 v[78:81], v[30:33], v[46:49], v[78:81]
	v_mfma_f32_16x16x32_bf16 v[82:85], v[38:41], v[46:49], v[82:85]
	v_mfma_f32_16x16x32_bf16 v[86:89], v[30:33], v[54:57], v[86:89]
	v_mfma_f32_16x16x32_bf16 v[90:93], v[38:41], v[54:57], v[90:93]
	v_mfma_f32_16x16x32_bf16 v[94:97], v[30:33], v[66:69], v[94:97]
	v_mfma_f32_16x16x32_bf16 v[98:101], v[38:41], v[66:69], v[98:101]
	v_mfma_f32_16x16x32_bf16 v[102:105], v[30:33], v[74:77], v[102:105]
	v_mfma_f32_16x16x32_bf16 v[106:109], v[38:41], v[74:77], v[106:109]
	s_barrier
	s_mov_b64 s[56:57], 0x100
	v_readfirstlane_b32 s55, v24
	v_lshl_add_u64 v[62:63], v[12:13], 0, s[56:57]
	s_mov_b32 m0, s55
	v_readfirstlane_b32 s55, v25
	ds_read_b128 v[110:113], v212
	ds_read_b128 v[114:117], v212 offset:1024
	ds_read_b128 v[118:121], v212 offset:2048
	ds_read_b128 v[122:125], v212 offset:3072
	global_load_lds_dwordx4 v[62:63], off
	v_lshl_add_u64 v[62:63], v[14:15], 0, s[56:57]
	s_mov_b32 m0, s55
	s_nop 0
	global_load_lds_dwordx4 v[62:63], off
	s_barrier
	s_waitcnt lgkmcnt(0)
	s_waitcnt lgkmcnt(0)
	v_mfma_f32_16x16x32_bf16 v[126:129], v[110:113], v[42:45], 0
	v_mfma_f32_16x16x32_bf16 v[42:45], v[118:121], v[42:45], 0
	v_mfma_f32_16x16x32_bf16 v[126:129], v[114:117], v[46:49], v[126:129]
	v_mfma_f32_16x16x32_bf16 v[42:45], v[122:125], v[46:49], v[42:45]
	v_mfma_f32_16x16x32_bf16 v[46:49], v[110:113], v[50:53], 0
	v_mfma_f32_16x16x32_bf16 v[50:53], v[118:121], v[50:53], 0
	v_mfma_f32_16x16x32_bf16 v[46:49], v[114:117], v[54:57], v[46:49]
	v_mfma_f32_16x16x32_bf16 v[50:53], v[122:125], v[54:57], v[50:53]
	v_mfma_f32_16x16x32_bf16 v[54:57], v[110:113], v[58:61], 0
	v_mfma_f32_16x16x32_bf16 v[58:61], v[118:121], v[58:61], 0
	v_mfma_f32_16x16x32_bf16 v[54:57], v[114:117], v[66:69], v[54:57]
	v_mfma_f32_16x16x32_bf16 v[58:61], v[122:125], v[66:69], v[58:61]
	v_mfma_f32_16x16x32_bf16 v[66:69], v[110:113], v[70:73], 0
	v_mfma_f32_16x16x32_bf16 v[70:73], v[118:121], v[70:73], 0
	v_mfma_f32_16x16x32_bf16 v[66:69], v[114:117], v[74:77], v[66:69]
	v_mfma_f32_16x16x32_bf16 v[70:73], v[122:125], v[74:77], v[70:73]
	v_readfirstlane_b32 s55, v20
	v_lshl_add_u64 v[24:25], v[8:9], 0, s[56:57]
	s_mov_b32 m0, s55
	v_readfirstlane_b32 s55, v23
	s_barrier
; #define STAGE_A(b, h, kt) { const u16* ap_ = A + (size_t)((h) * ahalf + (unsigned)(kt) * 64u); glds16(ap_ + ao0, l0 + SA_(b, h)); glds16(ap_ + ao1, l0 + SA_(b, h) + 8192); }
; #define STAGE_B(b, h, kt) { const u16* bp_ = ((h) ? B1 : B0) + (unsigned)(kt) * 64u; glds16(bp_ + bo0, l0 + SB_(b, h)); glds16(bp_ + bo1, l0 + SB_(b, h) + 8192); }
; #define LDA(dst, b, h) _Pragma("unroll") for (int m = 0; m < 4; ++m) _Pragma("unroll") for (int k = 0; k < 2; ++k) \
;     dst[m][k] = *(const bf16x8*)(lds + SA_(b, h) + lds_byte(wr * 64 + m * 16 + fr, k * 32 + fq * 8));
; #define LDB(dst, b, h) _Pragma("unroll") for (int n = 0; n < 2; ++n) _Pragma("unroll") for (int k = 0; k < 2; ++k) \
;     dst[n][k] = *(const bf16x8*)(lds + SB_(b, h) + lds_byte(wc * 32 + n * 16 + fr, k * 32 + fq * 8));
; #define MMA(ai, bj, At_, Bt_) { __builtin_amdgcn_s_setprio(1); \
;     _Pragma("unroll") for (int m = 0; m < 4; ++m) _Pragma("unroll") for (int n = 0; n < 2; ++n) _Pragma("unroll") for (int k = 0; k < 2; ++k) \
;       acc[ai][bj][m][n] = MFMA16(Bt_[n][k], At_[m][k], acc[ai][bj][m][n]); \
;     __builtin_amdgcn_s_setprio(0); }
; #define WAIT_V(n) asm volatile("s_waitcnt vmcnt(" #n ")" ::: "memory");
; #define WAIT_L(n) asm volatile("s_waitcnt lgkmcnt(" #n ")" ::: "memory");
; #define BAR __builtin_amdgcn_s_barrier();
; #define SCHED __builtin_amdgcn_sched_barrier(0);
; DI void gemm256(const u16* __restrict__ A, int lda, const u16* __restrict__ B0, const u16* __restrict__ B1, int ldb, int nt, acc_t& acc, char* lds) {
;     ...
;     LDA(At, 0, 1) STAGE_A(0, 0, t + 2)
;     BAR WAIT_L(0) MMA(1, 0, At, Bq0) BAR SCHED
;     STAGE_B(0, 1, t + 2)
;     WAIT_V(6) BAR MMA(1, 1, At, Bq1) BAR
;     LDB(Bq0, 1, 0) SCHED LDA(At, 1, 0) STAGE_A(0, 1, t + 2)
;     WAIT_L(8) BAR WAIT_L(0) MMA(0, 0, At, Bq0) BAR SCHED
;     LDB(Bq1, 1, 1) STAGE_B(1, 0, t + 3)
	ds_read_b128 v[74:77], v17 offset:16384
	ds_read_b128 v[132:135], v17 offset:17408
	ds_read_b128 v[136:139], v16 offset:18432
	ds_read_b128 v[140:143], v16 offset:19456
	ds_read_b128 v[144:147], v16 offset:20480
	ds_read_b128 v[148:151], v16 offset:21504
	ds_read_b128 v[152:155], v16 offset:22528
	ds_read_b128 v[156:159], v16 offset:23552
	global_load_lds_dwordx4 v[24:25], off
	v_lshl_add_u64 v[24:25], v[10:11], 0, s[56:57]
	s_mov_b32 m0, s55
	s_nop 0
	global_load_lds_dwordx4 v[24:25], off
	s_barrier
	s_waitcnt lgkmcnt(0)
	s_waitcnt lgkmcnt(0)
	v_mfma_f32_16x16x32_bf16 v[160:163], v[26:29], v[74:77], 0
	v_mfma_f32_16x16x32_bf16 v[168:171], v[26:29], v[136:139], 0
	v_mfma_f32_16x16x32_bf16 v[176:179], v[26:29], v[144:147], 0
	v_mfma_f32_16x16x32_bf16 v[24:27], v[26:29], v[152:155], 0
	v_mfma_f32_16x16x32_bf16 v[160:163], v[30:33], v[132:135], v[160:163]
	v_mfma_f32_16x16x32_bf16 v[168:171], v[30:33], v[140:143], v[168:171]
	v_mfma_f32_16x16x32_bf16 v[176:179], v[30:33], v[148:151], v[176:179]
	v_mfma_f32_16x16x32_bf16 v[24:27], v[30:33], v[156:159], v[24:27]
	v_mfma_f32_16x16x32_bf16 v[28:31], v[34:37], v[152:155], 0
	v_mfma_f32_16x16x32_bf16 v[164:167], v[34:37], v[74:77], 0
	v_mfma_f32_16x16x32_bf16 v[172:175], v[34:37], v[136:139], 0
	v_mfma_f32_16x16x32_bf16 v[180:183], v[34:37], v[144:147], 0
	v_mfma_f32_16x16x32_bf16 v[28:31], v[38:41], v[156:159], v[28:31]
	v_mfma_f32_16x16x32_bf16 v[164:167], v[38:41], v[132:135], v[164:167]
	v_mfma_f32_16x16x32_bf16 v[172:175], v[38:41], v[140:143], v[172:175]
	v_mfma_f32_16x16x32_bf16 v[180:183], v[38:41], v[148:151], v[180:183]
	s_barrier
	v_readfirstlane_b32 s55, v21
	v_lshl_add_u64 v[32:33], v[4:5], 0, s[56:57]
	s_mov_b32 m0, s55
	v_readfirstlane_b32 s55, v22
	global_load_lds_dwordx4 v[32:33], off
	v_lshl_add_u64 v[20:21], v[6:7], 0, s[56:57]
	s_mov_b32 m0, s55
	s_nop 0
	global_load_lds_dwordx4 v[20:21], off
	s_waitcnt vmcnt(6)
	s_barrier
	v_mfma_f32_16x16x32_bf16 v[20:23], v[110:113], v[74:77], 0
	v_mfma_f32_16x16x32_bf16 v[32:35], v[118:121], v[74:77], 0
	v_mfma_f32_16x16x32_bf16 v[20:23], v[114:117], v[132:135], v[20:23]
	v_mfma_f32_16x16x32_bf16 v[32:35], v[122:125], v[132:135], v[32:35]
	v_mfma_f32_16x16x32_bf16 v[36:39], v[110:113], v[136:139], 0
	v_mfma_f32_16x16x32_bf16 v[132:135], v[110:113], v[144:147], 0
	v_mfma_f32_16x16x32_bf16 v[110:113], v[110:113], v[152:155], 0
	v_mfma_f32_16x16x32_bf16 v[36:39], v[114:117], v[140:143], v[36:39]
	v_mfma_f32_16x16x32_bf16 v[74:77], v[118:121], v[136:139], 0
	v_mfma_f32_16x16x32_bf16 v[132:135], v[114:117], v[148:151], v[132:135]
	v_mfma_f32_16x16x32_bf16 v[110:113], v[114:117], v[156:159], v[110:113]
	v_mfma_f32_16x16x32_bf16 v[114:117], v[118:121], v[152:155], 0
	v_mfma_f32_16x16x32_bf16 v[74:77], v[122:125], v[140:143], v[74:77]
	v_mfma_f32_16x16x32_bf16 v[136:139], v[118:121], v[144:147], 0
	v_mfma_f32_16x16x32_bf16 v[114:117], v[122:125], v[156:159], v[114:117]
	v_mfma_f32_16x16x32_bf16 v[136:139], v[122:125], v[148:151], v[136:139]
	s_barrier
	ds_read_b128 v[118:121], v213
	ds_read_b128 v[122:125], v213 offset:1024
	ds_read_b128 v[140:143], v213 offset:2048
	ds_read_b128 v[144:147], v213 offset:3072
	s_add_u32 s56, s22, 0x10100
	s_addc_u32 s57, s23, 0
	v_readfirstlane_b32 s55, v18
	v_lshl_add_u64 v[40:41], s[56:57], 0, v[0:1]
	s_mov_b32 m0, s55
	v_readfirstlane_b32 s55, v19
	ds_read_b128 v[148:151], v17 offset:32768
	ds_read_b128 v[152:155], v17 offset:33792
	ds_read_b128 v[156:159], v16 offset:34816
	ds_read_b128 v[184:187], v16 offset:35840
	ds_read_b128 v[188:191], v16 offset:36864
	ds_read_b128 v[192:195], v16 offset:37888
	ds_read_b128 v[196:199], v16 offset:38912
	ds_read_b128 v[200:203], v16 offset:39936
	global_load_lds_dwordx4 v[40:41], off
	v_lshl_add_u64 v[40:41], s[56:57], 0, v[2:3]
	s_mov_b32 m0, s55
	s_nop 0
	global_load_lds_dwordx4 v[40:41], off
	s_waitcnt lgkmcnt(8)
	s_barrier
	s_waitcnt lgkmcnt(0)
	s_waitcnt lgkmcnt(0)
	v_mfma_f32_16x16x32_bf16 v[78:81], v[118:121], v[148:151], v[78:81]
	v_mfma_f32_16x16x32_bf16 v[82:85], v[140:143], v[148:151], v[82:85]
	v_mfma_f32_16x16x32_bf16 v[86:89], v[118:121], v[156:159], v[86:89]
	v_mfma_f32_16x16x32_bf16 v[90:93], v[140:143], v[156:159], v[90:93]
	v_mfma_f32_16x16x32_bf16 v[94:97], v[118:121], v[188:191], v[94:97]
	v_mfma_f32_16x16x32_bf16 v[98:101], v[140:143], v[188:191], v[98:101]
	v_mfma_f32_16x16x32_bf16 v[102:105], v[118:121], v[196:199], v[102:105]
	v_mfma_f32_16x16x32_bf16 v[106:109], v[140:143], v[196:199], v[106:109]
	v_mfma_f32_16x16x32_bf16 v[78:81], v[122:125], v[152:155], v[78:81]
	v_mfma_f32_16x16x32_bf16 v[82:85], v[144:147], v[152:155], v[82:85]
	v_mfma_f32_16x16x32_bf16 v[86:89], v[122:125], v[184:187], v[86:89]
	v_mfma_f32_16x16x32_bf16 v[90:93], v[144:147], v[184:187], v[90:93]
	v_mfma_f32_16x16x32_bf16 v[94:97], v[122:125], v[192:195], v[94:97]
	v_mfma_f32_16x16x32_bf16 v[98:101], v[144:147], v[192:195], v[98:101]
	v_mfma_f32_16x16x32_bf16 v[102:105], v[122:125], v[200:203], v[102:105]
	v_mfma_f32_16x16x32_bf16 v[106:109], v[144:147], v[200:203], v[106:109]
	s_barrier
	s_mov_b32 m0, s47
	v_lshl_add_u64 v[12:13], v[12:13], 0, s[26:27]
	ds_read_b128 v[204:207], v222
	ds_read_b128 v[208:211], v222 offset:1024
	ds_read_b128 v[216:219], v222 offset:2048
	ds_read_b128 v[226:229], v222 offset:3072
	global_load_lds_dwordx4 v[12:13], off
	v_lshl_add_u64 v[12:13], v[14:15], 0, s[26:27]
	s_mov_b32 m0, s46
	s_nop 0
	global_load_lds_dwordx4 v[12:13], off
	s_barrier
; #define STAGE_A(b, h, kt) { const u16* ap_ = A + (size_t)((h) * ahalf + (unsigned)(kt) * 64u); glds16(ap_ + ao0, l0 + SA_(b, h)); glds16(ap_ + ao1, l0 + SA_(b, h) + 8192); }
; #define STAGE_B(b, h, kt) { const u16* bp_ = ((h) ? B1 : B0) + (unsigned)(kt) * 64u; glds16(bp_ + bo0, l0 + SB_(b, h)); glds16(bp_ + bo1, l0 + SB_(b, h) + 8192); }
; #define LDA(dst, b, h) _Pragma("unroll") for (int m = 0; m < 4; ++m) _Pragma("unroll") for (int k = 0; k < 2; ++k) \
;     dst[m][k] = *(const bf16x8*)(lds + SA_(b, h) + lds_byte(wr * 64 + m * 16 + fr, k * 32 + fq * 8));
; #define LDB(dst, b, h) _Pragma("unroll") for (int n = 0; n < 2; ++n) _Pragma("unroll") for (int k = 0; k < 2; ++k) \
;     dst[n][k] = *(const bf16x8*)(lds + SB_(b, h) + lds_byte(wc * 32 + n * 16 + fr, k * 32 + fq * 8));
; #define MMA(ai, bj, At_, Bt_) { __builtin_amdgcn_s_setprio(1); \
;     _Pragma("unroll") for (int m = 0; m < 4; ++m) _Pragma("unroll") for (int n = 0; n < 2; ++n) _Pragma("unroll") for (int k = 0; k < 2; ++k) \
;       acc[ai][bj][m][n] = MFMA16(Bt_[n][k], At_[m][k], acc[ai][bj][m][n]); \
;     __builtin_amdgcn_s_setprio(0); }
; #define WAIT_V(n) asm volatile("s_waitcnt vmcnt(" #n ")" ::: "memory");
; #define WAIT_L(n) asm volatile("s_waitcnt lgkmcnt(" #n ")" ::: "memory");
; #define BAR __builtin_amdgcn_s_barrier();
; #define SCHED __builtin_amdgcn_sched_barrier(0);
; DI void gemm256(const u16* __restrict__ A, int lda, const u16* __restrict__ B0, const u16* __restrict__ B1, int ldb, int nt, acc_t& acc, char* lds) {
;     ...
;     BAR WAIT_L(0) MMA(0, 1, At, Bq1) BAR
;     LDA(At, 1, 1) STAGE_A(1, 0, t + 3)
;     BAR WAIT_L(0) MMA(1, 0, At, Bq0) BAR SCHED
;     STAGE_B(1, 1, t + 3)
;     WAIT_V(6) BAR MMA(1, 1, At, Bq1) BAR
;   }
;   { LDB(Bq0, 0, 0) LDA(At, 0, 0) STAGE_A(1, 1, nt - 1)
;     BAR WAIT_L(0) MMA(0, 0, At, Bq0) BAR
	s_waitcnt lgkmcnt(0)
	s_waitcnt lgkmcnt(0)
	v_mfma_f32_16x16x32_bf16 v[12:15], v[204:207], v[148:151], v[126:129]
	v_mfma_f32_16x16x32_bf16 v[40:43], v[216:219], v[148:151], v[42:45]
	v_mfma_f32_16x16x32_bf16 v[44:47], v[204:207], v[156:159], v[46:49]
	v_mfma_f32_16x16x32_bf16 v[48:51], v[216:219], v[156:159], v[50:53]
	v_mfma_f32_16x16x32_bf16 v[52:55], v[204:207], v[188:191], v[54:57]
	v_mfma_f32_16x16x32_bf16 v[56:59], v[216:219], v[188:191], v[58:61]
	v_mfma_f32_16x16x32_bf16 v[60:63], v[204:207], v[196:199], v[66:69]
	v_mfma_f32_16x16x32_bf16 v[66:69], v[216:219], v[196:199], v[70:73]
	v_mfma_f32_16x16x32_bf16 v[12:15], v[208:211], v[152:155], v[12:15]
	v_mfma_f32_16x16x32_bf16 v[40:43], v[226:229], v[152:155], v[40:43]
	v_mfma_f32_16x16x32_bf16 v[44:47], v[208:211], v[184:187], v[44:47]
	v_mfma_f32_16x16x32_bf16 v[48:51], v[226:229], v[184:187], v[48:51]
	v_mfma_f32_16x16x32_bf16 v[52:55], v[208:211], v[192:195], v[52:55]
	v_mfma_f32_16x16x32_bf16 v[56:59], v[226:229], v[192:195], v[56:59]
	v_mfma_f32_16x16x32_bf16 v[60:63], v[208:211], v[200:203], v[60:63]
	v_mfma_f32_16x16x32_bf16 v[66:69], v[226:229], v[200:203], v[66:69]
	s_mov_b32 m0, s44
	v_lshl_add_u64 v[8:9], v[8:9], 0, s[26:27]
	s_barrier
	ds_read_b128 v[70:73], v17 offset:49152
	ds_read_b128 v[126:129], v17 offset:50176
	ds_read_b128 v[148:151], v16 offset:51200
	ds_read_b128 v[152:155], v16 offset:52224
	ds_read_b128 v[156:159], v16 offset:53248
	ds_read_b128 v[184:187], v16 offset:54272
	ds_read_b128 v[188:191], v16 offset:55296
	ds_read_b128 v[192:195], v16 offset:56320
	global_load_lds_dwordx4 v[8:9], off
	v_lshl_add_u64 v[8:9], v[10:11], 0, s[26:27]
	s_mov_b32 m0, s29
	s_nop 0
	global_load_lds_dwordx4 v[8:9], off
	s_barrier
	s_waitcnt lgkmcnt(0)
	s_waitcnt lgkmcnt(0)
	v_mfma_f32_16x16x32_bf16 v[8:11], v[118:121], v[70:73], v[160:163]
	v_mfma_f32_16x16x32_bf16 v[24:27], v[118:121], v[188:191], v[24:27]
	v_mfma_f32_16x16x32_bf16 v[28:31], v[140:143], v[188:191], v[28:31]
	v_mfma_f32_16x16x32_bf16 v[8:11], v[122:125], v[126:129], v[8:11]
	v_mfma_f32_16x16x32_bf16 v[160:163], v[140:143], v[70:73], v[164:167]
	v_mfma_f32_16x16x32_bf16 v[164:167], v[118:121], v[148:151], v[168:171]
	v_mfma_f32_16x16x32_bf16 v[168:171], v[140:143], v[148:151], v[172:175]
	v_mfma_f32_16x16x32_bf16 v[172:175], v[118:121], v[156:159], v[176:179]
	v_mfma_f32_16x16x32_bf16 v[176:179], v[140:143], v[156:159], v[180:183]
	v_mfma_f32_16x16x32_bf16 v[24:27], v[122:125], v[192:195], v[24:27]
	v_mfma_f32_16x16x32_bf16 v[28:31], v[144:147], v[192:195], v[28:31]
	v_mfma_f32_16x16x32_bf16 v[160:163], v[144:147], v[126:129], v[160:163]
	v_mfma_f32_16x16x32_bf16 v[164:167], v[122:125], v[152:155], v[164:167]
	v_mfma_f32_16x16x32_bf16 v[168:171], v[144:147], v[152:155], v[168:171]
	v_mfma_f32_16x16x32_bf16 v[172:175], v[122:125], v[184:187], v[172:175]
	v_mfma_f32_16x16x32_bf16 v[176:179], v[144:147], v[184:187], v[176:179]
	s_barrier
	s_mov_b32 m0, s28
	v_lshl_add_u64 v[4:5], v[4:5], 0, s[26:27]
	global_load_lds_dwordx4 v[4:5], off
	v_lshl_add_u64 v[4:5], v[6:7], 0, s[26:27]
	s_mov_b32 m0, s2
	s_nop 0
	global_load_lds_dwordx4 v[4:5], off
	s_waitcnt vmcnt(6)
	s_barrier
	v_mfma_f32_16x16x32_bf16 v[4:7], v[204:207], v[70:73], v[20:23]
	v_mfma_f32_16x16x32_bf16 v[18:21], v[216:219], v[70:73], v[32:35]
	v_mfma_f32_16x16x32_bf16 v[32:35], v[204:207], v[148:151], v[36:39]
	v_mfma_f32_16x16x32_bf16 v[36:39], v[216:219], v[148:151], v[74:77]
	v_mfma_f32_16x16x32_bf16 v[70:73], v[204:207], v[156:159], v[132:135]
	v_mfma_f32_16x16x32_bf16 v[74:77], v[216:219], v[156:159], v[136:139]
	v_mfma_f32_16x16x32_bf16 v[110:113], v[204:207], v[188:191], v[110:113]
	v_mfma_f32_16x16x32_bf16 v[114:117], v[216:219], v[188:191], v[114:117]
	v_mfma_f32_16x16x32_bf16 v[4:7], v[208:211], v[126:129], v[4:7]
	v_mfma_f32_16x16x32_bf16 v[18:21], v[226:229], v[126:129], v[18:21]
	v_mfma_f32_16x16x32_bf16 v[32:35], v[208:211], v[152:155], v[32:35]
	v_mfma_f32_16x16x32_bf16 v[36:39], v[226:229], v[152:155], v[36:39]
	v_mfma_f32_16x16x32_bf16 v[70:73], v[208:211], v[184:187], v[70:73]
	v_mfma_f32_16x16x32_bf16 v[74:77], v[226:229], v[184:187], v[74:77]
	v_mfma_f32_16x16x32_bf16 v[110:113], v[208:211], v[192:195], v[110:113]
	v_mfma_f32_16x16x32_bf16 v[114:117], v[226:229], v[192:195], v[114:117]
	s_add_u32 s22, s22, 0x10180
	s_addc_u32 s23, s23, 0
	s_mov_b32 m0, s54
	v_lshl_add_u64 v[0:1], s[22:23], 0, v[0:1]
	s_barrier
	ds_read_b128 v[118:121], v131
	ds_read_b128 v[122:125], v131 offset:1024
	ds_read_b128 v[126:129], v131 offset:2048
	ds_read_b128 v[132:135], v131 offset:3072
	ds_read_b128 v[136:139], v17
	ds_read_b128 v[140:143], v17 offset:1024
	ds_read_b128 v[144:147], v16 offset:2048
	ds_read_b128 v[148:151], v16 offset:3072
	ds_read_b128 v[152:155], v16 offset:4096
	ds_read_b128 v[156:159], v16 offset:5120
	ds_read_b128 v[180:183], v16 offset:6144
	ds_read_b128 v[184:187], v16 offset:7168
	global_load_lds_dwordx4 v[0:1], off
	v_lshl_add_u64 v[0:1], s[22:23], 0, v[2:3]
	s_mov_b32 m0, s45
	s_nop 0
	global_load_lds_dwordx4 v[0:1], off
	s_barrier
	s_waitcnt lgkmcnt(0)
	s_waitcnt lgkmcnt(0)
	v_mfma_f32_16x16x32_bf16 v[0:3], v[118:121], v[136:139], v[78:81]
	v_mfma_f32_16x16x32_bf16 v[78:81], v[126:129], v[136:139], v[82:85]
	v_mfma_f32_16x16x32_bf16 v[82:85], v[118:121], v[144:147], v[86:89]
	v_mfma_f32_16x16x32_bf16 v[86:89], v[126:129], v[144:147], v[90:93]
	v_mfma_f32_16x16x32_bf16 v[90:93], v[118:121], v[152:155], v[94:97]
	v_mfma_f32_16x16x32_bf16 v[94:97], v[126:129], v[152:155], v[98:101]
	v_mfma_f32_16x16x32_bf16 v[98:101], v[118:121], v[180:183], v[102:105]
	v_mfma_f32_16x16x32_bf16 v[0:3], v[122:125], v[140:143], v[0:3]
	v_mfma_f32_16x16x32_bf16 v[78:81], v[132:135], v[140:143], v[78:81]
	v_mfma_f32_16x16x32_bf16 v[82:85], v[122:125], v[148:151], v[82:85]
	v_mfma_f32_16x16x32_bf16 v[86:89], v[132:135], v[148:151], v[86:89]
	v_mfma_f32_16x16x32_bf16 v[90:93], v[122:125], v[156:159], v[90:93]
	v_mfma_f32_16x16x32_bf16 v[94:97], v[132:135], v[156:159], v[94:97]
	v_mfma_f32_16x16x32_bf16 v[102:105], v[122:125], v[184:187], v[98:101]
	v_mfma_f32_16x16x32_bf16 v[98:101], v[126:129], v[180:183], v[106:109]
	v_mfma_f32_16x16x32_bf16 v[188:191], v[132:135], v[184:187], v[98:101]
	s_barrier
; #define LDA(dst, b, h) _Pragma("unroll") for (int m = 0; m < 4; ++m) _Pragma("unroll") for (int k = 0; k < 2; ++k) \
;     dst[m][k] = *(const bf16x8*)(lds + SA_(b, h) + lds_byte(wr * 64 + m * 16 + fr, k * 32 + fq * 8));
; #define LDB(dst, b, h) _Pragma("unroll") for (int n = 0; n < 2; ++n) _Pragma("unroll") for (int k = 0; k < 2; ++k) \
;     dst[n][k] = *(const bf16x8*)(lds + SB_(b, h) + lds_byte(wc * 32 + n * 16 + fr, k * 32 + fq * 8));
; #define MMA(ai, bj, At_, Bt_) { __builtin_amdgcn_s_setprio(1); \
;     _Pragma("unroll") for (int m = 0; m < 4; ++m) _Pragma("unroll") for (int n = 0; n < 2; ++n) _Pragma("unroll") for (int k = 0; k < 2; ++k) \
;       acc[ai][bj][m][n] = MFMA16(Bt_[n][k], At_[m][k], acc[ai][bj][m][n]); \
;     __builtin_amdgcn_s_setprio(0); }
; #define WAIT_V(n) asm volatile("s_waitcnt vmcnt(" #n ")" ::: "memory");
; #define WAIT_L(n) asm volatile("s_waitcnt lgkmcnt(" #n ")" ::: "memory");
; #define BAR __builtin_amdgcn_s_barrier();
; DI void gemm256(const u16* __restrict__ A, int lda, const u16* __restrict__ B0, const u16* __restrict__ B1, int ldb, int nt, acc_t& acc, char* lds) {
;     ...
;     LDB(Bq1, 0, 1) BAR WAIT_L(0) MMA(0, 1, At, Bq1) BAR
;     LDA(At, 0, 1) WAIT_V(4) BAR WAIT_L(0) MMA(1, 0, At, Bq0) MMA(1, 1, At, Bq1) BAR }
;   { LDB(Bq0, 1, 0) LDA(At, 1, 0) WAIT_V(2) BAR WAIT_L(0) MMA(0, 0, At, Bq0) BAR
	s_nop 4
	ds_read_b128 v[98:101], v212
	ds_read_b128 v[106:109], v212 offset:1024
	ds_read_b128 v[192:195], v212 offset:2048
	ds_read_b128 v[196:199], v212 offset:3072
	s_barrier
	s_waitcnt lgkmcnt(0)
	s_waitcnt lgkmcnt(0)
	v_mfma_f32_16x16x32_bf16 v[48:51], v[192:195], v[144:147], v[48:51]
	v_mfma_f32_16x16x32_bf16 v[12:15], v[98:101], v[136:139], v[12:15]
	v_mfma_f32_16x16x32_bf16 v[40:43], v[192:195], v[136:139], v[40:43]
	v_mfma_f32_16x16x32_bf16 v[136:139], v[196:199], v[148:151], v[48:51]
	v_mfma_f32_16x16x32_bf16 v[48:51], v[98:101], v[152:155], v[52:55]
	v_mfma_f32_16x16x32_bf16 v[52:55], v[106:109], v[156:159], v[48:51]
	v_mfma_f32_16x16x32_bf16 v[48:51], v[192:195], v[152:155], v[56:59]
	v_mfma_f32_16x16x32_bf16 v[44:47], v[98:101], v[144:147], v[44:47]
	v_mfma_f32_16x16x32_bf16 v[56:59], v[196:199], v[156:159], v[48:51]
	v_mfma_f32_16x16x32_bf16 v[48:51], v[98:101], v[180:183], v[60:63]
	v_mfma_f32_16x16x32_bf16 v[12:15], v[106:109], v[140:143], v[12:15]
	v_mfma_f32_16x16x32_bf16 v[40:43], v[196:199], v[140:143], v[40:43]
	v_mfma_f32_16x16x32_bf16 v[44:47], v[106:109], v[148:151], v[44:47]
	v_mfma_f32_16x16x32_bf16 v[60:63], v[106:109], v[184:187], v[48:51]
	v_mfma_f32_16x16x32_bf16 v[48:51], v[192:195], v[180:183], v[66:69]
	v_mfma_f32_16x16x32_bf16 v[140:143], v[196:199], v[184:187], v[48:51]
	s_barrier
	s_nop 4
	ds_read_b128 v[48:51], v17 offset:16384
	ds_read_b128 v[66:69], v17 offset:17408
	ds_read_b128 v[144:147], v16 offset:18432
	ds_read_b128 v[148:151], v16 offset:19456
	ds_read_b128 v[152:155], v16 offset:20480
	ds_read_b128 v[156:159], v16 offset:21504
	ds_read_b128 v[180:183], v16 offset:22528
	ds_read_b128 v[184:187], v16 offset:23552
	s_waitcnt vmcnt(4)
	s_barrier
	s_waitcnt lgkmcnt(0)
	s_waitcnt lgkmcnt(0)
	v_mfma_f32_16x16x32_bf16 v[8:11], v[118:121], v[48:51], v[8:11]
	v_mfma_f32_16x16x32_bf16 v[22:25], v[118:121], v[180:183], v[24:27]
	v_mfma_f32_16x16x32_bf16 v[8:11], v[122:125], v[66:69], v[8:11]
	v_mfma_f32_16x16x32_bf16 v[160:163], v[126:129], v[48:51], v[160:163]
	v_mfma_f32_16x16x32_bf16 v[164:167], v[118:121], v[144:147], v[164:167]
	v_mfma_f32_16x16x32_bf16 v[168:171], v[126:129], v[144:147], v[168:171]
	v_mfma_f32_16x16x32_bf16 v[172:175], v[118:121], v[152:155], v[172:175]
	v_mfma_f32_16x16x32_bf16 v[176:179], v[126:129], v[152:155], v[176:179]
	v_mfma_f32_16x16x32_bf16 v[24:27], v[122:125], v[184:187], v[22:25]
	v_mfma_f32_16x16x32_bf16 v[28:31], v[126:129], v[180:183], v[28:31]
	v_mfma_f32_16x16x32_bf16 v[160:163], v[132:135], v[66:69], v[160:163]
	v_mfma_f32_16x16x32_bf16 v[164:167], v[122:125], v[148:151], v[164:167]
	v_mfma_f32_16x16x32_bf16 v[168:171], v[132:135], v[148:151], v[168:171]
	v_mfma_f32_16x16x32_bf16 v[172:175], v[122:125], v[156:159], v[172:175]
	v_mfma_f32_16x16x32_bf16 v[176:179], v[132:135], v[156:159], v[176:179]
	v_mfma_f32_16x16x32_bf16 v[132:135], v[132:135], v[184:187], v[28:31]
	v_mfma_f32_16x16x32_bf16 v[4:7], v[98:101], v[48:51], v[4:7]
	v_mfma_f32_16x16x32_bf16 v[200:203], v[106:109], v[66:69], v[4:7]
	v_mfma_f32_16x16x32_bf16 v[4:7], v[192:195], v[48:51], v[18:21]
	v_mfma_f32_16x16x32_bf16 v[204:207], v[196:199], v[66:69], v[4:7]
	v_mfma_f32_16x16x32_bf16 v[4:7], v[98:101], v[144:147], v[32:35]
	v_mfma_f32_16x16x32_bf16 v[32:35], v[106:109], v[148:151], v[4:7]
	v_mfma_f32_16x16x32_bf16 v[4:7], v[192:195], v[144:147], v[36:39]
	v_mfma_f32_16x16x32_bf16 v[144:147], v[196:199], v[148:151], v[4:7]
	v_mfma_f32_16x16x32_bf16 v[4:7], v[98:101], v[152:155], v[70:73]
	v_mfma_f32_16x16x32_bf16 v[148:151], v[106:109], v[156:159], v[4:7]
	v_mfma_f32_16x16x32_bf16 v[4:7], v[192:195], v[152:155], v[74:77]
	v_mfma_f32_16x16x32_bf16 v[152:155], v[196:199], v[156:159], v[4:7]
	v_mfma_f32_16x16x32_bf16 v[4:7], v[98:101], v[180:183], v[110:113]
	v_mfma_f32_16x16x32_bf16 v[156:159], v[106:109], v[184:187], v[4:7]
	v_mfma_f32_16x16x32_bf16 v[4:7], v[192:195], v[180:183], v[114:117]
	v_mfma_f32_16x16x32_bf16 v[180:183], v[196:199], v[184:187], v[4:7]
	s_barrier
	s_nop 4
	ds_read_b128 v[4:7], v213
	ds_read_b128 v[70:73], v213 offset:1024
	ds_read_b128 v[184:187], v213 offset:2048
	ds_read_b128 v[192:195], v213 offset:3072
	ds_read_b128 v[18:21], v17 offset:32768
	ds_read_b128 v[28:31], v17 offset:33792
	ds_read_b128 v[36:39], v16 offset:34816
	ds_read_b128 v[74:77], v16 offset:35840
	ds_read_b128 v[196:199], v16 offset:36864
	ds_read_b128 v[208:211], v16 offset:37888
	ds_read_b128 v[216:219], v16 offset:38912
	ds_read_b128 v[226:229], v16 offset:39936
	s_waitcnt vmcnt(2)
	s_barrier
; #define LDA(dst, b, h) _Pragma("unroll") for (int m = 0; m < 4; ++m) _Pragma("unroll") for (int k = 0; k < 2; ++k) \
;     dst[m][k] = *(const bf16x8*)(lds + SA_(b, h) + lds_byte(wr * 64 + m * 16 + fr, k * 32 + fq * 8));
; #define LDB(dst, b, h) _Pragma("unroll") for (int n = 0; n < 2; ++n) _Pragma("unroll") for (int k = 0; k < 2; ++k) \
;     dst[n][k] = *(const bf16x8*)(lds + SB_(b, h) + lds_byte(wc * 32 + n * 16 + fr, k * 32 + fq * 8));
; #define MMA(ai, bj, At_, Bt_) { __builtin_amdgcn_s_setprio(1); \
;     _Pragma("unroll") for (int m = 0; m < 4; ++m) _Pragma("unroll") for (int n = 0; n < 2; ++n) _Pragma("unroll") for (int k = 0; k < 2; ++k) \
;       acc[ai][bj][m][n] = MFMA16(Bt_[n][k], At_[m][k], acc[ai][bj][m][n]); \
;     __builtin_amdgcn_s_setprio(0); }
; #define WAIT_V(n) asm volatile("s_waitcnt vmcnt(" #n ")" ::: "memory");
; #define WAIT_L(n) asm volatile("s_waitcnt lgkmcnt(" #n ")" ::: "memory");
; #define BAR __builtin_amdgcn_s_barrier();
; DI void gemm256(const u16* __restrict__ A, int lda, const u16* __restrict__ B0, const u16* __restrict__ B1, int ldb, int nt, acc_t& acc, char* lds) {
;     ...
;   { LDB(Bq0, 1, 0) LDA(At, 1, 0) WAIT_V(2) BAR WAIT_L(0) MMA(0, 0, At, Bq0) BAR
;     LDB(Bq1, 1, 1) WAIT_V(0) BAR WAIT_L(0) MMA(0, 1, At, Bq1) BAR
;     LDA(At, 1, 1) BAR WAIT_L(0) MMA(1, 0, At, Bq0) MMA(1, 1, At, Bq1) BAR }
;   if (wr == 0) BAR
	s_waitcnt lgkmcnt(0)
	s_waitcnt lgkmcnt(0)
	v_mfma_f32_16x16x32_bf16 v[0:3], v[4:7], v[18:21], v[0:3]
	v_mfma_f32_16x16x32_bf16 v[122:125], v[70:73], v[28:31], v[0:3]
	v_mfma_f32_16x16x32_bf16 v[0:3], v[184:187], v[18:21], v[78:81]
	v_mfma_f32_16x16x32_bf16 v[114:117], v[192:195], v[28:31], v[0:3]
	v_mfma_f32_16x16x32_bf16 v[0:3], v[4:7], v[36:39], v[82:85]
	v_mfma_f32_16x16x32_bf16 v[106:109], v[70:73], v[74:77], v[0:3]
	v_mfma_f32_16x16x32_bf16 v[0:3], v[184:187], v[36:39], v[86:89]
	v_mfma_f32_16x16x32_bf16 v[98:101], v[192:195], v[74:77], v[0:3]
	v_mfma_f32_16x16x32_bf16 v[0:3], v[4:7], v[196:199], v[90:93]
	v_mfma_f32_16x16x32_bf16 v[90:93], v[70:73], v[208:211], v[0:3]
	v_mfma_f32_16x16x32_bf16 v[0:3], v[184:187], v[196:199], v[94:97]
	v_mfma_f32_16x16x32_bf16 v[82:85], v[192:195], v[208:211], v[0:3]
	v_mfma_f32_16x16x32_bf16 v[0:3], v[4:7], v[216:219], v[102:105]
	v_mfma_f32_16x16x32_bf16 v[66:69], v[70:73], v[226:229], v[0:3]
	v_mfma_f32_16x16x32_bf16 v[0:3], v[184:187], v[216:219], v[188:191]
	v_mfma_f32_16x16x32_bf16 v[48:51], v[192:195], v[226:229], v[0:3]
	s_barrier
	s_nop 4
	ds_read_b128 v[0:3], v222
	ds_read_b128 v[188:191], v222 offset:1024
	ds_read_b128 v[230:233], v222 offset:2048
	ds_read_b128 v[234:237], v222 offset:3072
	s_waitcnt vmcnt(0)
	s_barrier
	s_waitcnt lgkmcnt(0)
	s_waitcnt lgkmcnt(0)
	v_mfma_f32_16x16x32_bf16 v[12:15], v[0:3], v[18:21], v[12:15]
	v_mfma_f32_16x16x32_bf16 v[126:129], v[188:191], v[28:31], v[12:15]
	v_mfma_f32_16x16x32_bf16 v[12:15], v[230:233], v[18:21], v[40:43]
	v_mfma_f32_16x16x32_bf16 v[118:121], v[234:237], v[28:31], v[12:15]
	v_mfma_f32_16x16x32_bf16 v[12:15], v[0:3], v[36:39], v[44:47]
	v_mfma_f32_16x16x32_bf16 v[110:113], v[188:191], v[74:77], v[12:15]
	v_mfma_f32_16x16x32_bf16 v[12:15], v[230:233], v[36:39], v[136:139]
	v_mfma_f32_16x16x32_bf16 v[102:105], v[234:237], v[74:77], v[12:15]
	v_mfma_f32_16x16x32_bf16 v[12:15], v[0:3], v[196:199], v[52:55]
	v_mfma_f32_16x16x32_bf16 v[94:97], v[188:191], v[208:211], v[12:15]
	v_mfma_f32_16x16x32_bf16 v[12:15], v[230:233], v[196:199], v[56:59]
	v_mfma_f32_16x16x32_bf16 v[86:89], v[234:237], v[208:211], v[12:15]
	v_mfma_f32_16x16x32_bf16 v[12:15], v[0:3], v[216:219], v[60:63]
	v_mfma_f32_16x16x32_bf16 v[78:81], v[188:191], v[226:229], v[12:15]
	v_mfma_f32_16x16x32_bf16 v[12:15], v[230:233], v[216:219], v[140:143]
	v_mfma_f32_16x16x32_bf16 v[60:63], v[234:237], v[226:229], v[12:15]
	s_barrier
	ds_read_b128 v[40:43], v17 offset:49152
	ds_read_b128 v[52:55], v17 offset:50176
	ds_read_b128 v[136:139], v16 offset:51200
	ds_read_b128 v[140:143], v16 offset:52224
	ds_read_b128 v[196:199], v16 offset:53248
	ds_read_b128 v[208:211], v16 offset:54272
	ds_read_b128 v[216:219], v16 offset:55296
	ds_read_b128 v[226:229], v16 offset:56320
	s_barrier
	s_waitcnt lgkmcnt(0)
	s_waitcnt lgkmcnt(0)
	v_mfma_f32_16x16x32_bf16 v[8:11], v[4:7], v[40:43], v[8:11]
	v_mfma_f32_16x16x32_bf16 v[74:77], v[70:73], v[52:55], v[8:11]
	v_mfma_f32_16x16x32_bf16 v[8:11], v[184:187], v[40:43], v[160:163]
	v_mfma_f32_16x16x32_bf16 v[56:59], v[192:195], v[52:55], v[8:11]
	v_mfma_f32_16x16x32_bf16 v[8:11], v[4:7], v[136:139], v[164:167]
	v_mfma_f32_16x16x32_bf16 v[44:47], v[70:73], v[140:143], v[8:11]
	v_mfma_f32_16x16x32_bf16 v[8:11], v[184:187], v[136:139], v[168:171]
	v_mfma_f32_16x16x32_bf16 v[36:39], v[192:195], v[140:143], v[8:11]
	v_mfma_f32_16x16x32_bf16 v[8:11], v[4:7], v[196:199], v[172:175]
	v_mfma_f32_16x16x32_bf16 v[4:7], v[4:7], v[216:219], v[24:27]
	v_mfma_f32_16x16x32_bf16 v[28:31], v[70:73], v[208:211], v[8:11]
	v_mfma_f32_16x16x32_bf16 v[8:11], v[184:187], v[196:199], v[176:179]
	v_mfma_f32_16x16x32_bf16 v[12:15], v[70:73], v[226:229], v[4:7]
	v_mfma_f32_16x16x32_bf16 v[4:7], v[184:187], v[216:219], v[132:135]
	v_mfma_f32_16x16x32_bf16 v[20:23], v[192:195], v[208:211], v[8:11]
	v_mfma_f32_16x16x32_bf16 v[4:7], v[192:195], v[226:229], v[4:7]
	v_mfma_f32_16x16x32_bf16 v[8:11], v[0:3], v[40:43], v[200:203]
	v_mfma_f32_16x16x32_bf16 v[70:73], v[188:191], v[52:55], v[8:11]
	v_mfma_f32_16x16x32_bf16 v[8:11], v[230:233], v[40:43], v[204:207]
	v_mfma_f32_16x16x32_bf16 v[52:55], v[234:237], v[52:55], v[8:11]
	v_mfma_f32_16x16x32_bf16 v[8:11], v[0:3], v[136:139], v[32:35]
	v_mfma_f32_16x16x32_bf16 v[40:43], v[188:191], v[140:143], v[8:11]
	v_mfma_f32_16x16x32_bf16 v[8:11], v[230:233], v[136:139], v[144:147]
	v_mfma_f32_16x16x32_bf16 v[32:35], v[234:237], v[140:143], v[8:11]
	v_mfma_f32_16x16x32_bf16 v[8:11], v[0:3], v[196:199], v[148:151]
	v_mfma_f32_16x16x32_bf16 v[24:27], v[188:191], v[208:211], v[8:11]
	v_mfma_f32_16x16x32_bf16 v[8:11], v[230:233], v[196:199], v[152:155]
	v_mfma_f32_16x16x32_bf16 v[0:3], v[0:3], v[216:219], v[156:159]
	v_mfma_f32_16x16x32_bf16 v[16:19], v[234:237], v[208:211], v[8:11]
	v_mfma_f32_16x16x32_bf16 v[8:11], v[188:191], v[226:229], v[0:3]
	v_mfma_f32_16x16x32_bf16 v[0:3], v[230:233], v[216:219], v[180:183]
	v_mfma_f32_16x16x32_bf16 v[0:3], v[234:237], v[226:229], v[0:3]
	s_movk_i32 s2, 0x100
	v_cmp_gt_u32_e32 vcc, s2, v130
	s_barrier
	s_and_saveexec_b64 s[22:23], vcc
	s_cbranch_execz .LBB0_1257
	s_barrier

; #define STAGE_A(b, h, kt) { const u16* ap_ = A + (size_t)((h) * ahalf + (unsigned)(kt) * 64u); glds16(ap_ + ao0, l0 + SA_(b, h)); glds16(ap_ + ao1, l0 + SA_(b, h) + 8192); }
; #define STAGE_B(b, h, kt) { const u16* bp_ = ((h) ? B1 : B0) + (unsigned)(kt) * 64u; glds16(bp_ + bo0, l0 + SB_(b, h)); glds16(bp_ + bo1, l0 + SB_(b, h) + 8192); }
; #define LDA(dst, b, h) _Pragma("unroll") for (int m = 0; m < 4; ++m) _Pragma("unroll") for (int k = 0; k < 2; ++k) \
;     dst[m][k] = *(const bf16x8*)(lds + SA_(b, h) + lds_byte(wr * 64 + m * 16 + fr, k * 32 + fq * 8));
; #define LDB(dst, b, h) _Pragma("unroll") for (int n = 0; n < 2; ++n) _Pragma("unroll") for (int k = 0; k < 2; ++k) \
;     dst[n][k] = *(const bf16x8*)(lds + SB_(b, h) + lds_byte(wc * 32 + n * 16 + fr, k * 32 + fq * 8));
; #define MMA(ai, bj, At_, Bt_) { __builtin_amdgcn_s_setprio(1); \
;     _Pragma("unroll") for (int m = 0; m < 4; ++m) _Pragma("unroll") for (int n = 0; n < 2; ++n) _Pragma("unroll") for (int k = 0; k < 2; ++k) \
;       acc[ai][bj][m][n] = MFMA16(Bt_[n][k], At_[m][k], acc[ai][bj][m][n]); \
;     __builtin_amdgcn_s_setprio(0); }
; #define WAIT_L(n) asm volatile("s_waitcnt lgkmcnt(" #n ")" ::: "memory");
; #define BAR __builtin_amdgcn_s_barrier();
; #define SCHED __builtin_amdgcn_sched_barrier(0);
; DI void gemm256(const u16* __restrict__ A, int lda, const u16* __restrict__ B0, const u16* __restrict__ B1, int ldb, int nt, acc_t& acc, char* lds) {
;     ...
;     LDB(Bq0, 0, 0) SCHED LDA(At, 0, 0) STAGE_A(1, 1, t + 1)
;     WAIT_L(8) BAR WAIT_L(0) MMA(0, 0, At, Bq0) BAR SCHED
;     LDB(Bq1, 0, 1) STAGE_B(0, 0, t + 2)
;     BAR WAIT_L(0) MMA(0, 1, At, Bq1) BAR
;     LDA(At, 0, 1) STAGE_A(0, 0, t + 2)
;     BAR WAIT_L(0) MMA(1, 0, At, Bq0) BAR SCHED
.LBB0_1260:
	ds_read_b128 v[142:145], v166
	ds_read_b128 v[170:173], v166 offset:1024
	ds_read_b128 v[174:177], v166 offset:2048
	ds_read_b128 v[178:181], v166 offset:3072
	v_add_u32_e32 v167, 0xc000, v140
	v_lshl_add_u64 v[222:223], s[28:29], 0, v[136:137]
	v_readfirstlane_b32 s7, v167
	v_lshl_add_u64 v[168:169], v[222:223], 0, s[76:77]
	s_mov_b32 m0, s7
	ds_read_b128 v[182:185], v150
	ds_read_b128 v[186:189], v150 offset:1024
	ds_read_b128 v[190:193], v149
	ds_read_b128 v[194:197], v149 offset:1024
	ds_read_b128 v[198:201], v148
	ds_read_b128 v[202:205], v148 offset:1024
	ds_read_b128 v[206:209], v147
	ds_read_b128 v[210:213], v147 offset:1024
	global_load_lds_dwordx4 v[168:169], off
	v_add_u32_e32 v168, 0xe000, v140
	v_lshl_add_u64 v[224:225], s[28:29], 0, v[138:139]
	v_readfirstlane_b32 s7, v168
	v_lshl_add_u64 v[216:217], v[224:225], 0, s[76:77]
	s_mov_b32 m0, s7
	s_nop 0
	global_load_lds_dwordx4 v[216:217], off
	s_waitcnt lgkmcnt(8)
	s_barrier
	s_waitcnt lgkmcnt(0)
	s_waitcnt lgkmcnt(0)
	v_mfma_f32_16x16x32_bf16 v[126:129], v[142:145], v[182:185], v[126:129]
	v_mfma_f32_16x16x32_bf16 v[122:125], v[174:177], v[182:185], v[122:125]
	v_mfma_f32_16x16x32_bf16 v[118:121], v[142:145], v[190:193], v[118:121]
	v_mfma_f32_16x16x32_bf16 v[114:117], v[174:177], v[190:193], v[114:117]
	v_mfma_f32_16x16x32_bf16 v[110:113], v[142:145], v[198:201], v[110:113]
	v_mfma_f32_16x16x32_bf16 v[106:109], v[174:177], v[198:201], v[106:109]
	v_mfma_f32_16x16x32_bf16 v[102:105], v[142:145], v[206:209], v[102:105]
	v_mfma_f32_16x16x32_bf16 v[98:101], v[174:177], v[206:209], v[98:101]
	v_mfma_f32_16x16x32_bf16 v[126:129], v[170:173], v[186:189], v[126:129]
	v_mfma_f32_16x16x32_bf16 v[122:125], v[178:181], v[186:189], v[122:125]
	v_mfma_f32_16x16x32_bf16 v[118:121], v[170:173], v[194:197], v[118:121]
	v_mfma_f32_16x16x32_bf16 v[114:117], v[178:181], v[194:197], v[114:117]
	v_mfma_f32_16x16x32_bf16 v[110:113], v[170:173], v[202:205], v[110:113]
	v_mfma_f32_16x16x32_bf16 v[106:109], v[178:181], v[202:205], v[106:109]
	v_mfma_f32_16x16x32_bf16 v[102:105], v[170:173], v[210:213], v[102:105]
	v_mfma_f32_16x16x32_bf16 v[98:101], v[178:181], v[210:213], v[98:101]
	s_barrier
	v_lshl_add_u64 v[238:239], s[28:29], 0, v[132:133]
	v_readfirstlane_b32 s7, v141
	v_lshl_add_u64 v[240:241], v[238:239], 0, s[44:45]
	s_mov_b32 m0, s7
	ds_read_b128 v[216:219], v165
	ds_read_b128 v[226:229], v165 offset:1024
	ds_read_b128 v[230:233], v165 offset:2048
	ds_read_b128 v[234:237], v165 offset:3072
	global_load_lds_dwordx4 v[240:241], off
	v_lshl_add_u64 v[240:241], s[28:29], 0, v[134:135]
	v_readfirstlane_b32 s7, v152
	v_lshl_add_u64 v[242:243], v[240:241], 0, s[44:45]
	s_mov_b32 m0, s7
	s_nop 0
	global_load_lds_dwordx4 v[242:243], off
	s_barrier
	s_waitcnt lgkmcnt(0)
	s_waitcnt lgkmcnt(0)
	v_mfma_f32_16x16x32_bf16 v[94:97], v[216:219], v[182:185], v[94:97]
	v_mfma_f32_16x16x32_bf16 v[90:93], v[230:233], v[182:185], v[90:93]
	v_mfma_f32_16x16x32_bf16 v[86:89], v[216:219], v[190:193], v[86:89]
	v_mfma_f32_16x16x32_bf16 v[82:85], v[230:233], v[190:193], v[82:85]
	v_mfma_f32_16x16x32_bf16 v[78:81], v[216:219], v[198:201], v[78:81]
	v_mfma_f32_16x16x32_bf16 v[74:77], v[230:233], v[198:201], v[74:77]
	v_mfma_f32_16x16x32_bf16 v[70:73], v[216:219], v[206:209], v[70:73]
	v_mfma_f32_16x16x32_bf16 v[66:69], v[230:233], v[206:209], v[66:69]
	v_mfma_f32_16x16x32_bf16 v[94:97], v[226:229], v[186:189], v[94:97]
	v_mfma_f32_16x16x32_bf16 v[90:93], v[234:237], v[186:189], v[90:93]
	v_mfma_f32_16x16x32_bf16 v[86:89], v[226:229], v[194:197], v[86:89]
	v_mfma_f32_16x16x32_bf16 v[82:85], v[234:237], v[194:197], v[82:85]
	v_mfma_f32_16x16x32_bf16 v[78:81], v[226:229], v[202:205], v[78:81]
	v_mfma_f32_16x16x32_bf16 v[74:77], v[234:237], v[202:205], v[74:77]
	v_mfma_f32_16x16x32_bf16 v[70:73], v[226:229], v[210:213], v[70:73]
	v_mfma_f32_16x16x32_bf16 v[66:69], v[234:237], v[210:213], v[66:69]
	v_readfirstlane_b32 s7, v140
	v_lshl_add_u64 v[242:243], v[222:223], 0, s[80:81]
	s_mov_b32 m0, s7
	v_readfirstlane_b32 s7, v153
	s_barrier
	ds_read_b128 v[182:185], v150 offset:16384
	ds_read_b128 v[186:189], v150 offset:17408
	ds_read_b128 v[190:193], v149 offset:16384
	ds_read_b128 v[194:197], v149 offset:17408
	ds_read_b128 v[198:201], v148 offset:16384
	ds_read_b128 v[202:205], v148 offset:17408
	ds_read_b128 v[206:209], v147 offset:16384
	ds_read_b128 v[210:213], v147 offset:17408
	global_load_lds_dwordx4 v[242:243], off
	v_lshl_add_u64 v[242:243], v[224:225], 0, s[80:81]
	s_mov_b32 m0, s7
	s_nop 0
	global_load_lds_dwordx4 v[242:243], off
	s_barrier
	s_waitcnt lgkmcnt(0)
	s_waitcnt lgkmcnt(0)
	v_mfma_f32_16x16x32_bf16 v[60:63], v[142:145], v[182:185], v[60:63]
	v_mfma_f32_16x16x32_bf16 v[56:59], v[174:177], v[182:185], v[56:59]
	v_mfma_f32_16x16x32_bf16 v[52:55], v[142:145], v[190:193], v[52:55]
	v_mfma_f32_16x16x32_bf16 v[48:51], v[174:177], v[190:193], v[48:51]
	v_mfma_f32_16x16x32_bf16 v[44:47], v[142:145], v[198:201], v[44:47]
	v_mfma_f32_16x16x32_bf16 v[40:43], v[174:177], v[198:201], v[40:43]
	v_mfma_f32_16x16x32_bf16 v[36:39], v[142:145], v[206:209], v[36:39]
	v_mfma_f32_16x16x32_bf16 v[32:35], v[174:177], v[206:209], v[32:35]
	v_mfma_f32_16x16x32_bf16 v[60:63], v[170:173], v[186:189], v[60:63]
	v_mfma_f32_16x16x32_bf16 v[56:59], v[178:181], v[186:189], v[56:59]
	v_mfma_f32_16x16x32_bf16 v[52:55], v[170:173], v[194:197], v[52:55]
	v_mfma_f32_16x16x32_bf16 v[48:51], v[178:181], v[194:197], v[48:51]
	v_mfma_f32_16x16x32_bf16 v[44:47], v[170:173], v[202:205], v[44:47]
	v_mfma_f32_16x16x32_bf16 v[40:43], v[178:181], v[202:205], v[40:43]
	v_mfma_f32_16x16x32_bf16 v[36:39], v[170:173], v[210:213], v[36:39]
	v_mfma_f32_16x16x32_bf16 v[32:35], v[178:181], v[210:213], v[32:35]
	s_barrier
; #define STAGE_A(b, h, kt) { const u16* ap_ = A + (size_t)((h) * ahalf + (unsigned)(kt) * 64u); glds16(ap_ + ao0, l0 + SA_(b, h)); glds16(ap_ + ao1, l0 + SA_(b, h) + 8192); }
; #define STAGE_B(b, h, kt) { const u16* bp_ = ((h) ? B1 : B0) + (unsigned)(kt) * 64u; glds16(bp_ + bo0, l0 + SB_(b, h)); glds16(bp_ + bo1, l0 + SB_(b, h) + 8192); }
; #define LDA(dst, b, h) _Pragma("unroll") for (int m = 0; m < 4; ++m) _Pragma("unroll") for (int k = 0; k < 2; ++k) \
;     dst[m][k] = *(const bf16x8*)(lds + SA_(b, h) + lds_byte(wr * 64 + m * 16 + fr, k * 32 + fq * 8));
; #define LDB(dst, b, h) _Pragma("unroll") for (int n = 0; n < 2; ++n) _Pragma("unroll") for (int k = 0; k < 2; ++k) \
;     dst[n][k] = *(const bf16x8*)(lds + SB_(b, h) + lds_byte(wc * 32 + n * 16 + fr, k * 32 + fq * 8));
; #define MMA(ai, bj, At_, Bt_) { __builtin_amdgcn_s_setprio(1); \
;     _Pragma("unroll") for (int m = 0; m < 4; ++m) _Pragma("unroll") for (int n = 0; n < 2; ++n) _Pragma("unroll") for (int k = 0; k < 2; ++k) \
;       acc[ai][bj][m][n] = MFMA16(Bt_[n][k], At_[m][k], acc[ai][bj][m][n]); \
;     __builtin_amdgcn_s_setprio(0); }
; #define WAIT_V(n) asm volatile("s_waitcnt vmcnt(" #n ")" ::: "memory");
; #define WAIT_L(n) asm volatile("s_waitcnt lgkmcnt(" #n ")" ::: "memory");
; #define BAR __builtin_amdgcn_s_barrier();
; #define SCHED __builtin_amdgcn_sched_barrier(0);
; DI void gemm256(const u16* __restrict__ A, int lda, const u16* __restrict__ B0, const u16* __restrict__ B1, int ldb, int nt, acc_t& acc, char* lds) {
;     ...
;     STAGE_B(0, 1, t + 2)
;     WAIT_V(6) BAR MMA(1, 1, At, Bq1) BAR
;     LDB(Bq0, 1, 0) SCHED LDA(At, 1, 0) STAGE_A(0, 1, t + 2)
;     WAIT_L(8) BAR WAIT_L(0) MMA(0, 0, At, Bq0) BAR SCHED
;     LDB(Bq1, 1, 1) STAGE_B(1, 0, t + 3)
;     BAR WAIT_L(0) MMA(0, 1, At, Bq1) BAR
;     LDA(At, 1, 1) STAGE_A(1, 0, t + 3)
	v_readfirstlane_b32 s7, v154
	v_lshl_add_u64 v[142:143], v[238:239], 0, s[46:47]
	s_mov_b32 m0, s7
	v_readfirstlane_b32 s7, v155
	global_load_lds_dwordx4 v[142:143], off
	v_lshl_add_u64 v[142:143], v[240:241], 0, s[46:47]
	s_mov_b32 m0, s7
	s_nop 0
	global_load_lds_dwordx4 v[142:143], off
	s_waitcnt vmcnt(6)
	s_barrier
	v_mfma_f32_16x16x32_bf16 v[28:31], v[216:219], v[182:185], v[28:31]
	v_mfma_f32_16x16x32_bf16 v[24:27], v[230:233], v[182:185], v[24:27]
	v_mfma_f32_16x16x32_bf16 v[20:23], v[216:219], v[190:193], v[20:23]
	v_mfma_f32_16x16x32_bf16 v[16:19], v[230:233], v[190:193], v[16:19]
	v_mfma_f32_16x16x32_bf16 v[12:15], v[216:219], v[198:201], v[12:15]
	v_mfma_f32_16x16x32_bf16 v[8:11], v[230:233], v[198:201], v[8:11]
	v_mfma_f32_16x16x32_bf16 v[4:7], v[216:219], v[206:209], v[4:7]
	v_mfma_f32_16x16x32_bf16 v[0:3], v[230:233], v[206:209], v[0:3]
	v_mfma_f32_16x16x32_bf16 v[28:31], v[226:229], v[186:189], v[28:31]
	v_mfma_f32_16x16x32_bf16 v[24:27], v[234:237], v[186:189], v[24:27]
	v_mfma_f32_16x16x32_bf16 v[20:23], v[226:229], v[194:197], v[20:23]
	v_mfma_f32_16x16x32_bf16 v[16:19], v[234:237], v[194:197], v[16:19]
	v_mfma_f32_16x16x32_bf16 v[12:15], v[226:229], v[202:205], v[12:15]
	v_mfma_f32_16x16x32_bf16 v[8:11], v[234:237], v[202:205], v[8:11]
	v_mfma_f32_16x16x32_bf16 v[4:7], v[226:229], v[210:213], v[4:7]
	v_mfma_f32_16x16x32_bf16 v[0:3], v[234:237], v[210:213], v[0:3]
	s_barrier
	ds_read_b128 v[142:145], v156
	ds_read_b128 v[170:173], v156 offset:1024
	ds_read_b128 v[174:177], v156 offset:2048
	ds_read_b128 v[178:181], v156 offset:3072
	v_readfirstlane_b32 s7, v157
	v_lshl_add_u64 v[216:217], v[222:223], 0, s[4:5]
	s_mov_b32 m0, s7
	v_readfirstlane_b32 s7, v158
	ds_read_b128 v[182:185], v150 offset:32768
	ds_read_b128 v[186:189], v150 offset:33792
	ds_read_b128 v[190:193], v149 offset:32768
	ds_read_b128 v[194:197], v149 offset:33792
	ds_read_b128 v[198:201], v148 offset:32768
	ds_read_b128 v[202:205], v148 offset:33792
	ds_read_b128 v[206:209], v147 offset:32768
	ds_read_b128 v[210:213], v147 offset:33792
	global_load_lds_dwordx4 v[216:217], off
	v_lshl_add_u64 v[216:217], v[224:225], 0, s[4:5]
	s_mov_b32 m0, s7
	s_nop 0
	global_load_lds_dwordx4 v[216:217], off
	s_waitcnt lgkmcnt(8)
	s_barrier
	s_waitcnt lgkmcnt(0)
	s_waitcnt lgkmcnt(0)
	v_mfma_f32_16x16x32_bf16 v[126:129], v[142:145], v[182:185], v[126:129]
	v_mfma_f32_16x16x32_bf16 v[122:125], v[174:177], v[182:185], v[122:125]
	v_mfma_f32_16x16x32_bf16 v[118:121], v[142:145], v[190:193], v[118:121]
	v_mfma_f32_16x16x32_bf16 v[114:117], v[174:177], v[190:193], v[114:117]
	v_mfma_f32_16x16x32_bf16 v[110:113], v[142:145], v[198:201], v[110:113]
	v_mfma_f32_16x16x32_bf16 v[106:109], v[174:177], v[198:201], v[106:109]
	v_mfma_f32_16x16x32_bf16 v[102:105], v[142:145], v[206:209], v[102:105]
	v_mfma_f32_16x16x32_bf16 v[98:101], v[174:177], v[206:209], v[98:101]
	v_mfma_f32_16x16x32_bf16 v[126:129], v[170:173], v[186:189], v[126:129]
	v_mfma_f32_16x16x32_bf16 v[122:125], v[178:181], v[186:189], v[122:125]
	v_mfma_f32_16x16x32_bf16 v[118:121], v[170:173], v[194:197], v[118:121]
	v_mfma_f32_16x16x32_bf16 v[114:117], v[178:181], v[194:197], v[114:117]
	v_mfma_f32_16x16x32_bf16 v[110:113], v[170:173], v[202:205], v[110:113]
	v_mfma_f32_16x16x32_bf16 v[106:109], v[178:181], v[202:205], v[106:109]
	v_mfma_f32_16x16x32_bf16 v[102:105], v[170:173], v[210:213], v[102:105]
	v_mfma_f32_16x16x32_bf16 v[98:101], v[178:181], v[210:213], v[98:101]
	s_barrier
	v_readfirstlane_b32 s7, v159
	v_lshl_add_u64 v[242:243], v[238:239], 0, s[54:55]
	s_mov_b32 m0, s7
	v_readfirstlane_b32 s7, v160
	ds_read_b128 v[216:219], v151
	ds_read_b128 v[226:229], v151 offset:1024
	ds_read_b128 v[230:233], v151 offset:2048
	ds_read_b128 v[234:237], v151 offset:3072
	global_load_lds_dwordx4 v[242:243], off
	v_lshl_add_u64 v[242:243], v[240:241], 0, s[54:55]
	s_mov_b32 m0, s7
	s_nop 0
	global_load_lds_dwordx4 v[242:243], off
	s_barrier
	s_waitcnt lgkmcnt(0)
	s_waitcnt lgkmcnt(0)
	v_mfma_f32_16x16x32_bf16 v[94:97], v[216:219], v[182:185], v[94:97]
	v_mfma_f32_16x16x32_bf16 v[90:93], v[230:233], v[182:185], v[90:93]
	v_mfma_f32_16x16x32_bf16 v[86:89], v[216:219], v[190:193], v[86:89]
	v_mfma_f32_16x16x32_bf16 v[82:85], v[230:233], v[190:193], v[82:85]
	v_mfma_f32_16x16x32_bf16 v[78:81], v[216:219], v[198:201], v[78:81]
	v_mfma_f32_16x16x32_bf16 v[74:77], v[230:233], v[198:201], v[74:77]
	v_mfma_f32_16x16x32_bf16 v[70:73], v[216:219], v[206:209], v[70:73]
	v_mfma_f32_16x16x32_bf16 v[66:69], v[230:233], v[206:209], v[66:69]
	v_mfma_f32_16x16x32_bf16 v[94:97], v[226:229], v[186:189], v[94:97]
	v_mfma_f32_16x16x32_bf16 v[90:93], v[234:237], v[186:189], v[90:93]
	v_mfma_f32_16x16x32_bf16 v[86:89], v[226:229], v[194:197], v[86:89]
	v_mfma_f32_16x16x32_bf16 v[82:85], v[234:237], v[194:197], v[82:85]
	v_mfma_f32_16x16x32_bf16 v[78:81], v[226:229], v[202:205], v[78:81]
	v_mfma_f32_16x16x32_bf16 v[74:77], v[234:237], v[202:205], v[74:77]
	v_mfma_f32_16x16x32_bf16 v[70:73], v[226:229], v[210:213], v[70:73]
	v_mfma_f32_16x16x32_bf16 v[66:69], v[234:237], v[210:213], v[66:69]
	v_readfirstlane_b32 s7, v161
	v_lshl_add_u64 v[222:223], v[222:223], 0, s[30:31]
	s_mov_b32 m0, s7
	v_readfirstlane_b32 s7, v162
	s_barrier
	ds_read_b128 v[182:185], v150 offset:49152
	ds_read_b128 v[186:189], v150 offset:50176
	ds_read_b128 v[190:193], v149 offset:49152
	ds_read_b128 v[194:197], v149 offset:50176
	ds_read_b128 v[198:201], v148 offset:49152
	ds_read_b128 v[202:205], v148 offset:50176
	ds_read_b128 v[206:209], v147 offset:49152
	ds_read_b128 v[210:213], v147 offset:50176
	global_load_lds_dwordx4 v[222:223], off
	v_lshl_add_u64 v[222:223], v[224:225], 0, s[30:31]
	s_mov_b32 m0, s7
	s_nop 0
	global_load_lds_dwordx4 v[222:223], off
	s_barrier
; #define STAGE_A(b, h, kt) { const u16* ap_ = A + (size_t)((h) * ahalf + (unsigned)(kt) * 64u); glds16(ap_ + ao0, l0 + SA_(b, h)); glds16(ap_ + ao1, l0 + SA_(b, h) + 8192); }
; #define STAGE_B(b, h, kt) { const u16* bp_ = ((h) ? B1 : B0) + (unsigned)(kt) * 64u; glds16(bp_ + bo0, l0 + SB_(b, h)); glds16(bp_ + bo1, l0 + SB_(b, h) + 8192); }
; #define LDA(dst, b, h) _Pragma("unroll") for (int m = 0; m < 4; ++m) _Pragma("unroll") for (int k = 0; k < 2; ++k) \
;     dst[m][k] = *(const bf16x8*)(lds + SA_(b, h) + lds_byte(wr * 64 + m * 16 + fr, k * 32 + fq * 8));
; #define LDB(dst, b, h) _Pragma("unroll") for (int n = 0; n < 2; ++n) _Pragma("unroll") for (int k = 0; k < 2; ++k) \
;     dst[n][k] = *(const bf16x8*)(lds + SB_(b, h) + lds_byte(wc * 32 + n * 16 + fr, k * 32 + fq * 8));
; #define MMA(ai, bj, At_, Bt_) { __builtin_amdgcn_s_setprio(1); \
;     _Pragma("unroll") for (int m = 0; m < 4; ++m) _Pragma("unroll") for (int n = 0; n < 2; ++n) _Pragma("unroll") for (int k = 0; k < 2; ++k) \
;       acc[ai][bj][m][n] = MFMA16(Bt_[n][k], At_[m][k], acc[ai][bj][m][n]); \
;     __builtin_amdgcn_s_setprio(0); }
; #define WAIT_V(n) asm volatile("s_waitcnt vmcnt(" #n ")" ::: "memory");
; #define WAIT_L(n) asm volatile("s_waitcnt lgkmcnt(" #n ")" ::: "memory");
; #define BAR __builtin_amdgcn_s_barrier();
; #define SCHED __builtin_amdgcn_sched_barrier(0);
; DI void gemm256(const u16* __restrict__ A, int lda, const u16* __restrict__ B0, const u16* __restrict__ B1, int ldb, int nt, acc_t& acc, char* lds) {
;     ...
;     BAR WAIT_L(0) MMA(1, 0, At, Bq0) BAR SCHED
;     STAGE_B(1, 1, t + 3)
;     WAIT_V(6) BAR MMA(1, 1, At, Bq1) BAR
;   }
;   { LDB(Bq0, 0, 0) LDA(At, 0, 0) STAGE_A(1, 1, nt - 1)
;     BAR WAIT_L(0) MMA(0, 0, At, Bq0) BAR
;     LDB(Bq1, 0, 1) BAR WAIT_L(0) MMA(0, 1, At, Bq1) BAR
	s_waitcnt lgkmcnt(0)
	s_waitcnt lgkmcnt(0)
	v_mfma_f32_16x16x32_bf16 v[60:63], v[142:145], v[182:185], v[60:63]
	v_mfma_f32_16x16x32_bf16 v[56:59], v[174:177], v[182:185], v[56:59]
	v_mfma_f32_16x16x32_bf16 v[52:55], v[142:145], v[190:193], v[52:55]
	v_mfma_f32_16x16x32_bf16 v[48:51], v[174:177], v[190:193], v[48:51]
	v_mfma_f32_16x16x32_bf16 v[44:47], v[142:145], v[198:201], v[44:47]
	v_mfma_f32_16x16x32_bf16 v[40:43], v[174:177], v[198:201], v[40:43]
	v_mfma_f32_16x16x32_bf16 v[36:39], v[142:145], v[206:209], v[36:39]
	v_mfma_f32_16x16x32_bf16 v[32:35], v[174:177], v[206:209], v[32:35]
	v_mfma_f32_16x16x32_bf16 v[60:63], v[170:173], v[186:189], v[60:63]
	v_mfma_f32_16x16x32_bf16 v[56:59], v[178:181], v[186:189], v[56:59]
	v_mfma_f32_16x16x32_bf16 v[52:55], v[170:173], v[194:197], v[52:55]
	v_mfma_f32_16x16x32_bf16 v[48:51], v[178:181], v[194:197], v[48:51]
	v_mfma_f32_16x16x32_bf16 v[44:47], v[170:173], v[202:205], v[44:47]
	v_mfma_f32_16x16x32_bf16 v[40:43], v[178:181], v[202:205], v[40:43]
	v_mfma_f32_16x16x32_bf16 v[36:39], v[170:173], v[210:213], v[36:39]
	v_mfma_f32_16x16x32_bf16 v[32:35], v[178:181], v[210:213], v[32:35]
	s_barrier
	v_readfirstlane_b32 s7, v163
	v_lshl_add_u64 v[142:143], v[238:239], 0, s[56:57]
	s_mov_b32 m0, s7
	v_readfirstlane_b32 s7, v164
	global_load_lds_dwordx4 v[142:143], off
	v_lshl_add_u64 v[142:143], v[240:241], 0, s[56:57]
	s_mov_b32 m0, s7
	s_nop 0
	global_load_lds_dwordx4 v[142:143], off
	s_waitcnt vmcnt(6)
	s_barrier
	v_mfma_f32_16x16x32_bf16 v[28:31], v[216:219], v[182:185], v[28:31]
	v_mfma_f32_16x16x32_bf16 v[24:27], v[230:233], v[182:185], v[24:27]
	v_mfma_f32_16x16x32_bf16 v[20:23], v[216:219], v[190:193], v[20:23]
	v_mfma_f32_16x16x32_bf16 v[16:19], v[230:233], v[190:193], v[16:19]
	v_mfma_f32_16x16x32_bf16 v[12:15], v[216:219], v[198:201], v[12:15]
	v_mfma_f32_16x16x32_bf16 v[8:11], v[230:233], v[198:201], v[8:11]
	v_mfma_f32_16x16x32_bf16 v[4:7], v[216:219], v[206:209], v[4:7]
	v_mfma_f32_16x16x32_bf16 v[0:3], v[230:233], v[206:209], v[0:3]
	v_mfma_f32_16x16x32_bf16 v[28:31], v[226:229], v[186:189], v[28:31]
	v_mfma_f32_16x16x32_bf16 v[24:27], v[234:237], v[186:189], v[24:27]
	v_mfma_f32_16x16x32_bf16 v[20:23], v[226:229], v[194:197], v[20:23]
	v_mfma_f32_16x16x32_bf16 v[16:19], v[234:237], v[194:197], v[16:19]
	v_mfma_f32_16x16x32_bf16 v[12:15], v[226:229], v[202:205], v[12:15]
	v_mfma_f32_16x16x32_bf16 v[8:11], v[234:237], v[202:205], v[8:11]
	v_mfma_f32_16x16x32_bf16 v[4:7], v[226:229], v[210:213], v[4:7]
	v_mfma_f32_16x16x32_bf16 v[0:3], v[234:237], v[210:213], v[0:3]
	s_add_i32 s3, s3, 2
	s_add_u32 s28, s28, 0x100
	s_addc_u32 s29, s29, 0
	s_cmp_lt_u32 s3, 12
	s_barrier
	s_cbranch_scc1 .LBB0_1260
	s_add_u32 s22, s22, 0x40780
	s_addc_u32 s23, s23, 0
	v_readfirstlane_b32 s3, v167
	v_lshl_add_u64 v[144:145], v[64:65], 1, s[22:23]
	s_mov_b32 m0, s3
	v_readfirstlane_b32 s3, v168
	ds_read_b128 v[132:135], v166
	ds_read_b128 v[136:139], v166 offset:1024
	ds_read_b128 v[140:143], v166 offset:2048
	ds_read_b128 v[152:155], v166 offset:3072
	ds_read_b128 v[158:161], v150
	ds_read_b128 v[170:173], v150 offset:1024
	ds_read_b128 v[174:177], v149
	ds_read_b128 v[178:181], v149 offset:1024
	ds_read_b128 v[182:185], v148
	ds_read_b128 v[186:189], v148 offset:1024
	ds_read_b128 v[190:193], v147
	ds_read_b128 v[194:197], v147 offset:1024
	global_load_lds_dwordx4 v[144:145], off
	v_lshl_add_u64 v[130:131], v[130:131], 1, s[22:23]
	s_mov_b32 m0, s3
	s_nop 0
	global_load_lds_dwordx4 v[130:131], off
	s_barrier
	s_waitcnt lgkmcnt(0)
	s_waitcnt lgkmcnt(0)
	v_mfma_f32_16x16x32_bf16 v[126:129], v[132:135], v[158:161], v[126:129]
	v_mfma_f32_16x16x32_bf16 v[122:125], v[140:143], v[158:161], v[122:125]
	v_mfma_f32_16x16x32_bf16 v[118:121], v[132:135], v[174:177], v[118:121]
	v_mfma_f32_16x16x32_bf16 v[114:117], v[140:143], v[174:177], v[114:117]
	v_mfma_f32_16x16x32_bf16 v[110:113], v[132:135], v[182:185], v[110:113]
	v_mfma_f32_16x16x32_bf16 v[106:109], v[140:143], v[182:185], v[106:109]
	v_mfma_f32_16x16x32_bf16 v[102:105], v[132:135], v[190:193], v[102:105]
	v_mfma_f32_16x16x32_bf16 v[126:129], v[136:139], v[170:173], v[126:129]
	v_mfma_f32_16x16x32_bf16 v[122:125], v[152:155], v[170:173], v[122:125]
	v_mfma_f32_16x16x32_bf16 v[118:121], v[136:139], v[178:181], v[118:121]
	v_mfma_f32_16x16x32_bf16 v[114:117], v[152:155], v[178:181], v[114:117]
	v_mfma_f32_16x16x32_bf16 v[110:113], v[136:139], v[186:189], v[110:113]
	v_mfma_f32_16x16x32_bf16 v[106:109], v[152:155], v[186:189], v[106:109]
	v_mfma_f32_16x16x32_bf16 v[102:105], v[136:139], v[194:197], v[102:105]
	v_mfma_f32_16x16x32_bf16 v[98:101], v[140:143], v[190:193], v[98:101]
	v_mfma_f32_16x16x32_bf16 v[98:101], v[152:155], v[194:197], v[98:101]
	s_barrier
	ds_read_b128 v[166:169], v165
	ds_read_b128 v[198:201], v165 offset:1024
	ds_read_b128 v[202:205], v165 offset:2048
	ds_read_b128 v[162:165], v165 offset:3072
	s_barrier
	s_waitcnt lgkmcnt(0)
	s_waitcnt lgkmcnt(0)
	v_mfma_f32_16x16x32_bf16 v[94:97], v[166:169], v[158:161], v[94:97]
	v_mfma_f32_16x16x32_bf16 v[90:93], v[202:205], v[158:161], v[90:93]
	v_mfma_f32_16x16x32_bf16 v[86:89], v[166:169], v[174:177], v[86:89]
	v_mfma_f32_16x16x32_bf16 v[82:85], v[202:205], v[174:177], v[82:85]
	v_mfma_f32_16x16x32_bf16 v[78:81], v[166:169], v[182:185], v[78:81]
	v_mfma_f32_16x16x32_bf16 v[74:77], v[202:205], v[182:185], v[74:77]
	v_mfma_f32_16x16x32_bf16 v[70:73], v[166:169], v[190:193], v[70:73]
	v_mfma_f32_16x16x32_bf16 v[66:69], v[202:205], v[190:193], v[66:69]
	v_mfma_f32_16x16x32_bf16 v[94:97], v[198:201], v[170:173], v[94:97]
	v_mfma_f32_16x16x32_bf16 v[90:93], v[162:165], v[170:173], v[90:93]
	v_mfma_f32_16x16x32_bf16 v[86:89], v[198:201], v[178:181], v[86:89]
	v_mfma_f32_16x16x32_bf16 v[82:85], v[162:165], v[178:181], v[82:85]
	v_mfma_f32_16x16x32_bf16 v[78:81], v[198:201], v[186:189], v[78:81]
	v_mfma_f32_16x16x32_bf16 v[74:77], v[162:165], v[186:189], v[74:77]
	v_mfma_f32_16x16x32_bf16 v[70:73], v[198:201], v[194:197], v[70:73]
	v_mfma_f32_16x16x32_bf16 v[66:69], v[162:165], v[194:197], v[66:69]
	s_barrier
; #define LDA(dst, b, h) _Pragma("unroll") for (int m = 0; m < 4; ++m) _Pragma("unroll") for (int k = 0; k < 2; ++k) \
;     dst[m][k] = *(const bf16x8*)(lds + SA_(b, h) + lds_byte(wr * 64 + m * 16 + fr, k * 32 + fq * 8));
; #define LDB(dst, b, h) _Pragma("unroll") for (int n = 0; n < 2; ++n) _Pragma("unroll") for (int k = 0; k < 2; ++k) \
;     dst[n][k] = *(const bf16x8*)(lds + SB_(b, h) + lds_byte(wc * 32 + n * 16 + fr, k * 32 + fq * 8));
; #define MMA(ai, bj, At_, Bt_) { __builtin_amdgcn_s_setprio(1); \
;     _Pragma("unroll") for (int m = 0; m < 4; ++m) _Pragma("unroll") for (int n = 0; n < 2; ++n) _Pragma("unroll") for (int k = 0; k < 2; ++k) \
;       acc[ai][bj][m][n] = MFMA16(Bt_[n][k], At_[m][k], acc[ai][bj][m][n]); \
;     __builtin_amdgcn_s_setprio(0); }
; #define WAIT_V(n) asm volatile("s_waitcnt vmcnt(" #n ")" ::: "memory");
; #define WAIT_L(n) asm volatile("s_waitcnt lgkmcnt(" #n ")" ::: "memory");
; #define BAR __builtin_amdgcn_s_barrier();
; DI void gemm256(const u16* __restrict__ A, int lda, const u16* __restrict__ B0, const u16* __restrict__ B1, int ldb, int nt, acc_t& acc, char* lds) {
;     ...
;     LDA(At, 0, 1) WAIT_V(4) BAR WAIT_L(0) MMA(1, 0, At, Bq0) MMA(1, 1, At, Bq1) BAR }
;   { LDB(Bq0, 1, 0) LDA(At, 1, 0) WAIT_V(2) BAR WAIT_L(0) MMA(0, 0, At, Bq0) BAR
	ds_read_b128 v[158:161], v150 offset:16384
	ds_read_b128 v[170:173], v150 offset:17408
	ds_read_b128 v[174:177], v149 offset:16384
	ds_read_b128 v[178:181], v149 offset:17408
	ds_read_b128 v[182:185], v148 offset:16384
	ds_read_b128 v[186:189], v148 offset:17408
	ds_read_b128 v[190:193], v147 offset:16384
	ds_read_b128 v[194:197], v147 offset:17408
	s_waitcnt vmcnt(4)
	s_barrier
	s_waitcnt lgkmcnt(0)
	s_waitcnt lgkmcnt(0)
	v_mfma_f32_16x16x32_bf16 v[36:39], v[132:135], v[190:193], v[36:39]
	v_mfma_f32_16x16x32_bf16 v[32:35], v[140:143], v[190:193], v[32:35]
	v_mfma_f32_16x16x32_bf16 v[60:63], v[132:135], v[158:161], v[60:63]
	v_mfma_f32_16x16x32_bf16 v[56:59], v[140:143], v[158:161], v[56:59]
	v_mfma_f32_16x16x32_bf16 v[52:55], v[132:135], v[174:177], v[52:55]
	v_mfma_f32_16x16x32_bf16 v[48:51], v[140:143], v[174:177], v[48:51]
	v_mfma_f32_16x16x32_bf16 v[44:47], v[132:135], v[182:185], v[44:47]
	v_mfma_f32_16x16x32_bf16 v[40:43], v[140:143], v[182:185], v[40:43]
	v_mfma_f32_16x16x32_bf16 v[130:133], v[136:139], v[194:197], v[36:39]
	v_mfma_f32_16x16x32_bf16 v[142:145], v[152:155], v[194:197], v[32:35]
	v_mfma_f32_16x16x32_bf16 v[206:209], v[136:139], v[170:173], v[60:63]
	v_mfma_f32_16x16x32_bf16 v[210:213], v[152:155], v[170:173], v[56:59]
	v_mfma_f32_16x16x32_bf16 v[216:219], v[136:139], v[178:181], v[52:55]
	v_mfma_f32_16x16x32_bf16 v[226:229], v[152:155], v[178:181], v[48:51]
	v_mfma_f32_16x16x32_bf16 v[230:233], v[136:139], v[186:189], v[44:47]
	v_mfma_f32_16x16x32_bf16 v[234:237], v[152:155], v[186:189], v[40:43]
	v_mfma_f32_16x16x32_bf16 v[28:31], v[166:169], v[158:161], v[28:31]
	v_mfma_f32_16x16x32_bf16 v[24:27], v[202:205], v[158:161], v[24:27]
	v_mfma_f32_16x16x32_bf16 v[20:23], v[166:169], v[174:177], v[20:23]
	v_mfma_f32_16x16x32_bf16 v[16:19], v[202:205], v[174:177], v[16:19]
	v_mfma_f32_16x16x32_bf16 v[12:15], v[166:169], v[182:185], v[12:15]
	v_mfma_f32_16x16x32_bf16 v[8:11], v[202:205], v[182:185], v[8:11]
	v_mfma_f32_16x16x32_bf16 v[4:7], v[166:169], v[190:193], v[4:7]
	v_mfma_f32_16x16x32_bf16 v[0:3], v[202:205], v[190:193], v[0:3]
	v_mfma_f32_16x16x32_bf16 v[152:155], v[198:201], v[170:173], v[28:31]
	v_mfma_f32_16x16x32_bf16 v[158:161], v[162:165], v[170:173], v[24:27]
	v_mfma_f32_16x16x32_bf16 v[170:173], v[198:201], v[178:181], v[20:23]
	v_mfma_f32_16x16x32_bf16 v[174:177], v[162:165], v[178:181], v[16:19]
	v_mfma_f32_16x16x32_bf16 v[178:181], v[198:201], v[186:189], v[12:15]
	v_mfma_f32_16x16x32_bf16 v[182:185], v[162:165], v[186:189], v[8:11]
	v_mfma_f32_16x16x32_bf16 v[166:169], v[198:201], v[194:197], v[4:7]
	v_mfma_f32_16x16x32_bf16 v[162:165], v[162:165], v[194:197], v[0:3]
	s_barrier
	ds_read_b128 v[186:189], v156
	ds_read_b128 v[190:193], v156 offset:1024
	ds_read_b128 v[194:197], v156 offset:2048
	ds_read_b128 v[198:201], v156 offset:3072
	ds_read_b128 v[10:13], v150 offset:32768
	ds_read_b128 v[22:25], v150 offset:33792
	ds_read_b128 v[26:29], v149 offset:32768
	ds_read_b128 v[38:41], v149 offset:33792
	ds_read_b128 v[42:45], v148 offset:32768
	ds_read_b128 v[54:57], v148 offset:33792
	ds_read_b128 v[58:61], v147 offset:32768
	ds_read_b128 v[134:137], v147 offset:33792
	s_waitcnt vmcnt(2)
	s_barrier
	s_waitcnt lgkmcnt(0)
	s_waitcnt lgkmcnt(0)
	v_mfma_f32_16x16x32_bf16 v[6:9], v[186:189], v[26:29], v[118:121]
	v_mfma_f32_16x16x32_bf16 v[14:17], v[190:193], v[38:41], v[6:9]
	v_mfma_f32_16x16x32_bf16 v[6:9], v[194:197], v[26:29], v[114:117]
	v_mfma_f32_16x16x32_bf16 v[18:21], v[198:201], v[38:41], v[6:9]
	v_mfma_f32_16x16x32_bf16 v[6:9], v[186:189], v[42:45], v[110:113]
	v_mfma_f32_16x16x32_bf16 v[30:33], v[190:193], v[54:57], v[6:9]
	v_mfma_f32_16x16x32_bf16 v[6:9], v[194:197], v[42:45], v[106:109]
	v_mfma_f32_16x16x32_bf16 v[0:3], v[186:189], v[10:13], v[126:129]
	v_mfma_f32_16x16x32_bf16 v[34:37], v[198:201], v[54:57], v[6:9]
	v_mfma_f32_16x16x32_bf16 v[6:9], v[186:189], v[58:61], v[102:105]
	v_mfma_f32_16x16x32_bf16 v[138:141], v[190:193], v[22:25], v[0:3]
	v_mfma_f32_16x16x32_bf16 v[0:3], v[194:197], v[10:13], v[122:125]
	v_mfma_f32_16x16x32_bf16 v[46:49], v[190:193], v[134:137], v[6:9]
	v_mfma_f32_16x16x32_bf16 v[6:9], v[194:197], v[58:61], v[98:101]
	v_mfma_f32_16x16x32_bf16 v[2:5], v[198:201], v[22:25], v[0:3]
	v_mfma_f32_16x16x32_bf16 v[50:53], v[198:201], v[134:137], v[6:9]
	s_barrier
; #define LDA(dst, b, h) _Pragma("unroll") for (int m = 0; m < 4; ++m) _Pragma("unroll") for (int k = 0; k < 2; ++k) \
;     dst[m][k] = *(const bf16x8*)(lds + SA_(b, h) + lds_byte(wr * 64 + m * 16 + fr, k * 32 + fq * 8));
; #define LDB(dst, b, h) _Pragma("unroll") for (int n = 0; n < 2; ++n) _Pragma("unroll") for (int k = 0; k < 2; ++k) \
;     dst[n][k] = *(const bf16x8*)(lds + SB_(b, h) + lds_byte(wc * 32 + n * 16 + fr, k * 32 + fq * 8));
; #define MMA(ai, bj, At_, Bt_) { __builtin_amdgcn_s_setprio(1); \
;     _Pragma("unroll") for (int m = 0; m < 4; ++m) _Pragma("unroll") for (int n = 0; n < 2; ++n) _Pragma("unroll") for (int k = 0; k < 2; ++k) \
;       acc[ai][bj][m][n] = MFMA16(Bt_[n][k], At_[m][k], acc[ai][bj][m][n]); \
;     __builtin_amdgcn_s_setprio(0); }
; #define WAIT_V(n) asm volatile("s_waitcnt vmcnt(" #n ")" ::: "memory");
; #define WAIT_L(n) asm volatile("s_waitcnt lgkmcnt(" #n ")" ::: "memory");
; #define BAR __builtin_amdgcn_s_barrier();
; DI void gemm256(const u16* __restrict__ A, int lda, const u16* __restrict__ B0, const u16* __restrict__ B1, int ldb, int nt, acc_t& acc, char* lds) {
;     ...
;     LDB(Bq1, 1, 1) WAIT_V(0) BAR WAIT_L(0) MMA(0, 1, At, Bq1) BAR
;     LDA(At, 1, 1) BAR WAIT_L(0) MMA(1, 0, At, Bq0) MMA(1, 1, At, Bq1) BAR }
;   if (wr == 0) BAR
	ds_read_b128 v[202:205], v151
	ds_read_b128 v[238:241], v151 offset:1024
	ds_read_b128 v[242:245], v151 offset:2048
	ds_read_b128 v[246:249], v151 offset:3072
	s_waitcnt vmcnt(0)
	s_barrier
	s_waitcnt lgkmcnt(0)
	s_waitcnt lgkmcnt(0)
	v_mfma_f32_16x16x32_bf16 v[6:9], v[202:205], v[10:13], v[94:97]
	v_mfma_f32_16x16x32_bf16 v[10:13], v[242:245], v[10:13], v[90:93]
	v_mfma_f32_16x16x32_bf16 v[6:9], v[238:241], v[22:25], v[6:9]
	v_mfma_f32_16x16x32_bf16 v[10:13], v[246:249], v[22:25], v[10:13]
	v_mfma_f32_16x16x32_bf16 v[22:25], v[202:205], v[26:29], v[86:89]
	v_mfma_f32_16x16x32_bf16 v[26:29], v[242:245], v[26:29], v[82:85]
	v_mfma_f32_16x16x32_bf16 v[22:25], v[238:241], v[38:41], v[22:25]
	v_mfma_f32_16x16x32_bf16 v[26:29], v[246:249], v[38:41], v[26:29]
	v_mfma_f32_16x16x32_bf16 v[38:41], v[202:205], v[42:45], v[78:81]
	v_mfma_f32_16x16x32_bf16 v[42:45], v[242:245], v[42:45], v[74:77]
	v_mfma_f32_16x16x32_bf16 v[38:41], v[238:241], v[54:57], v[38:41]
	v_mfma_f32_16x16x32_bf16 v[42:45], v[246:249], v[54:57], v[42:45]
	v_mfma_f32_16x16x32_bf16 v[54:57], v[202:205], v[58:61], v[70:73]
	v_mfma_f32_16x16x32_bf16 v[58:61], v[242:245], v[58:61], v[66:69]
	v_mfma_f32_16x16x32_bf16 v[54:57], v[238:241], v[134:137], v[54:57]
	v_mfma_f32_16x16x32_bf16 v[58:61], v[246:249], v[134:137], v[58:61]
	s_barrier
	ds_read_b128 v[76:79], v150 offset:49152
	ds_read_b128 v[80:83], v150 offset:50176
	ds_read_b128 v[88:91], v149 offset:49152
	ds_read_b128 v[110:113], v149 offset:50176
	ds_read_b128 v[114:117], v148 offset:49152
	ds_read_b128 v[148:151], v148 offset:50176
	ds_read_b128 v[222:225], v147 offset:49152
	ds_read_b128 v[98:101], v147 offset:50176
	s_barrier
	s_waitcnt lgkmcnt(0)
	s_waitcnt lgkmcnt(0)
	v_mfma_f32_16x16x32_bf16 v[72:75], v[186:189], v[88:91], v[216:219]
	v_mfma_f32_16x16x32_bf16 v[84:87], v[190:193], v[110:113], v[72:75]
	v_mfma_f32_16x16x32_bf16 v[72:75], v[194:197], v[88:91], v[226:229]
	v_mfma_f32_16x16x32_bf16 v[94:97], v[198:201], v[110:113], v[72:75]
	v_mfma_f32_16x16x32_bf16 v[72:75], v[186:189], v[114:117], v[230:233]
	v_mfma_f32_16x16x32_bf16 v[118:121], v[190:193], v[148:151], v[72:75]
	v_mfma_f32_16x16x32_bf16 v[72:75], v[194:197], v[114:117], v[234:237]
	v_mfma_f32_16x16x32_bf16 v[66:69], v[186:189], v[76:79], v[206:209]
	v_mfma_f32_16x16x32_bf16 v[126:129], v[198:201], v[148:151], v[72:75]
	v_mfma_f32_16x16x32_bf16 v[72:75], v[186:189], v[222:225], v[130:133]
	v_mfma_f32_16x16x32_bf16 v[134:137], v[190:193], v[80:83], v[66:69]
	v_mfma_f32_16x16x32_bf16 v[66:69], v[194:197], v[76:79], v[210:213]
	v_mfma_f32_16x16x32_bf16 v[106:109], v[190:193], v[98:101], v[72:75]
	v_mfma_f32_16x16x32_bf16 v[72:75], v[194:197], v[222:225], v[142:145]
	v_mfma_f32_16x16x32_bf16 v[68:71], v[198:201], v[80:83], v[66:69]
	v_mfma_f32_16x16x32_bf16 v[142:145], v[198:201], v[98:101], v[72:75]
	v_mfma_f32_16x16x32_bf16 v[72:75], v[202:205], v[76:79], v[152:155]
	v_mfma_f32_16x16x32_bf16 v[76:79], v[242:245], v[76:79], v[158:161]
	v_mfma_f32_16x16x32_bf16 v[130:133], v[246:249], v[80:83], v[76:79]
	v_mfma_f32_16x16x32_bf16 v[76:79], v[202:205], v[88:91], v[170:173]
	v_mfma_f32_16x16x32_bf16 v[102:105], v[238:241], v[110:113], v[76:79]
	v_mfma_f32_16x16x32_bf16 v[76:79], v[242:245], v[88:91], v[174:177]
	v_mfma_f32_16x16x32_bf16 v[110:113], v[246:249], v[110:113], v[76:79]
	v_mfma_f32_16x16x32_bf16 v[76:79], v[202:205], v[114:117], v[178:181]
	v_mfma_f32_16x16x32_bf16 v[122:125], v[238:241], v[148:151], v[76:79]
	v_mfma_f32_16x16x32_bf16 v[76:79], v[242:245], v[114:117], v[182:185]
	v_mfma_f32_16x16x32_bf16 v[114:117], v[246:249], v[148:151], v[76:79]
	v_mfma_f32_16x16x32_bf16 v[76:79], v[202:205], v[222:225], v[166:169]
	v_mfma_f32_16x16x32_bf16 v[90:93], v[238:241], v[98:101], v[76:79]
	v_mfma_f32_16x16x32_bf16 v[76:79], v[242:245], v[222:225], v[162:165]
	v_mfma_f32_16x16x32_bf16 v[72:75], v[238:241], v[80:83], v[72:75]
	v_mfma_f32_16x16x32_bf16 v[78:81], v[246:249], v[98:101], v[76:79]
	s_movk_i32 s3, 0x100
	v_cmp_gt_u32_e32 vcc, s3, v146
	s_barrier
	s_and_saveexec_b64 s[22:23], vcc
	s_cbranch_execz .LBB0_1263
	s_barrier

; #define STAGE_A(b, h, kt) { const u16* ap_ = A + (size_t)((h) * ahalf + (unsigned)(kt) * 64u); glds16(ap_ + ao0, l0 + SA_(b, h)); glds16(ap_ + ao1, l0 + SA_(b, h) + 8192); }
; #define STAGE_B(b, h, kt) { const u16* bp_ = ((h) ? B1 : B0) + (unsigned)(kt) * 64u; glds16(bp_ + bo0, l0 + SB_(b, h)); glds16(bp_ + bo1, l0 + SB_(b, h) + 8192); }
; #define LDA(dst, b, h) _Pragma("unroll") for (int m = 0; m < 4; ++m) _Pragma("unroll") for (int k = 0; k < 2; ++k) \
;     dst[m][k] = *(const bf16x8*)(lds + SA_(b, h) + lds_byte(wr * 64 + m * 16 + fr, k * 32 + fq * 8));
; #define LDB(dst, b, h) _Pragma("unroll") for (int n = 0; n < 2; ++n) _Pragma("unroll") for (int k = 0; k < 2; ++k) \
;     dst[n][k] = *(const bf16x8*)(lds + SB_(b, h) + lds_byte(wc * 32 + n * 16 + fr, k * 32 + fq * 8));
; #define MMA(ai, bj, At_, Bt_) { __builtin_amdgcn_s_setprio(1); \
;     _Pragma("unroll") for (int m = 0; m < 4; ++m) _Pragma("unroll") for (int n = 0; n < 2; ++n) _Pragma("unroll") for (int k = 0; k < 2; ++k) \
;       acc[ai][bj][m][n] = MFMA16(Bt_[n][k], At_[m][k], acc[ai][bj][m][n]); \
;     __builtin_amdgcn_s_setprio(0); }
; #define WAIT_L(n) asm volatile("s_waitcnt lgkmcnt(" #n ")" ::: "memory");
; #define BAR __builtin_amdgcn_s_barrier();
; #define SCHED __builtin_amdgcn_sched_barrier(0);
; DI void gemm256(const u16* __restrict__ A, int lda, const u16* __restrict__ B0, const u16* __restrict__ B1, int ldb, int nt, acc_t& acc, char* lds) {
;     ...
;     LDB(Bq0, 0, 0) SCHED LDA(At, 0, 0) STAGE_A(1, 1, t + 1)
;     WAIT_L(8) BAR WAIT_L(0) MMA(0, 0, At, Bq0) BAR SCHED
;     LDB(Bq1, 0, 1) STAGE_B(0, 0, t + 2)
;     BAR WAIT_L(0) MMA(0, 1, At, Bq1) BAR
;     LDA(At, 0, 1) STAGE_A(0, 0, t + 2)
;     BAR WAIT_L(0) MMA(1, 0, At, Bq0) BAR SCHED
.LBB0_1266:
	ds_read_b128 v[142:145], v157
	ds_read_b128 v[160:163], v157 offset:1024
	ds_read_b128 v[164:167], v157 offset:2048
	ds_read_b128 v[168:171], v157 offset:3072
	v_add_u32_e32 v158, 0xc000, v226
	v_lshl_add_u64 v[212:213], s[8:9], 0, v[134:135]
	v_readfirstlane_b32 s3, v158
	v_add_u32_e32 v159, 0xe000, v226
	v_lshl_add_u64 v[204:205], v[212:213], 0, s[28:29]
	s_mov_b32 m0, s3
	v_lshl_add_u64 v[222:223], s[8:9], 0, v[136:137]
	v_readfirstlane_b32 s3, v159
	ds_read_b128 v[172:175], v151
	ds_read_b128 v[176:179], v151 offset:1024
	ds_read_b128 v[180:183], v150
	ds_read_b128 v[184:187], v150 offset:1024
	ds_read_b128 v[188:191], v149
	ds_read_b128 v[192:195], v149 offset:1024
	ds_read_b128 v[196:199], v148
	ds_read_b128 v[200:203], v148 offset:1024
	global_load_lds_dwordx4 v[204:205], off
	v_lshl_add_u64 v[204:205], v[222:223], 0, s[28:29]
	s_mov_b32 m0, s3
	s_nop 0
	global_load_lds_dwordx4 v[204:205], off
	s_waitcnt lgkmcnt(8)
	s_barrier
	s_waitcnt lgkmcnt(0)
	s_waitcnt lgkmcnt(0)
	v_mfma_f32_16x16x32_bf16 v[0:3], v[142:145], v[172:175], v[0:3]
	v_mfma_f32_16x16x32_bf16 v[4:7], v[164:167], v[172:175], v[4:7]
	v_mfma_f32_16x16x32_bf16 v[16:19], v[142:145], v[180:183], v[16:19]
	v_mfma_f32_16x16x32_bf16 v[20:23], v[164:167], v[180:183], v[20:23]
	v_mfma_f32_16x16x32_bf16 v[32:35], v[142:145], v[188:191], v[32:35]
	v_mfma_f32_16x16x32_bf16 v[36:39], v[164:167], v[188:191], v[36:39]
	v_mfma_f32_16x16x32_bf16 v[48:51], v[142:145], v[196:199], v[48:51]
	v_mfma_f32_16x16x32_bf16 v[52:55], v[164:167], v[196:199], v[52:55]
	v_mfma_f32_16x16x32_bf16 v[0:3], v[160:163], v[176:179], v[0:3]
	v_mfma_f32_16x16x32_bf16 v[4:7], v[168:171], v[176:179], v[4:7]
	v_mfma_f32_16x16x32_bf16 v[16:19], v[160:163], v[184:187], v[16:19]
	v_mfma_f32_16x16x32_bf16 v[20:23], v[168:171], v[184:187], v[20:23]
	v_mfma_f32_16x16x32_bf16 v[32:35], v[160:163], v[192:195], v[32:35]
	v_mfma_f32_16x16x32_bf16 v[36:39], v[168:171], v[192:195], v[36:39]
	v_mfma_f32_16x16x32_bf16 v[48:51], v[160:163], v[200:203], v[48:51]
	v_mfma_f32_16x16x32_bf16 v[52:55], v[168:171], v[200:203], v[52:55]
	s_barrier
	v_lshl_add_u64 v[238:239], s[8:9], 0, v[130:131]
	v_readfirstlane_b32 s3, v227
	v_lshl_add_u64 v[240:241], v[238:239], 0, s[44:45]
	s_mov_b32 m0, s3
	ds_read_b128 v[204:207], v156
	ds_read_b128 v[208:211], v156 offset:1024
	ds_read_b128 v[216:219], v156 offset:2048
	ds_read_b128 v[234:237], v156 offset:3072
	global_load_lds_dwordx4 v[240:241], off
	v_lshl_add_u64 v[240:241], s[8:9], 0, v[132:133]
	v_readfirstlane_b32 s3, v228
	v_lshl_add_u64 v[242:243], v[240:241], 0, s[44:45]
	s_mov_b32 m0, s3
	s_nop 0
	global_load_lds_dwordx4 v[242:243], off
	s_barrier
	s_waitcnt lgkmcnt(0)
	s_waitcnt lgkmcnt(0)
	v_mfma_f32_16x16x32_bf16 v[8:11], v[204:207], v[172:175], v[8:11]
	v_mfma_f32_16x16x32_bf16 v[12:15], v[216:219], v[172:175], v[12:15]
	v_mfma_f32_16x16x32_bf16 v[24:27], v[204:207], v[180:183], v[24:27]
	v_mfma_f32_16x16x32_bf16 v[28:31], v[216:219], v[180:183], v[28:31]
	v_mfma_f32_16x16x32_bf16 v[40:43], v[204:207], v[188:191], v[40:43]
	v_mfma_f32_16x16x32_bf16 v[44:47], v[216:219], v[188:191], v[44:47]
	v_mfma_f32_16x16x32_bf16 v[56:59], v[204:207], v[196:199], v[56:59]
	v_mfma_f32_16x16x32_bf16 v[60:63], v[216:219], v[196:199], v[60:63]
	v_mfma_f32_16x16x32_bf16 v[8:11], v[208:211], v[176:179], v[8:11]
	v_mfma_f32_16x16x32_bf16 v[12:15], v[234:237], v[176:179], v[12:15]
	v_mfma_f32_16x16x32_bf16 v[24:27], v[208:211], v[184:187], v[24:27]
	v_mfma_f32_16x16x32_bf16 v[28:31], v[234:237], v[184:187], v[28:31]
	v_mfma_f32_16x16x32_bf16 v[40:43], v[208:211], v[192:195], v[40:43]
	v_mfma_f32_16x16x32_bf16 v[44:47], v[234:237], v[192:195], v[44:47]
	v_mfma_f32_16x16x32_bf16 v[56:59], v[208:211], v[200:203], v[56:59]
	v_mfma_f32_16x16x32_bf16 v[60:63], v[234:237], v[200:203], v[60:63]
	v_readfirstlane_b32 s3, v226
	v_lshl_add_u64 v[242:243], v[212:213], 0, s[70:71]
	s_mov_b32 m0, s3
	v_readfirstlane_b32 s3, v229
	s_barrier
	ds_read_b128 v[172:175], v151 offset:16384
	ds_read_b128 v[176:179], v151 offset:17408
	ds_read_b128 v[180:183], v150 offset:16384
	ds_read_b128 v[184:187], v150 offset:17408
	ds_read_b128 v[188:191], v149 offset:16384
	ds_read_b128 v[192:195], v149 offset:17408
	ds_read_b128 v[196:199], v148 offset:16384
	ds_read_b128 v[200:203], v148 offset:17408
	global_load_lds_dwordx4 v[242:243], off
	v_lshl_add_u64 v[242:243], v[222:223], 0, s[70:71]
	s_mov_b32 m0, s3
	s_nop 0
	global_load_lds_dwordx4 v[242:243], off
	s_barrier
	s_waitcnt lgkmcnt(0)
	s_waitcnt lgkmcnt(0)
	v_mfma_f32_16x16x32_bf16 v[66:69], v[142:145], v[172:175], v[66:69]
	v_mfma_f32_16x16x32_bf16 v[70:73], v[164:167], v[172:175], v[70:73]
	v_mfma_f32_16x16x32_bf16 v[86:89], v[142:145], v[180:183], v[86:89]
	v_mfma_f32_16x16x32_bf16 v[94:97], v[164:167], v[180:183], v[94:97]
	v_mfma_f32_16x16x32_bf16 v[118:121], v[142:145], v[188:191], v[118:121]
	v_mfma_f32_16x16x32_bf16 v[126:129], v[164:167], v[188:191], v[126:129]
	v_mfma_f32_16x16x32_bf16 v[106:109], v[142:145], v[196:199], v[106:109]
	v_mfma_f32_16x16x32_bf16 v[98:101], v[164:167], v[196:199], v[98:101]
	v_mfma_f32_16x16x32_bf16 v[66:69], v[160:163], v[176:179], v[66:69]
	v_mfma_f32_16x16x32_bf16 v[70:73], v[168:171], v[176:179], v[70:73]
	v_mfma_f32_16x16x32_bf16 v[86:89], v[160:163], v[184:187], v[86:89]
	v_mfma_f32_16x16x32_bf16 v[94:97], v[168:171], v[184:187], v[94:97]
	v_mfma_f32_16x16x32_bf16 v[118:121], v[160:163], v[192:195], v[118:121]
	v_mfma_f32_16x16x32_bf16 v[126:129], v[168:171], v[192:195], v[126:129]
	v_mfma_f32_16x16x32_bf16 v[106:109], v[160:163], v[200:203], v[106:109]
	v_mfma_f32_16x16x32_bf16 v[98:101], v[168:171], v[200:203], v[98:101]
	s_barrier
; #define STAGE_A(b, h, kt) { const u16* ap_ = A + (size_t)((h) * ahalf + (unsigned)(kt) * 64u); glds16(ap_ + ao0, l0 + SA_(b, h)); glds16(ap_ + ao1, l0 + SA_(b, h) + 8192); }
; #define STAGE_B(b, h, kt) { const u16* bp_ = ((h) ? B1 : B0) + (unsigned)(kt) * 64u; glds16(bp_ + bo0, l0 + SB_(b, h)); glds16(bp_ + bo1, l0 + SB_(b, h) + 8192); }
; #define LDA(dst, b, h) _Pragma("unroll") for (int m = 0; m < 4; ++m) _Pragma("unroll") for (int k = 0; k < 2; ++k) \
;     dst[m][k] = *(const bf16x8*)(lds + SA_(b, h) + lds_byte(wr * 64 + m * 16 + fr, k * 32 + fq * 8));
; #define LDB(dst, b, h) _Pragma("unroll") for (int n = 0; n < 2; ++n) _Pragma("unroll") for (int k = 0; k < 2; ++k) \
;     dst[n][k] = *(const bf16x8*)(lds + SB_(b, h) + lds_byte(wc * 32 + n * 16 + fr, k * 32 + fq * 8));
; #define MMA(ai, bj, At_, Bt_) { __builtin_amdgcn_s_setprio(1); \
;     _Pragma("unroll") for (int m = 0; m < 4; ++m) _Pragma("unroll") for (int n = 0; n < 2; ++n) _Pragma("unroll") for (int k = 0; k < 2; ++k) \
;       acc[ai][bj][m][n] = MFMA16(Bt_[n][k], At_[m][k], acc[ai][bj][m][n]); \
;     __builtin_amdgcn_s_setprio(0); }
; #define WAIT_V(n) asm volatile("s_waitcnt vmcnt(" #n ")" ::: "memory");
; #define WAIT_L(n) asm volatile("s_waitcnt lgkmcnt(" #n ")" ::: "memory");
; #define BAR __builtin_amdgcn_s_barrier();
; #define SCHED __builtin_amdgcn_sched_barrier(0);
; DI void gemm256(const u16* __restrict__ A, int lda, const u16* __restrict__ B0, const u16* __restrict__ B1, int ldb, int nt, acc_t& acc, char* lds) {
;     ...
;     STAGE_B(0, 1, t + 2)
;     WAIT_V(6) BAR MMA(1, 1, At, Bq1) BAR
;     LDB(Bq0, 1, 0) SCHED LDA(At, 1, 0) STAGE_A(0, 1, t + 2)
;     WAIT_L(8) BAR WAIT_L(0) MMA(0, 0, At, Bq0) BAR SCHED
;     LDB(Bq1, 1, 1) STAGE_B(1, 0, t + 3)
;     BAR WAIT_L(0) MMA(0, 1, At, Bq1) BAR
;     LDA(At, 1, 1) STAGE_A(1, 0, t + 3)
	v_readfirstlane_b32 s3, v230
	v_lshl_add_u64 v[142:143], v[238:239], 0, s[46:47]
	s_mov_b32 m0, s3
	v_readfirstlane_b32 s3, v231
	global_load_lds_dwordx4 v[142:143], off
	v_lshl_add_u64 v[142:143], v[240:241], 0, s[46:47]
	s_mov_b32 m0, s3
	s_nop 0
	global_load_lds_dwordx4 v[142:143], off
	s_waitcnt vmcnt(6)
	s_barrier
	v_mfma_f32_16x16x32_bf16 v[74:77], v[204:207], v[172:175], v[74:77]
	v_mfma_f32_16x16x32_bf16 v[82:85], v[216:219], v[172:175], v[82:85]
	v_mfma_f32_16x16x32_bf16 v[102:105], v[204:207], v[180:183], v[102:105]
	v_mfma_f32_16x16x32_bf16 v[110:113], v[216:219], v[180:183], v[110:113]
	v_mfma_f32_16x16x32_bf16 v[122:125], v[204:207], v[188:191], v[122:125]
	v_mfma_f32_16x16x32_bf16 v[114:117], v[216:219], v[188:191], v[114:117]
	v_mfma_f32_16x16x32_bf16 v[90:93], v[204:207], v[196:199], v[90:93]
	v_mfma_f32_16x16x32_bf16 v[78:81], v[216:219], v[196:199], v[78:81]
	v_mfma_f32_16x16x32_bf16 v[74:77], v[208:211], v[176:179], v[74:77]
	v_mfma_f32_16x16x32_bf16 v[82:85], v[234:237], v[176:179], v[82:85]
	v_mfma_f32_16x16x32_bf16 v[102:105], v[208:211], v[184:187], v[102:105]
	v_mfma_f32_16x16x32_bf16 v[110:113], v[234:237], v[184:187], v[110:113]
	v_mfma_f32_16x16x32_bf16 v[122:125], v[208:211], v[192:195], v[122:125]
	v_mfma_f32_16x16x32_bf16 v[114:117], v[234:237], v[192:195], v[114:117]
	v_mfma_f32_16x16x32_bf16 v[90:93], v[208:211], v[200:203], v[90:93]
	v_mfma_f32_16x16x32_bf16 v[78:81], v[234:237], v[200:203], v[78:81]
	s_barrier
	ds_read_b128 v[142:145], v155
	ds_read_b128 v[160:163], v155 offset:1024
	ds_read_b128 v[164:167], v155 offset:2048
	ds_read_b128 v[168:171], v155 offset:3072
	v_readfirstlane_b32 s3, v232
	v_lshl_add_u64 v[204:205], v[212:213], 0, s[48:49]
	s_mov_b32 m0, s3
	v_readfirstlane_b32 s3, v233
	ds_read_b128 v[172:175], v151 offset:32768
	ds_read_b128 v[176:179], v151 offset:33792
	ds_read_b128 v[180:183], v150 offset:32768
	ds_read_b128 v[184:187], v150 offset:33792
	ds_read_b128 v[188:191], v149 offset:32768
	ds_read_b128 v[192:195], v149 offset:33792
	ds_read_b128 v[196:199], v148 offset:32768
	ds_read_b128 v[200:203], v148 offset:33792
	global_load_lds_dwordx4 v[204:205], off
	v_lshl_add_u64 v[204:205], v[222:223], 0, s[48:49]
	s_mov_b32 m0, s3
	s_nop 0
	global_load_lds_dwordx4 v[204:205], off
	s_waitcnt lgkmcnt(8)
	s_barrier
	s_waitcnt lgkmcnt(0)
	s_waitcnt lgkmcnt(0)
	v_mfma_f32_16x16x32_bf16 v[0:3], v[142:145], v[172:175], v[0:3]
	v_mfma_f32_16x16x32_bf16 v[4:7], v[164:167], v[172:175], v[4:7]
	v_mfma_f32_16x16x32_bf16 v[16:19], v[142:145], v[180:183], v[16:19]
	v_mfma_f32_16x16x32_bf16 v[20:23], v[164:167], v[180:183], v[20:23]
	v_mfma_f32_16x16x32_bf16 v[32:35], v[142:145], v[188:191], v[32:35]
	v_mfma_f32_16x16x32_bf16 v[36:39], v[164:167], v[188:191], v[36:39]
	v_mfma_f32_16x16x32_bf16 v[48:51], v[142:145], v[196:199], v[48:51]
	v_mfma_f32_16x16x32_bf16 v[52:55], v[164:167], v[196:199], v[52:55]
	v_mfma_f32_16x16x32_bf16 v[0:3], v[160:163], v[176:179], v[0:3]
	v_mfma_f32_16x16x32_bf16 v[4:7], v[168:171], v[176:179], v[4:7]
	v_mfma_f32_16x16x32_bf16 v[16:19], v[160:163], v[184:187], v[16:19]
	v_mfma_f32_16x16x32_bf16 v[20:23], v[168:171], v[184:187], v[20:23]
	v_mfma_f32_16x16x32_bf16 v[32:35], v[160:163], v[192:195], v[32:35]
	v_mfma_f32_16x16x32_bf16 v[36:39], v[168:171], v[192:195], v[36:39]
	v_mfma_f32_16x16x32_bf16 v[48:51], v[160:163], v[200:203], v[48:51]
	v_mfma_f32_16x16x32_bf16 v[52:55], v[168:171], v[200:203], v[52:55]
	s_barrier
	v_readfirstlane_b32 s3, v138
	v_lshl_add_u64 v[242:243], v[238:239], 0, s[52:53]
	s_mov_b32 m0, s3
	v_readfirstlane_b32 s3, v139
	ds_read_b128 v[204:207], v154
	ds_read_b128 v[208:211], v154 offset:1024
	ds_read_b128 v[216:219], v154 offset:2048
	ds_read_b128 v[234:237], v154 offset:3072
	global_load_lds_dwordx4 v[242:243], off
	v_lshl_add_u64 v[242:243], v[240:241], 0, s[52:53]
	s_mov_b32 m0, s3
	s_nop 0
	global_load_lds_dwordx4 v[242:243], off
	s_barrier
	s_waitcnt lgkmcnt(0)
	s_waitcnt lgkmcnt(0)
	v_mfma_f32_16x16x32_bf16 v[8:11], v[204:207], v[172:175], v[8:11]
	v_mfma_f32_16x16x32_bf16 v[12:15], v[216:219], v[172:175], v[12:15]
	v_mfma_f32_16x16x32_bf16 v[24:27], v[204:207], v[180:183], v[24:27]
	v_mfma_f32_16x16x32_bf16 v[28:31], v[216:219], v[180:183], v[28:31]
	v_mfma_f32_16x16x32_bf16 v[40:43], v[204:207], v[188:191], v[40:43]
	v_mfma_f32_16x16x32_bf16 v[44:47], v[216:219], v[188:191], v[44:47]
	v_mfma_f32_16x16x32_bf16 v[56:59], v[204:207], v[196:199], v[56:59]
	v_mfma_f32_16x16x32_bf16 v[60:63], v[216:219], v[196:199], v[60:63]
	v_mfma_f32_16x16x32_bf16 v[8:11], v[208:211], v[176:179], v[8:11]
	v_mfma_f32_16x16x32_bf16 v[12:15], v[234:237], v[176:179], v[12:15]
	v_mfma_f32_16x16x32_bf16 v[24:27], v[208:211], v[184:187], v[24:27]
	v_mfma_f32_16x16x32_bf16 v[28:31], v[234:237], v[184:187], v[28:31]
	v_mfma_f32_16x16x32_bf16 v[40:43], v[208:211], v[192:195], v[40:43]
	v_mfma_f32_16x16x32_bf16 v[44:47], v[234:237], v[192:195], v[44:47]
	v_mfma_f32_16x16x32_bf16 v[56:59], v[208:211], v[200:203], v[56:59]
	v_mfma_f32_16x16x32_bf16 v[60:63], v[234:237], v[200:203], v[60:63]
	v_readfirstlane_b32 s3, v140
	v_lshl_add_u64 v[212:213], v[212:213], 0, s[72:73]
	s_mov_b32 m0, s3
	v_readfirstlane_b32 s3, v141
	s_barrier
	ds_read_b128 v[172:175], v151 offset:49152
	ds_read_b128 v[176:179], v151 offset:50176
	ds_read_b128 v[180:183], v150 offset:49152
	ds_read_b128 v[184:187], v150 offset:50176
	ds_read_b128 v[188:191], v149 offset:49152
	ds_read_b128 v[192:195], v149 offset:50176
	ds_read_b128 v[196:199], v148 offset:49152
	ds_read_b128 v[200:203], v148 offset:50176
	global_load_lds_dwordx4 v[212:213], off
	v_lshl_add_u64 v[212:213], v[222:223], 0, s[72:73]
	s_mov_b32 m0, s3
	s_nop 0
	global_load_lds_dwordx4 v[212:213], off
	s_barrier
; #define STAGE_A(b, h, kt) { const u16* ap_ = A + (size_t)((h) * ahalf + (unsigned)(kt) * 64u); glds16(ap_ + ao0, l0 + SA_(b, h)); glds16(ap_ + ao1, l0 + SA_(b, h) + 8192); }
; #define STAGE_B(b, h, kt) { const u16* bp_ = ((h) ? B1 : B0) + (unsigned)(kt) * 64u; glds16(bp_ + bo0, l0 + SB_(b, h)); glds16(bp_ + bo1, l0 + SB_(b, h) + 8192); }
; #define LDA(dst, b, h) _Pragma("unroll") for (int m = 0; m < 4; ++m) _Pragma("unroll") for (int k = 0; k < 2; ++k) \
;     dst[m][k] = *(const bf16x8*)(lds + SA_(b, h) + lds_byte(wr * 64 + m * 16 + fr, k * 32 + fq * 8));
; #define LDB(dst, b, h) _Pragma("unroll") for (int n = 0; n < 2; ++n) _Pragma("unroll") for (int k = 0; k < 2; ++k) \
;     dst[n][k] = *(const bf16x8*)(lds + SB_(b, h) + lds_byte(wc * 32 + n * 16 + fr, k * 32 + fq * 8));
; #define MMA(ai, bj, At_, Bt_) { __builtin_amdgcn_s_setprio(1); \
;     _Pragma("unroll") for (int m = 0; m < 4; ++m) _Pragma("unroll") for (int n = 0; n < 2; ++n) _Pragma("unroll") for (int k = 0; k < 2; ++k) \
;       acc[ai][bj][m][n] = MFMA16(Bt_[n][k], At_[m][k], acc[ai][bj][m][n]); \
;     __builtin_amdgcn_s_setprio(0); }
; #define WAIT_V(n) asm volatile("s_waitcnt vmcnt(" #n ")" ::: "memory");
; #define WAIT_L(n) asm volatile("s_waitcnt lgkmcnt(" #n ")" ::: "memory");
; #define BAR __builtin_amdgcn_s_barrier();
; #define SCHED __builtin_amdgcn_sched_barrier(0);
; DI void gemm256(const u16* __restrict__ A, int lda, const u16* __restrict__ B0, const u16* __restrict__ B1, int ldb, int nt, acc_t& acc, char* lds) {
;     ...
;     BAR WAIT_L(0) MMA(1, 0, At, Bq0) BAR SCHED
;     STAGE_B(1, 1, t + 3)
;     WAIT_V(6) BAR MMA(1, 1, At, Bq1) BAR
;   }
;   { LDB(Bq0, 0, 0) LDA(At, 0, 0) STAGE_A(1, 1, nt - 1)
;     BAR WAIT_L(0) MMA(0, 0, At, Bq0) BAR
;     LDB(Bq1, 0, 1) BAR WAIT_L(0) MMA(0, 1, At, Bq1) BAR
	s_waitcnt lgkmcnt(0)
	s_waitcnt lgkmcnt(0)
	v_mfma_f32_16x16x32_bf16 v[66:69], v[142:145], v[172:175], v[66:69]
	v_mfma_f32_16x16x32_bf16 v[70:73], v[164:167], v[172:175], v[70:73]
	v_mfma_f32_16x16x32_bf16 v[86:89], v[142:145], v[180:183], v[86:89]
	v_mfma_f32_16x16x32_bf16 v[94:97], v[164:167], v[180:183], v[94:97]
	v_mfma_f32_16x16x32_bf16 v[118:121], v[142:145], v[188:191], v[118:121]
	v_mfma_f32_16x16x32_bf16 v[126:129], v[164:167], v[188:191], v[126:129]
	v_mfma_f32_16x16x32_bf16 v[106:109], v[142:145], v[196:199], v[106:109]
	v_mfma_f32_16x16x32_bf16 v[98:101], v[164:167], v[196:199], v[98:101]
	v_mfma_f32_16x16x32_bf16 v[66:69], v[160:163], v[176:179], v[66:69]
	v_mfma_f32_16x16x32_bf16 v[70:73], v[168:171], v[176:179], v[70:73]
	v_mfma_f32_16x16x32_bf16 v[86:89], v[160:163], v[184:187], v[86:89]
	v_mfma_f32_16x16x32_bf16 v[94:97], v[168:171], v[184:187], v[94:97]
	v_mfma_f32_16x16x32_bf16 v[118:121], v[160:163], v[192:195], v[118:121]
	v_mfma_f32_16x16x32_bf16 v[126:129], v[168:171], v[192:195], v[126:129]
	v_mfma_f32_16x16x32_bf16 v[106:109], v[160:163], v[200:203], v[106:109]
	v_mfma_f32_16x16x32_bf16 v[98:101], v[168:171], v[200:203], v[98:101]
	s_barrier
	v_readfirstlane_b32 s3, v152
	v_lshl_add_u64 v[142:143], v[238:239], 0, s[54:55]
	s_mov_b32 m0, s3
	v_readfirstlane_b32 s3, v153
	global_load_lds_dwordx4 v[142:143], off
	v_lshl_add_u64 v[142:143], v[240:241], 0, s[54:55]
	s_mov_b32 m0, s3
	s_nop 0
	global_load_lds_dwordx4 v[142:143], off
	s_waitcnt vmcnt(6)
	s_barrier
	v_mfma_f32_16x16x32_bf16 v[74:77], v[204:207], v[172:175], v[74:77]
	v_mfma_f32_16x16x32_bf16 v[82:85], v[216:219], v[172:175], v[82:85]
	v_mfma_f32_16x16x32_bf16 v[102:105], v[204:207], v[180:183], v[102:105]
	v_mfma_f32_16x16x32_bf16 v[110:113], v[216:219], v[180:183], v[110:113]
	v_mfma_f32_16x16x32_bf16 v[122:125], v[204:207], v[188:191], v[122:125]
	v_mfma_f32_16x16x32_bf16 v[114:117], v[216:219], v[188:191], v[114:117]
	v_mfma_f32_16x16x32_bf16 v[90:93], v[204:207], v[196:199], v[90:93]
	v_mfma_f32_16x16x32_bf16 v[78:81], v[216:219], v[196:199], v[78:81]
	v_mfma_f32_16x16x32_bf16 v[74:77], v[208:211], v[176:179], v[74:77]
	v_mfma_f32_16x16x32_bf16 v[82:85], v[234:237], v[176:179], v[82:85]
	v_mfma_f32_16x16x32_bf16 v[102:105], v[208:211], v[184:187], v[102:105]
	v_mfma_f32_16x16x32_bf16 v[110:113], v[234:237], v[184:187], v[110:113]
	v_mfma_f32_16x16x32_bf16 v[122:125], v[208:211], v[192:195], v[122:125]
	v_mfma_f32_16x16x32_bf16 v[114:117], v[234:237], v[192:195], v[114:117]
	v_mfma_f32_16x16x32_bf16 v[90:93], v[208:211], v[200:203], v[90:93]
	v_mfma_f32_16x16x32_bf16 v[78:81], v[234:237], v[200:203], v[78:81]
	s_add_i32 s2, s2, 2
	s_add_u32 s8, s8, 0x100
	s_addc_u32 s9, s9, 0
	s_cmp_lt_u32 s2, 40
	s_barrier
	s_cbranch_scc1 .LBB0_1266
	s_add_u32 s2, s22, 0xb1580
	s_addc_u32 s3, s23, 0
	v_readfirstlane_b32 s7, v158
	v_lshl_add_u64 v[152:153], v[64:65], 1, s[2:3]
	s_mov_b32 m0, s7
	v_lshl_add_u64 v[146:147], v[146:147], 1, s[2:3]
	v_readfirstlane_b32 s2, v159
	ds_read_b128 v[130:133], v157
	ds_read_b128 v[134:137], v157 offset:1024
	ds_read_b128 v[138:141], v157 offset:2048
	ds_read_b128 v[142:145], v157 offset:3072
	ds_read_b128 v[160:163], v151
	ds_read_b128 v[164:167], v151 offset:1024
	ds_read_b128 v[168:171], v150
	ds_read_b128 v[172:175], v150 offset:1024
	ds_read_b128 v[176:179], v149
	ds_read_b128 v[180:183], v149 offset:1024
	ds_read_b128 v[184:187], v148
	ds_read_b128 v[188:191], v148 offset:1024
	global_load_lds_dwordx4 v[152:153], off
	s_mov_b32 m0, s2
	s_nop 0
	global_load_lds_dwordx4 v[146:147], off
	s_barrier
	s_waitcnt lgkmcnt(0)
	s_waitcnt lgkmcnt(0)
	v_mfma_f32_16x16x32_bf16 v[0:3], v[130:133], v[160:163], v[0:3]
	v_mfma_f32_16x16x32_bf16 v[4:7], v[138:141], v[160:163], v[4:7]
	v_mfma_f32_16x16x32_bf16 v[16:19], v[130:133], v[168:171], v[16:19]
	v_mfma_f32_16x16x32_bf16 v[20:23], v[138:141], v[168:171], v[20:23]
	v_mfma_f32_16x16x32_bf16 v[32:35], v[130:133], v[176:179], v[32:35]
	v_mfma_f32_16x16x32_bf16 v[36:39], v[138:141], v[176:179], v[36:39]
	v_mfma_f32_16x16x32_bf16 v[48:51], v[130:133], v[184:187], v[48:51]
	v_mfma_f32_16x16x32_bf16 v[52:55], v[138:141], v[184:187], v[52:55]
	v_mfma_f32_16x16x32_bf16 v[0:3], v[134:137], v[164:167], v[0:3]
	v_mfma_f32_16x16x32_bf16 v[4:7], v[142:145], v[164:167], v[4:7]
	v_mfma_f32_16x16x32_bf16 v[16:19], v[134:137], v[172:175], v[16:19]
	v_mfma_f32_16x16x32_bf16 v[20:23], v[142:145], v[172:175], v[20:23]
	v_mfma_f32_16x16x32_bf16 v[32:35], v[134:137], v[180:183], v[32:35]
	v_mfma_f32_16x16x32_bf16 v[36:39], v[142:145], v[180:183], v[36:39]
	v_mfma_f32_16x16x32_bf16 v[48:51], v[134:137], v[188:191], v[48:51]
	v_mfma_f32_16x16x32_bf16 v[52:55], v[142:145], v[188:191], v[52:55]
	s_barrier
	ds_read_b128 v[192:195], v156
	ds_read_b128 v[196:199], v156 offset:1024
	ds_read_b128 v[200:203], v156 offset:2048
	ds_read_b128 v[156:159], v156 offset:3072
	s_barrier
	s_waitcnt lgkmcnt(0)
	s_waitcnt lgkmcnt(0)
	v_mfma_f32_16x16x32_bf16 v[8:11], v[192:195], v[160:163], v[8:11]
	v_mfma_f32_16x16x32_bf16 v[12:15], v[200:203], v[160:163], v[12:15]
	v_mfma_f32_16x16x32_bf16 v[24:27], v[192:195], v[168:171], v[24:27]
	v_mfma_f32_16x16x32_bf16 v[28:31], v[200:203], v[168:171], v[28:31]
	v_mfma_f32_16x16x32_bf16 v[40:43], v[192:195], v[176:179], v[40:43]
	v_mfma_f32_16x16x32_bf16 v[44:47], v[200:203], v[176:179], v[44:47]
	v_mfma_f32_16x16x32_bf16 v[56:59], v[192:195], v[184:187], v[56:59]
	v_mfma_f32_16x16x32_bf16 v[60:63], v[200:203], v[184:187], v[60:63]
	v_mfma_f32_16x16x32_bf16 v[8:11], v[196:199], v[164:167], v[8:11]
	v_mfma_f32_16x16x32_bf16 v[12:15], v[156:159], v[164:167], v[12:15]
	v_mfma_f32_16x16x32_bf16 v[24:27], v[196:199], v[172:175], v[24:27]
	v_mfma_f32_16x16x32_bf16 v[28:31], v[156:159], v[172:175], v[28:31]
	v_mfma_f32_16x16x32_bf16 v[40:43], v[196:199], v[180:183], v[40:43]
	v_mfma_f32_16x16x32_bf16 v[44:47], v[156:159], v[180:183], v[44:47]
	v_mfma_f32_16x16x32_bf16 v[56:59], v[196:199], v[188:191], v[56:59]
	v_mfma_f32_16x16x32_bf16 v[60:63], v[156:159], v[188:191], v[60:63]
	s_barrier
; #define LDA(dst, b, h) _Pragma("unroll") for (int m = 0; m < 4; ++m) _Pragma("unroll") for (int k = 0; k < 2; ++k) \
;     dst[m][k] = *(const bf16x8*)(lds + SA_(b, h) + lds_byte(wr * 64 + m * 16 + fr, k * 32 + fq * 8));
; #define LDB(dst, b, h) _Pragma("unroll") for (int n = 0; n < 2; ++n) _Pragma("unroll") for (int k = 0; k < 2; ++k) \
;     dst[n][k] = *(const bf16x8*)(lds + SB_(b, h) + lds_byte(wc * 32 + n * 16 + fr, k * 32 + fq * 8));
; #define MMA(ai, bj, At_, Bt_) { __builtin_amdgcn_s_setprio(1); \
;     _Pragma("unroll") for (int m = 0; m < 4; ++m) _Pragma("unroll") for (int n = 0; n < 2; ++n) _Pragma("unroll") for (int k = 0; k < 2; ++k) \
;       acc[ai][bj][m][n] = MFMA16(Bt_[n][k], At_[m][k], acc[ai][bj][m][n]); \
;     __builtin_amdgcn_s_setprio(0); }
; #define WAIT_V(n) asm volatile("s_waitcnt vmcnt(" #n ")" ::: "memory");
; #define WAIT_L(n) asm volatile("s_waitcnt lgkmcnt(" #n ")" ::: "memory");
; #define BAR __builtin_amdgcn_s_barrier();
; DI void gemm256(const u16* __restrict__ A, int lda, const u16* __restrict__ B0, const u16* __restrict__ B1, int ldb, int nt, acc_t& acc, char* lds) {
;     ...
;     LDA(At, 0, 1) WAIT_V(4) BAR WAIT_L(0) MMA(1, 0, At, Bq0) MMA(1, 1, At, Bq1) BAR }
;   { LDB(Bq0, 1, 0) LDA(At, 1, 0) WAIT_V(2) BAR WAIT_L(0) MMA(0, 0, At, Bq0) BAR
	ds_read_b128 v[160:163], v151 offset:16384
	ds_read_b128 v[164:167], v151 offset:17408
	ds_read_b128 v[168:171], v150 offset:16384
	ds_read_b128 v[172:175], v150 offset:17408
	ds_read_b128 v[176:179], v149 offset:16384
	ds_read_b128 v[180:183], v149 offset:17408
	ds_read_b128 v[184:187], v148 offset:16384
	ds_read_b128 v[188:191], v148 offset:17408
	s_waitcnt vmcnt(4)
	s_barrier
	s_waitcnt lgkmcnt(0)
	s_waitcnt lgkmcnt(0)
	v_mfma_f32_16x16x32_bf16 v[66:69], v[130:133], v[160:163], v[66:69]
	v_mfma_f32_16x16x32_bf16 v[204:207], v[134:137], v[164:167], v[66:69]
	v_mfma_f32_16x16x32_bf16 v[66:69], v[138:141], v[160:163], v[70:73]
	v_mfma_f32_16x16x32_bf16 v[208:211], v[142:145], v[164:167], v[66:69]
	v_mfma_f32_16x16x32_bf16 v[66:69], v[130:133], v[168:171], v[86:89]
	v_mfma_f32_16x16x32_bf16 v[216:219], v[134:137], v[172:175], v[66:69]
	v_mfma_f32_16x16x32_bf16 v[66:69], v[138:141], v[168:171], v[94:97]
	v_mfma_f32_16x16x32_bf16 v[226:229], v[142:145], v[172:175], v[66:69]
	v_mfma_f32_16x16x32_bf16 v[66:69], v[130:133], v[176:179], v[118:121]
	v_mfma_f32_16x16x32_bf16 v[230:233], v[134:137], v[180:183], v[66:69]
	v_mfma_f32_16x16x32_bf16 v[66:69], v[138:141], v[176:179], v[126:129]
	v_mfma_f32_16x16x32_bf16 v[234:237], v[142:145], v[180:183], v[66:69]
	v_mfma_f32_16x16x32_bf16 v[66:69], v[130:133], v[184:187], v[106:109]
	v_mfma_f32_16x16x32_bf16 v[134:137], v[134:137], v[188:191], v[66:69]
	v_mfma_f32_16x16x32_bf16 v[66:69], v[138:141], v[184:187], v[98:101]
	v_mfma_f32_16x16x32_bf16 v[138:141], v[142:145], v[188:191], v[66:69]
	v_mfma_f32_16x16x32_bf16 v[66:69], v[192:195], v[160:163], v[74:77]
	v_mfma_f32_16x16x32_bf16 v[142:145], v[196:199], v[164:167], v[66:69]
	v_mfma_f32_16x16x32_bf16 v[66:69], v[200:203], v[160:163], v[82:85]
	v_mfma_f32_16x16x32_bf16 v[160:163], v[156:159], v[164:167], v[66:69]
	v_mfma_f32_16x16x32_bf16 v[66:69], v[192:195], v[168:171], v[102:105]
	v_mfma_f32_16x16x32_bf16 v[164:167], v[196:199], v[172:175], v[66:69]
	v_mfma_f32_16x16x32_bf16 v[66:69], v[200:203], v[168:171], v[110:113]
	v_mfma_f32_16x16x32_bf16 v[168:171], v[156:159], v[172:175], v[66:69]
	v_mfma_f32_16x16x32_bf16 v[66:69], v[192:195], v[176:179], v[122:125]
	v_mfma_f32_16x16x32_bf16 v[122:125], v[196:199], v[180:183], v[66:69]
	v_mfma_f32_16x16x32_bf16 v[66:69], v[200:203], v[176:179], v[114:117]
	v_mfma_f32_16x16x32_bf16 v[172:175], v[156:159], v[180:183], v[66:69]
	v_mfma_f32_16x16x32_bf16 v[66:69], v[192:195], v[184:187], v[90:93]
	v_mfma_f32_16x16x32_bf16 v[176:179], v[196:199], v[188:191], v[66:69]
	v_mfma_f32_16x16x32_bf16 v[66:69], v[200:203], v[184:187], v[78:81]
	v_mfma_f32_16x16x32_bf16 v[156:159], v[156:159], v[188:191], v[66:69]
	s_barrier
	ds_read_b128 v[180:183], v155
	ds_read_b128 v[184:187], v155 offset:1024
	ds_read_b128 v[188:191], v155 offset:2048
	ds_read_b128 v[192:195], v155 offset:3072
	s_nop 0
	ds_read_b128 v[66:69], v151 offset:32768
	ds_read_b128 v[70:73], v151 offset:33792
	ds_read_b128 v[82:85], v150 offset:32768
	ds_read_b128 v[86:89], v150 offset:33792
	ds_read_b128 v[196:199], v149 offset:32768
	ds_read_b128 v[200:203], v149 offset:33792
	ds_read_b128 v[238:241], v148 offset:32768
	ds_read_b128 v[242:245], v148 offset:33792
	s_waitcnt vmcnt(2)
	s_barrier
	s_waitcnt lgkmcnt(0)
	s_waitcnt lgkmcnt(0)
	v_mfma_f32_16x16x32_bf16 v[0:3], v[180:183], v[66:69], v[0:3]
	v_mfma_f32_16x16x32_bf16 v[126:129], v[184:187], v[70:73], v[0:3]
	v_mfma_f32_16x16x32_bf16 v[0:3], v[188:191], v[66:69], v[4:7]
	v_mfma_f32_16x16x32_bf16 v[130:133], v[192:195], v[70:73], v[0:3]
	v_mfma_f32_16x16x32_bf16 v[0:3], v[180:183], v[82:85], v[16:19]
	v_mfma_f32_16x16x32_bf16 v[110:113], v[184:187], v[86:89], v[0:3]
	v_mfma_f32_16x16x32_bf16 v[0:3], v[188:191], v[82:85], v[20:23]
	v_mfma_f32_16x16x32_bf16 v[106:109], v[192:195], v[86:89], v[0:3]
	v_mfma_f32_16x16x32_bf16 v[0:3], v[180:183], v[196:199], v[32:35]
	v_mfma_f32_16x16x32_bf16 v[94:97], v[184:187], v[200:203], v[0:3]
	v_mfma_f32_16x16x32_bf16 v[0:3], v[188:191], v[196:199], v[36:39]
	v_mfma_f32_16x16x32_bf16 v[90:93], v[192:195], v[200:203], v[0:3]
	v_mfma_f32_16x16x32_bf16 v[0:3], v[180:183], v[238:241], v[48:51]
	v_mfma_f32_16x16x32_bf16 v[78:81], v[184:187], v[242:245], v[0:3]
	v_mfma_f32_16x16x32_bf16 v[0:3], v[188:191], v[238:241], v[52:55]
	v_mfma_f32_16x16x32_bf16 v[74:77], v[192:195], v[242:245], v[0:3]
	s_barrier
; #define LDA(dst, b, h) _Pragma("unroll") for (int m = 0; m < 4; ++m) _Pragma("unroll") for (int k = 0; k < 2; ++k) \
;     dst[m][k] = *(const bf16x8*)(lds + SA_(b, h) + lds_byte(wr * 64 + m * 16 + fr, k * 32 + fq * 8));
; #define LDB(dst, b, h) _Pragma("unroll") for (int n = 0; n < 2; ++n) _Pragma("unroll") for (int k = 0; k < 2; ++k) \
;     dst[n][k] = *(const bf16x8*)(lds + SB_(b, h) + lds_byte(wc * 32 + n * 16 + fr, k * 32 + fq * 8));
; #define MMA(ai, bj, At_, Bt_) { __builtin_amdgcn_s_setprio(1); \
;     _Pragma("unroll") for (int m = 0; m < 4; ++m) _Pragma("unroll") for (int n = 0; n < 2; ++n) _Pragma("unroll") for (int k = 0; k < 2; ++k) \
;       acc[ai][bj][m][n] = MFMA16(Bt_[n][k], At_[m][k], acc[ai][bj][m][n]); \
;     __builtin_amdgcn_s_setprio(0); }
; #define WAIT_V(n) asm volatile("s_waitcnt vmcnt(" #n ")" ::: "memory");
; #define WAIT_L(n) asm volatile("s_waitcnt lgkmcnt(" #n ")" ::: "memory");
; #define BAR __builtin_amdgcn_s_barrier();
; DI void gemm256(const u16* __restrict__ A, int lda, const u16* __restrict__ B0, const u16* __restrict__ B1, int ldb, int nt, acc_t& acc, char* lds) {
;     ...
;     LDB(Bq1, 1, 1) WAIT_V(0) BAR WAIT_L(0) MMA(0, 1, At, Bq1) BAR
;     LDA(At, 1, 1) BAR WAIT_L(0) MMA(1, 0, At, Bq0) MMA(1, 1, At, Bq1) BAR }
;   if (wr == 0) BAR
	s_nop 4
	ds_read_b128 v[0:3], v154
	ds_read_b128 v[4:7], v154 offset:1024
	ds_read_b128 v[246:249], v154 offset:2048
	ds_read_b128 v[152:155], v154 offset:3072
	s_waitcnt vmcnt(0)
	s_barrier
	s_waitcnt lgkmcnt(0)
	s_waitcnt lgkmcnt(0)
	v_mfma_f32_16x16x32_bf16 v[8:11], v[0:3], v[66:69], v[8:11]
	v_mfma_f32_16x16x32_bf16 v[118:121], v[4:7], v[70:73], v[8:11]
	v_mfma_f32_16x16x32_bf16 v[8:11], v[246:249], v[66:69], v[12:15]
	v_mfma_f32_16x16x32_bf16 v[114:117], v[152:155], v[70:73], v[8:11]
	v_mfma_f32_16x16x32_bf16 v[8:11], v[0:3], v[82:85], v[24:27]
	v_mfma_f32_16x16x32_bf16 v[102:105], v[4:7], v[86:89], v[8:11]
	v_mfma_f32_16x16x32_bf16 v[8:11], v[246:249], v[82:85], v[28:31]
	v_mfma_f32_16x16x32_bf16 v[98:101], v[152:155], v[86:89], v[8:11]
	v_mfma_f32_16x16x32_bf16 v[8:11], v[0:3], v[196:199], v[40:43]
	v_mfma_f32_16x16x32_bf16 v[86:89], v[4:7], v[200:203], v[8:11]
	v_mfma_f32_16x16x32_bf16 v[8:11], v[246:249], v[196:199], v[44:47]
	v_mfma_f32_16x16x32_bf16 v[82:85], v[152:155], v[200:203], v[8:11]
	v_mfma_f32_16x16x32_bf16 v[8:11], v[0:3], v[238:241], v[56:59]
	v_mfma_f32_16x16x32_bf16 v[70:73], v[4:7], v[242:245], v[8:11]
	v_mfma_f32_16x16x32_bf16 v[8:11], v[246:249], v[238:241], v[60:63]
	v_mfma_f32_16x16x32_bf16 v[66:69], v[152:155], v[242:245], v[8:11]
	s_barrier
	ds_read_b128 v[16:19], v151 offset:49152
	ds_read_b128 v[20:23], v151 offset:50176
	ds_read_b128 v[32:35], v150 offset:49152
	ds_read_b128 v[196:199], v150 offset:50176
	ds_read_b128 v[200:203], v149 offset:49152
	ds_read_b128 v[238:241], v149 offset:50176
	ds_read_b128 v[242:245], v148 offset:49152
	ds_read_b128 v[146:149], v148 offset:50176
	s_barrier
	s_waitcnt lgkmcnt(0)
	s_waitcnt lgkmcnt(0)
	v_mfma_f32_16x16x32_bf16 v[8:11], v[180:183], v[16:19], v[204:207]
	v_mfma_f32_16x16x32_bf16 v[60:63], v[184:187], v[20:23], v[8:11]
	v_mfma_f32_16x16x32_bf16 v[8:11], v[188:191], v[16:19], v[208:211]
	v_mfma_f32_16x16x32_bf16 v[56:59], v[192:195], v[20:23], v[8:11]
	v_mfma_f32_16x16x32_bf16 v[8:11], v[180:183], v[32:35], v[216:219]
	v_mfma_f32_16x16x32_bf16 v[44:47], v[184:187], v[196:199], v[8:11]
	v_mfma_f32_16x16x32_bf16 v[8:11], v[188:191], v[32:35], v[226:229]
	v_mfma_f32_16x16x32_bf16 v[40:43], v[192:195], v[196:199], v[8:11]
	v_mfma_f32_16x16x32_bf16 v[8:11], v[180:183], v[200:203], v[230:233]
	v_mfma_f32_16x16x32_bf16 v[28:31], v[184:187], v[238:241], v[8:11]
	v_mfma_f32_16x16x32_bf16 v[8:11], v[188:191], v[200:203], v[234:237]
	v_mfma_f32_16x16x32_bf16 v[24:27], v[192:195], v[238:241], v[8:11]
	v_mfma_f32_16x16x32_bf16 v[8:11], v[180:183], v[242:245], v[134:137]
	v_mfma_f32_16x16x32_bf16 v[12:15], v[184:187], v[146:149], v[8:11]
	v_mfma_f32_16x16x32_bf16 v[8:11], v[188:191], v[242:245], v[138:141]
	v_mfma_f32_16x16x32_bf16 v[8:11], v[192:195], v[146:149], v[8:11]
	v_mfma_f32_16x16x32_bf16 v[36:39], v[0:3], v[16:19], v[142:145]
	v_mfma_f32_16x16x32_bf16 v[16:19], v[246:249], v[16:19], v[160:163]
	v_mfma_f32_16x16x32_bf16 v[48:51], v[152:155], v[20:23], v[16:19]
	v_mfma_f32_16x16x32_bf16 v[16:19], v[0:3], v[32:35], v[164:167]
	v_mfma_f32_16x16x32_bf16 v[52:55], v[4:7], v[20:23], v[36:39]
	v_mfma_f32_16x16x32_bf16 v[36:39], v[4:7], v[196:199], v[16:19]
	v_mfma_f32_16x16x32_bf16 v[16:19], v[246:249], v[32:35], v[168:171]
	v_mfma_f32_16x16x32_bf16 v[32:35], v[152:155], v[196:199], v[16:19]
	v_mfma_f32_16x16x32_bf16 v[16:19], v[0:3], v[200:203], v[122:125]
	v_mfma_f32_16x16x32_bf16 v[0:3], v[0:3], v[242:245], v[176:179]
	v_mfma_f32_16x16x32_bf16 v[20:23], v[4:7], v[238:241], v[16:19]
	v_mfma_f32_16x16x32_bf16 v[16:19], v[246:249], v[200:203], v[172:175]
	v_mfma_f32_16x16x32_bf16 v[4:7], v[4:7], v[146:149], v[0:3]
	v_mfma_f32_16x16x32_bf16 v[0:3], v[246:249], v[242:245], v[156:159]
	v_mfma_f32_16x16x32_bf16 v[16:19], v[152:155], v[238:241], v[16:19]
	v_mfma_f32_16x16x32_bf16 v[0:3], v[152:155], v[146:149], v[0:3]
	s_movk_i32 s2, 0x100
	v_cmp_gt_u32_e32 vcc, s2, v225
	s_barrier
	s_and_saveexec_b64 s[8:9], vcc
	s_cbranch_execz .LBB0_1240
	s_barrier
	s_branch .LBB0_1240
